# LDS-DMA GEMM staging (FFN_GU, SSD_IN, QKV) with DMA issue moved behind first fragment reads; scan look-ahead + boundary prefetch; attention LDS pipelining; drop dead PREP phases
# speedup vs baseline: 1.0059x; 1.0059x over previous
; DEVI int TID() { int t = threadIdx.x; asm volatile("" : "+v"(t)); return t; }
;     ...
;   const int tid = TID(), lane = tid & 63, wave = tid >> 6, wm = wave >> 1, wn = wave & 1;
;   f32x16 acc[2][2];
; #pragma unroll
;   for (int i = 0; i < 2; ++i)
; #pragma unroll
;     for (int j = 0; j < 2; ++j) acc[i][j] = zero16();
;   const int lrow = tid >> 3, lkc = (tid & 7) * 8;
;   const bf16* Ag = jb.A + (size_t)max(m0 + lrow, 0) * jb.lda + lkc;
;   const bf16* Ag1 = jb.A + (ptrdiff_t)(m0 + lrow) * jb.lda + lkc;
;   const bf16* Bg = jb.Bt + (size_t)(n0 + lrow) * jb.K + lkc;
;   const size_t astep = (size_t)32 * jb.lda, bstep = (size_t)32 * jb.K;
;   if (kt1 < 0) kt1 = jb.K >> 6;
;   const int nk = kt1 - kt0;
;   Ag += (size_t)kt0 * 64; Ag1 += (size_t)kt0 * 64; Bg += (size_t)kt0 * 64;
;   u32x4 ra0[4], rb0[4], ra1[4], rb1[4];
;     ...
;   bf16* As1 = As + 2 * 128 * 72;
;   bf16* Bs1 = As1 + 128 * 72;
;   G_LOAD(ra0, rb0, 0);
;   if (nk > 1) G_LOAD(ra1, rb1, 1);
;   G_STORE(ra0, rb0, As, Bs);
;   __syncthreads();
.LBB0_1557:
	s_cmpk_gt_i32 s17, 0xc47
	s_cbranch_scc1 .LBB0_1814
	s_mul_hi_i32 s2, s17, 0x2aaaaaab
	s_lshr_b32 s3, s2, 31
	s_ashr_i32 s2, s2, 6
	s_add_i32 s2, s2, s3
	s_lshl_b32 s3, s2, 4
	s_sub_i32 s4, 0x83, s3
	s_min_u32 s4, s4, 16
	v_cvt_f32_ubyte0_e32 v0, s4
	v_rcp_iflag_f32_e32 v0, v0
	s_sub_i32 s7, 0, s4
	s_mulk_i32 s2, 0xfe80
	s_add_i32 s5, s17, s2
	v_mul_f32_e32 v0, 0x4f7ffffe, v0
	v_cvt_u32_f32_e32 v0, v0
	s_abs_i32 s6, s5
	s_ashr_i32 s2, s5, 31
	v_mov_b32_e32 v85, v208
	v_readfirstlane_b32 s8, v0
	s_mul_i32 s7, s7, s8
	s_mul_hi_u32 s7, s8, s7
	s_add_i32 s8, s8, s7
	s_mul_hi_u32 s7, s6, s8
	s_mul_i32 s8, s7, s4
	s_sub_i32 s6, s6, s8
	s_add_i32 s8, s7, 1
	s_sub_i32 s9, s6, s4
	s_cmp_ge_u32 s6, s4
	s_cselect_b32 s7, s8, s7
	s_cselect_b32 s6, s9, s6
	s_add_i32 s8, s7, 1
	s_cmp_ge_u32 s6, s4
	s_cselect_b32 s6, s8, s7
	s_xor_b32 s6, s6, s2
	s_sub_i32 s2, s6, s2
	s_mul_i32 s4, s2, s4
	s_sub_i32 s4, s5, s4
	s_add_i32 s3, s3, s4
	s_lshl_b32 s3, s3, 7
	s_lshl_b32 s4, s2, 7
	v_ashrrev_i32_e32 v82, 3, v85
	v_add_u32_e32 v0, s3, v82
	v_max_i32_e32 v96, 0, v0
	v_lshlrev_b32_e32 v1, 4, v85
	v_lshlrev_b64 v[2:3], 11, v[96:97]
	v_and_b32_e32 v96, 0x70, v1
	s_mov_b64 s[96:97], 0x80
	v_lshrrev_b32_e32 v178, 4, v208
	v_and_b32_e32 v178, 7, v178
	v_lshlrev_b32_e32 v178, 4, v178
	v_xor_b32_e32 v96, v96, v178
	v_lshrrev_b32_e32 v179, 6, v208
	v_lshlrev_b32_e32 v179, 10, v179
	v_lshrrev_b32_e32 v180, 5, v208
	v_lshrrev_b32_e32 v181, 1, v208
	v_xor_b32_e32 v180, v180, v181
	v_readfirstlane_b32 s94, v179
	v_and_b32_e32 v180, 1, v180
	v_lshlrev_b32_e32 v180, 4, v180
	v_and_b32_e32 v181, 31, v208
	v_lshlrev_b32_e32 v181, 7, v181
	v_or_b32_e32 v180, v180, v181
	v_lshrrev_b32_e32 v181, 7, v208
	v_lshlrev_b32_e32 v181, 13, v181
	v_or_b32_e32 v194, v180, v181
	v_bfe_u32 v181, v208, 6, 1
	v_lshlrev_b32_e32 v181, 13, v181
	v_or_b32_e32 v195, v180, v181
	v_bfe_u32 v178, v208, 2, 2
	v_xor_b32_e32 v179, 0, v178
	v_lshlrev_b32_e32 v179, 5, v179
	v_or_b32_e32 v170, v194, v179
	v_or_b32_e32 v174, v195, v179
	v_xor_b32_e32 v179, 1, v178
	v_lshlrev_b32_e32 v179, 5, v179
	v_or_b32_e32 v171, v194, v179
	v_or_b32_e32 v175, v195, v179
	v_xor_b32_e32 v179, 2, v178
	v_lshlrev_b32_e32 v179, 5, v179
	v_or_b32_e32 v172, v194, v179
	v_or_b32_e32 v176, v195, v179
	v_xor_b32_e32 v179, 3, v178
	v_lshlrev_b32_e32 v179, 5, v179
	v_or_b32_e32 v173, v194, v179
	v_or_b32_e32 v177, v195, v179
	v_ashrrev_i32_e32 v1, 31, v0
	v_lshlrev_b64 v[0:1], 11, v[0:1]
	v_lshl_add_u64 v[0:1], s[12:13], 0, v[0:1]
	v_lshl_add_u64 v[28:29], v[0:1], 0, v[96:97]
	v_add_u32_e32 v0, s4, v82
	v_ashrrev_i32_e32 v1, 31, v0
	v_lshlrev_b64 v[0:1], 11, v[0:1]
	v_lshl_add_u64 v[0:1], s[14:15], 0, v[0:1]
	v_add_co_u32_e32 v70, vcc, s63, v28
	v_lshl_add_u64 v[68:69], v[0:1], 0, v[96:97]
	s_nop 0
	v_addc_co_u32_e32 v71, vcc, 0, v29, vcc
	v_add_co_u32_e32 v72, vcc, s63, v68
	v_lshl_add_u64 v[2:3], s[12:13], 0, v[2:3]
	s_nop 0
	v_addc_co_u32_e32 v73, vcc, 0, v69, vcc
	v_add_co_u32_e32 v74, vcc, s64, v28
	v_lshl_add_u64 v[66:67], v[2:3], 0, v[96:97]
	s_nop 0
	v_addc_co_u32_e32 v75, vcc, 0, v29, vcc
	v_add_co_u32_e32 v76, vcc, s64, v68
	v_addc_co_u32_e32 v77, vcc, 0, v69, vcc
	v_add_co_u32_e32 v78, vcc, s65, v68
	s_nop 0
	v_addc_co_u32_e32 v79, vcc, 0, v69, vcc
	v_add_co_u32_e32 v80, vcc, s65, v28
	s_nop 0
	v_addc_co_u32_e32 v81, vcc, 0, v29, vcc
	v_ashrrev_i32_e32 v64, 1, v85
	v_and_b32_e32 v84, 31, v85
	v_lshrrev_b32_e32 v65, 1, v85
	v_and_b32_e32 v86, 0xffffffc0, v64
	v_and_b32_e32 v88, 16, v65
	v_or_b32_e32 v64, v86, v84
	v_mad_u64_u32 v[82:83], s[6:7], v82, s91, v[96:97]
	v_mad_u64_u32 v[64:65], s[6:7], v64, s91, v[88:89]
	v_add_u32_e32 v83, 0xd800, v82
	s_ashr_i32 s5, s2, 3
	s_and_b32 s2, s4, 0x380
	s_mov_b64 s[22:23], s[74:75]
	s_mov_b64 s[6:7], 0x1e05c060
	s_add_u32 m0, s94, 0x4000
	s_nop 1
	global_load_lds_dwordx4 v[68:69], off
	s_add_u32 m0, s94, 0x0
	s_nop 1
	global_load_lds_dwordx4 v[66:67], off
	s_add_u32 m0, s94, 0x5000
	s_nop 1
	global_load_lds_dwordx4 v[72:73], off
	s_add_u32 m0, s94, 0x6000
	s_nop 1
	global_load_lds_dwordx4 v[76:77], off
	s_add_u32 m0, s94, 0x7000
	s_nop 1
	global_load_lds_dwordx4 v[78:79], off
	s_add_u32 m0, s94, 0x1000
	s_nop 1
	global_load_lds_dwordx4 v[70:71], off
	s_add_u32 m0, s94, 0x2000
	s_nop 1
	global_load_lds_dwordx4 v[74:75], off
	s_add_u32 m0, s94, 0x3000
	s_nop 1
	global_load_lds_dwordx4 v[80:81], off
	s_waitcnt lgkmcnt(0)
	s_waitcnt vmcnt(0)
	s_barrier
;     ...
;   bf16* As1 = As + 2 * 128 * 72;
;   bf16* Bs1 = As1 + 128 * 72;
;   G_LOAD(ra0, rb0, 0);
;   if (nk > 1) G_LOAD(ra1, rb1, 1);
;   G_STORE(ra0, rb0, As, Bs);
;   __syncthreads();
;   for (int kt = 0; kt < nk; kt += 2) {
;     if (kt + 2 < nk) G_LOAD(ra0, rb0, kt + 2);
;     if (kt + 1 < nk) G_STORE(ra1, rb1, As1, Bs1);
;     G_COMPUTE(As, Bs);
;     __syncthreads();
;     if (kt + 1 < nk) {
;       if (kt + 3 < nk) G_LOAD(ra1, rb1, kt + 3);
;       if (kt + 2 < nk) G_STORE(ra0, rb0, As, Bs);
;       G_COMPUTE(As1, Bs1);
;       __syncthreads();
;     }
;   }
	ds_read_b128 v[0:3], v170 offset:0
	v_and_b32_e32 v4, 0x5f, v85
	v_mad_u32_u24 v65, v4, s91, v88
	ds_read_b128 v[4:7], v174 offset:16384
	ds_read_b128 v[88:91], v171 offset:0
	ds_read_b128 v[92:95], v175 offset:16384
	ds_read_b128 v[16:19], v174 offset:20480
	ds_read_b128 v[98:101], v175 offset:20480
	v_lshl_add_u64 v[66:67], v[66:67], 0, s[96:97]
	s_add_u32 m0, s94, 0x8000
	s_nop 1
	global_load_lds_dwordx4 v[66:67], off
	v_lshl_add_u64 v[68:69], v[68:69], 0, s[96:97]
	s_add_u32 m0, s94, 0xc000
	s_nop 1
	global_load_lds_dwordx4 v[68:69], off
	v_lshl_add_u64 v[70:71], v[70:71], 0, s[96:97]
	s_add_u32 m0, s94, 0x9000
	s_nop 1
	global_load_lds_dwordx4 v[70:71], off
	v_lshl_add_u64 v[72:73], v[72:73], 0, s[96:97]
	s_add_u32 m0, s94, 0xd000
	s_nop 1
	global_load_lds_dwordx4 v[72:73], off
	v_lshl_add_u64 v[74:75], v[74:75], 0, s[96:97]
	s_add_u32 m0, s94, 0xa000
	s_nop 1
	global_load_lds_dwordx4 v[74:75], off
	v_lshl_add_u64 v[76:77], v[76:77], 0, s[96:97]
	s_add_u32 m0, s94, 0xe000
	s_nop 1
	global_load_lds_dwordx4 v[76:77], off
	v_lshl_add_u64 v[80:81], v[80:81], 0, s[96:97]
	s_add_u32 m0, s94, 0xb000
	s_nop 1
	global_load_lds_dwordx4 v[80:81], off
	v_lshl_add_u64 v[78:79], v[78:79], 0, s[96:97]
	s_add_u32 m0, s94, 0xf000
	s_nop 1
	global_load_lds_dwordx4 v[78:79], off
	s_waitcnt lgkmcnt(4)
	v_mfma_f32_32x32x16_bf16 v[32:47], v[0:3], v[4:7], 0
	ds_read_b128 v[20:23], v170 offset:4096
	ds_read_b128 v[102:105], v171 offset:4096
	s_waitcnt lgkmcnt(3)
	v_mfma_f32_32x32x16_bf16 v[48:63], v[0:3], v[16:19], 0
	s_waitcnt lgkmcnt(1)
	v_mfma_f32_32x32x16_bf16 v[0:15], v[20:23], v[4:7], 0
	v_mfma_f32_32x32x16_bf16 v[16:31], v[20:23], v[16:19], 0
	v_mfma_f32_32x32x16_bf16 v[32:47], v[88:91], v[92:95], v[32:47]
	v_mfma_f32_32x32x16_bf16 v[48:63], v[88:91], v[98:101], v[48:63]
	s_waitcnt lgkmcnt(0)
	v_mfma_f32_32x32x16_bf16 v[0:15], v[102:105], v[92:95], v[0:15]
	v_mfma_f32_32x32x16_bf16 v[16:31], v[102:105], v[98:101], v[16:31]
	ds_read_b128 v[88:91], v172 offset:0
	ds_read_b128 v[92:95], v176 offset:16384
	ds_read_b128 v[98:101], v173 offset:0
	ds_read_b128 v[102:105], v177 offset:16384
	ds_read_b128 v[106:109], v176 offset:20480
	ds_read_b128 v[110:113], v177 offset:20480
	s_waitcnt lgkmcnt(4)
	v_mfma_f32_32x32x16_bf16 v[32:47], v[88:91], v[92:95], v[32:47]
	s_waitcnt lgkmcnt(1)
	v_mfma_f32_32x32x16_bf16 v[48:63], v[88:91], v[106:109], v[48:63]
	ds_read_b128 v[88:91], v172 offset:4096
	ds_read_b128 v[114:117], v173 offset:4096
	s_waitcnt lgkmcnt(1)
	v_mfma_f32_32x32x16_bf16 v[0:15], v[88:91], v[92:95], v[0:15]
	v_mfma_f32_32x32x16_bf16 v[16:31], v[88:91], v[106:109], v[16:31]
	v_mfma_f32_32x32x16_bf16 v[32:47], v[98:101], v[102:105], v[32:47]
	v_mfma_f32_32x32x16_bf16 v[48:63], v[98:101], v[110:113], v[48:63]
	s_waitcnt lgkmcnt(0)
	v_mfma_f32_32x32x16_bf16 v[0:15], v[114:117], v[102:105], v[0:15]
	s_waitcnt vmcnt(0)
	s_barrier
	v_mfma_f32_32x32x16_bf16 v[16:31], v[114:117], v[110:113], v[16:31]
	ds_read_b128 v[88:91], v170 offset:32768
	ds_read_b128 v[92:95], v174 offset:49152
	ds_read_b128 v[98:101], v171 offset:32768
	ds_read_b128 v[102:105], v175 offset:49152
	ds_read_b128 v[106:109], v174 offset:53248
	ds_read_b128 v[110:113], v175 offset:53248
	v_lshl_add_u64 v[66:67], v[66:67], 0, s[96:97]
	s_add_u32 m0, s94, 0x0
	s_nop 1
	global_load_lds_dwordx4 v[66:67], off
	v_lshl_add_u64 v[68:69], v[68:69], 0, s[96:97]
	s_add_u32 m0, s94, 0x4000
	s_nop 1
	global_load_lds_dwordx4 v[68:69], off
	v_lshl_add_u64 v[70:71], v[70:71], 0, s[96:97]
	s_add_u32 m0, s94, 0x1000
	s_nop 1
	global_load_lds_dwordx4 v[70:71], off
	v_lshl_add_u64 v[72:73], v[72:73], 0, s[96:97]
	s_add_u32 m0, s94, 0x5000
	s_nop 1
	global_load_lds_dwordx4 v[72:73], off
	v_lshl_add_u64 v[74:75], v[74:75], 0, s[96:97]
	s_add_u32 m0, s94, 0x2000
	s_nop 1
	global_load_lds_dwordx4 v[74:75], off
	v_lshl_add_u64 v[76:77], v[76:77], 0, s[96:97]
	s_add_u32 m0, s94, 0x6000
	s_nop 1
	global_load_lds_dwordx4 v[76:77], off
	v_lshl_add_u64 v[80:81], v[80:81], 0, s[96:97]
	s_add_u32 m0, s94, 0x3000
	s_nop 1
	global_load_lds_dwordx4 v[80:81], off
	v_lshl_add_u64 v[78:79], v[78:79], 0, s[96:97]
	s_add_u32 m0, s94, 0x7000
	s_nop 1
	global_load_lds_dwordx4 v[78:79], off
	s_waitcnt lgkmcnt(4)
	v_mfma_f32_32x32x16_bf16 v[32:47], v[88:91], v[92:95], v[32:47]
	s_waitcnt lgkmcnt(1)
	v_mfma_f32_32x32x16_bf16 v[48:63], v[88:91], v[106:109], v[48:63]
	ds_read_b128 v[88:91], v170 offset:36864
	ds_read_b128 v[114:117], v171 offset:36864
	s_waitcnt lgkmcnt(1)
	v_mfma_f32_32x32x16_bf16 v[0:15], v[88:91], v[92:95], v[0:15]
	v_mfma_f32_32x32x16_bf16 v[16:31], v[88:91], v[106:109], v[16:31]
	v_mfma_f32_32x32x16_bf16 v[32:47], v[98:101], v[102:105], v[32:47]
	v_mfma_f32_32x32x16_bf16 v[48:63], v[98:101], v[110:113], v[48:63]
	s_waitcnt lgkmcnt(0)
	v_mfma_f32_32x32x16_bf16 v[0:15], v[114:117], v[102:105], v[0:15]
	ds_read_b128 v[88:91], v172 offset:32768
	ds_read_b128 v[92:95], v176 offset:49152
	ds_read_b128 v[98:101], v173 offset:32768
	ds_read_b128 v[102:105], v177 offset:49152
	v_mfma_f32_32x32x16_bf16 v[16:31], v[114:117], v[110:113], v[16:31]
	ds_read_b128 v[106:109], v176 offset:53248
	ds_read_b128 v[110:113], v177 offset:53248
	s_waitcnt lgkmcnt(4)
	v_mfma_f32_32x32x16_bf16 v[32:47], v[88:91], v[92:95], v[32:47]
	s_waitcnt lgkmcnt(1)
	v_mfma_f32_32x32x16_bf16 v[48:63], v[88:91], v[106:109], v[48:63]
	ds_read_b128 v[88:91], v172 offset:36864
	ds_read_b128 v[114:117], v173 offset:36864
	s_waitcnt lgkmcnt(1)
	v_mfma_f32_32x32x16_bf16 v[0:15], v[88:91], v[92:95], v[0:15]
	v_mfma_f32_32x32x16_bf16 v[16:31], v[88:91], v[106:109], v[16:31]
	v_mfma_f32_32x32x16_bf16 v[32:47], v[98:101], v[102:105], v[32:47]
	v_mfma_f32_32x32x16_bf16 v[48:63], v[98:101], v[110:113], v[48:63]
	s_waitcnt lgkmcnt(0)
	v_mfma_f32_32x32x16_bf16 v[0:15], v[114:117], v[102:105], v[0:15]
	s_waitcnt vmcnt(0)
	s_barrier
;     ...
;   bf16* As1 = As + 2 * 128 * 72;
;   bf16* Bs1 = As1 + 128 * 72;
;   G_LOAD(ra0, rb0, 0);
;   if (nk > 1) G_LOAD(ra1, rb1, 1);
;   G_STORE(ra0, rb0, As, Bs);
;   __syncthreads();
;   for (int kt = 0; kt < nk; kt += 2) {
;     if (kt + 2 < nk) G_LOAD(ra0, rb0, kt + 2);
;     if (kt + 1 < nk) G_STORE(ra1, rb1, As1, Bs1);
;     G_COMPUTE(As, Bs);
;     __syncthreads();
;     if (kt + 1 < nk) {
;       if (kt + 3 < nk) G_LOAD(ra1, rb1, kt + 3);
;       if (kt + 2 < nk) G_STORE(ra0, rb0, As, Bs);
;       G_COMPUTE(As1, Bs1);
;       __syncthreads();
;     }
;   }
	v_mfma_f32_32x32x16_bf16 v[16:31], v[114:117], v[110:113], v[16:31]
	ds_read_b128 v[88:91], v170 offset:0
	ds_read_b128 v[92:95], v174 offset:16384
	ds_read_b128 v[98:101], v171 offset:0
	ds_read_b128 v[102:105], v175 offset:16384
	ds_read_b128 v[106:109], v174 offset:20480
	ds_read_b128 v[110:113], v175 offset:20480
	v_lshl_add_u64 v[66:67], v[66:67], 0, s[96:97]
	s_add_u32 m0, s94, 0x8000
	s_nop 1
	global_load_lds_dwordx4 v[66:67], off
	v_lshl_add_u64 v[68:69], v[68:69], 0, s[96:97]
	s_add_u32 m0, s94, 0xc000
	s_nop 1
	global_load_lds_dwordx4 v[68:69], off
	v_lshl_add_u64 v[70:71], v[70:71], 0, s[96:97]
	s_add_u32 m0, s94, 0x9000
	s_nop 1
	global_load_lds_dwordx4 v[70:71], off
	v_lshl_add_u64 v[72:73], v[72:73], 0, s[96:97]
	s_add_u32 m0, s94, 0xd000
	s_nop 1
	global_load_lds_dwordx4 v[72:73], off
	v_lshl_add_u64 v[74:75], v[74:75], 0, s[96:97]
	s_add_u32 m0, s94, 0xa000
	s_nop 1
	global_load_lds_dwordx4 v[74:75], off
	v_lshl_add_u64 v[76:77], v[76:77], 0, s[96:97]
	s_add_u32 m0, s94, 0xe000
	s_nop 1
	global_load_lds_dwordx4 v[76:77], off
	v_lshl_add_u64 v[80:81], v[80:81], 0, s[96:97]
	s_add_u32 m0, s94, 0xb000
	s_nop 1
	global_load_lds_dwordx4 v[80:81], off
	v_lshl_add_u64 v[78:79], v[78:79], 0, s[96:97]
	s_add_u32 m0, s94, 0xf000
	s_nop 1
	global_load_lds_dwordx4 v[78:79], off
	s_waitcnt lgkmcnt(4)
	v_mfma_f32_32x32x16_bf16 v[32:47], v[88:91], v[92:95], v[32:47]
	s_waitcnt lgkmcnt(1)
	v_mfma_f32_32x32x16_bf16 v[48:63], v[88:91], v[106:109], v[48:63]
	ds_read_b128 v[88:91], v170 offset:4096
	ds_read_b128 v[114:117], v171 offset:4096
	s_waitcnt lgkmcnt(1)
	v_mfma_f32_32x32x16_bf16 v[0:15], v[88:91], v[92:95], v[0:15]
	v_mfma_f32_32x32x16_bf16 v[16:31], v[88:91], v[106:109], v[16:31]
	v_mfma_f32_32x32x16_bf16 v[32:47], v[98:101], v[102:105], v[32:47]
	v_mfma_f32_32x32x16_bf16 v[48:63], v[98:101], v[110:113], v[48:63]
	s_waitcnt lgkmcnt(0)
	v_mfma_f32_32x32x16_bf16 v[0:15], v[114:117], v[102:105], v[0:15]
	ds_read_b128 v[88:91], v172 offset:0
	ds_read_b128 v[92:95], v176 offset:16384
	ds_read_b128 v[98:101], v173 offset:0
	ds_read_b128 v[102:105], v177 offset:16384
	v_mfma_f32_32x32x16_bf16 v[16:31], v[114:117], v[110:113], v[16:31]
	ds_read_b128 v[106:109], v176 offset:20480
	ds_read_b128 v[110:113], v177 offset:20480
	s_waitcnt lgkmcnt(4)
	v_mfma_f32_32x32x16_bf16 v[32:47], v[88:91], v[92:95], v[32:47]
	s_waitcnt lgkmcnt(1)
	v_mfma_f32_32x32x16_bf16 v[48:63], v[88:91], v[106:109], v[48:63]
	ds_read_b128 v[88:91], v172 offset:4096
	ds_read_b128 v[114:117], v173 offset:4096
	s_waitcnt lgkmcnt(1)
	v_mfma_f32_32x32x16_bf16 v[0:15], v[88:91], v[92:95], v[0:15]
	v_mfma_f32_32x32x16_bf16 v[16:31], v[88:91], v[106:109], v[16:31]
	v_mfma_f32_32x32x16_bf16 v[32:47], v[98:101], v[102:105], v[32:47]
	v_mfma_f32_32x32x16_bf16 v[48:63], v[98:101], v[110:113], v[48:63]
	s_waitcnt lgkmcnt(0)
	v_mfma_f32_32x32x16_bf16 v[0:15], v[114:117], v[102:105], v[0:15]
	s_waitcnt vmcnt(0)
	s_barrier
	v_mfma_f32_32x32x16_bf16 v[16:31], v[114:117], v[110:113], v[16:31]
	ds_read_b128 v[88:91], v170 offset:32768
	ds_read_b128 v[92:95], v174 offset:49152
	ds_read_b128 v[98:101], v171 offset:32768
	ds_read_b128 v[102:105], v175 offset:49152
	ds_read_b128 v[106:109], v174 offset:53248
	ds_read_b128 v[110:113], v175 offset:53248
	v_lshl_add_u64 v[66:67], v[66:67], 0, s[96:97]
	s_add_u32 m0, s94, 0x0
	s_nop 1
	global_load_lds_dwordx4 v[66:67], off
	v_lshl_add_u64 v[68:69], v[68:69], 0, s[96:97]
	s_add_u32 m0, s94, 0x4000
	s_nop 1
	global_load_lds_dwordx4 v[68:69], off
	v_lshl_add_u64 v[70:71], v[70:71], 0, s[96:97]
	s_add_u32 m0, s94, 0x1000
	s_nop 1
	global_load_lds_dwordx4 v[70:71], off
	v_lshl_add_u64 v[72:73], v[72:73], 0, s[96:97]
	s_add_u32 m0, s94, 0x5000
	s_nop 1
	global_load_lds_dwordx4 v[72:73], off
	v_lshl_add_u64 v[74:75], v[74:75], 0, s[96:97]
	s_add_u32 m0, s94, 0x2000
	s_nop 1
	global_load_lds_dwordx4 v[74:75], off
	v_lshl_add_u64 v[76:77], v[76:77], 0, s[96:97]
	s_add_u32 m0, s94, 0x6000
	s_nop 1
	global_load_lds_dwordx4 v[76:77], off
	v_lshl_add_u64 v[80:81], v[80:81], 0, s[96:97]
	s_add_u32 m0, s94, 0x3000
	s_nop 1
	global_load_lds_dwordx4 v[80:81], off
	v_lshl_add_u64 v[78:79], v[78:79], 0, s[96:97]
	s_add_u32 m0, s94, 0x7000
	s_nop 1
	global_load_lds_dwordx4 v[78:79], off
	s_waitcnt lgkmcnt(4)
	v_mfma_f32_32x32x16_bf16 v[32:47], v[88:91], v[92:95], v[32:47]
	s_waitcnt lgkmcnt(1)
	v_mfma_f32_32x32x16_bf16 v[48:63], v[88:91], v[106:109], v[48:63]
	ds_read_b128 v[88:91], v170 offset:36864
	ds_read_b128 v[114:117], v171 offset:36864
	s_waitcnt lgkmcnt(1)
	v_mfma_f32_32x32x16_bf16 v[0:15], v[88:91], v[92:95], v[0:15]
	v_mfma_f32_32x32x16_bf16 v[16:31], v[88:91], v[106:109], v[16:31]
	v_mfma_f32_32x32x16_bf16 v[32:47], v[98:101], v[102:105], v[32:47]
	v_mfma_f32_32x32x16_bf16 v[48:63], v[98:101], v[110:113], v[48:63]
	s_waitcnt lgkmcnt(0)
	v_mfma_f32_32x32x16_bf16 v[0:15], v[114:117], v[102:105], v[0:15]
	ds_read_b128 v[88:91], v172 offset:32768
	ds_read_b128 v[92:95], v176 offset:49152
	ds_read_b128 v[98:101], v173 offset:32768
	ds_read_b128 v[102:105], v177 offset:49152
	v_mfma_f32_32x32x16_bf16 v[16:31], v[114:117], v[110:113], v[16:31]
	ds_read_b128 v[106:109], v176 offset:53248
	ds_read_b128 v[110:113], v177 offset:53248
	s_waitcnt lgkmcnt(4)
	v_mfma_f32_32x32x16_bf16 v[32:47], v[88:91], v[92:95], v[32:47]
	s_waitcnt lgkmcnt(1)
	v_mfma_f32_32x32x16_bf16 v[48:63], v[88:91], v[106:109], v[48:63]
	ds_read_b128 v[88:91], v172 offset:36864
	ds_read_b128 v[114:117], v173 offset:36864
	s_waitcnt lgkmcnt(1)
	v_mfma_f32_32x32x16_bf16 v[0:15], v[88:91], v[92:95], v[0:15]
	v_mfma_f32_32x32x16_bf16 v[16:31], v[88:91], v[106:109], v[16:31]
	v_mfma_f32_32x32x16_bf16 v[32:47], v[98:101], v[102:105], v[32:47]
	v_mfma_f32_32x32x16_bf16 v[48:63], v[98:101], v[110:113], v[48:63]
	s_waitcnt lgkmcnt(0)
	v_mfma_f32_32x32x16_bf16 v[0:15], v[114:117], v[102:105], v[0:15]
	s_waitcnt vmcnt(0)
	s_barrier
;     ...
;   bf16* As1 = As + 2 * 128 * 72;
;   bf16* Bs1 = As1 + 128 * 72;
;   G_LOAD(ra0, rb0, 0);
;   if (nk > 1) G_LOAD(ra1, rb1, 1);
;   G_STORE(ra0, rb0, As, Bs);
;   __syncthreads();
;   for (int kt = 0; kt < nk; kt += 2) {
;     if (kt + 2 < nk) G_LOAD(ra0, rb0, kt + 2);
;     if (kt + 1 < nk) G_STORE(ra1, rb1, As1, Bs1);
;     G_COMPUTE(As, Bs);
;     __syncthreads();
;     if (kt + 1 < nk) {
;       if (kt + 3 < nk) G_LOAD(ra1, rb1, kt + 3);
;       if (kt + 2 < nk) G_STORE(ra0, rb0, As, Bs);
;       G_COMPUTE(As1, Bs1);
;       __syncthreads();
;     }
;   }
	v_mfma_f32_32x32x16_bf16 v[16:31], v[114:117], v[110:113], v[16:31]
	ds_read_b128 v[88:91], v170 offset:0
	ds_read_b128 v[92:95], v174 offset:16384
	ds_read_b128 v[98:101], v171 offset:0
	ds_read_b128 v[102:105], v175 offset:16384
	ds_read_b128 v[106:109], v174 offset:20480
	ds_read_b128 v[110:113], v175 offset:20480
	v_lshl_add_u64 v[66:67], v[66:67], 0, s[96:97]
	s_add_u32 m0, s94, 0x8000
	s_nop 1
	global_load_lds_dwordx4 v[66:67], off
	v_lshl_add_u64 v[68:69], v[68:69], 0, s[96:97]
	s_add_u32 m0, s94, 0xc000
	s_nop 1
	global_load_lds_dwordx4 v[68:69], off
	v_lshl_add_u64 v[70:71], v[70:71], 0, s[96:97]
	s_add_u32 m0, s94, 0x9000
	s_nop 1
	global_load_lds_dwordx4 v[70:71], off
	v_lshl_add_u64 v[72:73], v[72:73], 0, s[96:97]
	s_add_u32 m0, s94, 0xd000
	s_nop 1
	global_load_lds_dwordx4 v[72:73], off
	v_lshl_add_u64 v[74:75], v[74:75], 0, s[96:97]
	s_add_u32 m0, s94, 0xa000
	s_nop 1
	global_load_lds_dwordx4 v[74:75], off
	v_lshl_add_u64 v[76:77], v[76:77], 0, s[96:97]
	s_add_u32 m0, s94, 0xe000
	s_nop 1
	global_load_lds_dwordx4 v[76:77], off
	v_lshl_add_u64 v[80:81], v[80:81], 0, s[96:97]
	s_add_u32 m0, s94, 0xb000
	s_nop 1
	global_load_lds_dwordx4 v[80:81], off
	v_lshl_add_u64 v[78:79], v[78:79], 0, s[96:97]
	s_add_u32 m0, s94, 0xf000
	s_nop 1
	global_load_lds_dwordx4 v[78:79], off
	s_waitcnt lgkmcnt(4)
	v_mfma_f32_32x32x16_bf16 v[32:47], v[88:91], v[92:95], v[32:47]
	s_waitcnt lgkmcnt(1)
	v_mfma_f32_32x32x16_bf16 v[48:63], v[88:91], v[106:109], v[48:63]
	ds_read_b128 v[88:91], v170 offset:4096
	ds_read_b128 v[114:117], v171 offset:4096
	s_waitcnt lgkmcnt(1)
	v_mfma_f32_32x32x16_bf16 v[0:15], v[88:91], v[92:95], v[0:15]
	v_mfma_f32_32x32x16_bf16 v[16:31], v[88:91], v[106:109], v[16:31]
	v_mfma_f32_32x32x16_bf16 v[32:47], v[98:101], v[102:105], v[32:47]
	v_mfma_f32_32x32x16_bf16 v[48:63], v[98:101], v[110:113], v[48:63]
	s_waitcnt lgkmcnt(0)
	v_mfma_f32_32x32x16_bf16 v[0:15], v[114:117], v[102:105], v[0:15]
	ds_read_b128 v[88:91], v172 offset:0
	ds_read_b128 v[92:95], v176 offset:16384
	ds_read_b128 v[98:101], v173 offset:0
	ds_read_b128 v[102:105], v177 offset:16384
	v_mfma_f32_32x32x16_bf16 v[16:31], v[114:117], v[110:113], v[16:31]
	ds_read_b128 v[106:109], v176 offset:20480
	ds_read_b128 v[110:113], v177 offset:20480
	s_waitcnt lgkmcnt(4)
	v_mfma_f32_32x32x16_bf16 v[32:47], v[88:91], v[92:95], v[32:47]
	s_waitcnt lgkmcnt(1)
	v_mfma_f32_32x32x16_bf16 v[48:63], v[88:91], v[106:109], v[48:63]
	ds_read_b128 v[88:91], v172 offset:4096
	ds_read_b128 v[114:117], v173 offset:4096
	s_waitcnt lgkmcnt(1)
	v_mfma_f32_32x32x16_bf16 v[0:15], v[88:91], v[92:95], v[0:15]
	v_mfma_f32_32x32x16_bf16 v[16:31], v[88:91], v[106:109], v[16:31]
	v_mfma_f32_32x32x16_bf16 v[32:47], v[98:101], v[102:105], v[32:47]
	v_mfma_f32_32x32x16_bf16 v[48:63], v[98:101], v[110:113], v[48:63]
	s_waitcnt lgkmcnt(0)
	v_mfma_f32_32x32x16_bf16 v[0:15], v[114:117], v[102:105], v[0:15]
	s_waitcnt vmcnt(0)
	s_barrier
	v_mfma_f32_32x32x16_bf16 v[16:31], v[114:117], v[110:113], v[16:31]
	ds_read_b128 v[88:91], v170 offset:32768
	ds_read_b128 v[92:95], v174 offset:49152
	ds_read_b128 v[98:101], v171 offset:32768
	ds_read_b128 v[102:105], v175 offset:49152
	ds_read_b128 v[106:109], v174 offset:53248
	ds_read_b128 v[110:113], v175 offset:53248
	v_lshl_add_u64 v[66:67], v[66:67], 0, s[96:97]
	s_add_u32 m0, s94, 0x0
	s_nop 1
	global_load_lds_dwordx4 v[66:67], off
	v_lshl_add_u64 v[68:69], v[68:69], 0, s[96:97]
	s_add_u32 m0, s94, 0x4000
	s_nop 1
	global_load_lds_dwordx4 v[68:69], off
	v_lshl_add_u64 v[70:71], v[70:71], 0, s[96:97]
	s_add_u32 m0, s94, 0x1000
	s_nop 1
	global_load_lds_dwordx4 v[70:71], off
	v_lshl_add_u64 v[72:73], v[72:73], 0, s[96:97]
	s_add_u32 m0, s94, 0x5000
	s_nop 1
	global_load_lds_dwordx4 v[72:73], off
	v_lshl_add_u64 v[74:75], v[74:75], 0, s[96:97]
	s_add_u32 m0, s94, 0x2000
	s_nop 1
	global_load_lds_dwordx4 v[74:75], off
	v_lshl_add_u64 v[76:77], v[76:77], 0, s[96:97]
	s_add_u32 m0, s94, 0x6000
	s_nop 1
	global_load_lds_dwordx4 v[76:77], off
	v_lshl_add_u64 v[80:81], v[80:81], 0, s[96:97]
	s_add_u32 m0, s94, 0x3000
	s_nop 1
	global_load_lds_dwordx4 v[80:81], off
	v_lshl_add_u64 v[78:79], v[78:79], 0, s[96:97]
	s_add_u32 m0, s94, 0x7000
	s_nop 1
	global_load_lds_dwordx4 v[78:79], off
	s_waitcnt lgkmcnt(4)
	v_mfma_f32_32x32x16_bf16 v[32:47], v[88:91], v[92:95], v[32:47]
	s_waitcnt lgkmcnt(1)
	v_mfma_f32_32x32x16_bf16 v[48:63], v[88:91], v[106:109], v[48:63]
	ds_read_b128 v[88:91], v170 offset:36864
	ds_read_b128 v[114:117], v171 offset:36864
	s_waitcnt lgkmcnt(1)
	v_mfma_f32_32x32x16_bf16 v[0:15], v[88:91], v[92:95], v[0:15]
	v_mfma_f32_32x32x16_bf16 v[16:31], v[88:91], v[106:109], v[16:31]
	v_mfma_f32_32x32x16_bf16 v[32:47], v[98:101], v[102:105], v[32:47]
	v_mfma_f32_32x32x16_bf16 v[48:63], v[98:101], v[110:113], v[48:63]
	s_waitcnt lgkmcnt(0)
	v_mfma_f32_32x32x16_bf16 v[0:15], v[114:117], v[102:105], v[0:15]
	ds_read_b128 v[88:91], v172 offset:32768
	ds_read_b128 v[92:95], v176 offset:49152
	ds_read_b128 v[98:101], v173 offset:32768
	ds_read_b128 v[102:105], v177 offset:49152
	v_mfma_f32_32x32x16_bf16 v[16:31], v[114:117], v[110:113], v[16:31]
	ds_read_b128 v[106:109], v176 offset:53248
	ds_read_b128 v[110:113], v177 offset:53248
	s_waitcnt lgkmcnt(4)
	v_mfma_f32_32x32x16_bf16 v[32:47], v[88:91], v[92:95], v[32:47]
	s_waitcnt lgkmcnt(1)
	v_mfma_f32_32x32x16_bf16 v[48:63], v[88:91], v[106:109], v[48:63]
	ds_read_b128 v[88:91], v172 offset:36864
	ds_read_b128 v[114:117], v173 offset:36864
	s_waitcnt lgkmcnt(1)
	v_mfma_f32_32x32x16_bf16 v[0:15], v[88:91], v[92:95], v[0:15]
	v_mfma_f32_32x32x16_bf16 v[16:31], v[88:91], v[106:109], v[16:31]
	v_mfma_f32_32x32x16_bf16 v[32:47], v[98:101], v[102:105], v[32:47]
	v_mfma_f32_32x32x16_bf16 v[48:63], v[98:101], v[110:113], v[48:63]
	s_waitcnt lgkmcnt(0)
	v_mfma_f32_32x32x16_bf16 v[0:15], v[114:117], v[102:105], v[0:15]
	s_waitcnt vmcnt(0)
	s_barrier
;     ...
;   bf16* As1 = As + 2 * 128 * 72;
;   bf16* Bs1 = As1 + 128 * 72;
;   G_LOAD(ra0, rb0, 0);
;   if (nk > 1) G_LOAD(ra1, rb1, 1);
;   G_STORE(ra0, rb0, As, Bs);
;   __syncthreads();
;   for (int kt = 0; kt < nk; kt += 2) {
;     if (kt + 2 < nk) G_LOAD(ra0, rb0, kt + 2);
;     if (kt + 1 < nk) G_STORE(ra1, rb1, As1, Bs1);
;     G_COMPUTE(As, Bs);
;     __syncthreads();
;     if (kt + 1 < nk) {
;       if (kt + 3 < nk) G_LOAD(ra1, rb1, kt + 3);
;       if (kt + 2 < nk) G_STORE(ra0, rb0, As, Bs);
;       G_COMPUTE(As1, Bs1);
;       __syncthreads();
;     }
;   }
	v_mfma_f32_32x32x16_bf16 v[16:31], v[114:117], v[110:113], v[16:31]
	ds_read_b128 v[88:91], v170 offset:0
	ds_read_b128 v[92:95], v174 offset:16384
	ds_read_b128 v[98:101], v171 offset:0
	ds_read_b128 v[102:105], v175 offset:16384
	ds_read_b128 v[106:109], v174 offset:20480
	ds_read_b128 v[110:113], v175 offset:20480
	v_lshl_add_u64 v[66:67], v[66:67], 0, s[96:97]
	s_add_u32 m0, s94, 0x8000
	s_nop 1
	global_load_lds_dwordx4 v[66:67], off
	v_lshl_add_u64 v[68:69], v[68:69], 0, s[96:97]
	s_add_u32 m0, s94, 0xc000
	s_nop 1
	global_load_lds_dwordx4 v[68:69], off
	v_lshl_add_u64 v[70:71], v[70:71], 0, s[96:97]
	s_add_u32 m0, s94, 0x9000
	s_nop 1
	global_load_lds_dwordx4 v[70:71], off
	v_lshl_add_u64 v[72:73], v[72:73], 0, s[96:97]
	s_add_u32 m0, s94, 0xd000
	s_nop 1
	global_load_lds_dwordx4 v[72:73], off
	v_lshl_add_u64 v[74:75], v[74:75], 0, s[96:97]
	s_add_u32 m0, s94, 0xa000
	s_nop 1
	global_load_lds_dwordx4 v[74:75], off
	v_lshl_add_u64 v[76:77], v[76:77], 0, s[96:97]
	s_add_u32 m0, s94, 0xe000
	s_nop 1
	global_load_lds_dwordx4 v[76:77], off
	v_lshl_add_u64 v[80:81], v[80:81], 0, s[96:97]
	s_add_u32 m0, s94, 0xb000
	s_nop 1
	global_load_lds_dwordx4 v[80:81], off
	v_lshl_add_u64 v[78:79], v[78:79], 0, s[96:97]
	s_add_u32 m0, s94, 0xf000
	s_nop 1
	global_load_lds_dwordx4 v[78:79], off
	s_waitcnt lgkmcnt(4)
	v_mfma_f32_32x32x16_bf16 v[32:47], v[88:91], v[92:95], v[32:47]
	s_waitcnt lgkmcnt(1)
	v_mfma_f32_32x32x16_bf16 v[48:63], v[88:91], v[106:109], v[48:63]
	ds_read_b128 v[88:91], v170 offset:4096
	ds_read_b128 v[114:117], v171 offset:4096
	s_waitcnt lgkmcnt(1)
	v_mfma_f32_32x32x16_bf16 v[0:15], v[88:91], v[92:95], v[0:15]
	v_mfma_f32_32x32x16_bf16 v[16:31], v[88:91], v[106:109], v[16:31]
	v_mfma_f32_32x32x16_bf16 v[32:47], v[98:101], v[102:105], v[32:47]
	v_mfma_f32_32x32x16_bf16 v[48:63], v[98:101], v[110:113], v[48:63]
	s_waitcnt lgkmcnt(0)
	v_mfma_f32_32x32x16_bf16 v[0:15], v[114:117], v[102:105], v[0:15]
	ds_read_b128 v[88:91], v172 offset:0
	ds_read_b128 v[92:95], v176 offset:16384
	ds_read_b128 v[98:101], v173 offset:0
	ds_read_b128 v[102:105], v177 offset:16384
	v_mfma_f32_32x32x16_bf16 v[16:31], v[114:117], v[110:113], v[16:31]
	ds_read_b128 v[106:109], v176 offset:20480
	ds_read_b128 v[110:113], v177 offset:20480
	s_waitcnt lgkmcnt(4)
	v_mfma_f32_32x32x16_bf16 v[32:47], v[88:91], v[92:95], v[32:47]
	s_waitcnt lgkmcnt(1)
	v_mfma_f32_32x32x16_bf16 v[48:63], v[88:91], v[106:109], v[48:63]
	ds_read_b128 v[88:91], v172 offset:4096
	ds_read_b128 v[114:117], v173 offset:4096
	s_waitcnt lgkmcnt(1)
	v_mfma_f32_32x32x16_bf16 v[0:15], v[88:91], v[92:95], v[0:15]
	v_mfma_f32_32x32x16_bf16 v[16:31], v[88:91], v[106:109], v[16:31]
	v_mfma_f32_32x32x16_bf16 v[32:47], v[98:101], v[102:105], v[32:47]
	v_mfma_f32_32x32x16_bf16 v[48:63], v[98:101], v[110:113], v[48:63]
	s_waitcnt lgkmcnt(0)
	v_mfma_f32_32x32x16_bf16 v[0:15], v[114:117], v[102:105], v[0:15]
	s_waitcnt vmcnt(0)
	s_barrier
	v_mfma_f32_32x32x16_bf16 v[16:31], v[114:117], v[110:113], v[16:31]
	ds_read_b128 v[88:91], v170 offset:32768
	ds_read_b128 v[92:95], v174 offset:49152
	ds_read_b128 v[98:101], v171 offset:32768
	ds_read_b128 v[102:105], v175 offset:49152
	ds_read_b128 v[106:109], v174 offset:53248
	ds_read_b128 v[110:113], v175 offset:53248
	v_lshl_add_u64 v[66:67], v[66:67], 0, s[96:97]
	s_add_u32 m0, s94, 0x0
	s_nop 1
	global_load_lds_dwordx4 v[66:67], off
	v_lshl_add_u64 v[68:69], v[68:69], 0, s[96:97]
	s_add_u32 m0, s94, 0x4000
	s_nop 1
	global_load_lds_dwordx4 v[68:69], off
	v_lshl_add_u64 v[70:71], v[70:71], 0, s[96:97]
	s_add_u32 m0, s94, 0x1000
	s_nop 1
	global_load_lds_dwordx4 v[70:71], off
	v_lshl_add_u64 v[72:73], v[72:73], 0, s[96:97]
	s_add_u32 m0, s94, 0x5000
	s_nop 1
	global_load_lds_dwordx4 v[72:73], off
	v_lshl_add_u64 v[74:75], v[74:75], 0, s[96:97]
	s_add_u32 m0, s94, 0x2000
	s_nop 1
	global_load_lds_dwordx4 v[74:75], off
	v_lshl_add_u64 v[76:77], v[76:77], 0, s[96:97]
	s_add_u32 m0, s94, 0x6000
	s_nop 1
	global_load_lds_dwordx4 v[76:77], off
	v_lshl_add_u64 v[80:81], v[80:81], 0, s[96:97]
	s_add_u32 m0, s94, 0x3000
	s_nop 1
	global_load_lds_dwordx4 v[80:81], off
	v_lshl_add_u64 v[78:79], v[78:79], 0, s[96:97]
	s_add_u32 m0, s94, 0x7000
	s_nop 1
	global_load_lds_dwordx4 v[78:79], off
	s_waitcnt lgkmcnt(4)
	v_mfma_f32_32x32x16_bf16 v[32:47], v[88:91], v[92:95], v[32:47]
	s_waitcnt lgkmcnt(1)
	v_mfma_f32_32x32x16_bf16 v[48:63], v[88:91], v[106:109], v[48:63]
	ds_read_b128 v[88:91], v170 offset:36864
	ds_read_b128 v[114:117], v171 offset:36864
	s_waitcnt lgkmcnt(1)
	v_mfma_f32_32x32x16_bf16 v[0:15], v[88:91], v[92:95], v[0:15]
	v_mfma_f32_32x32x16_bf16 v[16:31], v[88:91], v[106:109], v[16:31]
	v_mfma_f32_32x32x16_bf16 v[32:47], v[98:101], v[102:105], v[32:47]
	v_mfma_f32_32x32x16_bf16 v[48:63], v[98:101], v[110:113], v[48:63]
	s_waitcnt lgkmcnt(0)
	v_mfma_f32_32x32x16_bf16 v[0:15], v[114:117], v[102:105], v[0:15]
	ds_read_b128 v[88:91], v172 offset:32768
	ds_read_b128 v[92:95], v176 offset:49152
	ds_read_b128 v[98:101], v173 offset:32768
	ds_read_b128 v[102:105], v177 offset:49152
	v_mfma_f32_32x32x16_bf16 v[16:31], v[114:117], v[110:113], v[16:31]
	ds_read_b128 v[106:109], v176 offset:53248
	ds_read_b128 v[110:113], v177 offset:53248
	s_waitcnt lgkmcnt(4)
	v_mfma_f32_32x32x16_bf16 v[32:47], v[88:91], v[92:95], v[32:47]
	s_waitcnt lgkmcnt(1)
	v_mfma_f32_32x32x16_bf16 v[48:63], v[88:91], v[106:109], v[48:63]
	ds_read_b128 v[88:91], v172 offset:36864
	ds_read_b128 v[114:117], v173 offset:36864
	s_waitcnt lgkmcnt(1)
	v_mfma_f32_32x32x16_bf16 v[0:15], v[88:91], v[92:95], v[0:15]
	v_mfma_f32_32x32x16_bf16 v[16:31], v[88:91], v[106:109], v[16:31]
	v_mfma_f32_32x32x16_bf16 v[32:47], v[98:101], v[102:105], v[32:47]
	v_mfma_f32_32x32x16_bf16 v[48:63], v[98:101], v[110:113], v[48:63]
	s_waitcnt lgkmcnt(0)
	v_mfma_f32_32x32x16_bf16 v[0:15], v[114:117], v[102:105], v[0:15]
	s_waitcnt vmcnt(0)
	s_barrier
;     ...
;   bf16* As1 = As + 2 * 128 * 72;
;   bf16* Bs1 = As1 + 128 * 72;
;   G_LOAD(ra0, rb0, 0);
;   if (nk > 1) G_LOAD(ra1, rb1, 1);
;   G_STORE(ra0, rb0, As, Bs);
;   __syncthreads();
;   for (int kt = 0; kt < nk; kt += 2) {
;     if (kt + 2 < nk) G_LOAD(ra0, rb0, kt + 2);
;     if (kt + 1 < nk) G_STORE(ra1, rb1, As1, Bs1);
;     G_COMPUTE(As, Bs);
;     __syncthreads();
;     if (kt + 1 < nk) {
;       if (kt + 3 < nk) G_LOAD(ra1, rb1, kt + 3);
;       if (kt + 2 < nk) G_STORE(ra0, rb0, As, Bs);
;       G_COMPUTE(As1, Bs1);
;       __syncthreads();
;     }
;   }
	v_mfma_f32_32x32x16_bf16 v[16:31], v[114:117], v[110:113], v[16:31]
	ds_read_b128 v[88:91], v170 offset:0
	ds_read_b128 v[92:95], v174 offset:16384
	ds_read_b128 v[98:101], v171 offset:0
	ds_read_b128 v[102:105], v175 offset:16384
	ds_read_b128 v[106:109], v174 offset:20480
	ds_read_b128 v[110:113], v175 offset:20480
	v_lshl_add_u64 v[66:67], v[66:67], 0, s[96:97]
	s_add_u32 m0, s94, 0x8000
	s_nop 1
	global_load_lds_dwordx4 v[66:67], off
	v_lshl_add_u64 v[68:69], v[68:69], 0, s[96:97]
	s_add_u32 m0, s94, 0xc000
	s_nop 1
	global_load_lds_dwordx4 v[68:69], off
	v_lshl_add_u64 v[70:71], v[70:71], 0, s[96:97]
	s_add_u32 m0, s94, 0x9000
	s_nop 1
	global_load_lds_dwordx4 v[70:71], off
	v_lshl_add_u64 v[72:73], v[72:73], 0, s[96:97]
	s_add_u32 m0, s94, 0xd000
	s_nop 1
	global_load_lds_dwordx4 v[72:73], off
	v_lshl_add_u64 v[74:75], v[74:75], 0, s[96:97]
	s_add_u32 m0, s94, 0xa000
	s_nop 1
	global_load_lds_dwordx4 v[74:75], off
	v_lshl_add_u64 v[76:77], v[76:77], 0, s[96:97]
	s_add_u32 m0, s94, 0xe000
	s_nop 1
	global_load_lds_dwordx4 v[76:77], off
	v_lshl_add_u64 v[80:81], v[80:81], 0, s[96:97]
	s_add_u32 m0, s94, 0xb000
	s_nop 1
	global_load_lds_dwordx4 v[80:81], off
	v_lshl_add_u64 v[78:79], v[78:79], 0, s[96:97]
	s_add_u32 m0, s94, 0xf000
	s_nop 1
	global_load_lds_dwordx4 v[78:79], off
	s_waitcnt lgkmcnt(4)
	v_mfma_f32_32x32x16_bf16 v[32:47], v[88:91], v[92:95], v[32:47]
	s_waitcnt lgkmcnt(1)
	v_mfma_f32_32x32x16_bf16 v[48:63], v[88:91], v[106:109], v[48:63]
	ds_read_b128 v[88:91], v170 offset:4096
	ds_read_b128 v[114:117], v171 offset:4096
	s_waitcnt lgkmcnt(1)
	v_mfma_f32_32x32x16_bf16 v[0:15], v[88:91], v[92:95], v[0:15]
	v_mfma_f32_32x32x16_bf16 v[16:31], v[88:91], v[106:109], v[16:31]
	v_mfma_f32_32x32x16_bf16 v[32:47], v[98:101], v[102:105], v[32:47]
	v_mfma_f32_32x32x16_bf16 v[48:63], v[98:101], v[110:113], v[48:63]
	s_waitcnt lgkmcnt(0)
	v_mfma_f32_32x32x16_bf16 v[0:15], v[114:117], v[102:105], v[0:15]
	ds_read_b128 v[88:91], v172 offset:0
	ds_read_b128 v[92:95], v176 offset:16384
	ds_read_b128 v[98:101], v173 offset:0
	ds_read_b128 v[102:105], v177 offset:16384
	v_mfma_f32_32x32x16_bf16 v[16:31], v[114:117], v[110:113], v[16:31]
	ds_read_b128 v[106:109], v176 offset:20480
	ds_read_b128 v[110:113], v177 offset:20480
	s_waitcnt lgkmcnt(4)
	v_mfma_f32_32x32x16_bf16 v[32:47], v[88:91], v[92:95], v[32:47]
	s_waitcnt lgkmcnt(1)
	v_mfma_f32_32x32x16_bf16 v[48:63], v[88:91], v[106:109], v[48:63]
	ds_read_b128 v[88:91], v172 offset:4096
	ds_read_b128 v[114:117], v173 offset:4096
	s_waitcnt lgkmcnt(1)
	v_mfma_f32_32x32x16_bf16 v[0:15], v[88:91], v[92:95], v[0:15]
	v_mfma_f32_32x32x16_bf16 v[16:31], v[88:91], v[106:109], v[16:31]
	v_mfma_f32_32x32x16_bf16 v[32:47], v[98:101], v[102:105], v[32:47]
	v_mfma_f32_32x32x16_bf16 v[48:63], v[98:101], v[110:113], v[48:63]
	s_waitcnt lgkmcnt(0)
	v_mfma_f32_32x32x16_bf16 v[0:15], v[114:117], v[102:105], v[0:15]
	s_waitcnt vmcnt(0)
	s_barrier
	v_mfma_f32_32x32x16_bf16 v[16:31], v[114:117], v[110:113], v[16:31]
	ds_read_b128 v[88:91], v170 offset:32768
	ds_read_b128 v[92:95], v174 offset:49152
	ds_read_b128 v[98:101], v171 offset:32768
	ds_read_b128 v[102:105], v175 offset:49152
	ds_read_b128 v[106:109], v174 offset:53248
	ds_read_b128 v[110:113], v175 offset:53248
	v_lshl_add_u64 v[66:67], v[66:67], 0, s[96:97]
	s_add_u32 m0, s94, 0x0
	s_nop 1
	global_load_lds_dwordx4 v[66:67], off
	v_lshl_add_u64 v[68:69], v[68:69], 0, s[96:97]
	s_add_u32 m0, s94, 0x4000
	s_nop 1
	global_load_lds_dwordx4 v[68:69], off
	v_lshl_add_u64 v[70:71], v[70:71], 0, s[96:97]
	s_add_u32 m0, s94, 0x1000
	s_nop 1
	global_load_lds_dwordx4 v[70:71], off
	v_lshl_add_u64 v[72:73], v[72:73], 0, s[96:97]
	s_add_u32 m0, s94, 0x5000
	s_nop 1
	global_load_lds_dwordx4 v[72:73], off
	v_lshl_add_u64 v[74:75], v[74:75], 0, s[96:97]
	s_add_u32 m0, s94, 0x2000
	s_nop 1
	global_load_lds_dwordx4 v[74:75], off
	v_lshl_add_u64 v[76:77], v[76:77], 0, s[96:97]
	s_add_u32 m0, s94, 0x6000
	s_nop 1
	global_load_lds_dwordx4 v[76:77], off
	v_lshl_add_u64 v[80:81], v[80:81], 0, s[96:97]
	s_add_u32 m0, s94, 0x3000
	s_nop 1
	global_load_lds_dwordx4 v[80:81], off
	v_lshl_add_u64 v[78:79], v[78:79], 0, s[96:97]
	s_add_u32 m0, s94, 0x7000
	s_nop 1
	global_load_lds_dwordx4 v[78:79], off
	s_waitcnt lgkmcnt(4)
	v_mfma_f32_32x32x16_bf16 v[32:47], v[88:91], v[92:95], v[32:47]
	s_waitcnt lgkmcnt(1)
	v_mfma_f32_32x32x16_bf16 v[48:63], v[88:91], v[106:109], v[48:63]
	ds_read_b128 v[88:91], v170 offset:36864
	ds_read_b128 v[114:117], v171 offset:36864
	s_waitcnt lgkmcnt(1)
	v_mfma_f32_32x32x16_bf16 v[0:15], v[88:91], v[92:95], v[0:15]
	v_mfma_f32_32x32x16_bf16 v[16:31], v[88:91], v[106:109], v[16:31]
	v_mfma_f32_32x32x16_bf16 v[32:47], v[98:101], v[102:105], v[32:47]
	v_mfma_f32_32x32x16_bf16 v[48:63], v[98:101], v[110:113], v[48:63]
	s_waitcnt lgkmcnt(0)
	v_mfma_f32_32x32x16_bf16 v[0:15], v[114:117], v[102:105], v[0:15]
	ds_read_b128 v[88:91], v172 offset:32768
	ds_read_b128 v[92:95], v176 offset:49152
	ds_read_b128 v[98:101], v173 offset:32768
	ds_read_b128 v[102:105], v177 offset:49152
	v_mfma_f32_32x32x16_bf16 v[16:31], v[114:117], v[110:113], v[16:31]
	ds_read_b128 v[106:109], v176 offset:53248
	ds_read_b128 v[110:113], v177 offset:53248
	s_waitcnt lgkmcnt(4)
	v_mfma_f32_32x32x16_bf16 v[32:47], v[88:91], v[92:95], v[32:47]
	s_waitcnt lgkmcnt(1)
	v_mfma_f32_32x32x16_bf16 v[48:63], v[88:91], v[106:109], v[48:63]
	ds_read_b128 v[88:91], v172 offset:36864
	ds_read_b128 v[114:117], v173 offset:36864
	s_waitcnt lgkmcnt(1)
	v_mfma_f32_32x32x16_bf16 v[0:15], v[88:91], v[92:95], v[0:15]
	v_mfma_f32_32x32x16_bf16 v[16:31], v[88:91], v[106:109], v[16:31]
	v_mfma_f32_32x32x16_bf16 v[32:47], v[98:101], v[102:105], v[32:47]
	v_mfma_f32_32x32x16_bf16 v[48:63], v[98:101], v[110:113], v[48:63]
	s_waitcnt lgkmcnt(0)
	v_mfma_f32_32x32x16_bf16 v[0:15], v[114:117], v[102:105], v[0:15]
	s_waitcnt vmcnt(0)
	s_barrier
;     ...
;   bf16* As1 = As + 2 * 128 * 72;
;   bf16* Bs1 = As1 + 128 * 72;
;   G_LOAD(ra0, rb0, 0);
;   if (nk > 1) G_LOAD(ra1, rb1, 1);
;   G_STORE(ra0, rb0, As, Bs);
;   __syncthreads();
;   for (int kt = 0; kt < nk; kt += 2) {
;     if (kt + 2 < nk) G_LOAD(ra0, rb0, kt + 2);
;     if (kt + 1 < nk) G_STORE(ra1, rb1, As1, Bs1);
;     G_COMPUTE(As, Bs);
;     __syncthreads();
;     if (kt + 1 < nk) {
;       if (kt + 3 < nk) G_LOAD(ra1, rb1, kt + 3);
;       if (kt + 2 < nk) G_STORE(ra0, rb0, As, Bs);
;       G_COMPUTE(As1, Bs1);
;       __syncthreads();
;     }
;   }
	v_mfma_f32_32x32x16_bf16 v[16:31], v[114:117], v[110:113], v[16:31]
	ds_read_b128 v[88:91], v170 offset:0
	ds_read_b128 v[92:95], v174 offset:16384
	ds_read_b128 v[98:101], v171 offset:0
	ds_read_b128 v[102:105], v175 offset:16384
	ds_read_b128 v[106:109], v174 offset:20480
	ds_read_b128 v[110:113], v175 offset:20480
	v_lshl_add_u64 v[66:67], v[66:67], 0, s[96:97]
	s_add_u32 m0, s94, 0x8000
	s_nop 1
	global_load_lds_dwordx4 v[66:67], off
	v_lshl_add_u64 v[68:69], v[68:69], 0, s[96:97]
	s_add_u32 m0, s94, 0xc000
	s_nop 1
	global_load_lds_dwordx4 v[68:69], off
	v_lshl_add_u64 v[70:71], v[70:71], 0, s[96:97]
	s_add_u32 m0, s94, 0x9000
	s_nop 1
	global_load_lds_dwordx4 v[70:71], off
	v_lshl_add_u64 v[72:73], v[72:73], 0, s[96:97]
	s_add_u32 m0, s94, 0xd000
	s_nop 1
	global_load_lds_dwordx4 v[72:73], off
	v_lshl_add_u64 v[74:75], v[74:75], 0, s[96:97]
	s_add_u32 m0, s94, 0xa000
	s_nop 1
	global_load_lds_dwordx4 v[74:75], off
	v_lshl_add_u64 v[76:77], v[76:77], 0, s[96:97]
	s_add_u32 m0, s94, 0xe000
	s_nop 1
	global_load_lds_dwordx4 v[76:77], off
	v_lshl_add_u64 v[80:81], v[80:81], 0, s[96:97]
	s_add_u32 m0, s94, 0xb000
	s_nop 1
	global_load_lds_dwordx4 v[80:81], off
	v_lshl_add_u64 v[78:79], v[78:79], 0, s[96:97]
	s_add_u32 m0, s94, 0xf000
	s_nop 1
	global_load_lds_dwordx4 v[78:79], off
	s_waitcnt lgkmcnt(4)
	v_mfma_f32_32x32x16_bf16 v[32:47], v[88:91], v[92:95], v[32:47]
	s_waitcnt lgkmcnt(1)
	v_mfma_f32_32x32x16_bf16 v[48:63], v[88:91], v[106:109], v[48:63]
	ds_read_b128 v[88:91], v170 offset:4096
	ds_read_b128 v[114:117], v171 offset:4096
	s_waitcnt lgkmcnt(1)
	v_mfma_f32_32x32x16_bf16 v[0:15], v[88:91], v[92:95], v[0:15]
	v_mfma_f32_32x32x16_bf16 v[16:31], v[88:91], v[106:109], v[16:31]
	v_mfma_f32_32x32x16_bf16 v[32:47], v[98:101], v[102:105], v[32:47]
	v_mfma_f32_32x32x16_bf16 v[48:63], v[98:101], v[110:113], v[48:63]
	s_waitcnt lgkmcnt(0)
	v_mfma_f32_32x32x16_bf16 v[0:15], v[114:117], v[102:105], v[0:15]
	ds_read_b128 v[88:91], v172 offset:0
	ds_read_b128 v[92:95], v176 offset:16384
	ds_read_b128 v[98:101], v173 offset:0
	ds_read_b128 v[102:105], v177 offset:16384
	v_mfma_f32_32x32x16_bf16 v[16:31], v[114:117], v[110:113], v[16:31]
	ds_read_b128 v[106:109], v176 offset:20480
	ds_read_b128 v[110:113], v177 offset:20480
	s_waitcnt lgkmcnt(4)
	v_mfma_f32_32x32x16_bf16 v[32:47], v[88:91], v[92:95], v[32:47]
	s_waitcnt lgkmcnt(1)
	v_mfma_f32_32x32x16_bf16 v[48:63], v[88:91], v[106:109], v[48:63]
	ds_read_b128 v[88:91], v172 offset:4096
	ds_read_b128 v[114:117], v173 offset:4096
	s_waitcnt lgkmcnt(1)
	v_mfma_f32_32x32x16_bf16 v[0:15], v[88:91], v[92:95], v[0:15]
	v_mfma_f32_32x32x16_bf16 v[16:31], v[88:91], v[106:109], v[16:31]
	v_mfma_f32_32x32x16_bf16 v[32:47], v[98:101], v[102:105], v[32:47]
	v_mfma_f32_32x32x16_bf16 v[48:63], v[98:101], v[110:113], v[48:63]
	s_waitcnt lgkmcnt(0)
	v_mfma_f32_32x32x16_bf16 v[0:15], v[114:117], v[102:105], v[0:15]
	s_waitcnt vmcnt(0)
	s_barrier
	v_mfma_f32_32x32x16_bf16 v[16:31], v[114:117], v[110:113], v[16:31]
	ds_read_b128 v[88:91], v170 offset:32768
	ds_read_b128 v[92:95], v174 offset:49152
	ds_read_b128 v[98:101], v171 offset:32768
	ds_read_b128 v[102:105], v175 offset:49152
	ds_read_b128 v[106:109], v174 offset:53248
	ds_read_b128 v[110:113], v175 offset:53248
	v_lshl_add_u64 v[66:67], v[66:67], 0, s[96:97]
	s_add_u32 m0, s94, 0x0
	s_nop 1
	global_load_lds_dwordx4 v[66:67], off
	v_lshl_add_u64 v[68:69], v[68:69], 0, s[96:97]
	s_add_u32 m0, s94, 0x4000
	s_nop 1
	global_load_lds_dwordx4 v[68:69], off
	v_lshl_add_u64 v[70:71], v[70:71], 0, s[96:97]
	s_add_u32 m0, s94, 0x1000
	s_nop 1
	global_load_lds_dwordx4 v[70:71], off
	v_lshl_add_u64 v[72:73], v[72:73], 0, s[96:97]
	s_add_u32 m0, s94, 0x5000
	s_nop 1
	global_load_lds_dwordx4 v[72:73], off
	v_lshl_add_u64 v[74:75], v[74:75], 0, s[96:97]
	s_add_u32 m0, s94, 0x2000
	s_nop 1
	global_load_lds_dwordx4 v[74:75], off
	v_lshl_add_u64 v[76:77], v[76:77], 0, s[96:97]
	s_add_u32 m0, s94, 0x6000
	s_nop 1
	global_load_lds_dwordx4 v[76:77], off
	v_lshl_add_u64 v[80:81], v[80:81], 0, s[96:97]
	s_add_u32 m0, s94, 0x3000
	s_nop 1
	global_load_lds_dwordx4 v[80:81], off
	v_lshl_add_u64 v[78:79], v[78:79], 0, s[96:97]
	s_add_u32 m0, s94, 0x7000
	s_nop 1
	global_load_lds_dwordx4 v[78:79], off
	s_waitcnt lgkmcnt(4)
	v_mfma_f32_32x32x16_bf16 v[32:47], v[88:91], v[92:95], v[32:47]
	s_waitcnt lgkmcnt(1)
	v_mfma_f32_32x32x16_bf16 v[48:63], v[88:91], v[106:109], v[48:63]
	ds_read_b128 v[88:91], v170 offset:36864
	ds_read_b128 v[114:117], v171 offset:36864
	s_waitcnt lgkmcnt(1)
	v_mfma_f32_32x32x16_bf16 v[0:15], v[88:91], v[92:95], v[0:15]
	v_mfma_f32_32x32x16_bf16 v[16:31], v[88:91], v[106:109], v[16:31]
	v_mfma_f32_32x32x16_bf16 v[32:47], v[98:101], v[102:105], v[32:47]
	v_mfma_f32_32x32x16_bf16 v[48:63], v[98:101], v[110:113], v[48:63]
	s_waitcnt lgkmcnt(0)
	v_mfma_f32_32x32x16_bf16 v[0:15], v[114:117], v[102:105], v[0:15]
	ds_read_b128 v[88:91], v172 offset:32768
	ds_read_b128 v[92:95], v176 offset:49152
	ds_read_b128 v[98:101], v173 offset:32768
	ds_read_b128 v[102:105], v177 offset:49152
	v_mfma_f32_32x32x16_bf16 v[16:31], v[114:117], v[110:113], v[16:31]
	ds_read_b128 v[106:109], v176 offset:53248
	ds_read_b128 v[110:113], v177 offset:53248
	s_waitcnt lgkmcnt(4)
	v_mfma_f32_32x32x16_bf16 v[32:47], v[88:91], v[92:95], v[32:47]
	s_waitcnt lgkmcnt(1)
	v_mfma_f32_32x32x16_bf16 v[48:63], v[88:91], v[106:109], v[48:63]
	ds_read_b128 v[88:91], v172 offset:36864
	ds_read_b128 v[114:117], v173 offset:36864
	s_waitcnt lgkmcnt(1)
	v_mfma_f32_32x32x16_bf16 v[0:15], v[88:91], v[92:95], v[0:15]
	v_mfma_f32_32x32x16_bf16 v[16:31], v[88:91], v[106:109], v[16:31]
	v_mfma_f32_32x32x16_bf16 v[32:47], v[98:101], v[102:105], v[32:47]
	v_mfma_f32_32x32x16_bf16 v[48:63], v[98:101], v[110:113], v[48:63]
	s_waitcnt lgkmcnt(0)
	v_mfma_f32_32x32x16_bf16 v[0:15], v[114:117], v[102:105], v[0:15]
	s_waitcnt vmcnt(0)
	s_barrier
;     ...
;   bf16* As1 = As + 2 * 128 * 72;
;   bf16* Bs1 = As1 + 128 * 72;
;   G_LOAD(ra0, rb0, 0);
;   if (nk > 1) G_LOAD(ra1, rb1, 1);
;   G_STORE(ra0, rb0, As, Bs);
;   __syncthreads();
;   for (int kt = 0; kt < nk; kt += 2) {
;     if (kt + 2 < nk) G_LOAD(ra0, rb0, kt + 2);
;     if (kt + 1 < nk) G_STORE(ra1, rb1, As1, Bs1);
;     G_COMPUTE(As, Bs);
;     __syncthreads();
;     if (kt + 1 < nk) {
;       if (kt + 3 < nk) G_LOAD(ra1, rb1, kt + 3);
;       if (kt + 2 < nk) G_STORE(ra0, rb0, As, Bs);
;       G_COMPUTE(As1, Bs1);
;       __syncthreads();
;     }
;   }
	v_mfma_f32_32x32x16_bf16 v[16:31], v[114:117], v[110:113], v[16:31]
	ds_read_b128 v[88:91], v170 offset:0
	ds_read_b128 v[92:95], v174 offset:16384
	ds_read_b128 v[98:101], v171 offset:0
	ds_read_b128 v[102:105], v175 offset:16384
	ds_read_b128 v[106:109], v174 offset:20480
	ds_read_b128 v[110:113], v175 offset:20480
	v_lshl_add_u64 v[66:67], v[66:67], 0, s[96:97]
	s_add_u32 m0, s94, 0x8000
	s_nop 1
	global_load_lds_dwordx4 v[66:67], off
	v_lshl_add_u64 v[68:69], v[68:69], 0, s[96:97]
	s_add_u32 m0, s94, 0xc000
	s_nop 1
	global_load_lds_dwordx4 v[68:69], off
	v_lshl_add_u64 v[70:71], v[70:71], 0, s[96:97]
	s_add_u32 m0, s94, 0x9000
	s_nop 1
	global_load_lds_dwordx4 v[70:71], off
	v_lshl_add_u64 v[72:73], v[72:73], 0, s[96:97]
	s_add_u32 m0, s94, 0xd000
	s_nop 1
	global_load_lds_dwordx4 v[72:73], off
	v_lshl_add_u64 v[74:75], v[74:75], 0, s[96:97]
	s_add_u32 m0, s94, 0xa000
	s_nop 1
	global_load_lds_dwordx4 v[74:75], off
	v_lshl_add_u64 v[76:77], v[76:77], 0, s[96:97]
	s_add_u32 m0, s94, 0xe000
	s_nop 1
	global_load_lds_dwordx4 v[76:77], off
	v_lshl_add_u64 v[80:81], v[80:81], 0, s[96:97]
	s_add_u32 m0, s94, 0xb000
	s_nop 1
	global_load_lds_dwordx4 v[80:81], off
	v_lshl_add_u64 v[78:79], v[78:79], 0, s[96:97]
	s_add_u32 m0, s94, 0xf000
	s_nop 1
	global_load_lds_dwordx4 v[78:79], off
	s_waitcnt lgkmcnt(4)
	v_mfma_f32_32x32x16_bf16 v[32:47], v[88:91], v[92:95], v[32:47]
	s_waitcnt lgkmcnt(1)
	v_mfma_f32_32x32x16_bf16 v[48:63], v[88:91], v[106:109], v[48:63]
	ds_read_b128 v[88:91], v170 offset:4096
	ds_read_b128 v[114:117], v171 offset:4096
	s_waitcnt lgkmcnt(1)
	v_mfma_f32_32x32x16_bf16 v[0:15], v[88:91], v[92:95], v[0:15]
	v_mfma_f32_32x32x16_bf16 v[16:31], v[88:91], v[106:109], v[16:31]
	v_mfma_f32_32x32x16_bf16 v[32:47], v[98:101], v[102:105], v[32:47]
	v_mfma_f32_32x32x16_bf16 v[48:63], v[98:101], v[110:113], v[48:63]
	s_waitcnt lgkmcnt(0)
	v_mfma_f32_32x32x16_bf16 v[0:15], v[114:117], v[102:105], v[0:15]
	ds_read_b128 v[88:91], v172 offset:0
	ds_read_b128 v[92:95], v176 offset:16384
	ds_read_b128 v[98:101], v173 offset:0
	ds_read_b128 v[102:105], v177 offset:16384
	v_mfma_f32_32x32x16_bf16 v[16:31], v[114:117], v[110:113], v[16:31]
	ds_read_b128 v[106:109], v176 offset:20480
	ds_read_b128 v[110:113], v177 offset:20480
	s_waitcnt lgkmcnt(4)
	v_mfma_f32_32x32x16_bf16 v[32:47], v[88:91], v[92:95], v[32:47]
	s_waitcnt lgkmcnt(1)
	v_mfma_f32_32x32x16_bf16 v[48:63], v[88:91], v[106:109], v[48:63]
	ds_read_b128 v[88:91], v172 offset:4096
	ds_read_b128 v[114:117], v173 offset:4096
	s_waitcnt lgkmcnt(1)
	v_mfma_f32_32x32x16_bf16 v[0:15], v[88:91], v[92:95], v[0:15]
	v_mfma_f32_32x32x16_bf16 v[16:31], v[88:91], v[106:109], v[16:31]
	v_mfma_f32_32x32x16_bf16 v[32:47], v[98:101], v[102:105], v[32:47]
	v_mfma_f32_32x32x16_bf16 v[48:63], v[98:101], v[110:113], v[48:63]
	s_waitcnt lgkmcnt(0)
	v_mfma_f32_32x32x16_bf16 v[0:15], v[114:117], v[102:105], v[0:15]
	s_waitcnt vmcnt(0)
	s_barrier
	v_mfma_f32_32x32x16_bf16 v[16:31], v[114:117], v[110:113], v[16:31]
	ds_read_b128 v[88:91], v170 offset:32768
	ds_read_b128 v[92:95], v174 offset:49152
	ds_read_b128 v[98:101], v171 offset:32768
	ds_read_b128 v[102:105], v175 offset:49152
	ds_read_b128 v[106:109], v174 offset:53248
	ds_read_b128 v[110:113], v175 offset:53248
	v_lshl_add_u64 v[66:67], v[66:67], 0, s[96:97]
	s_add_u32 m0, s94, 0x0
	s_nop 1
	global_load_lds_dwordx4 v[66:67], off
	v_lshl_add_u64 v[68:69], v[68:69], 0, s[96:97]
	s_add_u32 m0, s94, 0x4000
	s_nop 1
	global_load_lds_dwordx4 v[68:69], off
	v_lshl_add_u64 v[70:71], v[70:71], 0, s[96:97]
	s_add_u32 m0, s94, 0x1000
	s_nop 1
	global_load_lds_dwordx4 v[70:71], off
	v_lshl_add_u64 v[72:73], v[72:73], 0, s[96:97]
	s_add_u32 m0, s94, 0x5000
	s_nop 1
	global_load_lds_dwordx4 v[72:73], off
	v_lshl_add_u64 v[74:75], v[74:75], 0, s[96:97]
	s_add_u32 m0, s94, 0x2000
	s_nop 1
	global_load_lds_dwordx4 v[74:75], off
	v_lshl_add_u64 v[76:77], v[76:77], 0, s[96:97]
	s_add_u32 m0, s94, 0x6000
	s_nop 1
	global_load_lds_dwordx4 v[76:77], off
	v_lshl_add_u64 v[80:81], v[80:81], 0, s[96:97]
	s_add_u32 m0, s94, 0x3000
	s_nop 1
	global_load_lds_dwordx4 v[80:81], off
	v_lshl_add_u64 v[78:79], v[78:79], 0, s[96:97]
	s_add_u32 m0, s94, 0x7000
	s_nop 1
	global_load_lds_dwordx4 v[78:79], off
	s_waitcnt lgkmcnt(4)
	v_mfma_f32_32x32x16_bf16 v[32:47], v[88:91], v[92:95], v[32:47]
	s_waitcnt lgkmcnt(1)
	v_mfma_f32_32x32x16_bf16 v[48:63], v[88:91], v[106:109], v[48:63]
	ds_read_b128 v[88:91], v170 offset:36864
	ds_read_b128 v[114:117], v171 offset:36864
	s_waitcnt lgkmcnt(1)
	v_mfma_f32_32x32x16_bf16 v[0:15], v[88:91], v[92:95], v[0:15]
	v_mfma_f32_32x32x16_bf16 v[16:31], v[88:91], v[106:109], v[16:31]
	v_mfma_f32_32x32x16_bf16 v[32:47], v[98:101], v[102:105], v[32:47]
	v_mfma_f32_32x32x16_bf16 v[48:63], v[98:101], v[110:113], v[48:63]
	s_waitcnt lgkmcnt(0)
	v_mfma_f32_32x32x16_bf16 v[0:15], v[114:117], v[102:105], v[0:15]
	ds_read_b128 v[88:91], v172 offset:32768
	ds_read_b128 v[92:95], v176 offset:49152
	ds_read_b128 v[98:101], v173 offset:32768
	ds_read_b128 v[102:105], v177 offset:49152
	v_mfma_f32_32x32x16_bf16 v[16:31], v[114:117], v[110:113], v[16:31]
	ds_read_b128 v[106:109], v176 offset:53248
	ds_read_b128 v[110:113], v177 offset:53248
	s_waitcnt lgkmcnt(4)
	v_mfma_f32_32x32x16_bf16 v[32:47], v[88:91], v[92:95], v[32:47]
	s_waitcnt lgkmcnt(1)
	v_mfma_f32_32x32x16_bf16 v[48:63], v[88:91], v[106:109], v[48:63]
	ds_read_b128 v[88:91], v172 offset:36864
	ds_read_b128 v[114:117], v173 offset:36864
	s_waitcnt lgkmcnt(1)
	v_mfma_f32_32x32x16_bf16 v[0:15], v[88:91], v[92:95], v[0:15]
	v_mfma_f32_32x32x16_bf16 v[16:31], v[88:91], v[106:109], v[16:31]
	v_mfma_f32_32x32x16_bf16 v[32:47], v[98:101], v[102:105], v[32:47]
	v_mfma_f32_32x32x16_bf16 v[48:63], v[98:101], v[110:113], v[48:63]
	s_nop 0
	s_nop 0
	s_nop 0
	s_nop 0
	s_nop 0
	s_nop 0
	s_nop 0
	s_waitcnt lgkmcnt(0)
	s_waitcnt vmcnt(0)
	s_barrier
; #define PW(T, off) ((T*)(lndp(p.ws) + (off)))
; DEVI void gemm_epi_qkv(const Params& p, f32x16 (&acc)[2][2], int rbase, int cbase, int lane) {
;   char* ar = PW(char, W_arena);
;   const int which = cbase >> 10, cc = cbase & 1023, d = lane & 31, hl = lane >> 5;
; #pragma unroll
;   for (int i = 0; i < 2; ++i) {
; #pragma unroll
;     for (int rq = 0; rq < 4; ++rq) {
;       const int row0 = rbase + i * 32 + 8 * rq + 4 * hl;
;       if (row0 >= M) continue;
;       const bool pr = row0 < TP;
;       const int b = pr ? 0 : (row0 - TP) >> 4, t0 = pr ? row0 : (row0 - TP) & 15;
;     ...
;   for (int kt = 0; kt < nk; kt += 2) {
;     if (kt + 2 < nk) G_LOAD(ra0, rb0, kt + 2);
;     if (kt + 1 < nk) G_STORE(ra1, rb1, As1, Bs1);
;     G_COMPUTE(As, Bs);
;     __syncthreads();
;     if (kt + 1 < nk) {
;       if (kt + 3 < nk) G_LOAD(ra1, rb1, kt + 3);
;       if (kt + 2 < nk) G_STORE(ra0, rb0, As, Bs);
;       G_COMPUTE(As1, Bs1);
;       __syncthreads();
;     }
;   }
	v_lshl_add_u64 v[66:67], v[66:67], 0, s[96:97]
	s_add_u32 m0, s94, 0x8000
	s_nop 1
	global_load_lds_dwordx4 v[66:67], off
	v_lshl_add_u64 v[68:69], v[68:69], 0, s[96:97]
	s_add_u32 m0, s94, 0xc000
	s_nop 1
	global_load_lds_dwordx4 v[68:69], off
	v_lshl_add_u64 v[70:71], v[70:71], 0, s[96:97]
	s_add_u32 m0, s94, 0x9000
	s_nop 1
	global_load_lds_dwordx4 v[70:71], off
	v_lshl_add_u64 v[72:73], v[72:73], 0, s[96:97]
	s_add_u32 m0, s94, 0xd000
	s_nop 1
	global_load_lds_dwordx4 v[72:73], off
	v_lshl_add_u64 v[74:75], v[74:75], 0, s[96:97]
	s_add_u32 m0, s94, 0xa000
	s_nop 1
	global_load_lds_dwordx4 v[74:75], off
	v_lshl_add_u64 v[76:77], v[76:77], 0, s[96:97]
	s_add_u32 m0, s94, 0xe000
	s_nop 1
	global_load_lds_dwordx4 v[76:77], off
	v_lshl_add_u64 v[80:81], v[80:81], 0, s[96:97]
	s_add_u32 m0, s94, 0xb000
	s_nop 1
	global_load_lds_dwordx4 v[80:81], off
	v_lshl_add_u64 v[78:79], v[78:79], 0, s[96:97]
	s_add_u32 m0, s94, 0xf000
	s_nop 1
	global_load_lds_dwordx4 v[78:79], off
	v_mfma_f32_32x32x16_bf16 v[0:15], v[114:117], v[102:105], v[0:15]
	ds_read_b128 v[66:69], v170 offset:0
	ds_read_b128 v[70:73], v174 offset:16384
	ds_read_b128 v[74:77], v171 offset:0
	ds_read_b128 v[78:81], v175 offset:16384
	ds_read_b128 v[88:91], v174 offset:20480
	ds_read_b128 v[92:95], v175 offset:20480
	v_mfma_f32_32x32x16_bf16 v[16:31], v[114:117], v[110:113], v[16:31]
	s_waitcnt lgkmcnt(4)
	v_mfma_f32_32x32x16_bf16 v[32:47], v[66:69], v[70:73], v[32:47]
	s_waitcnt lgkmcnt(1)
	v_mfma_f32_32x32x16_bf16 v[48:63], v[66:69], v[88:91], v[48:63]
	ds_read_b128 v[66:69], v170 offset:4096
	ds_read_b128 v[98:101], v171 offset:4096
	s_waitcnt lgkmcnt(1)
	v_mfma_f32_32x32x16_bf16 v[0:15], v[66:69], v[70:73], v[0:15]
	v_mfma_f32_32x32x16_bf16 v[16:31], v[66:69], v[88:91], v[16:31]
	v_mfma_f32_32x32x16_bf16 v[32:47], v[74:77], v[78:81], v[32:47]
	v_mfma_f32_32x32x16_bf16 v[48:63], v[74:77], v[92:95], v[48:63]
	s_waitcnt lgkmcnt(0)
	v_mfma_f32_32x32x16_bf16 v[0:15], v[98:101], v[78:81], v[0:15]
	ds_read_b128 v[66:69], v172 offset:0
	ds_read_b128 v[70:73], v176 offset:16384
	ds_read_b128 v[74:77], v173 offset:0
	ds_read_b128 v[78:81], v177 offset:16384
	v_mfma_f32_32x32x16_bf16 v[16:31], v[98:101], v[92:95], v[16:31]
	ds_read_b128 v[88:91], v176 offset:20480
	ds_read_b128 v[92:95], v177 offset:20480
	s_waitcnt lgkmcnt(4)
	v_mfma_f32_32x32x16_bf16 v[32:47], v[66:69], v[70:73], v[32:47]
	s_waitcnt lgkmcnt(1)
	v_mfma_f32_32x32x16_bf16 v[48:63], v[66:69], v[88:91], v[48:63]
	ds_read_b128 v[66:69], v172 offset:4096
	ds_read_b128 v[98:101], v173 offset:4096
	s_waitcnt lgkmcnt(0)
	s_waitcnt vmcnt(0)
	s_barrier
	v_mfma_f32_32x32x16_bf16 v[0:15], v[66:69], v[70:73], v[0:15]
	v_mfma_f32_32x32x16_bf16 v[32:47], v[74:77], v[78:81], v[32:47]
	v_mfma_f32_32x32x16_bf16 v[48:63], v[74:77], v[92:95], v[48:63]
	v_mfma_f32_32x32x16_bf16 v[16:31], v[66:69], v[88:91], v[16:31]
	v_mfma_f32_32x32x16_bf16 v[0:15], v[98:101], v[78:81], v[0:15]
	ds_read_b128 v[66:69], v170 offset:32768
	ds_read_b128 v[70:73], v174 offset:49152
	ds_read_b128 v[74:77], v175 offset:49152
	ds_read_b128 v[78:81], v171 offset:32768
	ds_read_b128 v[88:91], v174 offset:53248
	s_waitcnt lgkmcnt(3)
	v_mfma_f32_32x32x16_bf16 v[32:47], v[66:69], v[70:73], v[32:47]
	s_waitcnt lgkmcnt(0)
	v_mfma_f32_32x32x16_bf16 v[48:63], v[66:69], v[88:91], v[48:63]
	ds_read_b128 v[66:69], v170 offset:36864
	v_mfma_f32_32x32x16_bf16 v[16:31], v[98:101], v[92:95], v[16:31]
	s_waitcnt lgkmcnt(0)
	v_mfma_f32_32x32x16_bf16 v[0:15], v[66:69], v[70:73], v[0:15]
	ds_read_b128 v[70:73], v171 offset:36864
	v_mfma_f32_32x32x16_bf16 v[16:31], v[66:69], v[88:91], v[16:31]
	ds_read_b128 v[66:69], v175 offset:53248
	v_mfma_f32_32x32x16_bf16 v[32:47], v[78:81], v[74:77], v[32:47]
	s_waitcnt lgkmcnt(0)
	v_mfma_f32_32x32x16_bf16 v[48:63], v[78:81], v[66:69], v[48:63]
	v_and_or_b32 v80, v85, 64, s2
	v_or_b32_e32 v81, v80, v84
	v_mfma_f32_32x32x16_bf16 v[0:15], v[70:73], v[74:77], v[0:15]
	v_mfma_f32_32x32x16_bf16 v[16:31], v[70:73], v[66:69], v[16:31]
	ds_read_b128 v[66:69], v172 offset:32768
	ds_read_b128 v[70:73], v176 offset:49152
	ds_read_b128 v[74:77], v176 offset:53248
	s_waitcnt lgkmcnt(1)
	v_mfma_f32_32x32x16_bf16 v[32:47], v[66:69], v[70:73], v[32:47]
	s_waitcnt lgkmcnt(0)
	v_mfma_f32_32x32x16_bf16 v[48:63], v[66:69], v[74:77], v[48:63]
	ds_read_b128 v[66:69], v172 offset:36864
	s_waitcnt lgkmcnt(0)
	v_mfma_f32_32x32x16_bf16 v[0:15], v[66:69], v[70:73], v[0:15]
	ds_read_b128 v[88:91], v177 offset:53248
	ds_read_b128 v[92:95], v177 offset:49152
	ds_read_b128 v[70:73], v173 offset:32768
	v_lshrrev_b32_e32 v65, 3, v85
	v_and_b32_e32 v82, 4, v65
	v_mfma_f32_32x32x16_bf16 v[16:31], v[66:69], v[74:77], v[16:31]
	ds_read_b128 v[74:77], v173 offset:36864
	v_add_u32_e32 v64, s3, v86
	v_or_b32_e32 v68, v64, v82
	v_mul_u32_u24_e32 v64, 0x4040, v81
	v_lshlrev_b32_e32 v96, 1, v64
	s_waitcnt lgkmcnt(0)
	s_barrier
	v_mfma_f32_32x32x16_bf16 v[32:47], v[70:73], v[92:95], v[32:47]
	s_cmp_gt_i32 s5, 1
	s_cselect_b64 s[2:3], -1, 0
	v_lshl_add_u64 v[64:65], s[22:23], 0, v[96:97]
	v_lshlrev_b32_e32 v96, 1, v80
	s_cmpk_gt_u32 s4, 0x3ff
	s_cselect_b64 s[20:21], -1, 0
	v_mfma_f32_32x32x16_bf16 v[48:63], v[70:73], v[88:91], v[48:63]
	v_lshl_add_u64 v[70:71], v[64:65], 0, s[6:7]
	v_lshl_add_u64 v[64:65], s[22:23], 0, v[96:97]
	s_mov_b64 s[6:7], 0x13e3c000
	v_lshl_add_u64 v[66:67], v[64:65], 0, s[6:7]
	s_mov_b64 s[6:7], 0x11d7c000
	s_cmp_eq_u32 s5, 1
	v_lshl_add_u64 v[64:65], v[64:65], 0, s[6:7]
	v_mfma_f32_32x32x16_bf16 v[0:15], v[74:77], v[92:95], v[0:15]
	s_cselect_b64 s[18:19], -1, 0
	v_cmp_gt_i32_e32 vcc, s90, v68
	v_mfma_f32_32x32x16_bf16 v[16:31], v[74:77], v[88:91], v[16:31]
	s_and_saveexec_b64 s[4:5], vcc
	s_cbranch_execz .LBB0_1590
	s_movk_i32 s6, 0x400f
	v_add_u32_e32 v72, 0xffffbff0, v68
	v_cmp_lt_i32_e64 s[6:7], s6, v68
	v_ashrrev_i32_e32 v78, 4, v72
	s_mov_b64 s[8:9], -1
	s_and_b64 vcc, exec, s[2:3]
	s_cbranch_vccz .LBB0_1569
	s_and_saveexec_b64 s[8:9], s[6:7]
	s_xor_b64 s[8:9], exec, s[8:9]
	s_cbranch_execz .LBB0_1562
	s_mov_b64 s[10:11], s[72:73]
	s_add_u32 s10, s10, 0xc48f000
	v_mov_b32_e32 v73, v97
	s_addc_u32 s11, s11, 0
	v_mov_b64_e32 v[74:75], v[72:73]

; DEVI int TID() { int t = threadIdx.x; asm volatile("" : "+v"(t)); return t; }
; DEVI int BID() { int b = blockIdx.x; asm volatile("" : "+s"(b)); return b; }
;   bf16* As = (bf16*)smem;
;   bf16* Bs = As + 128 * 72;
;   const int tid = TID(), lane = tid & 63, wave = tid >> 6, wm = wave >> 1, wn = wave & 1;
;   f32x16 acc[2][2];
; #pragma unroll
;   for (int i = 0; i < 2; ++i)
; #pragma unroll
;     for (int j = 0; j < 2; ++j) acc[i][j] = zero16();
;   const int lrow = tid >> 3, lkc = (tid & 7) * 8;
;   const bf16* Ag = jb.A + (size_t)max(m0 + lrow, 0) * jb.lda + lkc;
;   const bf16* Ag1 = jb.A + (ptrdiff_t)(m0 + lrow) * jb.lda + lkc;
;   const bf16* Bg = jb.Bt + (size_t)(n0 + lrow) * jb.K + lkc;
;   const size_t astep = (size_t)32 * jb.lda, bstep = (size_t)32 * jb.K;
;   if (kt1 < 0) kt1 = jb.K >> 6;
;   const int nk = kt1 - kt0;
;   Ag += (size_t)kt0 * 64; Ag1 += (size_t)kt0 * 64; Bg += (size_t)kt0 * 64;
;   u32x4 ra0[4], rb0[4], ra1[4], rb1[4];
;     ...
;   bf16* As1 = As + 2 * 128 * 72;
;   bf16* Bs1 = As1 + 128 * 72;
;   G_LOAD(ra0, rb0, 0);
;   if (nk > 1) G_LOAD(ra1, rb1, 1);
;   G_STORE(ra0, rb0, As, Bs);
;   __syncthreads();
;   for (int kt = 0; kt < nk; kt += 2) {
;     if (kt + 2 < nk) G_LOAD(ra0, rb0, kt + 2);
;     if (kt + 1 < nk) G_STORE(ra1, rb1, As1, Bs1);
;     G_COMPUTE(As, Bs);
; DEVI void gemm_single(const Params& p, const GJob& jb, int nt, char* smem) {
;     ...
;   if (nt >= 16 && (gridDim.x & 7) == 0) {
;     const int b = BID(), x = b & 7, lb = b >> 3, nlb = gridDim.x >> 3;
;     const int ng = x & 3, mh = x >> 2;
;     const int n_lo = ng * nt / 4, nnt = (ng + 1) * nt / 4 - n_lo;
;     const int m_lo = mh * mtn / 2, nmt = (mh + 1) * mtn / 2 - m_lo;
;     for (int t = lb; t < nmt * nnt; t += nlb) {
;       const int mt = m_lo + t / nnt, ntg = n_lo + t % nnt;
;       gemm_tile(p, jb, fused ? mt * 126 - 2 : mt * 128, ntg * 128, smem);
.LBB0_1819:
	s_abs_i32 s3, s22
	s_mul_hi_u32 s4, s3, s29
	s_mul_i32 s5, s4, s26
	s_ashr_i32 s2, s22, 31
	s_sub_i32 s3, s3, s5
	s_xor_b32 s2, s2, s28
	s_add_i32 s5, s4, 1
	s_sub_i32 s6, s3, s26
	s_cmp_ge_u32 s3, s26
	s_cselect_b32 s4, s5, s4
	s_cselect_b32 s3, s6, s3
	s_add_i32 s5, s4, 1
	s_cmp_ge_u32 s3, s26
	s_cselect_b32 s3, s5, s4
	s_xor_b32 s3, s3, s2
	s_sub_i32 s4, s3, s2
	s_mul_i32 s2, s2, 6
	s_mul_i32 s3, s3, 6
	s_add_i32 s4, s4, s24
	s_sub_i32 s2, s2, s3
	s_add_i32 s3, s23, s22
	v_mov_b32_e32 v85, v208
	s_add_i32 s2, s3, s2
	s_lshl_b32 s3, s4, 7
	s_lshl_b32 s4, s2, 7
	v_ashrrev_i32_e32 v64, 3, v85
	v_add_u32_e32 v0, s3, v64
	v_max_i32_e32 v96, 0, v0
	v_lshlrev_b32_e32 v1, 4, v85
	v_lshlrev_b64 v[2:3], 11, v[96:97]
	v_and_b32_e32 v96, 0x70, v1
	s_mov_b64 s[96:97], 0x80
	v_lshrrev_b32_e32 v178, 4, v208
	v_and_b32_e32 v178, 7, v178
	v_lshlrev_b32_e32 v178, 4, v178
	v_xor_b32_e32 v96, v96, v178
	v_lshrrev_b32_e32 v179, 6, v208
	v_lshlrev_b32_e32 v179, 10, v179
	v_lshrrev_b32_e32 v180, 5, v208
	v_lshrrev_b32_e32 v181, 1, v208
	v_xor_b32_e32 v180, v180, v181
	v_readfirstlane_b32 s94, v179
	v_and_b32_e32 v180, 1, v180
	v_lshlrev_b32_e32 v180, 4, v180
	v_and_b32_e32 v181, 31, v208
	v_lshlrev_b32_e32 v181, 7, v181
	v_or_b32_e32 v180, v180, v181
	v_lshrrev_b32_e32 v181, 7, v208
	v_lshlrev_b32_e32 v181, 13, v181
	v_or_b32_e32 v194, v180, v181
	v_bfe_u32 v181, v208, 6, 1
	v_lshlrev_b32_e32 v181, 13, v181
	v_or_b32_e32 v195, v180, v181
	v_bfe_u32 v178, v208, 2, 2
	v_xor_b32_e32 v179, 0, v178
	v_lshlrev_b32_e32 v179, 5, v179
	v_or_b32_e32 v170, v194, v179
	v_or_b32_e32 v174, v195, v179
	v_xor_b32_e32 v179, 1, v178
	v_lshlrev_b32_e32 v179, 5, v179
	v_or_b32_e32 v171, v194, v179
	v_or_b32_e32 v175, v195, v179
	v_xor_b32_e32 v179, 2, v178
	v_lshlrev_b32_e32 v179, 5, v179
	v_or_b32_e32 v172, v194, v179
	v_or_b32_e32 v176, v195, v179
	v_xor_b32_e32 v179, 3, v178
	v_lshlrev_b32_e32 v179, 5, v179
	v_or_b32_e32 v173, v194, v179
	v_or_b32_e32 v177, v195, v179
	v_ashrrev_i32_e32 v1, 31, v0
	v_lshlrev_b64 v[0:1], 11, v[0:1]
	v_lshl_add_u64 v[0:1], s[12:13], 0, v[0:1]
	v_lshl_add_u64 v[24:25], v[0:1], 0, v[96:97]
	v_add_u32_e32 v0, s4, v64
	v_ashrrev_i32_e32 v1, 31, v0
	v_lshlrev_b64 v[0:1], 11, v[0:1]
	v_lshl_add_u64 v[0:1], s[14:15], 0, v[0:1]
	v_add_co_u32_e32 v70, vcc, s63, v24
	v_lshl_add_u64 v[68:69], v[0:1], 0, v[96:97]
	s_nop 0
	v_addc_co_u32_e32 v71, vcc, 0, v25, vcc
	v_add_co_u32_e32 v72, vcc, s63, v68
	v_lshl_add_u64 v[2:3], s[12:13], 0, v[2:3]
	s_nop 0
	v_addc_co_u32_e32 v73, vcc, 0, v69, vcc
	v_add_co_u32_e32 v74, vcc, s64, v24
	v_lshl_add_u64 v[66:67], v[2:3], 0, v[96:97]
	s_nop 0
	v_addc_co_u32_e32 v75, vcc, 0, v25, vcc
	v_add_co_u32_e32 v76, vcc, s64, v68
	v_addc_co_u32_e32 v77, vcc, 0, v69, vcc
	v_add_co_u32_e32 v78, vcc, s65, v24
	s_nop 0
	v_addc_co_u32_e32 v79, vcc, 0, v25, vcc
	v_add_co_u32_e32 v80, vcc, s65, v68
	s_nop 0
	v_addc_co_u32_e32 v81, vcc, 0, v69, vcc
	v_ashrrev_i32_e32 v65, 1, v85
	v_and_b32_e32 v84, 31, v85
	v_lshrrev_b32_e32 v82, 1, v85
	v_and_b32_e32 v86, 0xffffffc0, v65
	v_and_b32_e32 v88, 16, v82
	v_or_b32_e32 v65, v86, v84
	v_mad_u64_u32 v[82:83], s[6:7], v64, s91, v[96:97]
	v_add_u32_e32 v87, 0xd800, v82
	v_mad_u64_u32 v[64:65], s[6:7], v65, s91, v[88:89]
	v_and_b32_e32 v65, 0x5f, v85
	v_mad_u32_u24 v83, v65, s91, v88
	s_and_b32 s6, s4, 0x380
	s_mov_b64 s[20:21], s[74:75]
	s_ashr_i32 s5, s2, 3
	s_add_u32 m0, s94, 0x0
	s_nop 1
	global_load_lds_dwordx4 v[66:67], off
	s_add_u32 m0, s94, 0x4000
	s_nop 1
	global_load_lds_dwordx4 v[68:69], off
	s_add_u32 m0, s94, 0x1000
	s_nop 1
	global_load_lds_dwordx4 v[70:71], off
	s_add_u32 m0, s94, 0x2000
	s_nop 1
	global_load_lds_dwordx4 v[74:75], off
	s_add_u32 m0, s94, 0x3000
	s_nop 1
	global_load_lds_dwordx4 v[78:79], off
	s_add_u32 m0, s94, 0x5000
	s_nop 1
	global_load_lds_dwordx4 v[72:73], off
	s_add_u32 m0, s94, 0x6000
	s_nop 1
	global_load_lds_dwordx4 v[76:77], off
	s_add_u32 m0, s94, 0x7000
	s_nop 1
	global_load_lds_dwordx4 v[80:81], off
	s_waitcnt lgkmcnt(0)
	s_waitcnt vmcnt(0)
	s_barrier
	ds_read_b128 v[0:3], v170 offset:0
	ds_read_b128 v[4:7], v174 offset:16384
	ds_read_b128 v[88:91], v171 offset:0
	ds_read_b128 v[92:95], v175 offset:16384
	ds_read_b128 v[16:19], v174 offset:20480
	ds_read_b128 v[98:101], v175 offset:20480
	v_lshl_add_u64 v[66:67], v[66:67], 0, s[96:97]
	s_add_u32 m0, s94, 0x8000
	s_nop 1
	global_load_lds_dwordx4 v[66:67], off
	v_lshl_add_u64 v[68:69], v[68:69], 0, s[96:97]
	s_add_u32 m0, s94, 0xc000
	s_nop 1
	global_load_lds_dwordx4 v[68:69], off
	v_lshl_add_u64 v[70:71], v[70:71], 0, s[96:97]
	s_add_u32 m0, s94, 0x9000
	s_nop 1
	global_load_lds_dwordx4 v[70:71], off
	v_lshl_add_u64 v[72:73], v[72:73], 0, s[96:97]
	s_add_u32 m0, s94, 0xd000
	s_nop 1
	global_load_lds_dwordx4 v[72:73], off
	v_lshl_add_u64 v[74:75], v[74:75], 0, s[96:97]
	s_add_u32 m0, s94, 0xa000
	s_nop 1
	global_load_lds_dwordx4 v[74:75], off
	v_lshl_add_u64 v[76:77], v[76:77], 0, s[96:97]
	s_add_u32 m0, s94, 0xe000
	s_nop 1
	global_load_lds_dwordx4 v[76:77], off
	v_lshl_add_u64 v[78:79], v[78:79], 0, s[96:97]
	s_add_u32 m0, s94, 0xb000
	s_nop 1
	global_load_lds_dwordx4 v[78:79], off
	v_lshl_add_u64 v[80:81], v[80:81], 0, s[96:97]
	s_add_u32 m0, s94, 0xf000
	s_nop 1
	global_load_lds_dwordx4 v[80:81], off
	s_waitcnt lgkmcnt(4)
	v_mfma_f32_32x32x16_bf16 v[32:47], v[0:3], v[4:7], 0
	ds_read_b128 v[20:23], v170 offset:4096
	ds_read_b128 v[102:105], v171 offset:4096
	s_waitcnt lgkmcnt(3)
	v_mfma_f32_32x32x16_bf16 v[48:63], v[0:3], v[16:19], 0
	s_waitcnt lgkmcnt(1)
	v_mfma_f32_32x32x16_bf16 v[0:15], v[20:23], v[4:7], 0
	v_mfma_f32_32x32x16_bf16 v[16:31], v[20:23], v[16:19], 0
	v_mfma_f32_32x32x16_bf16 v[32:47], v[88:91], v[92:95], v[32:47]
	v_mfma_f32_32x32x16_bf16 v[48:63], v[88:91], v[98:101], v[48:63]
	s_waitcnt lgkmcnt(0)
	v_mfma_f32_32x32x16_bf16 v[0:15], v[102:105], v[92:95], v[0:15]
	v_mfma_f32_32x32x16_bf16 v[16:31], v[102:105], v[98:101], v[16:31]
	ds_read_b128 v[88:91], v172 offset:0
	ds_read_b128 v[92:95], v176 offset:16384
	ds_read_b128 v[98:101], v173 offset:0
	ds_read_b128 v[102:105], v177 offset:16384
	ds_read_b128 v[106:109], v176 offset:20480
	ds_read_b128 v[110:113], v177 offset:20480
	s_waitcnt lgkmcnt(4)
	v_mfma_f32_32x32x16_bf16 v[32:47], v[88:91], v[92:95], v[32:47]
	s_waitcnt lgkmcnt(1)
	v_mfma_f32_32x32x16_bf16 v[48:63], v[88:91], v[106:109], v[48:63]
	ds_read_b128 v[88:91], v172 offset:4096
	ds_read_b128 v[114:117], v173 offset:4096
	s_waitcnt lgkmcnt(1)
	v_mfma_f32_32x32x16_bf16 v[0:15], v[88:91], v[92:95], v[0:15]
	v_mfma_f32_32x32x16_bf16 v[16:31], v[88:91], v[106:109], v[16:31]
	v_mfma_f32_32x32x16_bf16 v[32:47], v[98:101], v[102:105], v[32:47]
	v_mfma_f32_32x32x16_bf16 v[48:63], v[98:101], v[110:113], v[48:63]
	s_waitcnt lgkmcnt(0)
	v_mfma_f32_32x32x16_bf16 v[0:15], v[114:117], v[102:105], v[0:15]
	s_waitcnt vmcnt(0)
	s_barrier
;     ...
;   bf16* As1 = As + 2 * 128 * 72;
;   bf16* Bs1 = As1 + 128 * 72;
;   G_LOAD(ra0, rb0, 0);
;   if (nk > 1) G_LOAD(ra1, rb1, 1);
;   G_STORE(ra0, rb0, As, Bs);
;   __syncthreads();
;   for (int kt = 0; kt < nk; kt += 2) {
;     if (kt + 2 < nk) G_LOAD(ra0, rb0, kt + 2);
;     if (kt + 1 < nk) G_STORE(ra1, rb1, As1, Bs1);
;     G_COMPUTE(As, Bs);
;     __syncthreads();
;     if (kt + 1 < nk) {
;       if (kt + 3 < nk) G_LOAD(ra1, rb1, kt + 3);
;       if (kt + 2 < nk) G_STORE(ra0, rb0, As, Bs);
;       G_COMPUTE(As1, Bs1);
;       __syncthreads();
;     }
;   }
	v_mfma_f32_32x32x16_bf16 v[16:31], v[114:117], v[110:113], v[16:31]
	ds_read_b128 v[88:91], v170 offset:32768
	ds_read_b128 v[92:95], v174 offset:49152
	ds_read_b128 v[98:101], v171 offset:32768
	ds_read_b128 v[102:105], v175 offset:49152
	ds_read_b128 v[106:109], v174 offset:53248
	ds_read_b128 v[110:113], v175 offset:53248
	v_lshl_add_u64 v[66:67], v[66:67], 0, s[96:97]
	s_add_u32 m0, s94, 0x0
	s_nop 1
	global_load_lds_dwordx4 v[66:67], off
	v_lshl_add_u64 v[68:69], v[68:69], 0, s[96:97]
	s_add_u32 m0, s94, 0x4000
	s_nop 1
	global_load_lds_dwordx4 v[68:69], off
	v_lshl_add_u64 v[70:71], v[70:71], 0, s[96:97]
	s_add_u32 m0, s94, 0x1000
	s_nop 1
	global_load_lds_dwordx4 v[70:71], off
	v_lshl_add_u64 v[72:73], v[72:73], 0, s[96:97]
	s_add_u32 m0, s94, 0x5000
	s_nop 1
	global_load_lds_dwordx4 v[72:73], off
	v_lshl_add_u64 v[74:75], v[74:75], 0, s[96:97]
	s_add_u32 m0, s94, 0x2000
	s_nop 1
	global_load_lds_dwordx4 v[74:75], off
	v_lshl_add_u64 v[76:77], v[76:77], 0, s[96:97]
	s_add_u32 m0, s94, 0x6000
	s_nop 1
	global_load_lds_dwordx4 v[76:77], off
	v_lshl_add_u64 v[78:79], v[78:79], 0, s[96:97]
	s_add_u32 m0, s94, 0x3000
	s_nop 1
	global_load_lds_dwordx4 v[78:79], off
	v_lshl_add_u64 v[80:81], v[80:81], 0, s[96:97]
	s_add_u32 m0, s94, 0x7000
	s_nop 1
	global_load_lds_dwordx4 v[80:81], off
	s_waitcnt lgkmcnt(4)
	v_mfma_f32_32x32x16_bf16 v[32:47], v[88:91], v[92:95], v[32:47]
	s_waitcnt lgkmcnt(1)
	v_mfma_f32_32x32x16_bf16 v[48:63], v[88:91], v[106:109], v[48:63]
	ds_read_b128 v[88:91], v170 offset:36864
	ds_read_b128 v[114:117], v171 offset:36864
	s_waitcnt lgkmcnt(1)
	v_mfma_f32_32x32x16_bf16 v[0:15], v[88:91], v[92:95], v[0:15]
	v_mfma_f32_32x32x16_bf16 v[16:31], v[88:91], v[106:109], v[16:31]
	v_mfma_f32_32x32x16_bf16 v[32:47], v[98:101], v[102:105], v[32:47]
	v_mfma_f32_32x32x16_bf16 v[48:63], v[98:101], v[110:113], v[48:63]
	s_waitcnt lgkmcnt(0)
	v_mfma_f32_32x32x16_bf16 v[0:15], v[114:117], v[102:105], v[0:15]
	ds_read_b128 v[88:91], v172 offset:32768
	ds_read_b128 v[92:95], v176 offset:49152
	ds_read_b128 v[98:101], v173 offset:32768
	ds_read_b128 v[102:105], v177 offset:49152
	v_mfma_f32_32x32x16_bf16 v[16:31], v[114:117], v[110:113], v[16:31]
	ds_read_b128 v[106:109], v176 offset:53248
	ds_read_b128 v[110:113], v177 offset:53248
	s_waitcnt lgkmcnt(4)
	v_mfma_f32_32x32x16_bf16 v[32:47], v[88:91], v[92:95], v[32:47]
	s_waitcnt lgkmcnt(1)
	v_mfma_f32_32x32x16_bf16 v[48:63], v[88:91], v[106:109], v[48:63]
	ds_read_b128 v[88:91], v172 offset:36864
	ds_read_b128 v[114:117], v173 offset:36864
	s_waitcnt lgkmcnt(1)
	v_mfma_f32_32x32x16_bf16 v[0:15], v[88:91], v[92:95], v[0:15]
	v_mfma_f32_32x32x16_bf16 v[16:31], v[88:91], v[106:109], v[16:31]
	v_mfma_f32_32x32x16_bf16 v[32:47], v[98:101], v[102:105], v[32:47]
	v_mfma_f32_32x32x16_bf16 v[48:63], v[98:101], v[110:113], v[48:63]
	s_waitcnt lgkmcnt(0)
	v_mfma_f32_32x32x16_bf16 v[0:15], v[114:117], v[102:105], v[0:15]
	s_waitcnt vmcnt(0)
	s_barrier
	v_mfma_f32_32x32x16_bf16 v[16:31], v[114:117], v[110:113], v[16:31]
	ds_read_b128 v[88:91], v170 offset:0
	ds_read_b128 v[92:95], v174 offset:16384
	ds_read_b128 v[98:101], v171 offset:0
	ds_read_b128 v[102:105], v175 offset:16384
	ds_read_b128 v[106:109], v174 offset:20480
	ds_read_b128 v[110:113], v175 offset:20480
	v_lshl_add_u64 v[66:67], v[66:67], 0, s[96:97]
	s_add_u32 m0, s94, 0x8000
	s_nop 1
	global_load_lds_dwordx4 v[66:67], off
	v_lshl_add_u64 v[68:69], v[68:69], 0, s[96:97]
	s_add_u32 m0, s94, 0xc000
	s_nop 1
	global_load_lds_dwordx4 v[68:69], off
	v_lshl_add_u64 v[70:71], v[70:71], 0, s[96:97]
	s_add_u32 m0, s94, 0x9000
	s_nop 1
	global_load_lds_dwordx4 v[70:71], off
	v_lshl_add_u64 v[72:73], v[72:73], 0, s[96:97]
	s_add_u32 m0, s94, 0xd000
	s_nop 1
	global_load_lds_dwordx4 v[72:73], off
	v_lshl_add_u64 v[74:75], v[74:75], 0, s[96:97]
	s_add_u32 m0, s94, 0xa000
	s_nop 1
	global_load_lds_dwordx4 v[74:75], off
	v_lshl_add_u64 v[76:77], v[76:77], 0, s[96:97]
	s_add_u32 m0, s94, 0xe000
	s_nop 1
	global_load_lds_dwordx4 v[76:77], off
	v_lshl_add_u64 v[78:79], v[78:79], 0, s[96:97]
	s_add_u32 m0, s94, 0xb000
	s_nop 1
	global_load_lds_dwordx4 v[78:79], off
	v_lshl_add_u64 v[80:81], v[80:81], 0, s[96:97]
	s_add_u32 m0, s94, 0xf000
	s_nop 1
	global_load_lds_dwordx4 v[80:81], off
	s_waitcnt lgkmcnt(4)
	v_mfma_f32_32x32x16_bf16 v[32:47], v[88:91], v[92:95], v[32:47]
	s_waitcnt lgkmcnt(1)
	v_mfma_f32_32x32x16_bf16 v[48:63], v[88:91], v[106:109], v[48:63]
	ds_read_b128 v[88:91], v170 offset:4096
	ds_read_b128 v[114:117], v171 offset:4096
	s_waitcnt lgkmcnt(1)
	v_mfma_f32_32x32x16_bf16 v[0:15], v[88:91], v[92:95], v[0:15]
	v_mfma_f32_32x32x16_bf16 v[16:31], v[88:91], v[106:109], v[16:31]
	v_mfma_f32_32x32x16_bf16 v[32:47], v[98:101], v[102:105], v[32:47]
	v_mfma_f32_32x32x16_bf16 v[48:63], v[98:101], v[110:113], v[48:63]
	s_waitcnt lgkmcnt(0)
	v_mfma_f32_32x32x16_bf16 v[0:15], v[114:117], v[102:105], v[0:15]
	ds_read_b128 v[88:91], v172 offset:0
	ds_read_b128 v[92:95], v176 offset:16384
	ds_read_b128 v[98:101], v173 offset:0
	ds_read_b128 v[102:105], v177 offset:16384
	v_mfma_f32_32x32x16_bf16 v[16:31], v[114:117], v[110:113], v[16:31]
	ds_read_b128 v[106:109], v176 offset:20480
	ds_read_b128 v[110:113], v177 offset:20480
	s_waitcnt lgkmcnt(4)
	v_mfma_f32_32x32x16_bf16 v[32:47], v[88:91], v[92:95], v[32:47]
	s_waitcnt lgkmcnt(1)
	v_mfma_f32_32x32x16_bf16 v[48:63], v[88:91], v[106:109], v[48:63]
	ds_read_b128 v[88:91], v172 offset:4096
	ds_read_b128 v[114:117], v173 offset:4096
	s_waitcnt lgkmcnt(1)
	v_mfma_f32_32x32x16_bf16 v[0:15], v[88:91], v[92:95], v[0:15]
	v_mfma_f32_32x32x16_bf16 v[16:31], v[88:91], v[106:109], v[16:31]
	v_mfma_f32_32x32x16_bf16 v[32:47], v[98:101], v[102:105], v[32:47]
	v_mfma_f32_32x32x16_bf16 v[48:63], v[98:101], v[110:113], v[48:63]
	s_waitcnt lgkmcnt(0)
	v_mfma_f32_32x32x16_bf16 v[0:15], v[114:117], v[102:105], v[0:15]
	s_waitcnt vmcnt(0)
	s_barrier
;     ...
;   bf16* As1 = As + 2 * 128 * 72;
;   bf16* Bs1 = As1 + 128 * 72;
;   G_LOAD(ra0, rb0, 0);
;   if (nk > 1) G_LOAD(ra1, rb1, 1);
;   G_STORE(ra0, rb0, As, Bs);
;   __syncthreads();
;   for (int kt = 0; kt < nk; kt += 2) {
;     if (kt + 2 < nk) G_LOAD(ra0, rb0, kt + 2);
;     if (kt + 1 < nk) G_STORE(ra1, rb1, As1, Bs1);
;     G_COMPUTE(As, Bs);
;     __syncthreads();
;     if (kt + 1 < nk) {
;       if (kt + 3 < nk) G_LOAD(ra1, rb1, kt + 3);
;       if (kt + 2 < nk) G_STORE(ra0, rb0, As, Bs);
;       G_COMPUTE(As1, Bs1);
;       __syncthreads();
;     }
;   }
	v_mfma_f32_32x32x16_bf16 v[16:31], v[114:117], v[110:113], v[16:31]
	ds_read_b128 v[88:91], v170 offset:32768
	ds_read_b128 v[92:95], v174 offset:49152
	ds_read_b128 v[98:101], v171 offset:32768
	ds_read_b128 v[102:105], v175 offset:49152
	ds_read_b128 v[106:109], v174 offset:53248
	ds_read_b128 v[110:113], v175 offset:53248
	v_lshl_add_u64 v[66:67], v[66:67], 0, s[96:97]
	s_add_u32 m0, s94, 0x0
	s_nop 1
	global_load_lds_dwordx4 v[66:67], off
	v_lshl_add_u64 v[68:69], v[68:69], 0, s[96:97]
	s_add_u32 m0, s94, 0x4000
	s_nop 1
	global_load_lds_dwordx4 v[68:69], off
	v_lshl_add_u64 v[70:71], v[70:71], 0, s[96:97]
	s_add_u32 m0, s94, 0x1000
	s_nop 1
	global_load_lds_dwordx4 v[70:71], off
	v_lshl_add_u64 v[72:73], v[72:73], 0, s[96:97]
	s_add_u32 m0, s94, 0x5000
	s_nop 1
	global_load_lds_dwordx4 v[72:73], off
	v_lshl_add_u64 v[74:75], v[74:75], 0, s[96:97]
	s_add_u32 m0, s94, 0x2000
	s_nop 1
	global_load_lds_dwordx4 v[74:75], off
	v_lshl_add_u64 v[76:77], v[76:77], 0, s[96:97]
	s_add_u32 m0, s94, 0x6000
	s_nop 1
	global_load_lds_dwordx4 v[76:77], off
	v_lshl_add_u64 v[78:79], v[78:79], 0, s[96:97]
	s_add_u32 m0, s94, 0x3000
	s_nop 1
	global_load_lds_dwordx4 v[78:79], off
	v_lshl_add_u64 v[80:81], v[80:81], 0, s[96:97]
	s_add_u32 m0, s94, 0x7000
	s_nop 1
	global_load_lds_dwordx4 v[80:81], off
	s_waitcnt lgkmcnt(4)
	v_mfma_f32_32x32x16_bf16 v[32:47], v[88:91], v[92:95], v[32:47]
	s_waitcnt lgkmcnt(1)
	v_mfma_f32_32x32x16_bf16 v[48:63], v[88:91], v[106:109], v[48:63]
	ds_read_b128 v[88:91], v170 offset:36864
	ds_read_b128 v[114:117], v171 offset:36864
	s_waitcnt lgkmcnt(1)
	v_mfma_f32_32x32x16_bf16 v[0:15], v[88:91], v[92:95], v[0:15]
	v_mfma_f32_32x32x16_bf16 v[16:31], v[88:91], v[106:109], v[16:31]
	v_mfma_f32_32x32x16_bf16 v[32:47], v[98:101], v[102:105], v[32:47]
	v_mfma_f32_32x32x16_bf16 v[48:63], v[98:101], v[110:113], v[48:63]
	s_waitcnt lgkmcnt(0)
	v_mfma_f32_32x32x16_bf16 v[0:15], v[114:117], v[102:105], v[0:15]
	ds_read_b128 v[88:91], v172 offset:32768
	ds_read_b128 v[92:95], v176 offset:49152
	ds_read_b128 v[98:101], v173 offset:32768
	ds_read_b128 v[102:105], v177 offset:49152
	v_mfma_f32_32x32x16_bf16 v[16:31], v[114:117], v[110:113], v[16:31]
	ds_read_b128 v[106:109], v176 offset:53248
	ds_read_b128 v[110:113], v177 offset:53248
	s_waitcnt lgkmcnt(4)
	v_mfma_f32_32x32x16_bf16 v[32:47], v[88:91], v[92:95], v[32:47]
	s_waitcnt lgkmcnt(1)
	v_mfma_f32_32x32x16_bf16 v[48:63], v[88:91], v[106:109], v[48:63]
	ds_read_b128 v[88:91], v172 offset:36864
	ds_read_b128 v[114:117], v173 offset:36864
	s_waitcnt lgkmcnt(1)
	v_mfma_f32_32x32x16_bf16 v[0:15], v[88:91], v[92:95], v[0:15]
	v_mfma_f32_32x32x16_bf16 v[16:31], v[88:91], v[106:109], v[16:31]
	v_mfma_f32_32x32x16_bf16 v[32:47], v[98:101], v[102:105], v[32:47]
	v_mfma_f32_32x32x16_bf16 v[48:63], v[98:101], v[110:113], v[48:63]
	s_waitcnt lgkmcnt(0)
	v_mfma_f32_32x32x16_bf16 v[0:15], v[114:117], v[102:105], v[0:15]
	s_waitcnt vmcnt(0)
	s_barrier
	v_mfma_f32_32x32x16_bf16 v[16:31], v[114:117], v[110:113], v[16:31]
	ds_read_b128 v[88:91], v170 offset:0
	ds_read_b128 v[92:95], v174 offset:16384
	ds_read_b128 v[98:101], v171 offset:0
	ds_read_b128 v[102:105], v175 offset:16384
	ds_read_b128 v[106:109], v174 offset:20480
	ds_read_b128 v[110:113], v175 offset:20480
	v_lshl_add_u64 v[66:67], v[66:67], 0, s[96:97]
	s_add_u32 m0, s94, 0x8000
	s_nop 1
	global_load_lds_dwordx4 v[66:67], off
	v_lshl_add_u64 v[68:69], v[68:69], 0, s[96:97]
	s_add_u32 m0, s94, 0xc000
	s_nop 1
	global_load_lds_dwordx4 v[68:69], off
	v_lshl_add_u64 v[70:71], v[70:71], 0, s[96:97]
	s_add_u32 m0, s94, 0x9000
	s_nop 1
	global_load_lds_dwordx4 v[70:71], off
	v_lshl_add_u64 v[72:73], v[72:73], 0, s[96:97]
	s_add_u32 m0, s94, 0xd000
	s_nop 1
	global_load_lds_dwordx4 v[72:73], off
	v_lshl_add_u64 v[74:75], v[74:75], 0, s[96:97]
	s_add_u32 m0, s94, 0xa000
	s_nop 1
	global_load_lds_dwordx4 v[74:75], off
	v_lshl_add_u64 v[76:77], v[76:77], 0, s[96:97]
	s_add_u32 m0, s94, 0xe000
	s_nop 1
	global_load_lds_dwordx4 v[76:77], off
	v_lshl_add_u64 v[78:79], v[78:79], 0, s[96:97]
	s_add_u32 m0, s94, 0xb000
	s_nop 1
	global_load_lds_dwordx4 v[78:79], off
	v_lshl_add_u64 v[80:81], v[80:81], 0, s[96:97]
	s_add_u32 m0, s94, 0xf000
	s_nop 1
	global_load_lds_dwordx4 v[80:81], off
	s_waitcnt lgkmcnt(4)
	v_mfma_f32_32x32x16_bf16 v[32:47], v[88:91], v[92:95], v[32:47]
	s_waitcnt lgkmcnt(1)
	v_mfma_f32_32x32x16_bf16 v[48:63], v[88:91], v[106:109], v[48:63]
	ds_read_b128 v[88:91], v170 offset:4096
	ds_read_b128 v[114:117], v171 offset:4096
	s_waitcnt lgkmcnt(1)
	v_mfma_f32_32x32x16_bf16 v[0:15], v[88:91], v[92:95], v[0:15]
	v_mfma_f32_32x32x16_bf16 v[16:31], v[88:91], v[106:109], v[16:31]
	v_mfma_f32_32x32x16_bf16 v[32:47], v[98:101], v[102:105], v[32:47]
	v_mfma_f32_32x32x16_bf16 v[48:63], v[98:101], v[110:113], v[48:63]
	s_waitcnt lgkmcnt(0)
	v_mfma_f32_32x32x16_bf16 v[0:15], v[114:117], v[102:105], v[0:15]
	ds_read_b128 v[88:91], v172 offset:0
	ds_read_b128 v[92:95], v176 offset:16384
	ds_read_b128 v[98:101], v173 offset:0
	ds_read_b128 v[102:105], v177 offset:16384
	v_mfma_f32_32x32x16_bf16 v[16:31], v[114:117], v[110:113], v[16:31]
	ds_read_b128 v[106:109], v176 offset:20480
	ds_read_b128 v[110:113], v177 offset:20480
	s_waitcnt lgkmcnt(4)
	v_mfma_f32_32x32x16_bf16 v[32:47], v[88:91], v[92:95], v[32:47]
	s_waitcnt lgkmcnt(1)
	v_mfma_f32_32x32x16_bf16 v[48:63], v[88:91], v[106:109], v[48:63]
	ds_read_b128 v[88:91], v172 offset:4096
	ds_read_b128 v[114:117], v173 offset:4096
	s_waitcnt lgkmcnt(1)
	v_mfma_f32_32x32x16_bf16 v[0:15], v[88:91], v[92:95], v[0:15]
	v_mfma_f32_32x32x16_bf16 v[16:31], v[88:91], v[106:109], v[16:31]
	v_mfma_f32_32x32x16_bf16 v[32:47], v[98:101], v[102:105], v[32:47]
	v_mfma_f32_32x32x16_bf16 v[48:63], v[98:101], v[110:113], v[48:63]
	s_waitcnt lgkmcnt(0)
	v_mfma_f32_32x32x16_bf16 v[0:15], v[114:117], v[102:105], v[0:15]
	s_waitcnt vmcnt(0)
	s_barrier
;     ...
;   bf16* As1 = As + 2 * 128 * 72;
;   bf16* Bs1 = As1 + 128 * 72;
;   G_LOAD(ra0, rb0, 0);
;   if (nk > 1) G_LOAD(ra1, rb1, 1);
;   G_STORE(ra0, rb0, As, Bs);
;   __syncthreads();
;   for (int kt = 0; kt < nk; kt += 2) {
;     if (kt + 2 < nk) G_LOAD(ra0, rb0, kt + 2);
;     if (kt + 1 < nk) G_STORE(ra1, rb1, As1, Bs1);
;     G_COMPUTE(As, Bs);
;     __syncthreads();
;     if (kt + 1 < nk) {
;       if (kt + 3 < nk) G_LOAD(ra1, rb1, kt + 3);
;       if (kt + 2 < nk) G_STORE(ra0, rb0, As, Bs);
;       G_COMPUTE(As1, Bs1);
;       __syncthreads();
;     }
;   }
	v_mfma_f32_32x32x16_bf16 v[16:31], v[114:117], v[110:113], v[16:31]
	ds_read_b128 v[88:91], v170 offset:32768
	ds_read_b128 v[92:95], v174 offset:49152
	ds_read_b128 v[98:101], v171 offset:32768
	ds_read_b128 v[102:105], v175 offset:49152
	ds_read_b128 v[106:109], v174 offset:53248
	ds_read_b128 v[110:113], v175 offset:53248
	v_lshl_add_u64 v[66:67], v[66:67], 0, s[96:97]
	s_add_u32 m0, s94, 0x0
	s_nop 1
	global_load_lds_dwordx4 v[66:67], off
	v_lshl_add_u64 v[68:69], v[68:69], 0, s[96:97]
	s_add_u32 m0, s94, 0x4000
	s_nop 1
	global_load_lds_dwordx4 v[68:69], off
	v_lshl_add_u64 v[70:71], v[70:71], 0, s[96:97]
	s_add_u32 m0, s94, 0x1000
	s_nop 1
	global_load_lds_dwordx4 v[70:71], off
	v_lshl_add_u64 v[72:73], v[72:73], 0, s[96:97]
	s_add_u32 m0, s94, 0x5000
	s_nop 1
	global_load_lds_dwordx4 v[72:73], off
	v_lshl_add_u64 v[74:75], v[74:75], 0, s[96:97]
	s_add_u32 m0, s94, 0x2000
	s_nop 1
	global_load_lds_dwordx4 v[74:75], off
	v_lshl_add_u64 v[76:77], v[76:77], 0, s[96:97]
	s_add_u32 m0, s94, 0x6000
	s_nop 1
	global_load_lds_dwordx4 v[76:77], off
	v_lshl_add_u64 v[78:79], v[78:79], 0, s[96:97]
	s_add_u32 m0, s94, 0x3000
	s_nop 1
	global_load_lds_dwordx4 v[78:79], off
	v_lshl_add_u64 v[80:81], v[80:81], 0, s[96:97]
	s_add_u32 m0, s94, 0x7000
	s_nop 1
	global_load_lds_dwordx4 v[80:81], off
	s_waitcnt lgkmcnt(4)
	v_mfma_f32_32x32x16_bf16 v[32:47], v[88:91], v[92:95], v[32:47]
	s_waitcnt lgkmcnt(1)
	v_mfma_f32_32x32x16_bf16 v[48:63], v[88:91], v[106:109], v[48:63]
	ds_read_b128 v[88:91], v170 offset:36864
	ds_read_b128 v[114:117], v171 offset:36864
	s_waitcnt lgkmcnt(1)
	v_mfma_f32_32x32x16_bf16 v[0:15], v[88:91], v[92:95], v[0:15]
	v_mfma_f32_32x32x16_bf16 v[16:31], v[88:91], v[106:109], v[16:31]
	v_mfma_f32_32x32x16_bf16 v[32:47], v[98:101], v[102:105], v[32:47]
	v_mfma_f32_32x32x16_bf16 v[48:63], v[98:101], v[110:113], v[48:63]
	s_waitcnt lgkmcnt(0)
	v_mfma_f32_32x32x16_bf16 v[0:15], v[114:117], v[102:105], v[0:15]
	ds_read_b128 v[88:91], v172 offset:32768
	ds_read_b128 v[92:95], v176 offset:49152
	ds_read_b128 v[98:101], v173 offset:32768
	ds_read_b128 v[102:105], v177 offset:49152
	v_mfma_f32_32x32x16_bf16 v[16:31], v[114:117], v[110:113], v[16:31]
	ds_read_b128 v[106:109], v176 offset:53248
	ds_read_b128 v[110:113], v177 offset:53248
	s_waitcnt lgkmcnt(4)
	v_mfma_f32_32x32x16_bf16 v[32:47], v[88:91], v[92:95], v[32:47]
	s_waitcnt lgkmcnt(1)
	v_mfma_f32_32x32x16_bf16 v[48:63], v[88:91], v[106:109], v[48:63]
	ds_read_b128 v[88:91], v172 offset:36864
	ds_read_b128 v[114:117], v173 offset:36864
	s_waitcnt lgkmcnt(1)
	v_mfma_f32_32x32x16_bf16 v[0:15], v[88:91], v[92:95], v[0:15]
	v_mfma_f32_32x32x16_bf16 v[16:31], v[88:91], v[106:109], v[16:31]
	v_mfma_f32_32x32x16_bf16 v[32:47], v[98:101], v[102:105], v[32:47]
	v_mfma_f32_32x32x16_bf16 v[48:63], v[98:101], v[110:113], v[48:63]
	s_waitcnt lgkmcnt(0)
	v_mfma_f32_32x32x16_bf16 v[0:15], v[114:117], v[102:105], v[0:15]
	s_waitcnt vmcnt(0)
	s_barrier
	v_mfma_f32_32x32x16_bf16 v[16:31], v[114:117], v[110:113], v[16:31]
	ds_read_b128 v[88:91], v170 offset:0
	ds_read_b128 v[92:95], v174 offset:16384
	ds_read_b128 v[98:101], v171 offset:0
	ds_read_b128 v[102:105], v175 offset:16384
	ds_read_b128 v[106:109], v174 offset:20480
	ds_read_b128 v[110:113], v175 offset:20480
	v_lshl_add_u64 v[66:67], v[66:67], 0, s[96:97]
	s_add_u32 m0, s94, 0x8000
	s_nop 1
	global_load_lds_dwordx4 v[66:67], off
	v_lshl_add_u64 v[68:69], v[68:69], 0, s[96:97]
	s_add_u32 m0, s94, 0xc000
	s_nop 1
	global_load_lds_dwordx4 v[68:69], off
	v_lshl_add_u64 v[70:71], v[70:71], 0, s[96:97]
	s_add_u32 m0, s94, 0x9000
	s_nop 1
	global_load_lds_dwordx4 v[70:71], off
	v_lshl_add_u64 v[72:73], v[72:73], 0, s[96:97]
	s_add_u32 m0, s94, 0xd000
	s_nop 1
	global_load_lds_dwordx4 v[72:73], off
	v_lshl_add_u64 v[74:75], v[74:75], 0, s[96:97]
	s_add_u32 m0, s94, 0xa000
	s_nop 1
	global_load_lds_dwordx4 v[74:75], off
	v_lshl_add_u64 v[76:77], v[76:77], 0, s[96:97]
	s_add_u32 m0, s94, 0xe000
	s_nop 1
	global_load_lds_dwordx4 v[76:77], off
	v_lshl_add_u64 v[78:79], v[78:79], 0, s[96:97]
	s_add_u32 m0, s94, 0xb000
	s_nop 1
	global_load_lds_dwordx4 v[78:79], off
	v_lshl_add_u64 v[80:81], v[80:81], 0, s[96:97]
	s_add_u32 m0, s94, 0xf000
	s_nop 1
	global_load_lds_dwordx4 v[80:81], off
	s_waitcnt lgkmcnt(4)
	v_mfma_f32_32x32x16_bf16 v[32:47], v[88:91], v[92:95], v[32:47]
	s_waitcnt lgkmcnt(1)
	v_mfma_f32_32x32x16_bf16 v[48:63], v[88:91], v[106:109], v[48:63]
	ds_read_b128 v[88:91], v170 offset:4096
	ds_read_b128 v[114:117], v171 offset:4096
	s_waitcnt lgkmcnt(1)
	v_mfma_f32_32x32x16_bf16 v[0:15], v[88:91], v[92:95], v[0:15]
	v_mfma_f32_32x32x16_bf16 v[16:31], v[88:91], v[106:109], v[16:31]
	v_mfma_f32_32x32x16_bf16 v[32:47], v[98:101], v[102:105], v[32:47]
	v_mfma_f32_32x32x16_bf16 v[48:63], v[98:101], v[110:113], v[48:63]
	s_waitcnt lgkmcnt(0)
	v_mfma_f32_32x32x16_bf16 v[0:15], v[114:117], v[102:105], v[0:15]
	ds_read_b128 v[88:91], v172 offset:0
	ds_read_b128 v[92:95], v176 offset:16384
	ds_read_b128 v[98:101], v173 offset:0
	ds_read_b128 v[102:105], v177 offset:16384
	v_mfma_f32_32x32x16_bf16 v[16:31], v[114:117], v[110:113], v[16:31]
	ds_read_b128 v[106:109], v176 offset:20480
	ds_read_b128 v[110:113], v177 offset:20480
	s_waitcnt lgkmcnt(4)
	v_mfma_f32_32x32x16_bf16 v[32:47], v[88:91], v[92:95], v[32:47]
	s_waitcnt lgkmcnt(1)
	v_mfma_f32_32x32x16_bf16 v[48:63], v[88:91], v[106:109], v[48:63]
	ds_read_b128 v[88:91], v172 offset:4096
	ds_read_b128 v[114:117], v173 offset:4096
	s_waitcnt lgkmcnt(1)
	v_mfma_f32_32x32x16_bf16 v[0:15], v[88:91], v[92:95], v[0:15]
	v_mfma_f32_32x32x16_bf16 v[16:31], v[88:91], v[106:109], v[16:31]
	v_mfma_f32_32x32x16_bf16 v[32:47], v[98:101], v[102:105], v[32:47]
	v_mfma_f32_32x32x16_bf16 v[48:63], v[98:101], v[110:113], v[48:63]
	s_waitcnt lgkmcnt(0)
	v_mfma_f32_32x32x16_bf16 v[0:15], v[114:117], v[102:105], v[0:15]
	s_waitcnt vmcnt(0)
	s_barrier
;     ...
;   bf16* As1 = As + 2 * 128 * 72;
;   bf16* Bs1 = As1 + 128 * 72;
;   G_LOAD(ra0, rb0, 0);
;   if (nk > 1) G_LOAD(ra1, rb1, 1);
;   G_STORE(ra0, rb0, As, Bs);
;   __syncthreads();
;   for (int kt = 0; kt < nk; kt += 2) {
;     if (kt + 2 < nk) G_LOAD(ra0, rb0, kt + 2);
;     if (kt + 1 < nk) G_STORE(ra1, rb1, As1, Bs1);
;     G_COMPUTE(As, Bs);
;     __syncthreads();
;     if (kt + 1 < nk) {
;       if (kt + 3 < nk) G_LOAD(ra1, rb1, kt + 3);
;       if (kt + 2 < nk) G_STORE(ra0, rb0, As, Bs);
;       G_COMPUTE(As1, Bs1);
;       __syncthreads();
;     }
;   }
	v_mfma_f32_32x32x16_bf16 v[16:31], v[114:117], v[110:113], v[16:31]
	ds_read_b128 v[88:91], v170 offset:32768
	ds_read_b128 v[92:95], v174 offset:49152
	ds_read_b128 v[98:101], v171 offset:32768
	ds_read_b128 v[102:105], v175 offset:49152
	ds_read_b128 v[106:109], v174 offset:53248
	ds_read_b128 v[110:113], v175 offset:53248
	v_lshl_add_u64 v[66:67], v[66:67], 0, s[96:97]
	s_add_u32 m0, s94, 0x0
	s_nop 1
	global_load_lds_dwordx4 v[66:67], off
	v_lshl_add_u64 v[68:69], v[68:69], 0, s[96:97]
	s_add_u32 m0, s94, 0x4000
	s_nop 1
	global_load_lds_dwordx4 v[68:69], off
	v_lshl_add_u64 v[70:71], v[70:71], 0, s[96:97]
	s_add_u32 m0, s94, 0x1000
	s_nop 1
	global_load_lds_dwordx4 v[70:71], off
	v_lshl_add_u64 v[72:73], v[72:73], 0, s[96:97]
	s_add_u32 m0, s94, 0x5000
	s_nop 1
	global_load_lds_dwordx4 v[72:73], off
	v_lshl_add_u64 v[74:75], v[74:75], 0, s[96:97]
	s_add_u32 m0, s94, 0x2000
	s_nop 1
	global_load_lds_dwordx4 v[74:75], off
	v_lshl_add_u64 v[76:77], v[76:77], 0, s[96:97]
	s_add_u32 m0, s94, 0x6000
	s_nop 1
	global_load_lds_dwordx4 v[76:77], off
	v_lshl_add_u64 v[78:79], v[78:79], 0, s[96:97]
	s_add_u32 m0, s94, 0x3000
	s_nop 1
	global_load_lds_dwordx4 v[78:79], off
	v_lshl_add_u64 v[80:81], v[80:81], 0, s[96:97]
	s_add_u32 m0, s94, 0x7000
	s_nop 1
	global_load_lds_dwordx4 v[80:81], off
	s_waitcnt lgkmcnt(4)
	v_mfma_f32_32x32x16_bf16 v[32:47], v[88:91], v[92:95], v[32:47]
	s_waitcnt lgkmcnt(1)
	v_mfma_f32_32x32x16_bf16 v[48:63], v[88:91], v[106:109], v[48:63]
	ds_read_b128 v[88:91], v170 offset:36864
	ds_read_b128 v[114:117], v171 offset:36864
	s_waitcnt lgkmcnt(1)
	v_mfma_f32_32x32x16_bf16 v[0:15], v[88:91], v[92:95], v[0:15]
	v_mfma_f32_32x32x16_bf16 v[16:31], v[88:91], v[106:109], v[16:31]
	v_mfma_f32_32x32x16_bf16 v[32:47], v[98:101], v[102:105], v[32:47]
	v_mfma_f32_32x32x16_bf16 v[48:63], v[98:101], v[110:113], v[48:63]
	s_waitcnt lgkmcnt(0)
	v_mfma_f32_32x32x16_bf16 v[0:15], v[114:117], v[102:105], v[0:15]
	ds_read_b128 v[88:91], v172 offset:32768
	ds_read_b128 v[92:95], v176 offset:49152
	ds_read_b128 v[98:101], v173 offset:32768
	ds_read_b128 v[102:105], v177 offset:49152
	v_mfma_f32_32x32x16_bf16 v[16:31], v[114:117], v[110:113], v[16:31]
	ds_read_b128 v[106:109], v176 offset:53248
	ds_read_b128 v[110:113], v177 offset:53248
	s_waitcnt lgkmcnt(4)
	v_mfma_f32_32x32x16_bf16 v[32:47], v[88:91], v[92:95], v[32:47]
	s_waitcnt lgkmcnt(1)
	v_mfma_f32_32x32x16_bf16 v[48:63], v[88:91], v[106:109], v[48:63]
	ds_read_b128 v[88:91], v172 offset:36864
	ds_read_b128 v[114:117], v173 offset:36864
	s_waitcnt lgkmcnt(1)
	v_mfma_f32_32x32x16_bf16 v[0:15], v[88:91], v[92:95], v[0:15]
	v_mfma_f32_32x32x16_bf16 v[16:31], v[88:91], v[106:109], v[16:31]
	v_mfma_f32_32x32x16_bf16 v[32:47], v[98:101], v[102:105], v[32:47]
	v_mfma_f32_32x32x16_bf16 v[48:63], v[98:101], v[110:113], v[48:63]
	s_waitcnt lgkmcnt(0)
	v_mfma_f32_32x32x16_bf16 v[0:15], v[114:117], v[102:105], v[0:15]
	s_waitcnt vmcnt(0)
	s_barrier
	v_mfma_f32_32x32x16_bf16 v[16:31], v[114:117], v[110:113], v[16:31]
	ds_read_b128 v[88:91], v170 offset:0
	ds_read_b128 v[92:95], v174 offset:16384
	ds_read_b128 v[98:101], v171 offset:0
	ds_read_b128 v[102:105], v175 offset:16384
	ds_read_b128 v[106:109], v174 offset:20480
	ds_read_b128 v[110:113], v175 offset:20480
	v_lshl_add_u64 v[66:67], v[66:67], 0, s[96:97]
	s_add_u32 m0, s94, 0x8000
	s_nop 1
	global_load_lds_dwordx4 v[66:67], off
	v_lshl_add_u64 v[68:69], v[68:69], 0, s[96:97]
	s_add_u32 m0, s94, 0xc000
	s_nop 1
	global_load_lds_dwordx4 v[68:69], off
	v_lshl_add_u64 v[70:71], v[70:71], 0, s[96:97]
	s_add_u32 m0, s94, 0x9000
	s_nop 1
	global_load_lds_dwordx4 v[70:71], off
	v_lshl_add_u64 v[72:73], v[72:73], 0, s[96:97]
	s_add_u32 m0, s94, 0xd000
	s_nop 1
	global_load_lds_dwordx4 v[72:73], off
	v_lshl_add_u64 v[74:75], v[74:75], 0, s[96:97]
	s_add_u32 m0, s94, 0xa000
	s_nop 1
	global_load_lds_dwordx4 v[74:75], off
	v_lshl_add_u64 v[76:77], v[76:77], 0, s[96:97]
	s_add_u32 m0, s94, 0xe000
	s_nop 1
	global_load_lds_dwordx4 v[76:77], off
	v_lshl_add_u64 v[78:79], v[78:79], 0, s[96:97]
	s_add_u32 m0, s94, 0xb000
	s_nop 1
	global_load_lds_dwordx4 v[78:79], off
	v_lshl_add_u64 v[80:81], v[80:81], 0, s[96:97]
	s_add_u32 m0, s94, 0xf000
	s_nop 1
	global_load_lds_dwordx4 v[80:81], off
	s_waitcnt lgkmcnt(4)
	v_mfma_f32_32x32x16_bf16 v[32:47], v[88:91], v[92:95], v[32:47]
	s_waitcnt lgkmcnt(1)
	v_mfma_f32_32x32x16_bf16 v[48:63], v[88:91], v[106:109], v[48:63]
	ds_read_b128 v[88:91], v170 offset:4096
	ds_read_b128 v[114:117], v171 offset:4096
	s_waitcnt lgkmcnt(1)
	v_mfma_f32_32x32x16_bf16 v[0:15], v[88:91], v[92:95], v[0:15]
	v_mfma_f32_32x32x16_bf16 v[16:31], v[88:91], v[106:109], v[16:31]
	v_mfma_f32_32x32x16_bf16 v[32:47], v[98:101], v[102:105], v[32:47]
	v_mfma_f32_32x32x16_bf16 v[48:63], v[98:101], v[110:113], v[48:63]
	s_waitcnt lgkmcnt(0)
	v_mfma_f32_32x32x16_bf16 v[0:15], v[114:117], v[102:105], v[0:15]
	ds_read_b128 v[88:91], v172 offset:0
	ds_read_b128 v[92:95], v176 offset:16384
	ds_read_b128 v[98:101], v173 offset:0
	ds_read_b128 v[102:105], v177 offset:16384
	v_mfma_f32_32x32x16_bf16 v[16:31], v[114:117], v[110:113], v[16:31]
	ds_read_b128 v[106:109], v176 offset:20480
	ds_read_b128 v[110:113], v177 offset:20480
	s_waitcnt lgkmcnt(4)
	v_mfma_f32_32x32x16_bf16 v[32:47], v[88:91], v[92:95], v[32:47]
	s_waitcnt lgkmcnt(1)
	v_mfma_f32_32x32x16_bf16 v[48:63], v[88:91], v[106:109], v[48:63]
	ds_read_b128 v[88:91], v172 offset:4096
	ds_read_b128 v[114:117], v173 offset:4096
	s_waitcnt lgkmcnt(1)
	v_mfma_f32_32x32x16_bf16 v[0:15], v[88:91], v[92:95], v[0:15]
	v_mfma_f32_32x32x16_bf16 v[16:31], v[88:91], v[106:109], v[16:31]
	v_mfma_f32_32x32x16_bf16 v[32:47], v[98:101], v[102:105], v[32:47]
	v_mfma_f32_32x32x16_bf16 v[48:63], v[98:101], v[110:113], v[48:63]
	s_waitcnt lgkmcnt(0)
	v_mfma_f32_32x32x16_bf16 v[0:15], v[114:117], v[102:105], v[0:15]
	s_waitcnt vmcnt(0)
	s_barrier
;     ...
;   bf16* As1 = As + 2 * 128 * 72;
;   bf16* Bs1 = As1 + 128 * 72;
;   G_LOAD(ra0, rb0, 0);
;   if (nk > 1) G_LOAD(ra1, rb1, 1);
;   G_STORE(ra0, rb0, As, Bs);
;   __syncthreads();
;   for (int kt = 0; kt < nk; kt += 2) {
;     if (kt + 2 < nk) G_LOAD(ra0, rb0, kt + 2);
;     if (kt + 1 < nk) G_STORE(ra1, rb1, As1, Bs1);
;     G_COMPUTE(As, Bs);
;     __syncthreads();
;     if (kt + 1 < nk) {
;       if (kt + 3 < nk) G_LOAD(ra1, rb1, kt + 3);
;       if (kt + 2 < nk) G_STORE(ra0, rb0, As, Bs);
;       G_COMPUTE(As1, Bs1);
;       __syncthreads();
;     }
;   }
	v_mfma_f32_32x32x16_bf16 v[16:31], v[114:117], v[110:113], v[16:31]
	ds_read_b128 v[88:91], v170 offset:32768
	ds_read_b128 v[92:95], v174 offset:49152
	ds_read_b128 v[98:101], v171 offset:32768
	ds_read_b128 v[102:105], v175 offset:49152
	ds_read_b128 v[106:109], v174 offset:53248
	ds_read_b128 v[110:113], v175 offset:53248
	v_lshl_add_u64 v[66:67], v[66:67], 0, s[96:97]
	s_add_u32 m0, s94, 0x0
	s_nop 1
	global_load_lds_dwordx4 v[66:67], off
	v_lshl_add_u64 v[68:69], v[68:69], 0, s[96:97]
	s_add_u32 m0, s94, 0x4000
	s_nop 1
	global_load_lds_dwordx4 v[68:69], off
	v_lshl_add_u64 v[70:71], v[70:71], 0, s[96:97]
	s_add_u32 m0, s94, 0x1000
	s_nop 1
	global_load_lds_dwordx4 v[70:71], off
	v_lshl_add_u64 v[72:73], v[72:73], 0, s[96:97]
	s_add_u32 m0, s94, 0x5000
	s_nop 1
	global_load_lds_dwordx4 v[72:73], off
	v_lshl_add_u64 v[74:75], v[74:75], 0, s[96:97]
	s_add_u32 m0, s94, 0x2000
	s_nop 1
	global_load_lds_dwordx4 v[74:75], off
	v_lshl_add_u64 v[76:77], v[76:77], 0, s[96:97]
	s_add_u32 m0, s94, 0x6000
	s_nop 1
	global_load_lds_dwordx4 v[76:77], off
	v_lshl_add_u64 v[78:79], v[78:79], 0, s[96:97]
	s_add_u32 m0, s94, 0x3000
	s_nop 1
	global_load_lds_dwordx4 v[78:79], off
	v_lshl_add_u64 v[80:81], v[80:81], 0, s[96:97]
	s_add_u32 m0, s94, 0x7000
	s_nop 1
	global_load_lds_dwordx4 v[80:81], off
	s_waitcnt lgkmcnt(4)
	v_mfma_f32_32x32x16_bf16 v[32:47], v[88:91], v[92:95], v[32:47]
	s_waitcnt lgkmcnt(1)
	v_mfma_f32_32x32x16_bf16 v[48:63], v[88:91], v[106:109], v[48:63]
	ds_read_b128 v[88:91], v170 offset:36864
	ds_read_b128 v[114:117], v171 offset:36864
	s_waitcnt lgkmcnt(1)
	v_mfma_f32_32x32x16_bf16 v[0:15], v[88:91], v[92:95], v[0:15]
	v_mfma_f32_32x32x16_bf16 v[16:31], v[88:91], v[106:109], v[16:31]
	v_mfma_f32_32x32x16_bf16 v[32:47], v[98:101], v[102:105], v[32:47]
	v_mfma_f32_32x32x16_bf16 v[48:63], v[98:101], v[110:113], v[48:63]
	s_waitcnt lgkmcnt(0)
	v_mfma_f32_32x32x16_bf16 v[0:15], v[114:117], v[102:105], v[0:15]
	ds_read_b128 v[88:91], v172 offset:32768
	ds_read_b128 v[92:95], v176 offset:49152
	ds_read_b128 v[98:101], v173 offset:32768
	ds_read_b128 v[102:105], v177 offset:49152
	v_mfma_f32_32x32x16_bf16 v[16:31], v[114:117], v[110:113], v[16:31]
	ds_read_b128 v[106:109], v176 offset:53248
	ds_read_b128 v[110:113], v177 offset:53248
	s_waitcnt lgkmcnt(4)
	v_mfma_f32_32x32x16_bf16 v[32:47], v[88:91], v[92:95], v[32:47]
	s_waitcnt lgkmcnt(1)
	v_mfma_f32_32x32x16_bf16 v[48:63], v[88:91], v[106:109], v[48:63]
	ds_read_b128 v[88:91], v172 offset:36864
	ds_read_b128 v[114:117], v173 offset:36864
	s_waitcnt lgkmcnt(1)
	v_mfma_f32_32x32x16_bf16 v[0:15], v[88:91], v[92:95], v[0:15]
	v_mfma_f32_32x32x16_bf16 v[16:31], v[88:91], v[106:109], v[16:31]
	v_mfma_f32_32x32x16_bf16 v[32:47], v[98:101], v[102:105], v[32:47]
	v_mfma_f32_32x32x16_bf16 v[48:63], v[98:101], v[110:113], v[48:63]
	s_waitcnt lgkmcnt(0)
	v_mfma_f32_32x32x16_bf16 v[0:15], v[114:117], v[102:105], v[0:15]
	s_waitcnt vmcnt(0)
	s_barrier
	v_mfma_f32_32x32x16_bf16 v[16:31], v[114:117], v[110:113], v[16:31]
	ds_read_b128 v[88:91], v170 offset:0
	ds_read_b128 v[92:95], v174 offset:16384
	ds_read_b128 v[98:101], v171 offset:0
	ds_read_b128 v[102:105], v175 offset:16384
	ds_read_b128 v[106:109], v174 offset:20480
	ds_read_b128 v[110:113], v175 offset:20480
	v_lshl_add_u64 v[66:67], v[66:67], 0, s[96:97]
	s_add_u32 m0, s94, 0x8000
	s_nop 1
	global_load_lds_dwordx4 v[66:67], off
	v_lshl_add_u64 v[68:69], v[68:69], 0, s[96:97]
	s_add_u32 m0, s94, 0xc000
	s_nop 1
	global_load_lds_dwordx4 v[68:69], off
	v_lshl_add_u64 v[70:71], v[70:71], 0, s[96:97]
	s_add_u32 m0, s94, 0x9000
	s_nop 1
	global_load_lds_dwordx4 v[70:71], off
	v_lshl_add_u64 v[72:73], v[72:73], 0, s[96:97]
	s_add_u32 m0, s94, 0xd000
	s_nop 1
	global_load_lds_dwordx4 v[72:73], off
	v_lshl_add_u64 v[74:75], v[74:75], 0, s[96:97]
	s_add_u32 m0, s94, 0xa000
	s_nop 1
	global_load_lds_dwordx4 v[74:75], off
	v_lshl_add_u64 v[76:77], v[76:77], 0, s[96:97]
	s_add_u32 m0, s94, 0xe000
	s_nop 1
	global_load_lds_dwordx4 v[76:77], off
	v_lshl_add_u64 v[78:79], v[78:79], 0, s[96:97]
	s_add_u32 m0, s94, 0xb000
	s_nop 1
	global_load_lds_dwordx4 v[78:79], off
	v_lshl_add_u64 v[80:81], v[80:81], 0, s[96:97]
	s_add_u32 m0, s94, 0xf000
	s_nop 1
	global_load_lds_dwordx4 v[80:81], off
	s_waitcnt lgkmcnt(4)
	v_mfma_f32_32x32x16_bf16 v[32:47], v[88:91], v[92:95], v[32:47]
	s_waitcnt lgkmcnt(1)
	v_mfma_f32_32x32x16_bf16 v[48:63], v[88:91], v[106:109], v[48:63]
	ds_read_b128 v[88:91], v170 offset:4096
	ds_read_b128 v[114:117], v171 offset:4096
	s_waitcnt lgkmcnt(1)
	v_mfma_f32_32x32x16_bf16 v[0:15], v[88:91], v[92:95], v[0:15]
	v_mfma_f32_32x32x16_bf16 v[16:31], v[88:91], v[106:109], v[16:31]
	v_mfma_f32_32x32x16_bf16 v[32:47], v[98:101], v[102:105], v[32:47]
	v_mfma_f32_32x32x16_bf16 v[48:63], v[98:101], v[110:113], v[48:63]
	s_waitcnt lgkmcnt(0)
	v_mfma_f32_32x32x16_bf16 v[0:15], v[114:117], v[102:105], v[0:15]
	ds_read_b128 v[88:91], v172 offset:0
	ds_read_b128 v[92:95], v176 offset:16384
	ds_read_b128 v[98:101], v173 offset:0
	ds_read_b128 v[102:105], v177 offset:16384
	v_mfma_f32_32x32x16_bf16 v[16:31], v[114:117], v[110:113], v[16:31]
	ds_read_b128 v[106:109], v176 offset:20480
	ds_read_b128 v[110:113], v177 offset:20480
	s_waitcnt lgkmcnt(4)
	v_mfma_f32_32x32x16_bf16 v[32:47], v[88:91], v[92:95], v[32:47]
	s_waitcnt lgkmcnt(1)
	v_mfma_f32_32x32x16_bf16 v[48:63], v[88:91], v[106:109], v[48:63]
	ds_read_b128 v[88:91], v172 offset:4096
	ds_read_b128 v[114:117], v173 offset:4096
	s_waitcnt lgkmcnt(1)
	v_mfma_f32_32x32x16_bf16 v[0:15], v[88:91], v[92:95], v[0:15]
	v_mfma_f32_32x32x16_bf16 v[16:31], v[88:91], v[106:109], v[16:31]
	v_mfma_f32_32x32x16_bf16 v[32:47], v[98:101], v[102:105], v[32:47]
	v_mfma_f32_32x32x16_bf16 v[48:63], v[98:101], v[110:113], v[48:63]
	s_waitcnt lgkmcnt(0)
	v_mfma_f32_32x32x16_bf16 v[0:15], v[114:117], v[102:105], v[0:15]
	s_waitcnt vmcnt(0)
	s_barrier
;     ...
;   bf16* As1 = As + 2 * 128 * 72;
;   bf16* Bs1 = As1 + 128 * 72;
;   G_LOAD(ra0, rb0, 0);
;   if (nk > 1) G_LOAD(ra1, rb1, 1);
;   G_STORE(ra0, rb0, As, Bs);
;   __syncthreads();
;   for (int kt = 0; kt < nk; kt += 2) {
;     if (kt + 2 < nk) G_LOAD(ra0, rb0, kt + 2);
;     if (kt + 1 < nk) G_STORE(ra1, rb1, As1, Bs1);
;     G_COMPUTE(As, Bs);
;     __syncthreads();
;     if (kt + 1 < nk) {
;       if (kt + 3 < nk) G_LOAD(ra1, rb1, kt + 3);
;       if (kt + 2 < nk) G_STORE(ra0, rb0, As, Bs);
;       G_COMPUTE(As1, Bs1);
;       __syncthreads();
;     }
;   }
	v_mfma_f32_32x32x16_bf16 v[16:31], v[114:117], v[110:113], v[16:31]
	ds_read_b128 v[88:91], v170 offset:32768
	ds_read_b128 v[92:95], v174 offset:49152
	ds_read_b128 v[98:101], v171 offset:32768
	ds_read_b128 v[102:105], v175 offset:49152
	ds_read_b128 v[106:109], v174 offset:53248
	ds_read_b128 v[110:113], v175 offset:53248
	v_lshl_add_u64 v[66:67], v[66:67], 0, s[96:97]
	s_add_u32 m0, s94, 0x0
	s_nop 1
	global_load_lds_dwordx4 v[66:67], off
	v_lshl_add_u64 v[68:69], v[68:69], 0, s[96:97]
	s_add_u32 m0, s94, 0x4000
	s_nop 1
	global_load_lds_dwordx4 v[68:69], off
	v_lshl_add_u64 v[70:71], v[70:71], 0, s[96:97]
	s_add_u32 m0, s94, 0x1000
	s_nop 1
	global_load_lds_dwordx4 v[70:71], off
	v_lshl_add_u64 v[72:73], v[72:73], 0, s[96:97]
	s_add_u32 m0, s94, 0x5000
	s_nop 1
	global_load_lds_dwordx4 v[72:73], off
	v_lshl_add_u64 v[74:75], v[74:75], 0, s[96:97]
	s_add_u32 m0, s94, 0x2000
	s_nop 1
	global_load_lds_dwordx4 v[74:75], off
	v_lshl_add_u64 v[76:77], v[76:77], 0, s[96:97]
	s_add_u32 m0, s94, 0x6000
	s_nop 1
	global_load_lds_dwordx4 v[76:77], off
	v_lshl_add_u64 v[78:79], v[78:79], 0, s[96:97]
	s_add_u32 m0, s94, 0x3000
	s_nop 1
	global_load_lds_dwordx4 v[78:79], off
	v_lshl_add_u64 v[80:81], v[80:81], 0, s[96:97]
	s_add_u32 m0, s94, 0x7000
	s_nop 1
	global_load_lds_dwordx4 v[80:81], off
	s_waitcnt lgkmcnt(4)
	v_mfma_f32_32x32x16_bf16 v[32:47], v[88:91], v[92:95], v[32:47]
	s_waitcnt lgkmcnt(1)
	v_mfma_f32_32x32x16_bf16 v[48:63], v[88:91], v[106:109], v[48:63]
	ds_read_b128 v[88:91], v170 offset:36864
	ds_read_b128 v[114:117], v171 offset:36864
	s_waitcnt lgkmcnt(1)
	v_mfma_f32_32x32x16_bf16 v[0:15], v[88:91], v[92:95], v[0:15]
	v_mfma_f32_32x32x16_bf16 v[16:31], v[88:91], v[106:109], v[16:31]
	v_mfma_f32_32x32x16_bf16 v[32:47], v[98:101], v[102:105], v[32:47]
	v_mfma_f32_32x32x16_bf16 v[48:63], v[98:101], v[110:113], v[48:63]
	s_waitcnt lgkmcnt(0)
	v_mfma_f32_32x32x16_bf16 v[0:15], v[114:117], v[102:105], v[0:15]
	ds_read_b128 v[88:91], v172 offset:32768
	ds_read_b128 v[92:95], v176 offset:49152
	ds_read_b128 v[98:101], v173 offset:32768
	ds_read_b128 v[102:105], v177 offset:49152
	v_mfma_f32_32x32x16_bf16 v[16:31], v[114:117], v[110:113], v[16:31]
	ds_read_b128 v[106:109], v176 offset:53248
	ds_read_b128 v[110:113], v177 offset:53248
	s_waitcnt lgkmcnt(4)
	v_mfma_f32_32x32x16_bf16 v[32:47], v[88:91], v[92:95], v[32:47]
	s_waitcnt lgkmcnt(1)
	v_mfma_f32_32x32x16_bf16 v[48:63], v[88:91], v[106:109], v[48:63]
	ds_read_b128 v[88:91], v172 offset:36864
	ds_read_b128 v[114:117], v173 offset:36864
	s_waitcnt lgkmcnt(1)
	v_mfma_f32_32x32x16_bf16 v[0:15], v[88:91], v[92:95], v[0:15]
	v_mfma_f32_32x32x16_bf16 v[16:31], v[88:91], v[106:109], v[16:31]
	v_mfma_f32_32x32x16_bf16 v[32:47], v[98:101], v[102:105], v[32:47]
	v_mfma_f32_32x32x16_bf16 v[48:63], v[98:101], v[110:113], v[48:63]
	s_waitcnt lgkmcnt(0)
	v_mfma_f32_32x32x16_bf16 v[0:15], v[114:117], v[102:105], v[0:15]
	s_waitcnt vmcnt(0)
	s_barrier
	v_mfma_f32_32x32x16_bf16 v[16:31], v[114:117], v[110:113], v[16:31]
	ds_read_b128 v[88:91], v170 offset:0
	ds_read_b128 v[92:95], v174 offset:16384
	ds_read_b128 v[98:101], v171 offset:0
	ds_read_b128 v[102:105], v175 offset:16384
	ds_read_b128 v[106:109], v174 offset:20480
	ds_read_b128 v[110:113], v175 offset:20480
	v_lshl_add_u64 v[66:67], v[66:67], 0, s[96:97]
	s_add_u32 m0, s94, 0x8000
	s_nop 1
	global_load_lds_dwordx4 v[66:67], off
	v_lshl_add_u64 v[68:69], v[68:69], 0, s[96:97]
	s_add_u32 m0, s94, 0xc000
	s_nop 1
	global_load_lds_dwordx4 v[68:69], off
	v_lshl_add_u64 v[70:71], v[70:71], 0, s[96:97]
	s_add_u32 m0, s94, 0x9000
	s_nop 1
	global_load_lds_dwordx4 v[70:71], off
	v_lshl_add_u64 v[72:73], v[72:73], 0, s[96:97]
	s_add_u32 m0, s94, 0xd000
	s_nop 1
	global_load_lds_dwordx4 v[72:73], off
	v_lshl_add_u64 v[74:75], v[74:75], 0, s[96:97]
	s_add_u32 m0, s94, 0xa000
	s_nop 1
	global_load_lds_dwordx4 v[74:75], off
	v_lshl_add_u64 v[76:77], v[76:77], 0, s[96:97]
	s_add_u32 m0, s94, 0xe000
	s_nop 1
	global_load_lds_dwordx4 v[76:77], off
	v_lshl_add_u64 v[78:79], v[78:79], 0, s[96:97]
	s_add_u32 m0, s94, 0xb000
	s_nop 1
	global_load_lds_dwordx4 v[78:79], off
	v_lshl_add_u64 v[80:81], v[80:81], 0, s[96:97]
	s_add_u32 m0, s94, 0xf000
	s_nop 1
	global_load_lds_dwordx4 v[80:81], off
	s_waitcnt lgkmcnt(4)
	v_mfma_f32_32x32x16_bf16 v[32:47], v[88:91], v[92:95], v[32:47]
	s_waitcnt lgkmcnt(1)
	v_mfma_f32_32x32x16_bf16 v[48:63], v[88:91], v[106:109], v[48:63]
	ds_read_b128 v[88:91], v170 offset:4096
	ds_read_b128 v[114:117], v171 offset:4096
	s_waitcnt lgkmcnt(1)
	v_mfma_f32_32x32x16_bf16 v[0:15], v[88:91], v[92:95], v[0:15]
	v_mfma_f32_32x32x16_bf16 v[16:31], v[88:91], v[106:109], v[16:31]
	v_mfma_f32_32x32x16_bf16 v[32:47], v[98:101], v[102:105], v[32:47]
	v_mfma_f32_32x32x16_bf16 v[48:63], v[98:101], v[110:113], v[48:63]
	s_waitcnt lgkmcnt(0)
	v_mfma_f32_32x32x16_bf16 v[0:15], v[114:117], v[102:105], v[0:15]
	ds_read_b128 v[88:91], v172 offset:0
	ds_read_b128 v[92:95], v176 offset:16384
	ds_read_b128 v[98:101], v173 offset:0
	ds_read_b128 v[102:105], v177 offset:16384
	v_mfma_f32_32x32x16_bf16 v[16:31], v[114:117], v[110:113], v[16:31]
	ds_read_b128 v[106:109], v176 offset:20480
	ds_read_b128 v[110:113], v177 offset:20480
	s_waitcnt lgkmcnt(4)
	v_mfma_f32_32x32x16_bf16 v[32:47], v[88:91], v[92:95], v[32:47]
	s_waitcnt lgkmcnt(1)
	v_mfma_f32_32x32x16_bf16 v[48:63], v[88:91], v[106:109], v[48:63]
	ds_read_b128 v[88:91], v172 offset:4096
	ds_read_b128 v[114:117], v173 offset:4096
	s_waitcnt lgkmcnt(1)
	v_mfma_f32_32x32x16_bf16 v[0:15], v[88:91], v[92:95], v[0:15]
	v_mfma_f32_32x32x16_bf16 v[16:31], v[88:91], v[106:109], v[16:31]
	v_mfma_f32_32x32x16_bf16 v[32:47], v[98:101], v[102:105], v[32:47]
	v_mfma_f32_32x32x16_bf16 v[48:63], v[98:101], v[110:113], v[48:63]
	s_waitcnt lgkmcnt(0)
	v_mfma_f32_32x32x16_bf16 v[0:15], v[114:117], v[102:105], v[0:15]
	s_waitcnt vmcnt(0)
	s_barrier
;     ...
;   bf16* As1 = As + 2 * 128 * 72;
;   bf16* Bs1 = As1 + 128 * 72;
;   G_LOAD(ra0, rb0, 0);
;   if (nk > 1) G_LOAD(ra1, rb1, 1);
;   G_STORE(ra0, rb0, As, Bs);
;   __syncthreads();
;   for (int kt = 0; kt < nk; kt += 2) {
;     if (kt + 2 < nk) G_LOAD(ra0, rb0, kt + 2);
;     if (kt + 1 < nk) G_STORE(ra1, rb1, As1, Bs1);
;     G_COMPUTE(As, Bs);
;     __syncthreads();
;     if (kt + 1 < nk) {
;       if (kt + 3 < nk) G_LOAD(ra1, rb1, kt + 3);
;       if (kt + 2 < nk) G_STORE(ra0, rb0, As, Bs);
;       G_COMPUTE(As1, Bs1);
;       __syncthreads();
;     }
;   }
	v_mfma_f32_32x32x16_bf16 v[16:31], v[114:117], v[110:113], v[16:31]
	ds_read_b128 v[88:91], v170 offset:32768
	ds_read_b128 v[92:95], v174 offset:49152
	ds_read_b128 v[98:101], v171 offset:32768
	ds_read_b128 v[102:105], v175 offset:49152
	ds_read_b128 v[106:109], v174 offset:53248
	ds_read_b128 v[110:113], v175 offset:53248
	v_lshl_add_u64 v[66:67], v[66:67], 0, s[96:97]
	s_add_u32 m0, s94, 0x0
	s_nop 1
	global_load_lds_dwordx4 v[66:67], off
	v_lshl_add_u64 v[68:69], v[68:69], 0, s[96:97]
	s_add_u32 m0, s94, 0x4000
	s_nop 1
	global_load_lds_dwordx4 v[68:69], off
	v_lshl_add_u64 v[70:71], v[70:71], 0, s[96:97]
	s_add_u32 m0, s94, 0x1000
	s_nop 1
	global_load_lds_dwordx4 v[70:71], off
	v_lshl_add_u64 v[72:73], v[72:73], 0, s[96:97]
	s_add_u32 m0, s94, 0x5000
	s_nop 1
	global_load_lds_dwordx4 v[72:73], off
	v_lshl_add_u64 v[74:75], v[74:75], 0, s[96:97]
	s_add_u32 m0, s94, 0x2000
	s_nop 1
	global_load_lds_dwordx4 v[74:75], off
	v_lshl_add_u64 v[76:77], v[76:77], 0, s[96:97]
	s_add_u32 m0, s94, 0x6000
	s_nop 1
	global_load_lds_dwordx4 v[76:77], off
	v_lshl_add_u64 v[78:79], v[78:79], 0, s[96:97]
	s_add_u32 m0, s94, 0x3000
	s_nop 1
	global_load_lds_dwordx4 v[78:79], off
	v_lshl_add_u64 v[80:81], v[80:81], 0, s[96:97]
	s_add_u32 m0, s94, 0x7000
	s_nop 1
	global_load_lds_dwordx4 v[80:81], off
	s_waitcnt lgkmcnt(4)
	v_mfma_f32_32x32x16_bf16 v[32:47], v[88:91], v[92:95], v[32:47]
	s_waitcnt lgkmcnt(1)
	v_mfma_f32_32x32x16_bf16 v[48:63], v[88:91], v[106:109], v[48:63]
	ds_read_b128 v[88:91], v170 offset:36864
	ds_read_b128 v[114:117], v171 offset:36864
	s_waitcnt lgkmcnt(1)
	v_mfma_f32_32x32x16_bf16 v[0:15], v[88:91], v[92:95], v[0:15]
	v_mfma_f32_32x32x16_bf16 v[16:31], v[88:91], v[106:109], v[16:31]
	v_mfma_f32_32x32x16_bf16 v[32:47], v[98:101], v[102:105], v[32:47]
	v_mfma_f32_32x32x16_bf16 v[48:63], v[98:101], v[110:113], v[48:63]
	s_waitcnt lgkmcnt(0)
	v_mfma_f32_32x32x16_bf16 v[0:15], v[114:117], v[102:105], v[0:15]
	ds_read_b128 v[88:91], v172 offset:32768
	ds_read_b128 v[92:95], v176 offset:49152
	ds_read_b128 v[98:101], v173 offset:32768
	ds_read_b128 v[102:105], v177 offset:49152
	v_mfma_f32_32x32x16_bf16 v[16:31], v[114:117], v[110:113], v[16:31]
	ds_read_b128 v[106:109], v176 offset:53248
	ds_read_b128 v[110:113], v177 offset:53248
	s_waitcnt lgkmcnt(4)
	v_mfma_f32_32x32x16_bf16 v[32:47], v[88:91], v[92:95], v[32:47]
	s_waitcnt lgkmcnt(1)
	v_mfma_f32_32x32x16_bf16 v[48:63], v[88:91], v[106:109], v[48:63]
	ds_read_b128 v[88:91], v172 offset:36864
	ds_read_b128 v[114:117], v173 offset:36864
	s_waitcnt lgkmcnt(1)
	v_mfma_f32_32x32x16_bf16 v[0:15], v[88:91], v[92:95], v[0:15]
	v_mfma_f32_32x32x16_bf16 v[16:31], v[88:91], v[106:109], v[16:31]
	v_mfma_f32_32x32x16_bf16 v[32:47], v[98:101], v[102:105], v[32:47]
	v_mfma_f32_32x32x16_bf16 v[48:63], v[98:101], v[110:113], v[48:63]
	s_nop 0
	s_nop 0
	s_nop 0
	s_nop 0
	s_nop 0
	s_nop 0
	s_nop 0
	s_waitcnt lgkmcnt(0)
	s_waitcnt vmcnt(0)
	s_barrier
	v_lshl_add_u64 v[66:67], v[66:67], 0, s[96:97]
	s_add_u32 m0, s94, 0x8000
	s_nop 1
	global_load_lds_dwordx4 v[66:67], off
	v_lshl_add_u64 v[68:69], v[68:69], 0, s[96:97]
	s_add_u32 m0, s94, 0xc000
	s_nop 1
	global_load_lds_dwordx4 v[68:69], off
	v_lshl_add_u64 v[70:71], v[70:71], 0, s[96:97]
	s_add_u32 m0, s94, 0x9000
	s_nop 1
	global_load_lds_dwordx4 v[70:71], off
	v_lshl_add_u64 v[72:73], v[72:73], 0, s[96:97]
	s_add_u32 m0, s94, 0xd000
	s_nop 1
	global_load_lds_dwordx4 v[72:73], off
	v_lshl_add_u64 v[74:75], v[74:75], 0, s[96:97]
	s_add_u32 m0, s94, 0xa000
	s_nop 1
	global_load_lds_dwordx4 v[74:75], off
	v_lshl_add_u64 v[76:77], v[76:77], 0, s[96:97]
	s_add_u32 m0, s94, 0xe000
	s_nop 1
	global_load_lds_dwordx4 v[76:77], off
	v_lshl_add_u64 v[78:79], v[78:79], 0, s[96:97]
	s_add_u32 m0, s94, 0xb000
	s_nop 1
	global_load_lds_dwordx4 v[78:79], off
	v_lshl_add_u64 v[80:81], v[80:81], 0, s[96:97]
	s_add_u32 m0, s94, 0xf000
	s_nop 1
	global_load_lds_dwordx4 v[80:81], off
	v_mfma_f32_32x32x16_bf16 v[0:15], v[114:117], v[102:105], v[0:15]
	ds_read_b128 v[66:69], v170 offset:0
	ds_read_b128 v[70:73], v174 offset:16384
	ds_read_b128 v[74:77], v171 offset:0
	ds_read_b128 v[78:81], v175 offset:16384
	ds_read_b128 v[88:91], v174 offset:20480
	ds_read_b128 v[92:95], v175 offset:20480
	v_mfma_f32_32x32x16_bf16 v[16:31], v[114:117], v[110:113], v[16:31]
	s_waitcnt lgkmcnt(4)
	v_mfma_f32_32x32x16_bf16 v[32:47], v[66:69], v[70:73], v[32:47]
	s_waitcnt lgkmcnt(1)
	v_mfma_f32_32x32x16_bf16 v[48:63], v[66:69], v[88:91], v[48:63]
	ds_read_b128 v[66:69], v170 offset:4096
	ds_read_b128 v[98:101], v171 offset:4096
	s_waitcnt lgkmcnt(1)
	v_mfma_f32_32x32x16_bf16 v[0:15], v[66:69], v[70:73], v[0:15]
	v_mfma_f32_32x32x16_bf16 v[16:31], v[66:69], v[88:91], v[16:31]
	v_mfma_f32_32x32x16_bf16 v[32:47], v[74:77], v[78:81], v[32:47]
	v_mfma_f32_32x32x16_bf16 v[48:63], v[74:77], v[92:95], v[48:63]
	s_waitcnt lgkmcnt(0)
	v_mfma_f32_32x32x16_bf16 v[0:15], v[98:101], v[78:81], v[0:15]
	ds_read_b128 v[66:69], v172 offset:0
	ds_read_b128 v[70:73], v176 offset:16384
	ds_read_b128 v[74:77], v173 offset:0
	ds_read_b128 v[78:81], v177 offset:16384
	v_mfma_f32_32x32x16_bf16 v[16:31], v[98:101], v[92:95], v[16:31]
	ds_read_b128 v[88:91], v176 offset:20480
	ds_read_b128 v[92:95], v177 offset:20480
	s_waitcnt lgkmcnt(4)
	v_mfma_f32_32x32x16_bf16 v[32:47], v[66:69], v[70:73], v[32:47]
	s_waitcnt lgkmcnt(1)
	v_mfma_f32_32x32x16_bf16 v[48:63], v[66:69], v[88:91], v[48:63]
	ds_read_b128 v[66:69], v172 offset:4096
	ds_read_b128 v[98:101], v173 offset:4096
	s_waitcnt lgkmcnt(0)
	s_waitcnt vmcnt(0)
	s_barrier
; #define PW(T, off) ((T*)(lndp(p.ws) + (off)))
; DEVI void gemm_epi_qkv(const Params& p, f32x16 (&acc)[2][2], int rbase, int cbase, int lane) {
;   char* ar = PW(char, W_arena);
;   const int which = cbase >> 10, cc = cbase & 1023, d = lane & 31, hl = lane >> 5;
; #pragma unroll
;   for (int i = 0; i < 2; ++i) {
; #pragma unroll
;     for (int rq = 0; rq < 4; ++rq) {
;       const int row0 = rbase + i * 32 + 8 * rq + 4 * hl;
;       if (row0 >= M) continue;
;       const bool pr = row0 < TP;
;       const int b = pr ? 0 : (row0 - TP) >> 4, t0 = pr ? row0 : (row0 - TP) & 15;
;     ...
;   for (int kt = 0; kt < nk; kt += 2) {
;     if (kt + 2 < nk) G_LOAD(ra0, rb0, kt + 2);
;     if (kt + 1 < nk) G_STORE(ra1, rb1, As1, Bs1);
;     G_COMPUTE(As, Bs);
;     __syncthreads();
;     if (kt + 1 < nk) {
;       if (kt + 3 < nk) G_LOAD(ra1, rb1, kt + 3);
;       if (kt + 2 < nk) G_STORE(ra0, rb0, As, Bs);
;       G_COMPUTE(As1, Bs1);
;       __syncthreads();
;     }
;   }
	v_mfma_f32_32x32x16_bf16 v[0:15], v[66:69], v[70:73], v[0:15]
	v_mfma_f32_32x32x16_bf16 v[32:47], v[74:77], v[78:81], v[32:47]
	v_mfma_f32_32x32x16_bf16 v[48:63], v[74:77], v[92:95], v[48:63]
	v_mfma_f32_32x32x16_bf16 v[16:31], v[66:69], v[88:91], v[16:31]
	v_mfma_f32_32x32x16_bf16 v[0:15], v[98:101], v[78:81], v[0:15]
	ds_read_b128 v[66:69], v170 offset:32768
	ds_read_b128 v[70:73], v174 offset:49152
	ds_read_b128 v[74:77], v175 offset:49152
	ds_read_b128 v[78:81], v171 offset:32768
	ds_read_b128 v[88:91], v174 offset:53248
	s_waitcnt lgkmcnt(3)
	v_mfma_f32_32x32x16_bf16 v[32:47], v[66:69], v[70:73], v[32:47]
	s_waitcnt lgkmcnt(0)
	v_mfma_f32_32x32x16_bf16 v[48:63], v[66:69], v[88:91], v[48:63]
	ds_read_b128 v[66:69], v170 offset:36864
	v_mfma_f32_32x32x16_bf16 v[16:31], v[98:101], v[92:95], v[16:31]
	s_waitcnt lgkmcnt(0)
	v_mfma_f32_32x32x16_bf16 v[0:15], v[66:69], v[70:73], v[0:15]
	ds_read_b128 v[70:73], v171 offset:36864
	v_mfma_f32_32x32x16_bf16 v[16:31], v[66:69], v[88:91], v[16:31]
	ds_read_b128 v[66:69], v175 offset:53248
	v_mfma_f32_32x32x16_bf16 v[32:47], v[78:81], v[74:77], v[32:47]
	s_waitcnt lgkmcnt(0)
	v_mfma_f32_32x32x16_bf16 v[48:63], v[78:81], v[66:69], v[48:63]
	v_or_b32_e32 v81, s6, v65
	v_and_or_b32 v80, v85, 64, s6
	s_mov_b64 s[6:7], 0x1e05c060
	v_mfma_f32_32x32x16_bf16 v[0:15], v[70:73], v[74:77], v[0:15]
	v_mfma_f32_32x32x16_bf16 v[16:31], v[70:73], v[66:69], v[16:31]
	ds_read_b128 v[66:69], v172 offset:32768
	ds_read_b128 v[70:73], v176 offset:49152
	ds_read_b128 v[74:77], v176 offset:53248
	s_waitcnt lgkmcnt(1)
	v_mfma_f32_32x32x16_bf16 v[32:47], v[66:69], v[70:73], v[32:47]
	s_waitcnt lgkmcnt(0)
	v_mfma_f32_32x32x16_bf16 v[48:63], v[66:69], v[74:77], v[48:63]
	ds_read_b128 v[66:69], v172 offset:36864
	s_waitcnt lgkmcnt(0)
	v_mfma_f32_32x32x16_bf16 v[0:15], v[66:69], v[70:73], v[0:15]
	ds_read_b128 v[88:91], v177 offset:53248
	ds_read_b128 v[92:95], v177 offset:49152
	ds_read_b128 v[70:73], v173 offset:32768
	v_mfma_f32_32x32x16_bf16 v[16:31], v[66:69], v[74:77], v[16:31]
	ds_read_b128 v[74:77], v173 offset:36864
	v_lshrrev_b32_e32 v66, 3, v85
	v_add_u32_e32 v64, s3, v86
	v_and_b32_e32 v82, 4, v66
	v_or_b32_e32 v68, v64, v82
	v_mul_u32_u24_e32 v64, 0x4040, v81
	v_lshlrev_b32_e32 v96, 1, v64
	s_waitcnt lgkmcnt(1)
	v_mfma_f32_32x32x16_bf16 v[32:47], v[70:73], v[92:95], v[32:47]
	s_waitcnt lgkmcnt(0)
	s_barrier
	s_cmp_gt_i32 s5, 1
	s_cselect_b64 s[2:3], -1, 0
	v_lshl_add_u64 v[64:65], s[20:21], 0, v[96:97]
	v_lshlrev_b32_e32 v96, 1, v80
	v_mfma_f32_32x32x16_bf16 v[48:63], v[70:73], v[88:91], v[48:63]
	v_lshl_add_u64 v[70:71], v[64:65], 0, s[6:7]
	s_cmpk_gt_u32 s4, 0x3ff
	v_lshl_add_u64 v[64:65], s[20:21], 0, v[96:97]
	s_mov_b64 s[6:7], 0x13e3c000
	s_cselect_b64 s[18:19], -1, 0
	v_lshl_add_u64 v[66:67], v[64:65], 0, s[6:7]
	s_mov_b64 s[6:7], 0x11d7c000
	v_mfma_f32_32x32x16_bf16 v[0:15], v[74:77], v[92:95], v[0:15]
	s_cmp_eq_u32 s5, 1
	v_lshl_add_u64 v[64:65], v[64:65], 0, s[6:7]
	s_cselect_b64 s[16:17], -1, 0
	v_cmp_gt_i32_e32 vcc, s90, v68
	v_mfma_f32_32x32x16_bf16 v[16:31], v[74:77], v[88:91], v[16:31]
	s_and_saveexec_b64 s[4:5], vcc
	s_cbranch_execz .LBB0_1851
	s_movk_i32 s6, 0x400f
	v_add_u32_e32 v72, 0xffffbff0, v68
	v_cmp_lt_i32_e64 s[6:7], s6, v68
	v_ashrrev_i32_e32 v78, 4, v72
	s_mov_b64 s[8:9], -1
	s_and_b64 vcc, exec, s[2:3]
	s_cbranch_vccz .LBB0_1830
	s_and_saveexec_b64 s[8:9], s[6:7]
	s_xor_b64 s[8:9], exec, s[8:9]
	s_cbranch_execz .LBB0_1823
	s_mov_b64 s[10:11], s[72:73]
	s_add_u32 s10, s10, 0xc48f000
	v_mov_b32_e32 v73, v97
	s_addc_u32 s11, s11, 0
	v_mov_b64_e32 v[74:75], v[72:73]

; DEVI int TID() { int t = threadIdx.x; asm volatile("" : "+v"(t)); return t; }
;   bf16* As = (bf16*)smem;
;   bf16* Bs = As + 128 * 72;
;   const int tid = TID(), lane = tid & 63, wave = tid >> 6, wm = wave >> 1, wn = wave & 1;
;   f32x16 acc[2][2];
; #pragma unroll
;   for (int i = 0; i < 2; ++i)
; #pragma unroll
;     for (int j = 0; j < 2; ++j) acc[i][j] = zero16();
;   const int lrow = tid >> 3, lkc = (tid & 7) * 8;
;   const bf16* Ag = jb.A + (size_t)max(m0 + lrow, 0) * jb.lda + lkc;
;   const bf16* Ag1 = jb.A + (ptrdiff_t)(m0 + lrow) * jb.lda + lkc;
;   const bf16* Bg = jb.Bt + (size_t)(n0 + lrow) * jb.K + lkc;
;   const size_t astep = (size_t)32 * jb.lda, bstep = (size_t)32 * jb.K;
;   if (kt1 < 0) kt1 = jb.K >> 6;
;   const int nk = kt1 - kt0;
;   Ag += (size_t)kt0 * 64; Ag1 += (size_t)kt0 * 64; Bg += (size_t)kt0 * 64;
;   u32x4 ra0[4], rb0[4], ra1[4], rb1[4];
;     ...
;   bf16* As1 = As + 2 * 128 * 72;
;   bf16* Bs1 = As1 + 128 * 72;
;   G_LOAD(ra0, rb0, 0);
;   if (nk > 1) G_LOAD(ra1, rb1, 1);
;   G_STORE(ra0, rb0, As, Bs);
;   __syncthreads();
;   for (int kt = 0; kt < nk; kt += 2) {
;     if (kt + 2 < nk) G_LOAD(ra0, rb0, kt + 2);
;     if (kt + 1 < nk) G_STORE(ra1, rb1, As1, Bs1);
;     G_COMPUTE(As, Bs);
.LBB0_2081:
	s_mul_hi_i32 s2, s17, 0x2aaaaaab
	s_lshr_b32 s3, s2, 31
	s_ashr_i32 s2, s2, 6
	s_add_i32 s2, s2, s3
	s_lshl_b32 s3, s2, 4
	s_sub_i32 s4, 0x83, s3
	s_min_u32 s4, s4, 16
	v_cvt_f32_ubyte0_e32 v0, s4
	v_rcp_iflag_f32_e32 v0, v0
	s_sub_i32 s7, 0, s4
	s_mulk_i32 s2, 0xfe80
	s_add_i32 s5, s17, s2
	v_mul_f32_e32 v0, 0x4f7ffffe, v0
	v_cvt_u32_f32_e32 v0, v0
	s_abs_i32 s6, s5
	s_ashr_i32 s2, s5, 31
	s_waitcnt vmcnt(2)
	v_mov_b32_e32 v85, v208
	v_readfirstlane_b32 s8, v0
	s_mul_i32 s7, s7, s8
	s_mul_hi_u32 s7, s8, s7
	s_add_i32 s8, s8, s7
	s_mul_hi_u32 s7, s6, s8
	s_mul_i32 s8, s7, s4
	s_sub_i32 s6, s6, s8
	s_add_i32 s8, s7, 1
	s_sub_i32 s9, s6, s4
	s_cmp_ge_u32 s6, s4
	s_cselect_b32 s7, s8, s7
	s_cselect_b32 s6, s9, s6
	s_add_i32 s8, s7, 1
	s_cmp_ge_u32 s6, s4
	s_cselect_b32 s6, s8, s7
	s_xor_b32 s6, s6, s2
	s_sub_i32 s2, s6, s2
	s_mul_i32 s4, s2, s4
	s_sub_i32 s4, s5, s4
	s_add_i32 s3, s3, s4
	s_lshl_b32 s3, s3, 7
	s_lshl_b32 s4, s2, 7
	v_ashrrev_i32_e32 v82, 3, v85
	v_add_u32_e32 v0, s3, v82
	v_max_i32_e32 v96, 0, v0
	v_lshlrev_b32_e32 v1, 4, v85
	v_lshlrev_b64 v[2:3], 11, v[96:97]
	v_and_b32_e32 v96, 0x70, v1
	s_mov_b64 s[96:97], 0x80
	v_lshrrev_b32_e32 v178, 4, v208
	v_and_b32_e32 v178, 7, v178
	v_lshlrev_b32_e32 v178, 4, v178
	v_xor_b32_e32 v96, v96, v178
	v_lshrrev_b32_e32 v179, 6, v208
	v_lshlrev_b32_e32 v179, 10, v179
	v_lshrrev_b32_e32 v180, 5, v208
	v_lshrrev_b32_e32 v181, 1, v208
	v_xor_b32_e32 v180, v180, v181
	v_readfirstlane_b32 s94, v179
	v_and_b32_e32 v180, 1, v180
	v_lshlrev_b32_e32 v180, 4, v180
	v_and_b32_e32 v181, 31, v208
	v_lshlrev_b32_e32 v181, 7, v181
	v_or_b32_e32 v180, v180, v181
	v_lshrrev_b32_e32 v181, 7, v208
	v_lshlrev_b32_e32 v181, 13, v181
	v_or_b32_e32 v194, v180, v181
	v_bfe_u32 v181, v208, 6, 1
	v_lshlrev_b32_e32 v181, 13, v181
	v_or_b32_e32 v195, v180, v181
	v_bfe_u32 v178, v208, 2, 2
	v_xor_b32_e32 v179, 0, v178
	v_lshlrev_b32_e32 v179, 5, v179
	v_or_b32_e32 v170, v194, v179
	v_or_b32_e32 v174, v195, v179
	v_xor_b32_e32 v179, 1, v178
	v_lshlrev_b32_e32 v179, 5, v179
	v_or_b32_e32 v171, v194, v179
	v_or_b32_e32 v175, v195, v179
	v_xor_b32_e32 v179, 2, v178
	v_lshlrev_b32_e32 v179, 5, v179
	v_or_b32_e32 v172, v194, v179
	v_or_b32_e32 v176, v195, v179
	v_xor_b32_e32 v179, 3, v178
	v_lshlrev_b32_e32 v179, 5, v179
	v_or_b32_e32 v173, v194, v179
	v_or_b32_e32 v177, v195, v179
	v_ashrrev_i32_e32 v1, 31, v0
	v_lshlrev_b64 v[0:1], 11, v[0:1]
	v_lshl_add_u64 v[0:1], s[12:13], 0, v[0:1]
	v_lshl_add_u64 v[28:29], v[0:1], 0, v[96:97]
	v_add_u32_e32 v0, s4, v82
	v_ashrrev_i32_e32 v1, 31, v0
	v_lshlrev_b64 v[0:1], 11, v[0:1]
	v_lshl_add_u64 v[0:1], s[14:15], 0, v[0:1]
	v_add_co_u32_e32 v70, vcc, s63, v28
	v_lshl_add_u64 v[68:69], v[0:1], 0, v[96:97]
	s_nop 0
	v_addc_co_u32_e32 v71, vcc, 0, v29, vcc
	v_add_co_u32_e32 v72, vcc, s63, v68
	v_lshl_add_u64 v[2:3], s[12:13], 0, v[2:3]
	s_nop 0
	v_addc_co_u32_e32 v73, vcc, 0, v69, vcc
	v_add_co_u32_e32 v74, vcc, s64, v28
	v_lshl_add_u64 v[66:67], v[2:3], 0, v[96:97]
	s_nop 0
	v_addc_co_u32_e32 v75, vcc, 0, v29, vcc
	v_add_co_u32_e32 v76, vcc, s64, v68
	v_addc_co_u32_e32 v77, vcc, 0, v69, vcc
	v_add_co_u32_e32 v78, vcc, s65, v68
	s_nop 0
	v_addc_co_u32_e32 v79, vcc, 0, v69, vcc
	v_add_co_u32_e32 v80, vcc, s65, v28
	s_nop 0
	v_addc_co_u32_e32 v81, vcc, 0, v29, vcc
	v_ashrrev_i32_e32 v64, 1, v85
	v_and_b32_e32 v84, 31, v85
	v_lshrrev_b32_e32 v65, 1, v85
	v_and_b32_e32 v86, 0xffffffc0, v64
	s_waitcnt vmcnt(0)
	v_and_b32_e32 v88, 16, v65
	v_or_b32_e32 v64, v86, v84
	v_mad_u64_u32 v[82:83], s[6:7], v82, s91, v[96:97]
	v_mad_u64_u32 v[64:65], s[6:7], v64, s91, v[88:89]
	v_add_u32_e32 v83, 0xd800, v82
	s_ashr_i32 s5, s2, 3
	s_and_b32 s2, s4, 0x380
	s_mov_b64 s[22:23], s[74:75]
	s_mov_b64 s[6:7], 0x1e05c060
	s_add_u32 m0, s94, 0x4000
	s_nop 1
	global_load_lds_dwordx4 v[68:69], off
	s_add_u32 m0, s94, 0x0
	s_nop 1
	global_load_lds_dwordx4 v[66:67], off
	s_add_u32 m0, s94, 0x5000
	s_nop 1
	global_load_lds_dwordx4 v[72:73], off
	s_add_u32 m0, s94, 0x6000
	s_nop 1
	global_load_lds_dwordx4 v[76:77], off
	s_add_u32 m0, s94, 0x7000
	s_nop 1
	global_load_lds_dwordx4 v[78:79], off
	s_add_u32 m0, s94, 0x1000
	s_nop 1
	global_load_lds_dwordx4 v[70:71], off
	s_add_u32 m0, s94, 0x2000
	s_nop 1
	global_load_lds_dwordx4 v[74:75], off
	s_add_u32 m0, s94, 0x3000
	s_nop 1
	global_load_lds_dwordx4 v[80:81], off
	s_waitcnt lgkmcnt(0)
	s_waitcnt vmcnt(0)
	s_barrier
; DEVI int TID() { int t = threadIdx.x; asm volatile("" : "+v"(t)); return t; }
;   bf16* As = (bf16*)smem;
;   bf16* Bs = As + 128 * 72;
;   const int tid = TID(), lane = tid & 63, wave = tid >> 6, wm = wave >> 1, wn = wave & 1;
;   f32x16 acc[2][2];
; #pragma unroll
;   for (int i = 0; i < 2; ++i)
; #pragma unroll
;     for (int j = 0; j < 2; ++j) acc[i][j] = zero16();
;   const int lrow = tid >> 3, lkc = (tid & 7) * 8;
;   const bf16* Ag = jb.A + (size_t)max(m0 + lrow, 0) * jb.lda + lkc;
;   const bf16* Ag1 = jb.A + (ptrdiff_t)(m0 + lrow) * jb.lda + lkc;
;   const bf16* Bg = jb.Bt + (size_t)(n0 + lrow) * jb.K + lkc;
;   const size_t astep = (size_t)32 * jb.lda, bstep = (size_t)32 * jb.K;
;   if (kt1 < 0) kt1 = jb.K >> 6;
;   const int nk = kt1 - kt0;
;   Ag += (size_t)kt0 * 64; Ag1 += (size_t)kt0 * 64; Bg += (size_t)kt0 * 64;
;   u32x4 ra0[4], rb0[4], ra1[4], rb1[4];
;     ...
;   bf16* As1 = As + 2 * 128 * 72;
;   bf16* Bs1 = As1 + 128 * 72;
;   G_LOAD(ra0, rb0, 0);
;   if (nk > 1) G_LOAD(ra1, rb1, 1);
;   G_STORE(ra0, rb0, As, Bs);
;   __syncthreads();
;   for (int kt = 0; kt < nk; kt += 2) {
;     if (kt + 2 < nk) G_LOAD(ra0, rb0, kt + 2);
;     if (kt + 1 < nk) G_STORE(ra1, rb1, As1, Bs1);
;     G_COMPUTE(As, Bs);
;     __syncthreads();
;     if (kt + 1 < nk) {
;       if (kt + 3 < nk) G_LOAD(ra1, rb1, kt + 3);
;       if (kt + 2 < nk) G_STORE(ra0, rb0, As, Bs);
;       G_COMPUTE(As1, Bs1);
;       __syncthreads();
;     }
;   }
	ds_read_b128 v[0:3], v170 offset:0
	v_and_b32_e32 v4, 0x5f, v85
	v_mad_u32_u24 v65, v4, s91, v88
	ds_read_b128 v[4:7], v174 offset:16384
	ds_read_b128 v[88:91], v171 offset:0
	ds_read_b128 v[92:95], v175 offset:16384
	ds_read_b128 v[16:19], v174 offset:20480
	ds_read_b128 v[98:101], v175 offset:20480
	v_lshl_add_u64 v[66:67], v[66:67], 0, s[96:97]
	s_add_u32 m0, s94, 0x8000
	s_nop 1
	global_load_lds_dwordx4 v[66:67], off
	v_lshl_add_u64 v[68:69], v[68:69], 0, s[96:97]
	s_add_u32 m0, s94, 0xc000
	s_nop 1
	global_load_lds_dwordx4 v[68:69], off
	v_lshl_add_u64 v[70:71], v[70:71], 0, s[96:97]
	s_add_u32 m0, s94, 0x9000
	s_nop 1
	global_load_lds_dwordx4 v[70:71], off
	v_lshl_add_u64 v[72:73], v[72:73], 0, s[96:97]
	s_add_u32 m0, s94, 0xd000
	s_nop 1
	global_load_lds_dwordx4 v[72:73], off
	v_lshl_add_u64 v[74:75], v[74:75], 0, s[96:97]
	s_add_u32 m0, s94, 0xa000
	s_nop 1
	global_load_lds_dwordx4 v[74:75], off
	v_lshl_add_u64 v[76:77], v[76:77], 0, s[96:97]
	s_add_u32 m0, s94, 0xe000
	s_nop 1
	global_load_lds_dwordx4 v[76:77], off
	v_lshl_add_u64 v[80:81], v[80:81], 0, s[96:97]
	s_add_u32 m0, s94, 0xb000
	s_nop 1
	global_load_lds_dwordx4 v[80:81], off
	v_lshl_add_u64 v[78:79], v[78:79], 0, s[96:97]
	s_add_u32 m0, s94, 0xf000
	s_nop 1
	global_load_lds_dwordx4 v[78:79], off
	s_waitcnt lgkmcnt(4)
	v_mfma_f32_32x32x16_bf16 v[32:47], v[0:3], v[4:7], 0
	ds_read_b128 v[20:23], v170 offset:4096
	ds_read_b128 v[102:105], v171 offset:4096
	s_waitcnt lgkmcnt(3)
	v_mfma_f32_32x32x16_bf16 v[48:63], v[0:3], v[16:19], 0
	s_waitcnt lgkmcnt(1)
	v_mfma_f32_32x32x16_bf16 v[0:15], v[20:23], v[4:7], 0
	v_mfma_f32_32x32x16_bf16 v[16:31], v[20:23], v[16:19], 0
	v_mfma_f32_32x32x16_bf16 v[32:47], v[88:91], v[92:95], v[32:47]
	v_mfma_f32_32x32x16_bf16 v[48:63], v[88:91], v[98:101], v[48:63]
	s_waitcnt lgkmcnt(0)
	v_mfma_f32_32x32x16_bf16 v[0:15], v[102:105], v[92:95], v[0:15]
	v_mfma_f32_32x32x16_bf16 v[16:31], v[102:105], v[98:101], v[16:31]
	ds_read_b128 v[88:91], v172 offset:0
	ds_read_b128 v[92:95], v176 offset:16384
	ds_read_b128 v[98:101], v173 offset:0
	ds_read_b128 v[102:105], v177 offset:16384
	ds_read_b128 v[106:109], v176 offset:20480
	ds_read_b128 v[110:113], v177 offset:20480
	s_waitcnt lgkmcnt(4)
	v_mfma_f32_32x32x16_bf16 v[32:47], v[88:91], v[92:95], v[32:47]
	s_waitcnt lgkmcnt(1)
	v_mfma_f32_32x32x16_bf16 v[48:63], v[88:91], v[106:109], v[48:63]
	ds_read_b128 v[88:91], v172 offset:4096
	ds_read_b128 v[114:117], v173 offset:4096
	s_waitcnt lgkmcnt(1)
	v_mfma_f32_32x32x16_bf16 v[0:15], v[88:91], v[92:95], v[0:15]
	v_mfma_f32_32x32x16_bf16 v[16:31], v[88:91], v[106:109], v[16:31]
	v_mfma_f32_32x32x16_bf16 v[32:47], v[98:101], v[102:105], v[32:47]
	v_mfma_f32_32x32x16_bf16 v[48:63], v[98:101], v[110:113], v[48:63]
	s_waitcnt lgkmcnt(0)
	v_mfma_f32_32x32x16_bf16 v[0:15], v[114:117], v[102:105], v[0:15]
	s_waitcnt vmcnt(0)
	s_barrier
	v_mfma_f32_32x32x16_bf16 v[16:31], v[114:117], v[110:113], v[16:31]
	ds_read_b128 v[88:91], v170 offset:32768
	ds_read_b128 v[92:95], v174 offset:49152
	ds_read_b128 v[98:101], v171 offset:32768
	ds_read_b128 v[102:105], v175 offset:49152
	ds_read_b128 v[106:109], v174 offset:53248
	ds_read_b128 v[110:113], v175 offset:53248
	v_lshl_add_u64 v[66:67], v[66:67], 0, s[96:97]
	s_add_u32 m0, s94, 0x0
	s_nop 1
	global_load_lds_dwordx4 v[66:67], off
	v_lshl_add_u64 v[68:69], v[68:69], 0, s[96:97]
	s_add_u32 m0, s94, 0x4000
	s_nop 1
	global_load_lds_dwordx4 v[68:69], off
	v_lshl_add_u64 v[70:71], v[70:71], 0, s[96:97]
	s_add_u32 m0, s94, 0x1000
	s_nop 1
	global_load_lds_dwordx4 v[70:71], off
	v_lshl_add_u64 v[72:73], v[72:73], 0, s[96:97]
	s_add_u32 m0, s94, 0x5000
	s_nop 1
	global_load_lds_dwordx4 v[72:73], off
	v_lshl_add_u64 v[74:75], v[74:75], 0, s[96:97]
	s_add_u32 m0, s94, 0x2000
	s_nop 1
	global_load_lds_dwordx4 v[74:75], off
	v_lshl_add_u64 v[76:77], v[76:77], 0, s[96:97]
	s_add_u32 m0, s94, 0x6000
	s_nop 1
	global_load_lds_dwordx4 v[76:77], off
	v_lshl_add_u64 v[80:81], v[80:81], 0, s[96:97]
	s_add_u32 m0, s94, 0x3000
	s_nop 1
	global_load_lds_dwordx4 v[80:81], off
	v_lshl_add_u64 v[78:79], v[78:79], 0, s[96:97]
	s_add_u32 m0, s94, 0x7000
	s_nop 1
	global_load_lds_dwordx4 v[78:79], off
	s_waitcnt lgkmcnt(4)
	v_mfma_f32_32x32x16_bf16 v[32:47], v[88:91], v[92:95], v[32:47]
	s_waitcnt lgkmcnt(1)
	v_mfma_f32_32x32x16_bf16 v[48:63], v[88:91], v[106:109], v[48:63]
	ds_read_b128 v[88:91], v170 offset:36864
	ds_read_b128 v[114:117], v171 offset:36864
	s_waitcnt lgkmcnt(1)
	v_mfma_f32_32x32x16_bf16 v[0:15], v[88:91], v[92:95], v[0:15]
	v_mfma_f32_32x32x16_bf16 v[16:31], v[88:91], v[106:109], v[16:31]
	v_mfma_f32_32x32x16_bf16 v[32:47], v[98:101], v[102:105], v[32:47]
	v_mfma_f32_32x32x16_bf16 v[48:63], v[98:101], v[110:113], v[48:63]
	s_waitcnt lgkmcnt(0)
	v_mfma_f32_32x32x16_bf16 v[0:15], v[114:117], v[102:105], v[0:15]
	ds_read_b128 v[88:91], v172 offset:32768
	ds_read_b128 v[92:95], v176 offset:49152
	ds_read_b128 v[98:101], v173 offset:32768
	ds_read_b128 v[102:105], v177 offset:49152
	v_mfma_f32_32x32x16_bf16 v[16:31], v[114:117], v[110:113], v[16:31]
	ds_read_b128 v[106:109], v176 offset:53248
	ds_read_b128 v[110:113], v177 offset:53248
	s_waitcnt lgkmcnt(4)
	v_mfma_f32_32x32x16_bf16 v[32:47], v[88:91], v[92:95], v[32:47]
	s_waitcnt lgkmcnt(1)
	v_mfma_f32_32x32x16_bf16 v[48:63], v[88:91], v[106:109], v[48:63]
	ds_read_b128 v[88:91], v172 offset:36864
	ds_read_b128 v[114:117], v173 offset:36864
	s_waitcnt lgkmcnt(1)
	v_mfma_f32_32x32x16_bf16 v[0:15], v[88:91], v[92:95], v[0:15]
	v_mfma_f32_32x32x16_bf16 v[16:31], v[88:91], v[106:109], v[16:31]
	v_mfma_f32_32x32x16_bf16 v[32:47], v[98:101], v[102:105], v[32:47]
	v_mfma_f32_32x32x16_bf16 v[48:63], v[98:101], v[110:113], v[48:63]
	s_waitcnt lgkmcnt(0)
	v_mfma_f32_32x32x16_bf16 v[0:15], v[114:117], v[102:105], v[0:15]
	s_waitcnt vmcnt(0)
	s_barrier
;     ...
;   bf16* As1 = As + 2 * 128 * 72;
;   bf16* Bs1 = As1 + 128 * 72;
;   G_LOAD(ra0, rb0, 0);
;   if (nk > 1) G_LOAD(ra1, rb1, 1);
;   G_STORE(ra0, rb0, As, Bs);
;   __syncthreads();
;   for (int kt = 0; kt < nk; kt += 2) {
;     if (kt + 2 < nk) G_LOAD(ra0, rb0, kt + 2);
;     if (kt + 1 < nk) G_STORE(ra1, rb1, As1, Bs1);
;     G_COMPUTE(As, Bs);
;     __syncthreads();
;     if (kt + 1 < nk) {
;       if (kt + 3 < nk) G_LOAD(ra1, rb1, kt + 3);
;       if (kt + 2 < nk) G_STORE(ra0, rb0, As, Bs);
;       G_COMPUTE(As1, Bs1);
;       __syncthreads();
;     }
;   }
	v_mfma_f32_32x32x16_bf16 v[16:31], v[114:117], v[110:113], v[16:31]
	ds_read_b128 v[88:91], v170 offset:0
	ds_read_b128 v[92:95], v174 offset:16384
	ds_read_b128 v[98:101], v171 offset:0
	ds_read_b128 v[102:105], v175 offset:16384
	ds_read_b128 v[106:109], v174 offset:20480
	ds_read_b128 v[110:113], v175 offset:20480
	v_lshl_add_u64 v[66:67], v[66:67], 0, s[96:97]
	s_add_u32 m0, s94, 0x8000
	s_nop 1
	global_load_lds_dwordx4 v[66:67], off
	v_lshl_add_u64 v[68:69], v[68:69], 0, s[96:97]
	s_add_u32 m0, s94, 0xc000
	s_nop 1
	global_load_lds_dwordx4 v[68:69], off
	v_lshl_add_u64 v[70:71], v[70:71], 0, s[96:97]
	s_add_u32 m0, s94, 0x9000
	s_nop 1
	global_load_lds_dwordx4 v[70:71], off
	v_lshl_add_u64 v[72:73], v[72:73], 0, s[96:97]
	s_add_u32 m0, s94, 0xd000
	s_nop 1
	global_load_lds_dwordx4 v[72:73], off
	v_lshl_add_u64 v[74:75], v[74:75], 0, s[96:97]
	s_add_u32 m0, s94, 0xa000
	s_nop 1
	global_load_lds_dwordx4 v[74:75], off
	v_lshl_add_u64 v[76:77], v[76:77], 0, s[96:97]
	s_add_u32 m0, s94, 0xe000
	s_nop 1
	global_load_lds_dwordx4 v[76:77], off
	v_lshl_add_u64 v[80:81], v[80:81], 0, s[96:97]
	s_add_u32 m0, s94, 0xb000
	s_nop 1
	global_load_lds_dwordx4 v[80:81], off
	v_lshl_add_u64 v[78:79], v[78:79], 0, s[96:97]
	s_add_u32 m0, s94, 0xf000
	s_nop 1
	global_load_lds_dwordx4 v[78:79], off
	s_waitcnt lgkmcnt(4)
	v_mfma_f32_32x32x16_bf16 v[32:47], v[88:91], v[92:95], v[32:47]
	s_waitcnt lgkmcnt(1)
	v_mfma_f32_32x32x16_bf16 v[48:63], v[88:91], v[106:109], v[48:63]
	ds_read_b128 v[88:91], v170 offset:4096
	ds_read_b128 v[114:117], v171 offset:4096
	s_waitcnt lgkmcnt(1)
	v_mfma_f32_32x32x16_bf16 v[0:15], v[88:91], v[92:95], v[0:15]
	v_mfma_f32_32x32x16_bf16 v[16:31], v[88:91], v[106:109], v[16:31]
	v_mfma_f32_32x32x16_bf16 v[32:47], v[98:101], v[102:105], v[32:47]
	v_mfma_f32_32x32x16_bf16 v[48:63], v[98:101], v[110:113], v[48:63]
	s_waitcnt lgkmcnt(0)
	v_mfma_f32_32x32x16_bf16 v[0:15], v[114:117], v[102:105], v[0:15]
	ds_read_b128 v[88:91], v172 offset:0
	ds_read_b128 v[92:95], v176 offset:16384
	ds_read_b128 v[98:101], v173 offset:0
	ds_read_b128 v[102:105], v177 offset:16384
	v_mfma_f32_32x32x16_bf16 v[16:31], v[114:117], v[110:113], v[16:31]
	ds_read_b128 v[106:109], v176 offset:20480
	ds_read_b128 v[110:113], v177 offset:20480
	s_waitcnt lgkmcnt(4)
	v_mfma_f32_32x32x16_bf16 v[32:47], v[88:91], v[92:95], v[32:47]
	s_waitcnt lgkmcnt(1)
	v_mfma_f32_32x32x16_bf16 v[48:63], v[88:91], v[106:109], v[48:63]
	ds_read_b128 v[88:91], v172 offset:4096
	ds_read_b128 v[114:117], v173 offset:4096
	s_waitcnt lgkmcnt(1)
	v_mfma_f32_32x32x16_bf16 v[0:15], v[88:91], v[92:95], v[0:15]
	v_mfma_f32_32x32x16_bf16 v[16:31], v[88:91], v[106:109], v[16:31]
	v_mfma_f32_32x32x16_bf16 v[32:47], v[98:101], v[102:105], v[32:47]
	v_mfma_f32_32x32x16_bf16 v[48:63], v[98:101], v[110:113], v[48:63]
	s_waitcnt lgkmcnt(0)
	v_mfma_f32_32x32x16_bf16 v[0:15], v[114:117], v[102:105], v[0:15]
	s_waitcnt vmcnt(0)
	s_barrier
	v_mfma_f32_32x32x16_bf16 v[16:31], v[114:117], v[110:113], v[16:31]
	ds_read_b128 v[88:91], v170 offset:32768
	ds_read_b128 v[92:95], v174 offset:49152
	ds_read_b128 v[98:101], v171 offset:32768
	ds_read_b128 v[102:105], v175 offset:49152
	ds_read_b128 v[106:109], v174 offset:53248
	ds_read_b128 v[110:113], v175 offset:53248
	v_lshl_add_u64 v[66:67], v[66:67], 0, s[96:97]
	s_add_u32 m0, s94, 0x0
	s_nop 1
	global_load_lds_dwordx4 v[66:67], off
	v_lshl_add_u64 v[68:69], v[68:69], 0, s[96:97]
	s_add_u32 m0, s94, 0x4000
	s_nop 1
	global_load_lds_dwordx4 v[68:69], off
	v_lshl_add_u64 v[70:71], v[70:71], 0, s[96:97]
	s_add_u32 m0, s94, 0x1000
	s_nop 1
	global_load_lds_dwordx4 v[70:71], off
	v_lshl_add_u64 v[72:73], v[72:73], 0, s[96:97]
	s_add_u32 m0, s94, 0x5000
	s_nop 1
	global_load_lds_dwordx4 v[72:73], off
	v_lshl_add_u64 v[74:75], v[74:75], 0, s[96:97]
	s_add_u32 m0, s94, 0x2000
	s_nop 1
	global_load_lds_dwordx4 v[74:75], off
	v_lshl_add_u64 v[76:77], v[76:77], 0, s[96:97]
	s_add_u32 m0, s94, 0x6000
	s_nop 1
	global_load_lds_dwordx4 v[76:77], off
	v_lshl_add_u64 v[80:81], v[80:81], 0, s[96:97]
	s_add_u32 m0, s94, 0x3000
	s_nop 1
	global_load_lds_dwordx4 v[80:81], off
	v_lshl_add_u64 v[78:79], v[78:79], 0, s[96:97]
	s_add_u32 m0, s94, 0x7000
	s_nop 1
	global_load_lds_dwordx4 v[78:79], off
	s_waitcnt lgkmcnt(4)
	v_mfma_f32_32x32x16_bf16 v[32:47], v[88:91], v[92:95], v[32:47]
	s_waitcnt lgkmcnt(1)
	v_mfma_f32_32x32x16_bf16 v[48:63], v[88:91], v[106:109], v[48:63]
	ds_read_b128 v[88:91], v170 offset:36864
	ds_read_b128 v[114:117], v171 offset:36864
	s_waitcnt lgkmcnt(1)
	v_mfma_f32_32x32x16_bf16 v[0:15], v[88:91], v[92:95], v[0:15]
	v_mfma_f32_32x32x16_bf16 v[16:31], v[88:91], v[106:109], v[16:31]
	v_mfma_f32_32x32x16_bf16 v[32:47], v[98:101], v[102:105], v[32:47]
	v_mfma_f32_32x32x16_bf16 v[48:63], v[98:101], v[110:113], v[48:63]
	s_waitcnt lgkmcnt(0)
	v_mfma_f32_32x32x16_bf16 v[0:15], v[114:117], v[102:105], v[0:15]
	ds_read_b128 v[88:91], v172 offset:32768
	ds_read_b128 v[92:95], v176 offset:49152
	ds_read_b128 v[98:101], v173 offset:32768
	ds_read_b128 v[102:105], v177 offset:49152
	v_mfma_f32_32x32x16_bf16 v[16:31], v[114:117], v[110:113], v[16:31]
	ds_read_b128 v[106:109], v176 offset:53248
	ds_read_b128 v[110:113], v177 offset:53248
	s_waitcnt lgkmcnt(4)
	v_mfma_f32_32x32x16_bf16 v[32:47], v[88:91], v[92:95], v[32:47]
	s_waitcnt lgkmcnt(1)
	v_mfma_f32_32x32x16_bf16 v[48:63], v[88:91], v[106:109], v[48:63]
	ds_read_b128 v[88:91], v172 offset:36864
	ds_read_b128 v[114:117], v173 offset:36864
	s_waitcnt lgkmcnt(1)
	v_mfma_f32_32x32x16_bf16 v[0:15], v[88:91], v[92:95], v[0:15]
	v_mfma_f32_32x32x16_bf16 v[16:31], v[88:91], v[106:109], v[16:31]
	v_mfma_f32_32x32x16_bf16 v[32:47], v[98:101], v[102:105], v[32:47]
	v_mfma_f32_32x32x16_bf16 v[48:63], v[98:101], v[110:113], v[48:63]
	s_waitcnt lgkmcnt(0)
	v_mfma_f32_32x32x16_bf16 v[0:15], v[114:117], v[102:105], v[0:15]
	s_waitcnt vmcnt(0)
	s_barrier
;     ...
;   bf16* As1 = As + 2 * 128 * 72;
;   bf16* Bs1 = As1 + 128 * 72;
;   G_LOAD(ra0, rb0, 0);
;   if (nk > 1) G_LOAD(ra1, rb1, 1);
;   G_STORE(ra0, rb0, As, Bs);
;   __syncthreads();
;   for (int kt = 0; kt < nk; kt += 2) {
;     if (kt + 2 < nk) G_LOAD(ra0, rb0, kt + 2);
;     if (kt + 1 < nk) G_STORE(ra1, rb1, As1, Bs1);
;     G_COMPUTE(As, Bs);
;     __syncthreads();
;     if (kt + 1 < nk) {
;       if (kt + 3 < nk) G_LOAD(ra1, rb1, kt + 3);
;       if (kt + 2 < nk) G_STORE(ra0, rb0, As, Bs);
;       G_COMPUTE(As1, Bs1);
;       __syncthreads();
;     }
;   }
	v_mfma_f32_32x32x16_bf16 v[16:31], v[114:117], v[110:113], v[16:31]
	ds_read_b128 v[88:91], v170 offset:0
	ds_read_b128 v[92:95], v174 offset:16384
	ds_read_b128 v[98:101], v171 offset:0
	ds_read_b128 v[102:105], v175 offset:16384
	ds_read_b128 v[106:109], v174 offset:20480
	ds_read_b128 v[110:113], v175 offset:20480
	v_lshl_add_u64 v[66:67], v[66:67], 0, s[96:97]
	s_add_u32 m0, s94, 0x8000
	s_nop 1
	global_load_lds_dwordx4 v[66:67], off
	v_lshl_add_u64 v[68:69], v[68:69], 0, s[96:97]
	s_add_u32 m0, s94, 0xc000
	s_nop 1
	global_load_lds_dwordx4 v[68:69], off
	v_lshl_add_u64 v[70:71], v[70:71], 0, s[96:97]
	s_add_u32 m0, s94, 0x9000
	s_nop 1
	global_load_lds_dwordx4 v[70:71], off
	v_lshl_add_u64 v[72:73], v[72:73], 0, s[96:97]
	s_add_u32 m0, s94, 0xd000
	s_nop 1
	global_load_lds_dwordx4 v[72:73], off
	v_lshl_add_u64 v[74:75], v[74:75], 0, s[96:97]
	s_add_u32 m0, s94, 0xa000
	s_nop 1
	global_load_lds_dwordx4 v[74:75], off
	v_lshl_add_u64 v[76:77], v[76:77], 0, s[96:97]
	s_add_u32 m0, s94, 0xe000
	s_nop 1
	global_load_lds_dwordx4 v[76:77], off
	v_lshl_add_u64 v[80:81], v[80:81], 0, s[96:97]
	s_add_u32 m0, s94, 0xb000
	s_nop 1
	global_load_lds_dwordx4 v[80:81], off
	v_lshl_add_u64 v[78:79], v[78:79], 0, s[96:97]
	s_add_u32 m0, s94, 0xf000
	s_nop 1
	global_load_lds_dwordx4 v[78:79], off
	s_waitcnt lgkmcnt(4)
	v_mfma_f32_32x32x16_bf16 v[32:47], v[88:91], v[92:95], v[32:47]
	s_waitcnt lgkmcnt(1)
	v_mfma_f32_32x32x16_bf16 v[48:63], v[88:91], v[106:109], v[48:63]
	ds_read_b128 v[88:91], v170 offset:4096
	ds_read_b128 v[114:117], v171 offset:4096
	s_waitcnt lgkmcnt(1)
	v_mfma_f32_32x32x16_bf16 v[0:15], v[88:91], v[92:95], v[0:15]
	v_mfma_f32_32x32x16_bf16 v[16:31], v[88:91], v[106:109], v[16:31]
	v_mfma_f32_32x32x16_bf16 v[32:47], v[98:101], v[102:105], v[32:47]
	v_mfma_f32_32x32x16_bf16 v[48:63], v[98:101], v[110:113], v[48:63]
	s_waitcnt lgkmcnt(0)
	v_mfma_f32_32x32x16_bf16 v[0:15], v[114:117], v[102:105], v[0:15]
	ds_read_b128 v[88:91], v172 offset:0
	ds_read_b128 v[92:95], v176 offset:16384
	ds_read_b128 v[98:101], v173 offset:0
	ds_read_b128 v[102:105], v177 offset:16384
	v_mfma_f32_32x32x16_bf16 v[16:31], v[114:117], v[110:113], v[16:31]
	ds_read_b128 v[106:109], v176 offset:20480
	ds_read_b128 v[110:113], v177 offset:20480
	s_waitcnt lgkmcnt(4)
	v_mfma_f32_32x32x16_bf16 v[32:47], v[88:91], v[92:95], v[32:47]
	s_waitcnt lgkmcnt(1)
	v_mfma_f32_32x32x16_bf16 v[48:63], v[88:91], v[106:109], v[48:63]
	ds_read_b128 v[88:91], v172 offset:4096
	ds_read_b128 v[114:117], v173 offset:4096
	s_waitcnt lgkmcnt(1)
	v_mfma_f32_32x32x16_bf16 v[0:15], v[88:91], v[92:95], v[0:15]
	v_mfma_f32_32x32x16_bf16 v[16:31], v[88:91], v[106:109], v[16:31]
	v_mfma_f32_32x32x16_bf16 v[32:47], v[98:101], v[102:105], v[32:47]
	v_mfma_f32_32x32x16_bf16 v[48:63], v[98:101], v[110:113], v[48:63]
	s_waitcnt lgkmcnt(0)
	v_mfma_f32_32x32x16_bf16 v[0:15], v[114:117], v[102:105], v[0:15]
	s_waitcnt vmcnt(0)
	s_barrier
	v_mfma_f32_32x32x16_bf16 v[16:31], v[114:117], v[110:113], v[16:31]
	ds_read_b128 v[88:91], v170 offset:32768
	ds_read_b128 v[92:95], v174 offset:49152
	ds_read_b128 v[98:101], v171 offset:32768
	ds_read_b128 v[102:105], v175 offset:49152
	ds_read_b128 v[106:109], v174 offset:53248
	ds_read_b128 v[110:113], v175 offset:53248
	v_lshl_add_u64 v[66:67], v[66:67], 0, s[96:97]
	s_add_u32 m0, s94, 0x0
	s_nop 1
	global_load_lds_dwordx4 v[66:67], off
	v_lshl_add_u64 v[68:69], v[68:69], 0, s[96:97]
	s_add_u32 m0, s94, 0x4000
	s_nop 1
	global_load_lds_dwordx4 v[68:69], off
	v_lshl_add_u64 v[70:71], v[70:71], 0, s[96:97]
	s_add_u32 m0, s94, 0x1000
	s_nop 1
	global_load_lds_dwordx4 v[70:71], off
	v_lshl_add_u64 v[72:73], v[72:73], 0, s[96:97]
	s_add_u32 m0, s94, 0x5000
	s_nop 1
	global_load_lds_dwordx4 v[72:73], off
	v_lshl_add_u64 v[74:75], v[74:75], 0, s[96:97]
	s_add_u32 m0, s94, 0x2000
	s_nop 1
	global_load_lds_dwordx4 v[74:75], off
	v_lshl_add_u64 v[76:77], v[76:77], 0, s[96:97]
	s_add_u32 m0, s94, 0x6000
	s_nop 1
	global_load_lds_dwordx4 v[76:77], off
	v_lshl_add_u64 v[80:81], v[80:81], 0, s[96:97]
	s_add_u32 m0, s94, 0x3000
	s_nop 1
	global_load_lds_dwordx4 v[80:81], off
	v_lshl_add_u64 v[78:79], v[78:79], 0, s[96:97]
	s_add_u32 m0, s94, 0x7000
	s_nop 1
	global_load_lds_dwordx4 v[78:79], off
	s_waitcnt lgkmcnt(4)
	v_mfma_f32_32x32x16_bf16 v[32:47], v[88:91], v[92:95], v[32:47]
	s_waitcnt lgkmcnt(1)
	v_mfma_f32_32x32x16_bf16 v[48:63], v[88:91], v[106:109], v[48:63]
	ds_read_b128 v[88:91], v170 offset:36864
	ds_read_b128 v[114:117], v171 offset:36864
	s_waitcnt lgkmcnt(1)
	v_mfma_f32_32x32x16_bf16 v[0:15], v[88:91], v[92:95], v[0:15]
	v_mfma_f32_32x32x16_bf16 v[16:31], v[88:91], v[106:109], v[16:31]
	v_mfma_f32_32x32x16_bf16 v[32:47], v[98:101], v[102:105], v[32:47]
	v_mfma_f32_32x32x16_bf16 v[48:63], v[98:101], v[110:113], v[48:63]
	s_waitcnt lgkmcnt(0)
	v_mfma_f32_32x32x16_bf16 v[0:15], v[114:117], v[102:105], v[0:15]
	ds_read_b128 v[88:91], v172 offset:32768
	ds_read_b128 v[92:95], v176 offset:49152
	ds_read_b128 v[98:101], v173 offset:32768
	ds_read_b128 v[102:105], v177 offset:49152
	v_mfma_f32_32x32x16_bf16 v[16:31], v[114:117], v[110:113], v[16:31]
	ds_read_b128 v[106:109], v176 offset:53248
	ds_read_b128 v[110:113], v177 offset:53248
	s_waitcnt lgkmcnt(4)
	v_mfma_f32_32x32x16_bf16 v[32:47], v[88:91], v[92:95], v[32:47]
	s_waitcnt lgkmcnt(1)
	v_mfma_f32_32x32x16_bf16 v[48:63], v[88:91], v[106:109], v[48:63]
	ds_read_b128 v[88:91], v172 offset:36864
	ds_read_b128 v[114:117], v173 offset:36864
	s_waitcnt lgkmcnt(1)
	v_mfma_f32_32x32x16_bf16 v[0:15], v[88:91], v[92:95], v[0:15]
	v_mfma_f32_32x32x16_bf16 v[16:31], v[88:91], v[106:109], v[16:31]
	v_mfma_f32_32x32x16_bf16 v[32:47], v[98:101], v[102:105], v[32:47]
	v_mfma_f32_32x32x16_bf16 v[48:63], v[98:101], v[110:113], v[48:63]
	s_waitcnt lgkmcnt(0)
	v_mfma_f32_32x32x16_bf16 v[0:15], v[114:117], v[102:105], v[0:15]
	s_waitcnt vmcnt(0)
	s_barrier
;     ...
;   bf16* As1 = As + 2 * 128 * 72;
;   bf16* Bs1 = As1 + 128 * 72;
;   G_LOAD(ra0, rb0, 0);
;   if (nk > 1) G_LOAD(ra1, rb1, 1);
;   G_STORE(ra0, rb0, As, Bs);
;   __syncthreads();
;   for (int kt = 0; kt < nk; kt += 2) {
;     if (kt + 2 < nk) G_LOAD(ra0, rb0, kt + 2);
;     if (kt + 1 < nk) G_STORE(ra1, rb1, As1, Bs1);
;     G_COMPUTE(As, Bs);
;     __syncthreads();
;     if (kt + 1 < nk) {
;       if (kt + 3 < nk) G_LOAD(ra1, rb1, kt + 3);
;       if (kt + 2 < nk) G_STORE(ra0, rb0, As, Bs);
;       G_COMPUTE(As1, Bs1);
;       __syncthreads();
;     }
;   }
	v_mfma_f32_32x32x16_bf16 v[16:31], v[114:117], v[110:113], v[16:31]
	ds_read_b128 v[88:91], v170 offset:0
	ds_read_b128 v[92:95], v174 offset:16384
	ds_read_b128 v[98:101], v171 offset:0
	ds_read_b128 v[102:105], v175 offset:16384
	ds_read_b128 v[106:109], v174 offset:20480
	ds_read_b128 v[110:113], v175 offset:20480
	v_lshl_add_u64 v[66:67], v[66:67], 0, s[96:97]
	s_add_u32 m0, s94, 0x8000
	s_nop 1
	global_load_lds_dwordx4 v[66:67], off
	v_lshl_add_u64 v[68:69], v[68:69], 0, s[96:97]
	s_add_u32 m0, s94, 0xc000
	s_nop 1
	global_load_lds_dwordx4 v[68:69], off
	v_lshl_add_u64 v[70:71], v[70:71], 0, s[96:97]
	s_add_u32 m0, s94, 0x9000
	s_nop 1
	global_load_lds_dwordx4 v[70:71], off
	v_lshl_add_u64 v[72:73], v[72:73], 0, s[96:97]
	s_add_u32 m0, s94, 0xd000
	s_nop 1
	global_load_lds_dwordx4 v[72:73], off
	v_lshl_add_u64 v[74:75], v[74:75], 0, s[96:97]
	s_add_u32 m0, s94, 0xa000
	s_nop 1
	global_load_lds_dwordx4 v[74:75], off
	v_lshl_add_u64 v[76:77], v[76:77], 0, s[96:97]
	s_add_u32 m0, s94, 0xe000
	s_nop 1
	global_load_lds_dwordx4 v[76:77], off
	v_lshl_add_u64 v[80:81], v[80:81], 0, s[96:97]
	s_add_u32 m0, s94, 0xb000
	s_nop 1
	global_load_lds_dwordx4 v[80:81], off
	v_lshl_add_u64 v[78:79], v[78:79], 0, s[96:97]
	s_add_u32 m0, s94, 0xf000
	s_nop 1
	global_load_lds_dwordx4 v[78:79], off
	s_waitcnt lgkmcnt(4)
	v_mfma_f32_32x32x16_bf16 v[32:47], v[88:91], v[92:95], v[32:47]
	s_waitcnt lgkmcnt(1)
	v_mfma_f32_32x32x16_bf16 v[48:63], v[88:91], v[106:109], v[48:63]
	ds_read_b128 v[88:91], v170 offset:4096
	ds_read_b128 v[114:117], v171 offset:4096
	s_waitcnt lgkmcnt(1)
	v_mfma_f32_32x32x16_bf16 v[0:15], v[88:91], v[92:95], v[0:15]
	v_mfma_f32_32x32x16_bf16 v[16:31], v[88:91], v[106:109], v[16:31]
	v_mfma_f32_32x32x16_bf16 v[32:47], v[98:101], v[102:105], v[32:47]
	v_mfma_f32_32x32x16_bf16 v[48:63], v[98:101], v[110:113], v[48:63]
	s_waitcnt lgkmcnt(0)
	v_mfma_f32_32x32x16_bf16 v[0:15], v[114:117], v[102:105], v[0:15]
	ds_read_b128 v[88:91], v172 offset:0
	ds_read_b128 v[92:95], v176 offset:16384
	ds_read_b128 v[98:101], v173 offset:0
	ds_read_b128 v[102:105], v177 offset:16384
	v_mfma_f32_32x32x16_bf16 v[16:31], v[114:117], v[110:113], v[16:31]
	ds_read_b128 v[106:109], v176 offset:20480
	ds_read_b128 v[110:113], v177 offset:20480
	s_waitcnt lgkmcnt(4)
	v_mfma_f32_32x32x16_bf16 v[32:47], v[88:91], v[92:95], v[32:47]
	s_waitcnt lgkmcnt(1)
	v_mfma_f32_32x32x16_bf16 v[48:63], v[88:91], v[106:109], v[48:63]
	ds_read_b128 v[88:91], v172 offset:4096
	ds_read_b128 v[114:117], v173 offset:4096
	s_waitcnt lgkmcnt(1)
	v_mfma_f32_32x32x16_bf16 v[0:15], v[88:91], v[92:95], v[0:15]
	v_mfma_f32_32x32x16_bf16 v[16:31], v[88:91], v[106:109], v[16:31]
	v_mfma_f32_32x32x16_bf16 v[32:47], v[98:101], v[102:105], v[32:47]
	v_mfma_f32_32x32x16_bf16 v[48:63], v[98:101], v[110:113], v[48:63]
	s_waitcnt lgkmcnt(0)
	v_mfma_f32_32x32x16_bf16 v[0:15], v[114:117], v[102:105], v[0:15]
	s_waitcnt vmcnt(0)
	s_barrier
	v_mfma_f32_32x32x16_bf16 v[16:31], v[114:117], v[110:113], v[16:31]
	ds_read_b128 v[88:91], v170 offset:32768
	ds_read_b128 v[92:95], v174 offset:49152
	ds_read_b128 v[98:101], v171 offset:32768
	ds_read_b128 v[102:105], v175 offset:49152
	ds_read_b128 v[106:109], v174 offset:53248
	ds_read_b128 v[110:113], v175 offset:53248
	v_lshl_add_u64 v[66:67], v[66:67], 0, s[96:97]
	s_add_u32 m0, s94, 0x0
	s_nop 1
	global_load_lds_dwordx4 v[66:67], off
	v_lshl_add_u64 v[68:69], v[68:69], 0, s[96:97]
	s_add_u32 m0, s94, 0x4000
	s_nop 1
	global_load_lds_dwordx4 v[68:69], off
	v_lshl_add_u64 v[70:71], v[70:71], 0, s[96:97]
	s_add_u32 m0, s94, 0x1000
	s_nop 1
	global_load_lds_dwordx4 v[70:71], off
	v_lshl_add_u64 v[72:73], v[72:73], 0, s[96:97]
	s_add_u32 m0, s94, 0x5000
	s_nop 1
	global_load_lds_dwordx4 v[72:73], off
	v_lshl_add_u64 v[74:75], v[74:75], 0, s[96:97]
	s_add_u32 m0, s94, 0x2000
	s_nop 1
	global_load_lds_dwordx4 v[74:75], off
	v_lshl_add_u64 v[76:77], v[76:77], 0, s[96:97]
	s_add_u32 m0, s94, 0x6000
	s_nop 1
	global_load_lds_dwordx4 v[76:77], off
	v_lshl_add_u64 v[80:81], v[80:81], 0, s[96:97]
	s_add_u32 m0, s94, 0x3000
	s_nop 1
	global_load_lds_dwordx4 v[80:81], off
	v_lshl_add_u64 v[78:79], v[78:79], 0, s[96:97]
	s_add_u32 m0, s94, 0x7000
	s_nop 1
	global_load_lds_dwordx4 v[78:79], off
	s_waitcnt lgkmcnt(4)
	v_mfma_f32_32x32x16_bf16 v[32:47], v[88:91], v[92:95], v[32:47]
	s_waitcnt lgkmcnt(1)
	v_mfma_f32_32x32x16_bf16 v[48:63], v[88:91], v[106:109], v[48:63]
	ds_read_b128 v[88:91], v170 offset:36864
	ds_read_b128 v[114:117], v171 offset:36864
	s_waitcnt lgkmcnt(1)
	v_mfma_f32_32x32x16_bf16 v[0:15], v[88:91], v[92:95], v[0:15]
	v_mfma_f32_32x32x16_bf16 v[16:31], v[88:91], v[106:109], v[16:31]
	v_mfma_f32_32x32x16_bf16 v[32:47], v[98:101], v[102:105], v[32:47]
	v_mfma_f32_32x32x16_bf16 v[48:63], v[98:101], v[110:113], v[48:63]
	s_waitcnt lgkmcnt(0)
	v_mfma_f32_32x32x16_bf16 v[0:15], v[114:117], v[102:105], v[0:15]
	ds_read_b128 v[88:91], v172 offset:32768
	ds_read_b128 v[92:95], v176 offset:49152
	ds_read_b128 v[98:101], v173 offset:32768
	ds_read_b128 v[102:105], v177 offset:49152
	v_mfma_f32_32x32x16_bf16 v[16:31], v[114:117], v[110:113], v[16:31]
	ds_read_b128 v[106:109], v176 offset:53248
	ds_read_b128 v[110:113], v177 offset:53248
	s_waitcnt lgkmcnt(4)
	v_mfma_f32_32x32x16_bf16 v[32:47], v[88:91], v[92:95], v[32:47]
	s_waitcnt lgkmcnt(1)
	v_mfma_f32_32x32x16_bf16 v[48:63], v[88:91], v[106:109], v[48:63]
	ds_read_b128 v[88:91], v172 offset:36864
	ds_read_b128 v[114:117], v173 offset:36864
	s_waitcnt lgkmcnt(1)
	v_mfma_f32_32x32x16_bf16 v[0:15], v[88:91], v[92:95], v[0:15]
	v_mfma_f32_32x32x16_bf16 v[16:31], v[88:91], v[106:109], v[16:31]
	v_mfma_f32_32x32x16_bf16 v[32:47], v[98:101], v[102:105], v[32:47]
	v_mfma_f32_32x32x16_bf16 v[48:63], v[98:101], v[110:113], v[48:63]
	s_waitcnt lgkmcnt(0)
	v_mfma_f32_32x32x16_bf16 v[0:15], v[114:117], v[102:105], v[0:15]
	s_waitcnt vmcnt(0)
	s_barrier
;     ...
;   bf16* As1 = As + 2 * 128 * 72;
;   bf16* Bs1 = As1 + 128 * 72;
;   G_LOAD(ra0, rb0, 0);
;   if (nk > 1) G_LOAD(ra1, rb1, 1);
;   G_STORE(ra0, rb0, As, Bs);
;   __syncthreads();
;   for (int kt = 0; kt < nk; kt += 2) {
;     if (kt + 2 < nk) G_LOAD(ra0, rb0, kt + 2);
;     if (kt + 1 < nk) G_STORE(ra1, rb1, As1, Bs1);
;     G_COMPUTE(As, Bs);
;     __syncthreads();
;     if (kt + 1 < nk) {
;       if (kt + 3 < nk) G_LOAD(ra1, rb1, kt + 3);
;       if (kt + 2 < nk) G_STORE(ra0, rb0, As, Bs);
;       G_COMPUTE(As1, Bs1);
;       __syncthreads();
;     }
;   }
	v_mfma_f32_32x32x16_bf16 v[16:31], v[114:117], v[110:113], v[16:31]
	ds_read_b128 v[88:91], v170 offset:0
	ds_read_b128 v[92:95], v174 offset:16384
	ds_read_b128 v[98:101], v171 offset:0
	ds_read_b128 v[102:105], v175 offset:16384
	ds_read_b128 v[106:109], v174 offset:20480
	ds_read_b128 v[110:113], v175 offset:20480
	v_lshl_add_u64 v[66:67], v[66:67], 0, s[96:97]
	s_add_u32 m0, s94, 0x8000
	s_nop 1
	global_load_lds_dwordx4 v[66:67], off
	v_lshl_add_u64 v[68:69], v[68:69], 0, s[96:97]
	s_add_u32 m0, s94, 0xc000
	s_nop 1
	global_load_lds_dwordx4 v[68:69], off
	v_lshl_add_u64 v[70:71], v[70:71], 0, s[96:97]
	s_add_u32 m0, s94, 0x9000
	s_nop 1
	global_load_lds_dwordx4 v[70:71], off
	v_lshl_add_u64 v[72:73], v[72:73], 0, s[96:97]
	s_add_u32 m0, s94, 0xd000
	s_nop 1
	global_load_lds_dwordx4 v[72:73], off
	v_lshl_add_u64 v[74:75], v[74:75], 0, s[96:97]
	s_add_u32 m0, s94, 0xa000
	s_nop 1
	global_load_lds_dwordx4 v[74:75], off
	v_lshl_add_u64 v[76:77], v[76:77], 0, s[96:97]
	s_add_u32 m0, s94, 0xe000
	s_nop 1
	global_load_lds_dwordx4 v[76:77], off
	v_lshl_add_u64 v[80:81], v[80:81], 0, s[96:97]
	s_add_u32 m0, s94, 0xb000
	s_nop 1
	global_load_lds_dwordx4 v[80:81], off
	v_lshl_add_u64 v[78:79], v[78:79], 0, s[96:97]
	s_add_u32 m0, s94, 0xf000
	s_nop 1
	global_load_lds_dwordx4 v[78:79], off
	s_waitcnt lgkmcnt(4)
	v_mfma_f32_32x32x16_bf16 v[32:47], v[88:91], v[92:95], v[32:47]
	s_waitcnt lgkmcnt(1)
	v_mfma_f32_32x32x16_bf16 v[48:63], v[88:91], v[106:109], v[48:63]
	ds_read_b128 v[88:91], v170 offset:4096
	ds_read_b128 v[114:117], v171 offset:4096
	s_waitcnt lgkmcnt(1)
	v_mfma_f32_32x32x16_bf16 v[0:15], v[88:91], v[92:95], v[0:15]
	v_mfma_f32_32x32x16_bf16 v[16:31], v[88:91], v[106:109], v[16:31]
	v_mfma_f32_32x32x16_bf16 v[32:47], v[98:101], v[102:105], v[32:47]
	v_mfma_f32_32x32x16_bf16 v[48:63], v[98:101], v[110:113], v[48:63]
	s_waitcnt lgkmcnt(0)
	v_mfma_f32_32x32x16_bf16 v[0:15], v[114:117], v[102:105], v[0:15]
	ds_read_b128 v[88:91], v172 offset:0
	ds_read_b128 v[92:95], v176 offset:16384
	ds_read_b128 v[98:101], v173 offset:0
	ds_read_b128 v[102:105], v177 offset:16384
	v_mfma_f32_32x32x16_bf16 v[16:31], v[114:117], v[110:113], v[16:31]
	ds_read_b128 v[106:109], v176 offset:20480
	ds_read_b128 v[110:113], v177 offset:20480
	s_waitcnt lgkmcnt(4)
	v_mfma_f32_32x32x16_bf16 v[32:47], v[88:91], v[92:95], v[32:47]
	s_waitcnt lgkmcnt(1)
	v_mfma_f32_32x32x16_bf16 v[48:63], v[88:91], v[106:109], v[48:63]
	ds_read_b128 v[88:91], v172 offset:4096
	ds_read_b128 v[114:117], v173 offset:4096
	s_waitcnt lgkmcnt(1)
	v_mfma_f32_32x32x16_bf16 v[0:15], v[88:91], v[92:95], v[0:15]
	v_mfma_f32_32x32x16_bf16 v[16:31], v[88:91], v[106:109], v[16:31]
	v_mfma_f32_32x32x16_bf16 v[32:47], v[98:101], v[102:105], v[32:47]
	v_mfma_f32_32x32x16_bf16 v[48:63], v[98:101], v[110:113], v[48:63]
	s_waitcnt lgkmcnt(0)
	v_mfma_f32_32x32x16_bf16 v[0:15], v[114:117], v[102:105], v[0:15]
	s_waitcnt vmcnt(0)
	s_barrier
	v_mfma_f32_32x32x16_bf16 v[16:31], v[114:117], v[110:113], v[16:31]
	ds_read_b128 v[88:91], v170 offset:32768
	ds_read_b128 v[92:95], v174 offset:49152
	ds_read_b128 v[98:101], v171 offset:32768
	ds_read_b128 v[102:105], v175 offset:49152
	ds_read_b128 v[106:109], v174 offset:53248
	ds_read_b128 v[110:113], v175 offset:53248
	v_lshl_add_u64 v[66:67], v[66:67], 0, s[96:97]
	s_add_u32 m0, s94, 0x0
	s_nop 1
	global_load_lds_dwordx4 v[66:67], off
	v_lshl_add_u64 v[68:69], v[68:69], 0, s[96:97]
	s_add_u32 m0, s94, 0x4000
	s_nop 1
	global_load_lds_dwordx4 v[68:69], off
	v_lshl_add_u64 v[70:71], v[70:71], 0, s[96:97]
	s_add_u32 m0, s94, 0x1000
	s_nop 1
	global_load_lds_dwordx4 v[70:71], off
	v_lshl_add_u64 v[72:73], v[72:73], 0, s[96:97]
	s_add_u32 m0, s94, 0x5000
	s_nop 1
	global_load_lds_dwordx4 v[72:73], off
	v_lshl_add_u64 v[74:75], v[74:75], 0, s[96:97]
	s_add_u32 m0, s94, 0x2000
	s_nop 1
	global_load_lds_dwordx4 v[74:75], off
	v_lshl_add_u64 v[76:77], v[76:77], 0, s[96:97]
	s_add_u32 m0, s94, 0x6000
	s_nop 1
	global_load_lds_dwordx4 v[76:77], off
	v_lshl_add_u64 v[80:81], v[80:81], 0, s[96:97]
	s_add_u32 m0, s94, 0x3000
	s_nop 1
	global_load_lds_dwordx4 v[80:81], off
	v_lshl_add_u64 v[78:79], v[78:79], 0, s[96:97]
	s_add_u32 m0, s94, 0x7000
	s_nop 1
	global_load_lds_dwordx4 v[78:79], off
	s_waitcnt lgkmcnt(4)
	v_mfma_f32_32x32x16_bf16 v[32:47], v[88:91], v[92:95], v[32:47]
	s_waitcnt lgkmcnt(1)
	v_mfma_f32_32x32x16_bf16 v[48:63], v[88:91], v[106:109], v[48:63]
	ds_read_b128 v[88:91], v170 offset:36864
	ds_read_b128 v[114:117], v171 offset:36864
	s_waitcnt lgkmcnt(1)
	v_mfma_f32_32x32x16_bf16 v[0:15], v[88:91], v[92:95], v[0:15]
	v_mfma_f32_32x32x16_bf16 v[16:31], v[88:91], v[106:109], v[16:31]
	v_mfma_f32_32x32x16_bf16 v[32:47], v[98:101], v[102:105], v[32:47]
	v_mfma_f32_32x32x16_bf16 v[48:63], v[98:101], v[110:113], v[48:63]
	s_waitcnt lgkmcnt(0)
	v_mfma_f32_32x32x16_bf16 v[0:15], v[114:117], v[102:105], v[0:15]
	ds_read_b128 v[88:91], v172 offset:32768
	ds_read_b128 v[92:95], v176 offset:49152
	ds_read_b128 v[98:101], v173 offset:32768
	ds_read_b128 v[102:105], v177 offset:49152
	v_mfma_f32_32x32x16_bf16 v[16:31], v[114:117], v[110:113], v[16:31]
	ds_read_b128 v[106:109], v176 offset:53248
	ds_read_b128 v[110:113], v177 offset:53248
	s_waitcnt lgkmcnt(4)
	v_mfma_f32_32x32x16_bf16 v[32:47], v[88:91], v[92:95], v[32:47]
	s_waitcnt lgkmcnt(1)
	v_mfma_f32_32x32x16_bf16 v[48:63], v[88:91], v[106:109], v[48:63]
	ds_read_b128 v[88:91], v172 offset:36864
	ds_read_b128 v[114:117], v173 offset:36864
	s_waitcnt lgkmcnt(1)
	v_mfma_f32_32x32x16_bf16 v[0:15], v[88:91], v[92:95], v[0:15]
	v_mfma_f32_32x32x16_bf16 v[16:31], v[88:91], v[106:109], v[16:31]
	v_mfma_f32_32x32x16_bf16 v[32:47], v[98:101], v[102:105], v[32:47]
	v_mfma_f32_32x32x16_bf16 v[48:63], v[98:101], v[110:113], v[48:63]
	s_waitcnt lgkmcnt(0)
	v_mfma_f32_32x32x16_bf16 v[0:15], v[114:117], v[102:105], v[0:15]
	s_waitcnt vmcnt(0)
	s_barrier
;     ...
;   bf16* As1 = As + 2 * 128 * 72;
;   bf16* Bs1 = As1 + 128 * 72;
;   G_LOAD(ra0, rb0, 0);
;   if (nk > 1) G_LOAD(ra1, rb1, 1);
;   G_STORE(ra0, rb0, As, Bs);
;   __syncthreads();
;   for (int kt = 0; kt < nk; kt += 2) {
;     if (kt + 2 < nk) G_LOAD(ra0, rb0, kt + 2);
;     if (kt + 1 < nk) G_STORE(ra1, rb1, As1, Bs1);
;     G_COMPUTE(As, Bs);
;     __syncthreads();
;     if (kt + 1 < nk) {
;       if (kt + 3 < nk) G_LOAD(ra1, rb1, kt + 3);
;       if (kt + 2 < nk) G_STORE(ra0, rb0, As, Bs);
;       G_COMPUTE(As1, Bs1);
;       __syncthreads();
;     }
;   }
	v_mfma_f32_32x32x16_bf16 v[16:31], v[114:117], v[110:113], v[16:31]
	ds_read_b128 v[88:91], v170 offset:0
	ds_read_b128 v[92:95], v174 offset:16384
	ds_read_b128 v[98:101], v171 offset:0
	ds_read_b128 v[102:105], v175 offset:16384
	ds_read_b128 v[106:109], v174 offset:20480
	ds_read_b128 v[110:113], v175 offset:20480
	v_lshl_add_u64 v[66:67], v[66:67], 0, s[96:97]
	s_add_u32 m0, s94, 0x8000
	s_nop 1
	global_load_lds_dwordx4 v[66:67], off
	v_lshl_add_u64 v[68:69], v[68:69], 0, s[96:97]
	s_add_u32 m0, s94, 0xc000
	s_nop 1
	global_load_lds_dwordx4 v[68:69], off
	v_lshl_add_u64 v[70:71], v[70:71], 0, s[96:97]
	s_add_u32 m0, s94, 0x9000
	s_nop 1
	global_load_lds_dwordx4 v[70:71], off
	v_lshl_add_u64 v[72:73], v[72:73], 0, s[96:97]
	s_add_u32 m0, s94, 0xd000
	s_nop 1
	global_load_lds_dwordx4 v[72:73], off
	v_lshl_add_u64 v[74:75], v[74:75], 0, s[96:97]
	s_add_u32 m0, s94, 0xa000
	s_nop 1
	global_load_lds_dwordx4 v[74:75], off
	v_lshl_add_u64 v[76:77], v[76:77], 0, s[96:97]
	s_add_u32 m0, s94, 0xe000
	s_nop 1
	global_load_lds_dwordx4 v[76:77], off
	v_lshl_add_u64 v[80:81], v[80:81], 0, s[96:97]
	s_add_u32 m0, s94, 0xb000
	s_nop 1
	global_load_lds_dwordx4 v[80:81], off
	v_lshl_add_u64 v[78:79], v[78:79], 0, s[96:97]
	s_add_u32 m0, s94, 0xf000
	s_nop 1
	global_load_lds_dwordx4 v[78:79], off
	s_waitcnt lgkmcnt(4)
	v_mfma_f32_32x32x16_bf16 v[32:47], v[88:91], v[92:95], v[32:47]
	s_waitcnt lgkmcnt(1)
	v_mfma_f32_32x32x16_bf16 v[48:63], v[88:91], v[106:109], v[48:63]
	ds_read_b128 v[88:91], v170 offset:4096
	ds_read_b128 v[114:117], v171 offset:4096
	s_waitcnt lgkmcnt(1)
	v_mfma_f32_32x32x16_bf16 v[0:15], v[88:91], v[92:95], v[0:15]
	v_mfma_f32_32x32x16_bf16 v[16:31], v[88:91], v[106:109], v[16:31]
	v_mfma_f32_32x32x16_bf16 v[32:47], v[98:101], v[102:105], v[32:47]
	v_mfma_f32_32x32x16_bf16 v[48:63], v[98:101], v[110:113], v[48:63]
	s_waitcnt lgkmcnt(0)
	v_mfma_f32_32x32x16_bf16 v[0:15], v[114:117], v[102:105], v[0:15]
	ds_read_b128 v[88:91], v172 offset:0
	ds_read_b128 v[92:95], v176 offset:16384
	ds_read_b128 v[98:101], v173 offset:0
	ds_read_b128 v[102:105], v177 offset:16384
	v_mfma_f32_32x32x16_bf16 v[16:31], v[114:117], v[110:113], v[16:31]
	ds_read_b128 v[106:109], v176 offset:20480
	ds_read_b128 v[110:113], v177 offset:20480
	s_waitcnt lgkmcnt(4)
	v_mfma_f32_32x32x16_bf16 v[32:47], v[88:91], v[92:95], v[32:47]
	s_waitcnt lgkmcnt(1)
	v_mfma_f32_32x32x16_bf16 v[48:63], v[88:91], v[106:109], v[48:63]
	ds_read_b128 v[88:91], v172 offset:4096
	ds_read_b128 v[114:117], v173 offset:4096
	s_waitcnt lgkmcnt(1)
	v_mfma_f32_32x32x16_bf16 v[0:15], v[88:91], v[92:95], v[0:15]
	v_mfma_f32_32x32x16_bf16 v[16:31], v[88:91], v[106:109], v[16:31]
	v_mfma_f32_32x32x16_bf16 v[32:47], v[98:101], v[102:105], v[32:47]
	v_mfma_f32_32x32x16_bf16 v[48:63], v[98:101], v[110:113], v[48:63]
	s_waitcnt lgkmcnt(0)
	v_mfma_f32_32x32x16_bf16 v[0:15], v[114:117], v[102:105], v[0:15]
	s_waitcnt vmcnt(0)
	s_barrier
	v_mfma_f32_32x32x16_bf16 v[16:31], v[114:117], v[110:113], v[16:31]
	ds_read_b128 v[88:91], v170 offset:32768
	ds_read_b128 v[92:95], v174 offset:49152
	ds_read_b128 v[98:101], v171 offset:32768
	ds_read_b128 v[102:105], v175 offset:49152
	ds_read_b128 v[106:109], v174 offset:53248
	ds_read_b128 v[110:113], v175 offset:53248
	v_lshl_add_u64 v[66:67], v[66:67], 0, s[96:97]
	s_add_u32 m0, s94, 0x0
	s_nop 1
	global_load_lds_dwordx4 v[66:67], off
	v_lshl_add_u64 v[68:69], v[68:69], 0, s[96:97]
	s_add_u32 m0, s94, 0x4000
	s_nop 1
	global_load_lds_dwordx4 v[68:69], off
	v_lshl_add_u64 v[70:71], v[70:71], 0, s[96:97]
	s_add_u32 m0, s94, 0x1000
	s_nop 1
	global_load_lds_dwordx4 v[70:71], off
	v_lshl_add_u64 v[72:73], v[72:73], 0, s[96:97]
	s_add_u32 m0, s94, 0x5000
	s_nop 1
	global_load_lds_dwordx4 v[72:73], off
	v_lshl_add_u64 v[74:75], v[74:75], 0, s[96:97]
	s_add_u32 m0, s94, 0x2000
	s_nop 1
	global_load_lds_dwordx4 v[74:75], off
	v_lshl_add_u64 v[76:77], v[76:77], 0, s[96:97]
	s_add_u32 m0, s94, 0x6000
	s_nop 1
	global_load_lds_dwordx4 v[76:77], off
	v_lshl_add_u64 v[80:81], v[80:81], 0, s[96:97]
	s_add_u32 m0, s94, 0x3000
	s_nop 1
	global_load_lds_dwordx4 v[80:81], off
	v_lshl_add_u64 v[78:79], v[78:79], 0, s[96:97]
	s_add_u32 m0, s94, 0x7000
	s_nop 1
	global_load_lds_dwordx4 v[78:79], off
	s_waitcnt lgkmcnt(4)
	v_mfma_f32_32x32x16_bf16 v[32:47], v[88:91], v[92:95], v[32:47]
	s_waitcnt lgkmcnt(1)
	v_mfma_f32_32x32x16_bf16 v[48:63], v[88:91], v[106:109], v[48:63]
	ds_read_b128 v[88:91], v170 offset:36864
	ds_read_b128 v[114:117], v171 offset:36864
	s_waitcnt lgkmcnt(1)
	v_mfma_f32_32x32x16_bf16 v[0:15], v[88:91], v[92:95], v[0:15]
	v_mfma_f32_32x32x16_bf16 v[16:31], v[88:91], v[106:109], v[16:31]
	v_mfma_f32_32x32x16_bf16 v[32:47], v[98:101], v[102:105], v[32:47]
	v_mfma_f32_32x32x16_bf16 v[48:63], v[98:101], v[110:113], v[48:63]
	s_waitcnt lgkmcnt(0)
	v_mfma_f32_32x32x16_bf16 v[0:15], v[114:117], v[102:105], v[0:15]
	ds_read_b128 v[88:91], v172 offset:32768
	ds_read_b128 v[92:95], v176 offset:49152
	ds_read_b128 v[98:101], v173 offset:32768
	ds_read_b128 v[102:105], v177 offset:49152
	v_mfma_f32_32x32x16_bf16 v[16:31], v[114:117], v[110:113], v[16:31]
	ds_read_b128 v[106:109], v176 offset:53248
	ds_read_b128 v[110:113], v177 offset:53248
	s_waitcnt lgkmcnt(4)
	v_mfma_f32_32x32x16_bf16 v[32:47], v[88:91], v[92:95], v[32:47]
	s_waitcnt lgkmcnt(1)
	v_mfma_f32_32x32x16_bf16 v[48:63], v[88:91], v[106:109], v[48:63]
	ds_read_b128 v[88:91], v172 offset:36864
	ds_read_b128 v[114:117], v173 offset:36864
	s_waitcnt lgkmcnt(1)
	v_mfma_f32_32x32x16_bf16 v[0:15], v[88:91], v[92:95], v[0:15]
	v_mfma_f32_32x32x16_bf16 v[16:31], v[88:91], v[106:109], v[16:31]
	v_mfma_f32_32x32x16_bf16 v[32:47], v[98:101], v[102:105], v[32:47]
	v_mfma_f32_32x32x16_bf16 v[48:63], v[98:101], v[110:113], v[48:63]
	s_waitcnt lgkmcnt(0)
	v_mfma_f32_32x32x16_bf16 v[0:15], v[114:117], v[102:105], v[0:15]
	s_waitcnt vmcnt(0)
	s_barrier
;     ...
;   bf16* As1 = As + 2 * 128 * 72;
;   bf16* Bs1 = As1 + 128 * 72;
;   G_LOAD(ra0, rb0, 0);
;   if (nk > 1) G_LOAD(ra1, rb1, 1);
;   G_STORE(ra0, rb0, As, Bs);
;   __syncthreads();
;   for (int kt = 0; kt < nk; kt += 2) {
;     if (kt + 2 < nk) G_LOAD(ra0, rb0, kt + 2);
;     if (kt + 1 < nk) G_STORE(ra1, rb1, As1, Bs1);
;     G_COMPUTE(As, Bs);
;     __syncthreads();
;     if (kt + 1 < nk) {
;       if (kt + 3 < nk) G_LOAD(ra1, rb1, kt + 3);
;       if (kt + 2 < nk) G_STORE(ra0, rb0, As, Bs);
;       G_COMPUTE(As1, Bs1);
;       __syncthreads();
;     }
;   }
	v_mfma_f32_32x32x16_bf16 v[16:31], v[114:117], v[110:113], v[16:31]
	ds_read_b128 v[88:91], v170 offset:0
	ds_read_b128 v[92:95], v174 offset:16384
	ds_read_b128 v[98:101], v171 offset:0
	ds_read_b128 v[102:105], v175 offset:16384
	ds_read_b128 v[106:109], v174 offset:20480
	ds_read_b128 v[110:113], v175 offset:20480
	v_lshl_add_u64 v[66:67], v[66:67], 0, s[96:97]
	s_add_u32 m0, s94, 0x8000
	s_nop 1
	global_load_lds_dwordx4 v[66:67], off
	v_lshl_add_u64 v[68:69], v[68:69], 0, s[96:97]
	s_add_u32 m0, s94, 0xc000
	s_nop 1
	global_load_lds_dwordx4 v[68:69], off
	v_lshl_add_u64 v[70:71], v[70:71], 0, s[96:97]
	s_add_u32 m0, s94, 0x9000
	s_nop 1
	global_load_lds_dwordx4 v[70:71], off
	v_lshl_add_u64 v[72:73], v[72:73], 0, s[96:97]
	s_add_u32 m0, s94, 0xd000
	s_nop 1
	global_load_lds_dwordx4 v[72:73], off
	v_lshl_add_u64 v[74:75], v[74:75], 0, s[96:97]
	s_add_u32 m0, s94, 0xa000
	s_nop 1
	global_load_lds_dwordx4 v[74:75], off
	v_lshl_add_u64 v[76:77], v[76:77], 0, s[96:97]
	s_add_u32 m0, s94, 0xe000
	s_nop 1
	global_load_lds_dwordx4 v[76:77], off
	v_lshl_add_u64 v[80:81], v[80:81], 0, s[96:97]
	s_add_u32 m0, s94, 0xb000
	s_nop 1
	global_load_lds_dwordx4 v[80:81], off
	v_lshl_add_u64 v[78:79], v[78:79], 0, s[96:97]
	s_add_u32 m0, s94, 0xf000
	s_nop 1
	global_load_lds_dwordx4 v[78:79], off
	s_waitcnt lgkmcnt(4)
	v_mfma_f32_32x32x16_bf16 v[32:47], v[88:91], v[92:95], v[32:47]
	s_waitcnt lgkmcnt(1)
	v_mfma_f32_32x32x16_bf16 v[48:63], v[88:91], v[106:109], v[48:63]
	ds_read_b128 v[88:91], v170 offset:4096
	ds_read_b128 v[114:117], v171 offset:4096
	s_waitcnt lgkmcnt(1)
	v_mfma_f32_32x32x16_bf16 v[0:15], v[88:91], v[92:95], v[0:15]
	v_mfma_f32_32x32x16_bf16 v[16:31], v[88:91], v[106:109], v[16:31]
	v_mfma_f32_32x32x16_bf16 v[32:47], v[98:101], v[102:105], v[32:47]
	v_mfma_f32_32x32x16_bf16 v[48:63], v[98:101], v[110:113], v[48:63]
	s_waitcnt lgkmcnt(0)
	v_mfma_f32_32x32x16_bf16 v[0:15], v[114:117], v[102:105], v[0:15]
	ds_read_b128 v[88:91], v172 offset:0
	ds_read_b128 v[92:95], v176 offset:16384
	ds_read_b128 v[98:101], v173 offset:0
	ds_read_b128 v[102:105], v177 offset:16384
	v_mfma_f32_32x32x16_bf16 v[16:31], v[114:117], v[110:113], v[16:31]
	ds_read_b128 v[106:109], v176 offset:20480
	ds_read_b128 v[110:113], v177 offset:20480
	s_waitcnt lgkmcnt(4)
	v_mfma_f32_32x32x16_bf16 v[32:47], v[88:91], v[92:95], v[32:47]
	s_waitcnt lgkmcnt(1)
	v_mfma_f32_32x32x16_bf16 v[48:63], v[88:91], v[106:109], v[48:63]
	ds_read_b128 v[88:91], v172 offset:4096
	ds_read_b128 v[114:117], v173 offset:4096
	s_waitcnt lgkmcnt(1)
	v_mfma_f32_32x32x16_bf16 v[0:15], v[88:91], v[92:95], v[0:15]
	v_mfma_f32_32x32x16_bf16 v[16:31], v[88:91], v[106:109], v[16:31]
	v_mfma_f32_32x32x16_bf16 v[32:47], v[98:101], v[102:105], v[32:47]
	v_mfma_f32_32x32x16_bf16 v[48:63], v[98:101], v[110:113], v[48:63]
	s_waitcnt lgkmcnt(0)
	v_mfma_f32_32x32x16_bf16 v[0:15], v[114:117], v[102:105], v[0:15]
	s_waitcnt vmcnt(0)
	s_barrier
	v_mfma_f32_32x32x16_bf16 v[16:31], v[114:117], v[110:113], v[16:31]
	ds_read_b128 v[88:91], v170 offset:32768
	ds_read_b128 v[92:95], v174 offset:49152
	ds_read_b128 v[98:101], v171 offset:32768
	ds_read_b128 v[102:105], v175 offset:49152
	ds_read_b128 v[106:109], v174 offset:53248
	ds_read_b128 v[110:113], v175 offset:53248
	v_lshl_add_u64 v[66:67], v[66:67], 0, s[96:97]
	s_add_u32 m0, s94, 0x0
	s_nop 1
	global_load_lds_dwordx4 v[66:67], off
	v_lshl_add_u64 v[68:69], v[68:69], 0, s[96:97]
	s_add_u32 m0, s94, 0x4000
	s_nop 1
	global_load_lds_dwordx4 v[68:69], off
	v_lshl_add_u64 v[70:71], v[70:71], 0, s[96:97]
	s_add_u32 m0, s94, 0x1000
	s_nop 1
	global_load_lds_dwordx4 v[70:71], off
	v_lshl_add_u64 v[72:73], v[72:73], 0, s[96:97]
	s_add_u32 m0, s94, 0x5000
	s_nop 1
	global_load_lds_dwordx4 v[72:73], off
	v_lshl_add_u64 v[74:75], v[74:75], 0, s[96:97]
	s_add_u32 m0, s94, 0x2000
	s_nop 1
	global_load_lds_dwordx4 v[74:75], off
	v_lshl_add_u64 v[76:77], v[76:77], 0, s[96:97]
	s_add_u32 m0, s94, 0x6000
	s_nop 1
	global_load_lds_dwordx4 v[76:77], off
	v_lshl_add_u64 v[80:81], v[80:81], 0, s[96:97]
	s_add_u32 m0, s94, 0x3000
	s_nop 1
	global_load_lds_dwordx4 v[80:81], off
	v_lshl_add_u64 v[78:79], v[78:79], 0, s[96:97]
	s_add_u32 m0, s94, 0x7000
	s_nop 1
	global_load_lds_dwordx4 v[78:79], off
	s_waitcnt lgkmcnt(4)
	v_mfma_f32_32x32x16_bf16 v[32:47], v[88:91], v[92:95], v[32:47]
	s_waitcnt lgkmcnt(1)
	v_mfma_f32_32x32x16_bf16 v[48:63], v[88:91], v[106:109], v[48:63]
	ds_read_b128 v[88:91], v170 offset:36864
	ds_read_b128 v[114:117], v171 offset:36864
	s_waitcnt lgkmcnt(1)
	v_mfma_f32_32x32x16_bf16 v[0:15], v[88:91], v[92:95], v[0:15]
	v_mfma_f32_32x32x16_bf16 v[16:31], v[88:91], v[106:109], v[16:31]
	v_mfma_f32_32x32x16_bf16 v[32:47], v[98:101], v[102:105], v[32:47]
	v_mfma_f32_32x32x16_bf16 v[48:63], v[98:101], v[110:113], v[48:63]
	s_waitcnt lgkmcnt(0)
	v_mfma_f32_32x32x16_bf16 v[0:15], v[114:117], v[102:105], v[0:15]
	ds_read_b128 v[88:91], v172 offset:32768
	ds_read_b128 v[92:95], v176 offset:49152
	ds_read_b128 v[98:101], v173 offset:32768
	ds_read_b128 v[102:105], v177 offset:49152
	v_mfma_f32_32x32x16_bf16 v[16:31], v[114:117], v[110:113], v[16:31]
	ds_read_b128 v[106:109], v176 offset:53248
	ds_read_b128 v[110:113], v177 offset:53248
	s_waitcnt lgkmcnt(4)
	v_mfma_f32_32x32x16_bf16 v[32:47], v[88:91], v[92:95], v[32:47]
	s_waitcnt lgkmcnt(1)
	v_mfma_f32_32x32x16_bf16 v[48:63], v[88:91], v[106:109], v[48:63]
	ds_read_b128 v[88:91], v172 offset:36864
	ds_read_b128 v[114:117], v173 offset:36864
	s_waitcnt lgkmcnt(1)
	v_mfma_f32_32x32x16_bf16 v[0:15], v[88:91], v[92:95], v[0:15]
	v_mfma_f32_32x32x16_bf16 v[16:31], v[88:91], v[106:109], v[16:31]
	v_mfma_f32_32x32x16_bf16 v[32:47], v[98:101], v[102:105], v[32:47]
	v_mfma_f32_32x32x16_bf16 v[48:63], v[98:101], v[110:113], v[48:63]
	s_nop 0
	s_nop 0
	s_nop 0
	s_nop 0
	s_nop 0
	s_nop 0
	s_nop 0
	s_waitcnt lgkmcnt(0)
	s_waitcnt vmcnt(0)
	s_barrier
; #define PW(T, off) ((T*)(lndp(p.ws) + (off)))
; DEVI void gemm_epi_qkv(const Params& p, f32x16 (&acc)[2][2], int rbase, int cbase, int lane) {
;   char* ar = PW(char, W_arena);
;   const int which = cbase >> 10, cc = cbase & 1023, d = lane & 31, hl = lane >> 5;
; #pragma unroll
;   for (int i = 0; i < 2; ++i) {
; #pragma unroll
;     for (int rq = 0; rq < 4; ++rq) {
;       const int row0 = rbase + i * 32 + 8 * rq + 4 * hl;
;       if (row0 >= M) continue;
;       const bool pr = row0 < TP;
;       const int b = pr ? 0 : (row0 - TP) >> 4, t0 = pr ? row0 : (row0 - TP) & 15;
;       if (which < 2) {
;     ...
;   for (int kt = 0; kt < nk; kt += 2) {
;     if (kt + 2 < nk) G_LOAD(ra0, rb0, kt + 2);
;     if (kt + 1 < nk) G_STORE(ra1, rb1, As1, Bs1);
;     G_COMPUTE(As, Bs);
;     __syncthreads();
;     if (kt + 1 < nk) {
;       if (kt + 3 < nk) G_LOAD(ra1, rb1, kt + 3);
;       if (kt + 2 < nk) G_STORE(ra0, rb0, As, Bs);
;       G_COMPUTE(As1, Bs1);
;       __syncthreads();
;     }
;   }
	v_lshl_add_u64 v[66:67], v[66:67], 0, s[96:97]
	s_add_u32 m0, s94, 0x8000
	s_nop 1
	global_load_lds_dwordx4 v[66:67], off
	v_lshl_add_u64 v[68:69], v[68:69], 0, s[96:97]
	s_add_u32 m0, s94, 0xc000
	s_nop 1
	global_load_lds_dwordx4 v[68:69], off
	v_lshl_add_u64 v[70:71], v[70:71], 0, s[96:97]
	s_add_u32 m0, s94, 0x9000
	s_nop 1
	global_load_lds_dwordx4 v[70:71], off
	v_lshl_add_u64 v[72:73], v[72:73], 0, s[96:97]
	s_add_u32 m0, s94, 0xd000
	s_nop 1
	global_load_lds_dwordx4 v[72:73], off
	v_lshl_add_u64 v[74:75], v[74:75], 0, s[96:97]
	s_add_u32 m0, s94, 0xa000
	s_nop 1
	global_load_lds_dwordx4 v[74:75], off
	v_lshl_add_u64 v[76:77], v[76:77], 0, s[96:97]
	s_add_u32 m0, s94, 0xe000
	s_nop 1
	global_load_lds_dwordx4 v[76:77], off
	v_lshl_add_u64 v[80:81], v[80:81], 0, s[96:97]
	s_add_u32 m0, s94, 0xb000
	s_nop 1
	global_load_lds_dwordx4 v[80:81], off
	v_lshl_add_u64 v[78:79], v[78:79], 0, s[96:97]
	s_add_u32 m0, s94, 0xf000
	s_nop 1
	global_load_lds_dwordx4 v[78:79], off
	v_mfma_f32_32x32x16_bf16 v[0:15], v[114:117], v[102:105], v[0:15]
	ds_read_b128 v[66:69], v170 offset:0
	ds_read_b128 v[70:73], v174 offset:16384
	ds_read_b128 v[74:77], v171 offset:0
	ds_read_b128 v[78:81], v175 offset:16384
	ds_read_b128 v[88:91], v174 offset:20480
	ds_read_b128 v[92:95], v175 offset:20480
	v_mfma_f32_32x32x16_bf16 v[16:31], v[114:117], v[110:113], v[16:31]
	s_waitcnt lgkmcnt(4)
	v_mfma_f32_32x32x16_bf16 v[32:47], v[66:69], v[70:73], v[32:47]
	s_waitcnt lgkmcnt(1)
	v_mfma_f32_32x32x16_bf16 v[48:63], v[66:69], v[88:91], v[48:63]
	ds_read_b128 v[66:69], v170 offset:4096
	ds_read_b128 v[98:101], v171 offset:4096
	s_waitcnt lgkmcnt(1)
	v_mfma_f32_32x32x16_bf16 v[0:15], v[66:69], v[70:73], v[0:15]
	v_mfma_f32_32x32x16_bf16 v[16:31], v[66:69], v[88:91], v[16:31]
	v_mfma_f32_32x32x16_bf16 v[32:47], v[74:77], v[78:81], v[32:47]
	v_mfma_f32_32x32x16_bf16 v[48:63], v[74:77], v[92:95], v[48:63]
	s_waitcnt lgkmcnt(0)
	v_mfma_f32_32x32x16_bf16 v[0:15], v[98:101], v[78:81], v[0:15]
	ds_read_b128 v[66:69], v172 offset:0
	ds_read_b128 v[70:73], v176 offset:16384
	ds_read_b128 v[74:77], v173 offset:0
	ds_read_b128 v[78:81], v177 offset:16384
	v_mfma_f32_32x32x16_bf16 v[16:31], v[98:101], v[92:95], v[16:31]
	ds_read_b128 v[88:91], v176 offset:20480
	ds_read_b128 v[92:95], v177 offset:20480
	s_waitcnt lgkmcnt(4)
	v_mfma_f32_32x32x16_bf16 v[32:47], v[66:69], v[70:73], v[32:47]
	s_waitcnt lgkmcnt(1)
	v_mfma_f32_32x32x16_bf16 v[48:63], v[66:69], v[88:91], v[48:63]
	ds_read_b128 v[66:69], v172 offset:4096
	ds_read_b128 v[98:101], v173 offset:4096
	s_waitcnt lgkmcnt(0)
	s_waitcnt vmcnt(0)
	s_barrier
	v_mfma_f32_32x32x16_bf16 v[0:15], v[66:69], v[70:73], v[0:15]
	v_mfma_f32_32x32x16_bf16 v[32:47], v[74:77], v[78:81], v[32:47]
	v_mfma_f32_32x32x16_bf16 v[48:63], v[74:77], v[92:95], v[48:63]
	v_mfma_f32_32x32x16_bf16 v[16:31], v[66:69], v[88:91], v[16:31]
	v_mfma_f32_32x32x16_bf16 v[0:15], v[98:101], v[78:81], v[0:15]
	ds_read_b128 v[66:69], v170 offset:32768
	ds_read_b128 v[70:73], v174 offset:49152
	ds_read_b128 v[74:77], v175 offset:49152
	ds_read_b128 v[78:81], v171 offset:32768
	ds_read_b128 v[88:91], v174 offset:53248
	s_waitcnt lgkmcnt(3)
	v_mfma_f32_32x32x16_bf16 v[32:47], v[66:69], v[70:73], v[32:47]
	s_waitcnt lgkmcnt(0)
	v_mfma_f32_32x32x16_bf16 v[48:63], v[66:69], v[88:91], v[48:63]
	ds_read_b128 v[66:69], v170 offset:36864
	v_mfma_f32_32x32x16_bf16 v[16:31], v[98:101], v[92:95], v[16:31]
	s_waitcnt lgkmcnt(0)
	v_mfma_f32_32x32x16_bf16 v[0:15], v[66:69], v[70:73], v[0:15]
	ds_read_b128 v[70:73], v171 offset:36864
	v_mfma_f32_32x32x16_bf16 v[16:31], v[66:69], v[88:91], v[16:31]
	ds_read_b128 v[66:69], v175 offset:53248
	v_mfma_f32_32x32x16_bf16 v[32:47], v[78:81], v[74:77], v[32:47]
	s_waitcnt lgkmcnt(0)
	v_mfma_f32_32x32x16_bf16 v[48:63], v[78:81], v[66:69], v[48:63]
	v_and_or_b32 v80, v85, 64, s2
	v_or_b32_e32 v81, v80, v84
	v_mfma_f32_32x32x16_bf16 v[0:15], v[70:73], v[74:77], v[0:15]
	v_mfma_f32_32x32x16_bf16 v[16:31], v[70:73], v[66:69], v[16:31]
	ds_read_b128 v[66:69], v172 offset:32768
	ds_read_b128 v[70:73], v176 offset:49152
	ds_read_b128 v[74:77], v176 offset:53248
	s_waitcnt lgkmcnt(1)
	v_mfma_f32_32x32x16_bf16 v[32:47], v[66:69], v[70:73], v[32:47]
	s_waitcnt lgkmcnt(0)
	v_mfma_f32_32x32x16_bf16 v[48:63], v[66:69], v[74:77], v[48:63]
	ds_read_b128 v[66:69], v172 offset:36864
	s_waitcnt lgkmcnt(0)
	v_mfma_f32_32x32x16_bf16 v[0:15], v[66:69], v[70:73], v[0:15]
	ds_read_b128 v[88:91], v177 offset:53248
	ds_read_b128 v[92:95], v177 offset:49152
	ds_read_b128 v[70:73], v173 offset:32768
	v_lshrrev_b32_e32 v65, 3, v85
	v_and_b32_e32 v82, 4, v65
	v_mfma_f32_32x32x16_bf16 v[16:31], v[66:69], v[74:77], v[16:31]
	ds_read_b128 v[74:77], v173 offset:36864
	v_add_u32_e32 v64, s3, v86
	v_or_b32_e32 v68, v64, v82
	v_mul_u32_u24_e32 v64, 0x4040, v81
	v_lshlrev_b32_e32 v96, 1, v64
	s_waitcnt lgkmcnt(0)
	s_barrier
	v_mfma_f32_32x32x16_bf16 v[32:47], v[70:73], v[92:95], v[32:47]
	s_cmp_gt_i32 s5, 1
	s_cselect_b64 s[2:3], -1, 0
	v_lshl_add_u64 v[64:65], s[22:23], 0, v[96:97]
	v_lshlrev_b32_e32 v96, 1, v80
	s_cmpk_gt_u32 s4, 0x3ff
	s_cselect_b64 s[20:21], -1, 0
	v_mfma_f32_32x32x16_bf16 v[48:63], v[70:73], v[88:91], v[48:63]
	v_lshl_add_u64 v[70:71], v[64:65], 0, s[6:7]
	v_lshl_add_u64 v[64:65], s[22:23], 0, v[96:97]
	s_mov_b64 s[6:7], 0x13e3c000
	v_lshl_add_u64 v[66:67], v[64:65], 0, s[6:7]
	s_mov_b64 s[6:7], 0x11d7c000
	s_cmp_eq_u32 s5, 1
	v_lshl_add_u64 v[64:65], v[64:65], 0, s[6:7]
	v_mfma_f32_32x32x16_bf16 v[0:15], v[74:77], v[92:95], v[0:15]
	s_cselect_b64 s[18:19], -1, 0
	v_cmp_gt_i32_e32 vcc, s90, v68
	v_mfma_f32_32x32x16_bf16 v[16:31], v[74:77], v[88:91], v[16:31]
	s_and_saveexec_b64 s[4:5], vcc
	s_cbranch_execz .LBB0_2113
	s_movk_i32 s6, 0x400f
	v_add_u32_e32 v72, 0xffffbff0, v68
	v_cmp_lt_i32_e64 s[6:7], s6, v68
	v_ashrrev_i32_e32 v78, 4, v72
	s_mov_b64 s[8:9], -1
	s_and_b64 vcc, exec, s[2:3]
	s_cbranch_vccz .LBB0_2092
	s_and_saveexec_b64 s[8:9], s[6:7]
	s_xor_b64 s[8:9], exec, s[8:9]
	s_cbranch_execz .LBB0_2085
	s_mov_b64 s[10:11], s[72:73]
	s_add_u32 s10, s10, 0xc48f000
	v_mov_b32_e32 v73, v97
	s_addc_u32 s11, s11, 0
	v_mov_b64_e32 v[74:75], v[72:73]

; DEVI int TID() { int t = threadIdx.x; asm volatile("" : "+v"(t)); return t; }
; DEVI int BID() { int b = blockIdx.x; asm volatile("" : "+s"(b)); return b; }
;     ...
;   const int tid = TID(), lane = tid & 63, wave = tid >> 6, wm = wave >> 1, wn = wave & 1;
;   f32x16 acc[2][2];
; #pragma unroll
;   for (int i = 0; i < 2; ++i)
; #pragma unroll
;     for (int j = 0; j < 2; ++j) acc[i][j] = zero16();
;   const int lrow = tid >> 3, lkc = (tid & 7) * 8;
;   const bf16* Ag = jb.A + (size_t)max(m0 + lrow, 0) * jb.lda + lkc;
;   const bf16* Ag1 = jb.A + (ptrdiff_t)(m0 + lrow) * jb.lda + lkc;
;   const bf16* Bg = jb.Bt + (size_t)(n0 + lrow) * jb.K + lkc;
;   const size_t astep = (size_t)32 * jb.lda, bstep = (size_t)32 * jb.K;
;   if (kt1 < 0) kt1 = jb.K >> 6;
;   const int nk = kt1 - kt0;
;   Ag += (size_t)kt0 * 64; Ag1 += (size_t)kt0 * 64; Bg += (size_t)kt0 * 64;
;   u32x4 ra0[4], rb0[4], ra1[4], rb1[4];
;     ...
;   bf16* As1 = As + 2 * 128 * 72;
;   bf16* Bs1 = As1 + 128 * 72;
;   G_LOAD(ra0, rb0, 0);
;   if (nk > 1) G_LOAD(ra1, rb1, 1);
;   G_STORE(ra0, rb0, As, Bs);
;   __syncthreads();
; DEVI void gemm_single(const Params& p, const GJob& jb, int nt, char* smem) {
;     ...
;     const int b = BID(), x = b & 7, lb = b >> 3, nlb = gridDim.x >> 3;
;     const int ng = x & 3, mh = x >> 2;
;     const int n_lo = ng * nt / 4, nnt = (ng + 1) * nt / 4 - n_lo;
;     const int m_lo = mh * mtn / 2, nmt = (mh + 1) * mtn / 2 - m_lo;
;     for (int t = lb; t < nmt * nnt; t += nlb) {
;       const int mt = m_lo + t / nnt, ntg = n_lo + t % nnt;
;       gemm_tile(p, jb, fused ? mt * 126 - 2 : mt * 128, ntg * 128, smem);
.LBB0_2341:
	s_abs_i32 s3, s17
	s_mul_hi_u32 s4, s3, s30
	s_mul_i32 s5, s4, s27
	s_ashr_i32 s2, s17, 31
	s_sub_i32 s3, s3, s5
	s_xor_b32 s2, s2, s29
	s_add_i32 s5, s4, 1
	s_sub_i32 s6, s3, s27
	s_cmp_ge_u32 s3, s27
	s_cselect_b32 s4, s5, s4
	s_cselect_b32 s3, s6, s3
	s_add_i32 s5, s4, 1
	s_cmp_ge_u32 s3, s27
	s_cselect_b32 s3, s5, s4
	s_xor_b32 s3, s3, s2
	s_sub_i32 s4, s3, s2
	s_mul_i32 s2, s2, 6
	s_mul_i32 s3, s3, 6
	s_add_i32 s4, s4, s25
	s_sub_i32 s2, s2, s3
	s_add_i32 s3, s24, s17
	s_waitcnt vmcnt(2)
	v_mov_b32_e32 v85, v208
	s_add_i32 s2, s3, s2
	s_lshl_b32 s3, s4, 7
	s_lshl_b32 s4, s2, 7
	v_ashrrev_i32_e32 v64, 3, v85
	v_add_u32_e32 v0, s3, v64
	v_max_i32_e32 v96, 0, v0
	v_lshlrev_b32_e32 v1, 4, v85
	v_lshlrev_b64 v[2:3], 11, v[96:97]
	v_and_b32_e32 v96, 0x70, v1
	s_mov_b64 s[96:97], 0x80
	v_lshrrev_b32_e32 v178, 4, v208
	v_and_b32_e32 v178, 7, v178
	v_lshlrev_b32_e32 v178, 4, v178
	v_xor_b32_e32 v96, v96, v178
	v_lshrrev_b32_e32 v179, 6, v208
	v_lshlrev_b32_e32 v179, 10, v179
	v_lshrrev_b32_e32 v180, 5, v208
	v_lshrrev_b32_e32 v181, 1, v208
	v_xor_b32_e32 v180, v180, v181
	v_readfirstlane_b32 s94, v179
	v_and_b32_e32 v180, 1, v180
	v_lshlrev_b32_e32 v180, 4, v180
	v_and_b32_e32 v181, 31, v208
	v_lshlrev_b32_e32 v181, 7, v181
	v_or_b32_e32 v180, v180, v181
	v_lshrrev_b32_e32 v181, 7, v208
	v_lshlrev_b32_e32 v181, 13, v181
	v_or_b32_e32 v194, v180, v181
	v_bfe_u32 v181, v208, 6, 1
	v_lshlrev_b32_e32 v181, 13, v181
	v_or_b32_e32 v195, v180, v181
	v_bfe_u32 v178, v208, 2, 2
	v_xor_b32_e32 v179, 0, v178
	v_lshlrev_b32_e32 v179, 5, v179
	v_or_b32_e32 v170, v194, v179
	v_or_b32_e32 v174, v195, v179
	v_xor_b32_e32 v179, 1, v178
	v_lshlrev_b32_e32 v179, 5, v179
	v_or_b32_e32 v171, v194, v179
	v_or_b32_e32 v175, v195, v179
	v_xor_b32_e32 v179, 2, v178
	v_lshlrev_b32_e32 v179, 5, v179
	v_or_b32_e32 v172, v194, v179
	v_or_b32_e32 v176, v195, v179
	v_xor_b32_e32 v179, 3, v178
	v_lshlrev_b32_e32 v179, 5, v179
	v_or_b32_e32 v173, v194, v179
	v_or_b32_e32 v177, v195, v179
	v_ashrrev_i32_e32 v1, 31, v0
	v_lshlrev_b64 v[0:1], 11, v[0:1]
	v_lshl_add_u64 v[0:1], s[12:13], 0, v[0:1]
	v_lshl_add_u64 v[24:25], v[0:1], 0, v[96:97]
	v_add_u32_e32 v0, s4, v64
	v_ashrrev_i32_e32 v1, 31, v0
	v_lshlrev_b64 v[0:1], 11, v[0:1]
	v_lshl_add_u64 v[0:1], s[14:15], 0, v[0:1]
	v_add_co_u32_e32 v70, vcc, s63, v24
	v_lshl_add_u64 v[68:69], v[0:1], 0, v[96:97]
	s_nop 0
	v_addc_co_u32_e32 v71, vcc, 0, v25, vcc
	v_add_co_u32_e32 v72, vcc, s63, v68
	v_lshl_add_u64 v[2:3], s[12:13], 0, v[2:3]
	s_nop 0
	v_addc_co_u32_e32 v73, vcc, 0, v69, vcc
	v_add_co_u32_e32 v74, vcc, s64, v24
	v_lshl_add_u64 v[66:67], v[2:3], 0, v[96:97]
	s_nop 0
	v_addc_co_u32_e32 v75, vcc, 0, v25, vcc
	v_add_co_u32_e32 v76, vcc, s64, v68
	v_addc_co_u32_e32 v77, vcc, 0, v69, vcc
	v_add_co_u32_e32 v78, vcc, s65, v24
	s_nop 0
	v_addc_co_u32_e32 v79, vcc, 0, v25, vcc
	v_add_co_u32_e32 v80, vcc, s65, v68
	s_nop 0
	v_addc_co_u32_e32 v81, vcc, 0, v69, vcc
	v_ashrrev_i32_e32 v65, 1, v85
	v_and_b32_e32 v84, 31, v85
	v_lshrrev_b32_e32 v82, 1, v85
	v_and_b32_e32 v86, 0xffffffc0, v65
	s_waitcnt vmcnt(0)
	v_and_b32_e32 v88, 16, v82
	v_or_b32_e32 v65, v86, v84
	v_mad_u64_u32 v[82:83], s[6:7], v64, s91, v[96:97]
	v_add_u32_e32 v87, 0xd800, v82
	v_mad_u64_u32 v[64:65], s[6:7], v65, s91, v[88:89]
	v_and_b32_e32 v65, 0x5f, v85
	v_mad_u32_u24 v83, v65, s91, v88
	s_and_b32 s6, s4, 0x380
	s_mov_b64 s[22:23], s[74:75]
	s_ashr_i32 s5, s2, 3
	s_add_u32 m0, s94, 0x0
	s_nop 1
	global_load_lds_dwordx4 v[66:67], off
	s_add_u32 m0, s94, 0x4000
	s_nop 1
	global_load_lds_dwordx4 v[68:69], off
	s_add_u32 m0, s94, 0x1000
	s_nop 1
	global_load_lds_dwordx4 v[70:71], off
	s_add_u32 m0, s94, 0x2000
	s_nop 1
	global_load_lds_dwordx4 v[74:75], off
	s_add_u32 m0, s94, 0x3000
	s_nop 1
	global_load_lds_dwordx4 v[78:79], off
	s_add_u32 m0, s94, 0x5000
	s_nop 1
	global_load_lds_dwordx4 v[72:73], off
	s_add_u32 m0, s94, 0x6000
	s_nop 1
	global_load_lds_dwordx4 v[76:77], off
	s_add_u32 m0, s94, 0x7000
	s_nop 1
	global_load_lds_dwordx4 v[80:81], off
	s_waitcnt lgkmcnt(0)
	s_waitcnt vmcnt(0)
	s_barrier
	ds_read_b128 v[0:3], v170 offset:0
	ds_read_b128 v[4:7], v174 offset:16384
	ds_read_b128 v[88:91], v171 offset:0
	ds_read_b128 v[92:95], v175 offset:16384
	ds_read_b128 v[16:19], v174 offset:20480
	ds_read_b128 v[98:101], v175 offset:20480
	v_lshl_add_u64 v[66:67], v[66:67], 0, s[96:97]
	s_add_u32 m0, s94, 0x8000
	s_nop 1
	global_load_lds_dwordx4 v[66:67], off
	v_lshl_add_u64 v[68:69], v[68:69], 0, s[96:97]
	s_add_u32 m0, s94, 0xc000
	s_nop 1
	global_load_lds_dwordx4 v[68:69], off
	v_lshl_add_u64 v[70:71], v[70:71], 0, s[96:97]
	s_add_u32 m0, s94, 0x9000
	s_nop 1
	global_load_lds_dwordx4 v[70:71], off
	v_lshl_add_u64 v[72:73], v[72:73], 0, s[96:97]
	s_add_u32 m0, s94, 0xd000
	s_nop 1
	global_load_lds_dwordx4 v[72:73], off
	v_lshl_add_u64 v[74:75], v[74:75], 0, s[96:97]
	s_add_u32 m0, s94, 0xa000
	s_nop 1
	global_load_lds_dwordx4 v[74:75], off
	v_lshl_add_u64 v[76:77], v[76:77], 0, s[96:97]
	s_add_u32 m0, s94, 0xe000
	s_nop 1
	global_load_lds_dwordx4 v[76:77], off
	v_lshl_add_u64 v[78:79], v[78:79], 0, s[96:97]
	s_add_u32 m0, s94, 0xb000
	s_nop 1
	global_load_lds_dwordx4 v[78:79], off
	v_lshl_add_u64 v[80:81], v[80:81], 0, s[96:97]
	s_add_u32 m0, s94, 0xf000
	s_nop 1
	global_load_lds_dwordx4 v[80:81], off
	s_waitcnt lgkmcnt(4)
	v_mfma_f32_32x32x16_bf16 v[32:47], v[0:3], v[4:7], 0
	ds_read_b128 v[20:23], v170 offset:4096
	ds_read_b128 v[102:105], v171 offset:4096
	s_waitcnt lgkmcnt(3)
	v_mfma_f32_32x32x16_bf16 v[48:63], v[0:3], v[16:19], 0
	s_waitcnt lgkmcnt(1)
	v_mfma_f32_32x32x16_bf16 v[0:15], v[20:23], v[4:7], 0
	v_mfma_f32_32x32x16_bf16 v[16:31], v[20:23], v[16:19], 0
	v_mfma_f32_32x32x16_bf16 v[32:47], v[88:91], v[92:95], v[32:47]
	v_mfma_f32_32x32x16_bf16 v[48:63], v[88:91], v[98:101], v[48:63]
	s_waitcnt lgkmcnt(0)
	v_mfma_f32_32x32x16_bf16 v[0:15], v[102:105], v[92:95], v[0:15]
	v_mfma_f32_32x32x16_bf16 v[16:31], v[102:105], v[98:101], v[16:31]
	ds_read_b128 v[88:91], v172 offset:0
	ds_read_b128 v[92:95], v176 offset:16384
	ds_read_b128 v[98:101], v173 offset:0
	ds_read_b128 v[102:105], v177 offset:16384
	ds_read_b128 v[106:109], v176 offset:20480
	ds_read_b128 v[110:113], v177 offset:20480
	s_waitcnt lgkmcnt(4)
	v_mfma_f32_32x32x16_bf16 v[32:47], v[88:91], v[92:95], v[32:47]
	s_waitcnt lgkmcnt(1)
	v_mfma_f32_32x32x16_bf16 v[48:63], v[88:91], v[106:109], v[48:63]
	ds_read_b128 v[88:91], v172 offset:4096
	ds_read_b128 v[114:117], v173 offset:4096
	s_waitcnt lgkmcnt(1)
	v_mfma_f32_32x32x16_bf16 v[0:15], v[88:91], v[92:95], v[0:15]
	v_mfma_f32_32x32x16_bf16 v[16:31], v[88:91], v[106:109], v[16:31]
	v_mfma_f32_32x32x16_bf16 v[32:47], v[98:101], v[102:105], v[32:47]
	v_mfma_f32_32x32x16_bf16 v[48:63], v[98:101], v[110:113], v[48:63]
	s_waitcnt lgkmcnt(0)
	v_mfma_f32_32x32x16_bf16 v[0:15], v[114:117], v[102:105], v[0:15]
	s_waitcnt vmcnt(0)
	s_barrier
;     ...
;   bf16* As1 = As + 2 * 128 * 72;
;   bf16* Bs1 = As1 + 128 * 72;
;   G_LOAD(ra0, rb0, 0);
;   if (nk > 1) G_LOAD(ra1, rb1, 1);
;   G_STORE(ra0, rb0, As, Bs);
;   __syncthreads();
;   for (int kt = 0; kt < nk; kt += 2) {
;     if (kt + 2 < nk) G_LOAD(ra0, rb0, kt + 2);
;     if (kt + 1 < nk) G_STORE(ra1, rb1, As1, Bs1);
;     G_COMPUTE(As, Bs);
;     __syncthreads();
;     if (kt + 1 < nk) {
;       if (kt + 3 < nk) G_LOAD(ra1, rb1, kt + 3);
;       if (kt + 2 < nk) G_STORE(ra0, rb0, As, Bs);
;       G_COMPUTE(As1, Bs1);
;       __syncthreads();
;     }
;   }
	v_mfma_f32_32x32x16_bf16 v[16:31], v[114:117], v[110:113], v[16:31]
	ds_read_b128 v[88:91], v170 offset:32768
	ds_read_b128 v[92:95], v174 offset:49152
	ds_read_b128 v[98:101], v171 offset:32768
	ds_read_b128 v[102:105], v175 offset:49152
	ds_read_b128 v[106:109], v174 offset:53248
	ds_read_b128 v[110:113], v175 offset:53248
	v_lshl_add_u64 v[66:67], v[66:67], 0, s[96:97]
	s_add_u32 m0, s94, 0x0
	s_nop 1
	global_load_lds_dwordx4 v[66:67], off
	v_lshl_add_u64 v[68:69], v[68:69], 0, s[96:97]
	s_add_u32 m0, s94, 0x4000
	s_nop 1
	global_load_lds_dwordx4 v[68:69], off
	v_lshl_add_u64 v[70:71], v[70:71], 0, s[96:97]
	s_add_u32 m0, s94, 0x1000
	s_nop 1
	global_load_lds_dwordx4 v[70:71], off
	v_lshl_add_u64 v[72:73], v[72:73], 0, s[96:97]
	s_add_u32 m0, s94, 0x5000
	s_nop 1
	global_load_lds_dwordx4 v[72:73], off
	v_lshl_add_u64 v[74:75], v[74:75], 0, s[96:97]
	s_add_u32 m0, s94, 0x2000
	s_nop 1
	global_load_lds_dwordx4 v[74:75], off
	v_lshl_add_u64 v[76:77], v[76:77], 0, s[96:97]
	s_add_u32 m0, s94, 0x6000
	s_nop 1
	global_load_lds_dwordx4 v[76:77], off
	v_lshl_add_u64 v[78:79], v[78:79], 0, s[96:97]
	s_add_u32 m0, s94, 0x3000
	s_nop 1
	global_load_lds_dwordx4 v[78:79], off
	v_lshl_add_u64 v[80:81], v[80:81], 0, s[96:97]
	s_add_u32 m0, s94, 0x7000
	s_nop 1
	global_load_lds_dwordx4 v[80:81], off
	s_waitcnt lgkmcnt(4)
	v_mfma_f32_32x32x16_bf16 v[32:47], v[88:91], v[92:95], v[32:47]
	s_waitcnt lgkmcnt(1)
	v_mfma_f32_32x32x16_bf16 v[48:63], v[88:91], v[106:109], v[48:63]
	ds_read_b128 v[88:91], v170 offset:36864
	ds_read_b128 v[114:117], v171 offset:36864
	s_waitcnt lgkmcnt(1)
	v_mfma_f32_32x32x16_bf16 v[0:15], v[88:91], v[92:95], v[0:15]
	v_mfma_f32_32x32x16_bf16 v[16:31], v[88:91], v[106:109], v[16:31]
	v_mfma_f32_32x32x16_bf16 v[32:47], v[98:101], v[102:105], v[32:47]
	v_mfma_f32_32x32x16_bf16 v[48:63], v[98:101], v[110:113], v[48:63]
	s_waitcnt lgkmcnt(0)
	v_mfma_f32_32x32x16_bf16 v[0:15], v[114:117], v[102:105], v[0:15]
	ds_read_b128 v[88:91], v172 offset:32768
	ds_read_b128 v[92:95], v176 offset:49152
	ds_read_b128 v[98:101], v173 offset:32768
	ds_read_b128 v[102:105], v177 offset:49152
	v_mfma_f32_32x32x16_bf16 v[16:31], v[114:117], v[110:113], v[16:31]
	ds_read_b128 v[106:109], v176 offset:53248
	ds_read_b128 v[110:113], v177 offset:53248
	s_waitcnt lgkmcnt(4)
	v_mfma_f32_32x32x16_bf16 v[32:47], v[88:91], v[92:95], v[32:47]
	s_waitcnt lgkmcnt(1)
	v_mfma_f32_32x32x16_bf16 v[48:63], v[88:91], v[106:109], v[48:63]
	ds_read_b128 v[88:91], v172 offset:36864
	ds_read_b128 v[114:117], v173 offset:36864
	s_waitcnt lgkmcnt(1)
	v_mfma_f32_32x32x16_bf16 v[0:15], v[88:91], v[92:95], v[0:15]
	v_mfma_f32_32x32x16_bf16 v[16:31], v[88:91], v[106:109], v[16:31]
	v_mfma_f32_32x32x16_bf16 v[32:47], v[98:101], v[102:105], v[32:47]
	v_mfma_f32_32x32x16_bf16 v[48:63], v[98:101], v[110:113], v[48:63]
	s_waitcnt lgkmcnt(0)
	v_mfma_f32_32x32x16_bf16 v[0:15], v[114:117], v[102:105], v[0:15]
	s_waitcnt vmcnt(0)
	s_barrier
	v_mfma_f32_32x32x16_bf16 v[16:31], v[114:117], v[110:113], v[16:31]
	ds_read_b128 v[88:91], v170 offset:0
	ds_read_b128 v[92:95], v174 offset:16384
	ds_read_b128 v[98:101], v171 offset:0
	ds_read_b128 v[102:105], v175 offset:16384
	ds_read_b128 v[106:109], v174 offset:20480
	ds_read_b128 v[110:113], v175 offset:20480
	v_lshl_add_u64 v[66:67], v[66:67], 0, s[96:97]
	s_add_u32 m0, s94, 0x8000
	s_nop 1
	global_load_lds_dwordx4 v[66:67], off
	v_lshl_add_u64 v[68:69], v[68:69], 0, s[96:97]
	s_add_u32 m0, s94, 0xc000
	s_nop 1
	global_load_lds_dwordx4 v[68:69], off
	v_lshl_add_u64 v[70:71], v[70:71], 0, s[96:97]
	s_add_u32 m0, s94, 0x9000
	s_nop 1
	global_load_lds_dwordx4 v[70:71], off
	v_lshl_add_u64 v[72:73], v[72:73], 0, s[96:97]
	s_add_u32 m0, s94, 0xd000
	s_nop 1
	global_load_lds_dwordx4 v[72:73], off
	v_lshl_add_u64 v[74:75], v[74:75], 0, s[96:97]
	s_add_u32 m0, s94, 0xa000
	s_nop 1
	global_load_lds_dwordx4 v[74:75], off
	v_lshl_add_u64 v[76:77], v[76:77], 0, s[96:97]
	s_add_u32 m0, s94, 0xe000
	s_nop 1
	global_load_lds_dwordx4 v[76:77], off
	v_lshl_add_u64 v[78:79], v[78:79], 0, s[96:97]
	s_add_u32 m0, s94, 0xb000
	s_nop 1
	global_load_lds_dwordx4 v[78:79], off
	v_lshl_add_u64 v[80:81], v[80:81], 0, s[96:97]
	s_add_u32 m0, s94, 0xf000
	s_nop 1
	global_load_lds_dwordx4 v[80:81], off
	s_waitcnt lgkmcnt(4)
	v_mfma_f32_32x32x16_bf16 v[32:47], v[88:91], v[92:95], v[32:47]
	s_waitcnt lgkmcnt(1)
	v_mfma_f32_32x32x16_bf16 v[48:63], v[88:91], v[106:109], v[48:63]
	ds_read_b128 v[88:91], v170 offset:4096
	ds_read_b128 v[114:117], v171 offset:4096
	s_waitcnt lgkmcnt(1)
	v_mfma_f32_32x32x16_bf16 v[0:15], v[88:91], v[92:95], v[0:15]
	v_mfma_f32_32x32x16_bf16 v[16:31], v[88:91], v[106:109], v[16:31]
	v_mfma_f32_32x32x16_bf16 v[32:47], v[98:101], v[102:105], v[32:47]
	v_mfma_f32_32x32x16_bf16 v[48:63], v[98:101], v[110:113], v[48:63]
	s_waitcnt lgkmcnt(0)
	v_mfma_f32_32x32x16_bf16 v[0:15], v[114:117], v[102:105], v[0:15]
	ds_read_b128 v[88:91], v172 offset:0
	ds_read_b128 v[92:95], v176 offset:16384
	ds_read_b128 v[98:101], v173 offset:0
	ds_read_b128 v[102:105], v177 offset:16384
	v_mfma_f32_32x32x16_bf16 v[16:31], v[114:117], v[110:113], v[16:31]
	ds_read_b128 v[106:109], v176 offset:20480
	ds_read_b128 v[110:113], v177 offset:20480
	s_waitcnt lgkmcnt(4)
	v_mfma_f32_32x32x16_bf16 v[32:47], v[88:91], v[92:95], v[32:47]
	s_waitcnt lgkmcnt(1)
	v_mfma_f32_32x32x16_bf16 v[48:63], v[88:91], v[106:109], v[48:63]
	ds_read_b128 v[88:91], v172 offset:4096
	ds_read_b128 v[114:117], v173 offset:4096
	s_waitcnt lgkmcnt(1)
	v_mfma_f32_32x32x16_bf16 v[0:15], v[88:91], v[92:95], v[0:15]
	v_mfma_f32_32x32x16_bf16 v[16:31], v[88:91], v[106:109], v[16:31]
	v_mfma_f32_32x32x16_bf16 v[32:47], v[98:101], v[102:105], v[32:47]
	v_mfma_f32_32x32x16_bf16 v[48:63], v[98:101], v[110:113], v[48:63]
	s_waitcnt lgkmcnt(0)
	v_mfma_f32_32x32x16_bf16 v[0:15], v[114:117], v[102:105], v[0:15]
	s_waitcnt vmcnt(0)
	s_barrier
;     ...
;   bf16* As1 = As + 2 * 128 * 72;
;   bf16* Bs1 = As1 + 128 * 72;
;   G_LOAD(ra0, rb0, 0);
;   if (nk > 1) G_LOAD(ra1, rb1, 1);
;   G_STORE(ra0, rb0, As, Bs);
;   __syncthreads();
;   for (int kt = 0; kt < nk; kt += 2) {
;     if (kt + 2 < nk) G_LOAD(ra0, rb0, kt + 2);
;     if (kt + 1 < nk) G_STORE(ra1, rb1, As1, Bs1);
;     G_COMPUTE(As, Bs);
;     __syncthreads();
;     if (kt + 1 < nk) {
;       if (kt + 3 < nk) G_LOAD(ra1, rb1, kt + 3);
;       if (kt + 2 < nk) G_STORE(ra0, rb0, As, Bs);
;       G_COMPUTE(As1, Bs1);
;       __syncthreads();
;     }
;   }
	v_mfma_f32_32x32x16_bf16 v[16:31], v[114:117], v[110:113], v[16:31]
	ds_read_b128 v[88:91], v170 offset:32768
	ds_read_b128 v[92:95], v174 offset:49152
	ds_read_b128 v[98:101], v171 offset:32768
	ds_read_b128 v[102:105], v175 offset:49152
	ds_read_b128 v[106:109], v174 offset:53248
	ds_read_b128 v[110:113], v175 offset:53248
	v_lshl_add_u64 v[66:67], v[66:67], 0, s[96:97]
	s_add_u32 m0, s94, 0x0
	s_nop 1
	global_load_lds_dwordx4 v[66:67], off
	v_lshl_add_u64 v[68:69], v[68:69], 0, s[96:97]
	s_add_u32 m0, s94, 0x4000
	s_nop 1
	global_load_lds_dwordx4 v[68:69], off
	v_lshl_add_u64 v[70:71], v[70:71], 0, s[96:97]
	s_add_u32 m0, s94, 0x1000
	s_nop 1
	global_load_lds_dwordx4 v[70:71], off
	v_lshl_add_u64 v[72:73], v[72:73], 0, s[96:97]
	s_add_u32 m0, s94, 0x5000
	s_nop 1
	global_load_lds_dwordx4 v[72:73], off
	v_lshl_add_u64 v[74:75], v[74:75], 0, s[96:97]
	s_add_u32 m0, s94, 0x2000
	s_nop 1
	global_load_lds_dwordx4 v[74:75], off
	v_lshl_add_u64 v[76:77], v[76:77], 0, s[96:97]
	s_add_u32 m0, s94, 0x6000
	s_nop 1
	global_load_lds_dwordx4 v[76:77], off
	v_lshl_add_u64 v[78:79], v[78:79], 0, s[96:97]
	s_add_u32 m0, s94, 0x3000
	s_nop 1
	global_load_lds_dwordx4 v[78:79], off
	v_lshl_add_u64 v[80:81], v[80:81], 0, s[96:97]
	s_add_u32 m0, s94, 0x7000
	s_nop 1
	global_load_lds_dwordx4 v[80:81], off
	s_waitcnt lgkmcnt(4)
	v_mfma_f32_32x32x16_bf16 v[32:47], v[88:91], v[92:95], v[32:47]
	s_waitcnt lgkmcnt(1)
	v_mfma_f32_32x32x16_bf16 v[48:63], v[88:91], v[106:109], v[48:63]
	ds_read_b128 v[88:91], v170 offset:36864
	ds_read_b128 v[114:117], v171 offset:36864
	s_waitcnt lgkmcnt(1)
	v_mfma_f32_32x32x16_bf16 v[0:15], v[88:91], v[92:95], v[0:15]
	v_mfma_f32_32x32x16_bf16 v[16:31], v[88:91], v[106:109], v[16:31]
	v_mfma_f32_32x32x16_bf16 v[32:47], v[98:101], v[102:105], v[32:47]
	v_mfma_f32_32x32x16_bf16 v[48:63], v[98:101], v[110:113], v[48:63]
	s_waitcnt lgkmcnt(0)
	v_mfma_f32_32x32x16_bf16 v[0:15], v[114:117], v[102:105], v[0:15]
	ds_read_b128 v[88:91], v172 offset:32768
	ds_read_b128 v[92:95], v176 offset:49152
	ds_read_b128 v[98:101], v173 offset:32768
	ds_read_b128 v[102:105], v177 offset:49152
	v_mfma_f32_32x32x16_bf16 v[16:31], v[114:117], v[110:113], v[16:31]
	ds_read_b128 v[106:109], v176 offset:53248
	ds_read_b128 v[110:113], v177 offset:53248
	s_waitcnt lgkmcnt(4)
	v_mfma_f32_32x32x16_bf16 v[32:47], v[88:91], v[92:95], v[32:47]
	s_waitcnt lgkmcnt(1)
	v_mfma_f32_32x32x16_bf16 v[48:63], v[88:91], v[106:109], v[48:63]
	ds_read_b128 v[88:91], v172 offset:36864
	ds_read_b128 v[114:117], v173 offset:36864
	s_waitcnt lgkmcnt(1)
	v_mfma_f32_32x32x16_bf16 v[0:15], v[88:91], v[92:95], v[0:15]
	v_mfma_f32_32x32x16_bf16 v[16:31], v[88:91], v[106:109], v[16:31]
	v_mfma_f32_32x32x16_bf16 v[32:47], v[98:101], v[102:105], v[32:47]
	v_mfma_f32_32x32x16_bf16 v[48:63], v[98:101], v[110:113], v[48:63]
	s_waitcnt lgkmcnt(0)
	v_mfma_f32_32x32x16_bf16 v[0:15], v[114:117], v[102:105], v[0:15]
	s_waitcnt vmcnt(0)
	s_barrier
	v_mfma_f32_32x32x16_bf16 v[16:31], v[114:117], v[110:113], v[16:31]
	ds_read_b128 v[88:91], v170 offset:0
	ds_read_b128 v[92:95], v174 offset:16384
	ds_read_b128 v[98:101], v171 offset:0
	ds_read_b128 v[102:105], v175 offset:16384
	ds_read_b128 v[106:109], v174 offset:20480
	ds_read_b128 v[110:113], v175 offset:20480
	v_lshl_add_u64 v[66:67], v[66:67], 0, s[96:97]
	s_add_u32 m0, s94, 0x8000
	s_nop 1
	global_load_lds_dwordx4 v[66:67], off
	v_lshl_add_u64 v[68:69], v[68:69], 0, s[96:97]
	s_add_u32 m0, s94, 0xc000
	s_nop 1
	global_load_lds_dwordx4 v[68:69], off
	v_lshl_add_u64 v[70:71], v[70:71], 0, s[96:97]
	s_add_u32 m0, s94, 0x9000
	s_nop 1
	global_load_lds_dwordx4 v[70:71], off
	v_lshl_add_u64 v[72:73], v[72:73], 0, s[96:97]
	s_add_u32 m0, s94, 0xd000
	s_nop 1
	global_load_lds_dwordx4 v[72:73], off
	v_lshl_add_u64 v[74:75], v[74:75], 0, s[96:97]
	s_add_u32 m0, s94, 0xa000
	s_nop 1
	global_load_lds_dwordx4 v[74:75], off
	v_lshl_add_u64 v[76:77], v[76:77], 0, s[96:97]
	s_add_u32 m0, s94, 0xe000
	s_nop 1
	global_load_lds_dwordx4 v[76:77], off
	v_lshl_add_u64 v[78:79], v[78:79], 0, s[96:97]
	s_add_u32 m0, s94, 0xb000
	s_nop 1
	global_load_lds_dwordx4 v[78:79], off
	v_lshl_add_u64 v[80:81], v[80:81], 0, s[96:97]
	s_add_u32 m0, s94, 0xf000
	s_nop 1
	global_load_lds_dwordx4 v[80:81], off
	s_waitcnt lgkmcnt(4)
	v_mfma_f32_32x32x16_bf16 v[32:47], v[88:91], v[92:95], v[32:47]
	s_waitcnt lgkmcnt(1)
	v_mfma_f32_32x32x16_bf16 v[48:63], v[88:91], v[106:109], v[48:63]
	ds_read_b128 v[88:91], v170 offset:4096
	ds_read_b128 v[114:117], v171 offset:4096
	s_waitcnt lgkmcnt(1)
	v_mfma_f32_32x32x16_bf16 v[0:15], v[88:91], v[92:95], v[0:15]
	v_mfma_f32_32x32x16_bf16 v[16:31], v[88:91], v[106:109], v[16:31]
	v_mfma_f32_32x32x16_bf16 v[32:47], v[98:101], v[102:105], v[32:47]
	v_mfma_f32_32x32x16_bf16 v[48:63], v[98:101], v[110:113], v[48:63]
	s_waitcnt lgkmcnt(0)
	v_mfma_f32_32x32x16_bf16 v[0:15], v[114:117], v[102:105], v[0:15]
	ds_read_b128 v[88:91], v172 offset:0
	ds_read_b128 v[92:95], v176 offset:16384
	ds_read_b128 v[98:101], v173 offset:0
	ds_read_b128 v[102:105], v177 offset:16384
	v_mfma_f32_32x32x16_bf16 v[16:31], v[114:117], v[110:113], v[16:31]
	ds_read_b128 v[106:109], v176 offset:20480
	ds_read_b128 v[110:113], v177 offset:20480
	s_waitcnt lgkmcnt(4)
	v_mfma_f32_32x32x16_bf16 v[32:47], v[88:91], v[92:95], v[32:47]
	s_waitcnt lgkmcnt(1)
	v_mfma_f32_32x32x16_bf16 v[48:63], v[88:91], v[106:109], v[48:63]
	ds_read_b128 v[88:91], v172 offset:4096
	ds_read_b128 v[114:117], v173 offset:4096
	s_waitcnt lgkmcnt(1)
	v_mfma_f32_32x32x16_bf16 v[0:15], v[88:91], v[92:95], v[0:15]
	v_mfma_f32_32x32x16_bf16 v[16:31], v[88:91], v[106:109], v[16:31]
	v_mfma_f32_32x32x16_bf16 v[32:47], v[98:101], v[102:105], v[32:47]
	v_mfma_f32_32x32x16_bf16 v[48:63], v[98:101], v[110:113], v[48:63]
	s_waitcnt lgkmcnt(0)
	v_mfma_f32_32x32x16_bf16 v[0:15], v[114:117], v[102:105], v[0:15]
	s_waitcnt vmcnt(0)
	s_barrier
;     ...
;   bf16* As1 = As + 2 * 128 * 72;
;   bf16* Bs1 = As1 + 128 * 72;
;   G_LOAD(ra0, rb0, 0);
;   if (nk > 1) G_LOAD(ra1, rb1, 1);
;   G_STORE(ra0, rb0, As, Bs);
;   __syncthreads();
;   for (int kt = 0; kt < nk; kt += 2) {
;     if (kt + 2 < nk) G_LOAD(ra0, rb0, kt + 2);
;     if (kt + 1 < nk) G_STORE(ra1, rb1, As1, Bs1);
;     G_COMPUTE(As, Bs);
;     __syncthreads();
;     if (kt + 1 < nk) {
;       if (kt + 3 < nk) G_LOAD(ra1, rb1, kt + 3);
;       if (kt + 2 < nk) G_STORE(ra0, rb0, As, Bs);
;       G_COMPUTE(As1, Bs1);
;       __syncthreads();
;     }
;   }
	v_mfma_f32_32x32x16_bf16 v[16:31], v[114:117], v[110:113], v[16:31]
	ds_read_b128 v[88:91], v170 offset:32768
	ds_read_b128 v[92:95], v174 offset:49152
	ds_read_b128 v[98:101], v171 offset:32768
	ds_read_b128 v[102:105], v175 offset:49152
	ds_read_b128 v[106:109], v174 offset:53248
	ds_read_b128 v[110:113], v175 offset:53248
	v_lshl_add_u64 v[66:67], v[66:67], 0, s[96:97]
	s_add_u32 m0, s94, 0x0
	s_nop 1
	global_load_lds_dwordx4 v[66:67], off
	v_lshl_add_u64 v[68:69], v[68:69], 0, s[96:97]
	s_add_u32 m0, s94, 0x4000
	s_nop 1
	global_load_lds_dwordx4 v[68:69], off
	v_lshl_add_u64 v[70:71], v[70:71], 0, s[96:97]
	s_add_u32 m0, s94, 0x1000
	s_nop 1
	global_load_lds_dwordx4 v[70:71], off
	v_lshl_add_u64 v[72:73], v[72:73], 0, s[96:97]
	s_add_u32 m0, s94, 0x5000
	s_nop 1
	global_load_lds_dwordx4 v[72:73], off
	v_lshl_add_u64 v[74:75], v[74:75], 0, s[96:97]
	s_add_u32 m0, s94, 0x2000
	s_nop 1
	global_load_lds_dwordx4 v[74:75], off
	v_lshl_add_u64 v[76:77], v[76:77], 0, s[96:97]
	s_add_u32 m0, s94, 0x6000
	s_nop 1
	global_load_lds_dwordx4 v[76:77], off
	v_lshl_add_u64 v[78:79], v[78:79], 0, s[96:97]
	s_add_u32 m0, s94, 0x3000
	s_nop 1
	global_load_lds_dwordx4 v[78:79], off
	v_lshl_add_u64 v[80:81], v[80:81], 0, s[96:97]
	s_add_u32 m0, s94, 0x7000
	s_nop 1
	global_load_lds_dwordx4 v[80:81], off
	s_waitcnt lgkmcnt(4)
	v_mfma_f32_32x32x16_bf16 v[32:47], v[88:91], v[92:95], v[32:47]
	s_waitcnt lgkmcnt(1)
	v_mfma_f32_32x32x16_bf16 v[48:63], v[88:91], v[106:109], v[48:63]
	ds_read_b128 v[88:91], v170 offset:36864
	ds_read_b128 v[114:117], v171 offset:36864
	s_waitcnt lgkmcnt(1)
	v_mfma_f32_32x32x16_bf16 v[0:15], v[88:91], v[92:95], v[0:15]
	v_mfma_f32_32x32x16_bf16 v[16:31], v[88:91], v[106:109], v[16:31]
	v_mfma_f32_32x32x16_bf16 v[32:47], v[98:101], v[102:105], v[32:47]
	v_mfma_f32_32x32x16_bf16 v[48:63], v[98:101], v[110:113], v[48:63]
	s_waitcnt lgkmcnt(0)
	v_mfma_f32_32x32x16_bf16 v[0:15], v[114:117], v[102:105], v[0:15]
	ds_read_b128 v[88:91], v172 offset:32768
	ds_read_b128 v[92:95], v176 offset:49152
	ds_read_b128 v[98:101], v173 offset:32768
	ds_read_b128 v[102:105], v177 offset:49152
	v_mfma_f32_32x32x16_bf16 v[16:31], v[114:117], v[110:113], v[16:31]
	ds_read_b128 v[106:109], v176 offset:53248
	ds_read_b128 v[110:113], v177 offset:53248
	s_waitcnt lgkmcnt(4)
	v_mfma_f32_32x32x16_bf16 v[32:47], v[88:91], v[92:95], v[32:47]
	s_waitcnt lgkmcnt(1)
	v_mfma_f32_32x32x16_bf16 v[48:63], v[88:91], v[106:109], v[48:63]
	ds_read_b128 v[88:91], v172 offset:36864
	ds_read_b128 v[114:117], v173 offset:36864
	s_waitcnt lgkmcnt(1)
	v_mfma_f32_32x32x16_bf16 v[0:15], v[88:91], v[92:95], v[0:15]
	v_mfma_f32_32x32x16_bf16 v[16:31], v[88:91], v[106:109], v[16:31]
	v_mfma_f32_32x32x16_bf16 v[32:47], v[98:101], v[102:105], v[32:47]
	v_mfma_f32_32x32x16_bf16 v[48:63], v[98:101], v[110:113], v[48:63]
	s_waitcnt lgkmcnt(0)
	v_mfma_f32_32x32x16_bf16 v[0:15], v[114:117], v[102:105], v[0:15]
	s_waitcnt vmcnt(0)
	s_barrier
	v_mfma_f32_32x32x16_bf16 v[16:31], v[114:117], v[110:113], v[16:31]
	ds_read_b128 v[88:91], v170 offset:0
	ds_read_b128 v[92:95], v174 offset:16384
	ds_read_b128 v[98:101], v171 offset:0
	ds_read_b128 v[102:105], v175 offset:16384
	ds_read_b128 v[106:109], v174 offset:20480
	ds_read_b128 v[110:113], v175 offset:20480
	v_lshl_add_u64 v[66:67], v[66:67], 0, s[96:97]
	s_add_u32 m0, s94, 0x8000
	s_nop 1
	global_load_lds_dwordx4 v[66:67], off
	v_lshl_add_u64 v[68:69], v[68:69], 0, s[96:97]
	s_add_u32 m0, s94, 0xc000
	s_nop 1
	global_load_lds_dwordx4 v[68:69], off
	v_lshl_add_u64 v[70:71], v[70:71], 0, s[96:97]
	s_add_u32 m0, s94, 0x9000
	s_nop 1
	global_load_lds_dwordx4 v[70:71], off
	v_lshl_add_u64 v[72:73], v[72:73], 0, s[96:97]
	s_add_u32 m0, s94, 0xd000
	s_nop 1
	global_load_lds_dwordx4 v[72:73], off
	v_lshl_add_u64 v[74:75], v[74:75], 0, s[96:97]
	s_add_u32 m0, s94, 0xa000
	s_nop 1
	global_load_lds_dwordx4 v[74:75], off
	v_lshl_add_u64 v[76:77], v[76:77], 0, s[96:97]
	s_add_u32 m0, s94, 0xe000
	s_nop 1
	global_load_lds_dwordx4 v[76:77], off
	v_lshl_add_u64 v[78:79], v[78:79], 0, s[96:97]
	s_add_u32 m0, s94, 0xb000
	s_nop 1
	global_load_lds_dwordx4 v[78:79], off
	v_lshl_add_u64 v[80:81], v[80:81], 0, s[96:97]
	s_add_u32 m0, s94, 0xf000
	s_nop 1
	global_load_lds_dwordx4 v[80:81], off
	s_waitcnt lgkmcnt(4)
	v_mfma_f32_32x32x16_bf16 v[32:47], v[88:91], v[92:95], v[32:47]
	s_waitcnt lgkmcnt(1)
	v_mfma_f32_32x32x16_bf16 v[48:63], v[88:91], v[106:109], v[48:63]
	ds_read_b128 v[88:91], v170 offset:4096
	ds_read_b128 v[114:117], v171 offset:4096
	s_waitcnt lgkmcnt(1)
	v_mfma_f32_32x32x16_bf16 v[0:15], v[88:91], v[92:95], v[0:15]
	v_mfma_f32_32x32x16_bf16 v[16:31], v[88:91], v[106:109], v[16:31]
	v_mfma_f32_32x32x16_bf16 v[32:47], v[98:101], v[102:105], v[32:47]
	v_mfma_f32_32x32x16_bf16 v[48:63], v[98:101], v[110:113], v[48:63]
	s_waitcnt lgkmcnt(0)
	v_mfma_f32_32x32x16_bf16 v[0:15], v[114:117], v[102:105], v[0:15]
	ds_read_b128 v[88:91], v172 offset:0
	ds_read_b128 v[92:95], v176 offset:16384
	ds_read_b128 v[98:101], v173 offset:0
	ds_read_b128 v[102:105], v177 offset:16384
	v_mfma_f32_32x32x16_bf16 v[16:31], v[114:117], v[110:113], v[16:31]
	ds_read_b128 v[106:109], v176 offset:20480
	ds_read_b128 v[110:113], v177 offset:20480
	s_waitcnt lgkmcnt(4)
	v_mfma_f32_32x32x16_bf16 v[32:47], v[88:91], v[92:95], v[32:47]
	s_waitcnt lgkmcnt(1)
	v_mfma_f32_32x32x16_bf16 v[48:63], v[88:91], v[106:109], v[48:63]
	ds_read_b128 v[88:91], v172 offset:4096
	ds_read_b128 v[114:117], v173 offset:4096
	s_waitcnt lgkmcnt(1)
	v_mfma_f32_32x32x16_bf16 v[0:15], v[88:91], v[92:95], v[0:15]
	v_mfma_f32_32x32x16_bf16 v[16:31], v[88:91], v[106:109], v[16:31]
	v_mfma_f32_32x32x16_bf16 v[32:47], v[98:101], v[102:105], v[32:47]
	v_mfma_f32_32x32x16_bf16 v[48:63], v[98:101], v[110:113], v[48:63]
	s_waitcnt lgkmcnt(0)
	v_mfma_f32_32x32x16_bf16 v[0:15], v[114:117], v[102:105], v[0:15]
	s_waitcnt vmcnt(0)
	s_barrier
;     ...
;   bf16* As1 = As + 2 * 128 * 72;
;   bf16* Bs1 = As1 + 128 * 72;
;   G_LOAD(ra0, rb0, 0);
;   if (nk > 1) G_LOAD(ra1, rb1, 1);
;   G_STORE(ra0, rb0, As, Bs);
;   __syncthreads();
;   for (int kt = 0; kt < nk; kt += 2) {
;     if (kt + 2 < nk) G_LOAD(ra0, rb0, kt + 2);
;     if (kt + 1 < nk) G_STORE(ra1, rb1, As1, Bs1);
;     G_COMPUTE(As, Bs);
;     __syncthreads();
;     if (kt + 1 < nk) {
;       if (kt + 3 < nk) G_LOAD(ra1, rb1, kt + 3);
;       if (kt + 2 < nk) G_STORE(ra0, rb0, As, Bs);
;       G_COMPUTE(As1, Bs1);
;       __syncthreads();
;     }
;   }
	v_mfma_f32_32x32x16_bf16 v[16:31], v[114:117], v[110:113], v[16:31]
	ds_read_b128 v[88:91], v170 offset:32768
	ds_read_b128 v[92:95], v174 offset:49152
	ds_read_b128 v[98:101], v171 offset:32768
	ds_read_b128 v[102:105], v175 offset:49152
	ds_read_b128 v[106:109], v174 offset:53248
	ds_read_b128 v[110:113], v175 offset:53248
	v_lshl_add_u64 v[66:67], v[66:67], 0, s[96:97]
	s_add_u32 m0, s94, 0x0
	s_nop 1
	global_load_lds_dwordx4 v[66:67], off
	v_lshl_add_u64 v[68:69], v[68:69], 0, s[96:97]
	s_add_u32 m0, s94, 0x4000
	s_nop 1
	global_load_lds_dwordx4 v[68:69], off
	v_lshl_add_u64 v[70:71], v[70:71], 0, s[96:97]
	s_add_u32 m0, s94, 0x1000
	s_nop 1
	global_load_lds_dwordx4 v[70:71], off
	v_lshl_add_u64 v[72:73], v[72:73], 0, s[96:97]
	s_add_u32 m0, s94, 0x5000
	s_nop 1
	global_load_lds_dwordx4 v[72:73], off
	v_lshl_add_u64 v[74:75], v[74:75], 0, s[96:97]
	s_add_u32 m0, s94, 0x2000
	s_nop 1
	global_load_lds_dwordx4 v[74:75], off
	v_lshl_add_u64 v[76:77], v[76:77], 0, s[96:97]
	s_add_u32 m0, s94, 0x6000
	s_nop 1
	global_load_lds_dwordx4 v[76:77], off
	v_lshl_add_u64 v[78:79], v[78:79], 0, s[96:97]
	s_add_u32 m0, s94, 0x3000
	s_nop 1
	global_load_lds_dwordx4 v[78:79], off
	v_lshl_add_u64 v[80:81], v[80:81], 0, s[96:97]
	s_add_u32 m0, s94, 0x7000
	s_nop 1
	global_load_lds_dwordx4 v[80:81], off
	s_waitcnt lgkmcnt(4)
	v_mfma_f32_32x32x16_bf16 v[32:47], v[88:91], v[92:95], v[32:47]
	s_waitcnt lgkmcnt(1)
	v_mfma_f32_32x32x16_bf16 v[48:63], v[88:91], v[106:109], v[48:63]
	ds_read_b128 v[88:91], v170 offset:36864
	ds_read_b128 v[114:117], v171 offset:36864
	s_waitcnt lgkmcnt(1)
	v_mfma_f32_32x32x16_bf16 v[0:15], v[88:91], v[92:95], v[0:15]
	v_mfma_f32_32x32x16_bf16 v[16:31], v[88:91], v[106:109], v[16:31]
	v_mfma_f32_32x32x16_bf16 v[32:47], v[98:101], v[102:105], v[32:47]
	v_mfma_f32_32x32x16_bf16 v[48:63], v[98:101], v[110:113], v[48:63]
	s_waitcnt lgkmcnt(0)
	v_mfma_f32_32x32x16_bf16 v[0:15], v[114:117], v[102:105], v[0:15]
	ds_read_b128 v[88:91], v172 offset:32768
	ds_read_b128 v[92:95], v176 offset:49152
	ds_read_b128 v[98:101], v173 offset:32768
	ds_read_b128 v[102:105], v177 offset:49152
	v_mfma_f32_32x32x16_bf16 v[16:31], v[114:117], v[110:113], v[16:31]
	ds_read_b128 v[106:109], v176 offset:53248
	ds_read_b128 v[110:113], v177 offset:53248
	s_waitcnt lgkmcnt(4)
	v_mfma_f32_32x32x16_bf16 v[32:47], v[88:91], v[92:95], v[32:47]
	s_waitcnt lgkmcnt(1)
	v_mfma_f32_32x32x16_bf16 v[48:63], v[88:91], v[106:109], v[48:63]
	ds_read_b128 v[88:91], v172 offset:36864
	ds_read_b128 v[114:117], v173 offset:36864
	s_waitcnt lgkmcnt(1)
	v_mfma_f32_32x32x16_bf16 v[0:15], v[88:91], v[92:95], v[0:15]
	v_mfma_f32_32x32x16_bf16 v[16:31], v[88:91], v[106:109], v[16:31]
	v_mfma_f32_32x32x16_bf16 v[32:47], v[98:101], v[102:105], v[32:47]
	v_mfma_f32_32x32x16_bf16 v[48:63], v[98:101], v[110:113], v[48:63]
	s_waitcnt lgkmcnt(0)
	v_mfma_f32_32x32x16_bf16 v[0:15], v[114:117], v[102:105], v[0:15]
	s_waitcnt vmcnt(0)
	s_barrier
	v_mfma_f32_32x32x16_bf16 v[16:31], v[114:117], v[110:113], v[16:31]
	ds_read_b128 v[88:91], v170 offset:0
	ds_read_b128 v[92:95], v174 offset:16384
	ds_read_b128 v[98:101], v171 offset:0
	ds_read_b128 v[102:105], v175 offset:16384
	ds_read_b128 v[106:109], v174 offset:20480
	ds_read_b128 v[110:113], v175 offset:20480
	v_lshl_add_u64 v[66:67], v[66:67], 0, s[96:97]
	s_add_u32 m0, s94, 0x8000
	s_nop 1
	global_load_lds_dwordx4 v[66:67], off
	v_lshl_add_u64 v[68:69], v[68:69], 0, s[96:97]
	s_add_u32 m0, s94, 0xc000
	s_nop 1
	global_load_lds_dwordx4 v[68:69], off
	v_lshl_add_u64 v[70:71], v[70:71], 0, s[96:97]
	s_add_u32 m0, s94, 0x9000
	s_nop 1
	global_load_lds_dwordx4 v[70:71], off
	v_lshl_add_u64 v[72:73], v[72:73], 0, s[96:97]
	s_add_u32 m0, s94, 0xd000
	s_nop 1
	global_load_lds_dwordx4 v[72:73], off
	v_lshl_add_u64 v[74:75], v[74:75], 0, s[96:97]
	s_add_u32 m0, s94, 0xa000
	s_nop 1
	global_load_lds_dwordx4 v[74:75], off
	v_lshl_add_u64 v[76:77], v[76:77], 0, s[96:97]
	s_add_u32 m0, s94, 0xe000
	s_nop 1
	global_load_lds_dwordx4 v[76:77], off
	v_lshl_add_u64 v[78:79], v[78:79], 0, s[96:97]
	s_add_u32 m0, s94, 0xb000
	s_nop 1
	global_load_lds_dwordx4 v[78:79], off
	v_lshl_add_u64 v[80:81], v[80:81], 0, s[96:97]
	s_add_u32 m0, s94, 0xf000
	s_nop 1
	global_load_lds_dwordx4 v[80:81], off
	s_waitcnt lgkmcnt(4)
	v_mfma_f32_32x32x16_bf16 v[32:47], v[88:91], v[92:95], v[32:47]
	s_waitcnt lgkmcnt(1)
	v_mfma_f32_32x32x16_bf16 v[48:63], v[88:91], v[106:109], v[48:63]
	ds_read_b128 v[88:91], v170 offset:4096
	ds_read_b128 v[114:117], v171 offset:4096
	s_waitcnt lgkmcnt(1)
	v_mfma_f32_32x32x16_bf16 v[0:15], v[88:91], v[92:95], v[0:15]
	v_mfma_f32_32x32x16_bf16 v[16:31], v[88:91], v[106:109], v[16:31]
	v_mfma_f32_32x32x16_bf16 v[32:47], v[98:101], v[102:105], v[32:47]
	v_mfma_f32_32x32x16_bf16 v[48:63], v[98:101], v[110:113], v[48:63]
	s_waitcnt lgkmcnt(0)
	v_mfma_f32_32x32x16_bf16 v[0:15], v[114:117], v[102:105], v[0:15]
	ds_read_b128 v[88:91], v172 offset:0
	ds_read_b128 v[92:95], v176 offset:16384
	ds_read_b128 v[98:101], v173 offset:0
	ds_read_b128 v[102:105], v177 offset:16384
	v_mfma_f32_32x32x16_bf16 v[16:31], v[114:117], v[110:113], v[16:31]
	ds_read_b128 v[106:109], v176 offset:20480
	ds_read_b128 v[110:113], v177 offset:20480
	s_waitcnt lgkmcnt(4)
	v_mfma_f32_32x32x16_bf16 v[32:47], v[88:91], v[92:95], v[32:47]
	s_waitcnt lgkmcnt(1)
	v_mfma_f32_32x32x16_bf16 v[48:63], v[88:91], v[106:109], v[48:63]
	ds_read_b128 v[88:91], v172 offset:4096
	ds_read_b128 v[114:117], v173 offset:4096
	s_waitcnt lgkmcnt(1)
	v_mfma_f32_32x32x16_bf16 v[0:15], v[88:91], v[92:95], v[0:15]
	v_mfma_f32_32x32x16_bf16 v[16:31], v[88:91], v[106:109], v[16:31]
	v_mfma_f32_32x32x16_bf16 v[32:47], v[98:101], v[102:105], v[32:47]
	v_mfma_f32_32x32x16_bf16 v[48:63], v[98:101], v[110:113], v[48:63]
	s_waitcnt lgkmcnt(0)
	v_mfma_f32_32x32x16_bf16 v[0:15], v[114:117], v[102:105], v[0:15]
	s_waitcnt vmcnt(0)
	s_barrier
;     ...
;   bf16* As1 = As + 2 * 128 * 72;
;   bf16* Bs1 = As1 + 128 * 72;
;   G_LOAD(ra0, rb0, 0);
;   if (nk > 1) G_LOAD(ra1, rb1, 1);
;   G_STORE(ra0, rb0, As, Bs);
;   __syncthreads();
;   for (int kt = 0; kt < nk; kt += 2) {
;     if (kt + 2 < nk) G_LOAD(ra0, rb0, kt + 2);
;     if (kt + 1 < nk) G_STORE(ra1, rb1, As1, Bs1);
;     G_COMPUTE(As, Bs);
;     __syncthreads();
;     if (kt + 1 < nk) {
;       if (kt + 3 < nk) G_LOAD(ra1, rb1, kt + 3);
;       if (kt + 2 < nk) G_STORE(ra0, rb0, As, Bs);
;       G_COMPUTE(As1, Bs1);
;       __syncthreads();
;     }
;   }
	v_mfma_f32_32x32x16_bf16 v[16:31], v[114:117], v[110:113], v[16:31]
	ds_read_b128 v[88:91], v170 offset:32768
	ds_read_b128 v[92:95], v174 offset:49152
	ds_read_b128 v[98:101], v171 offset:32768
	ds_read_b128 v[102:105], v175 offset:49152
	ds_read_b128 v[106:109], v174 offset:53248
	ds_read_b128 v[110:113], v175 offset:53248
	v_lshl_add_u64 v[66:67], v[66:67], 0, s[96:97]
	s_add_u32 m0, s94, 0x0
	s_nop 1
	global_load_lds_dwordx4 v[66:67], off
	v_lshl_add_u64 v[68:69], v[68:69], 0, s[96:97]
	s_add_u32 m0, s94, 0x4000
	s_nop 1
	global_load_lds_dwordx4 v[68:69], off
	v_lshl_add_u64 v[70:71], v[70:71], 0, s[96:97]
	s_add_u32 m0, s94, 0x1000
	s_nop 1
	global_load_lds_dwordx4 v[70:71], off
	v_lshl_add_u64 v[72:73], v[72:73], 0, s[96:97]
	s_add_u32 m0, s94, 0x5000
	s_nop 1
	global_load_lds_dwordx4 v[72:73], off
	v_lshl_add_u64 v[74:75], v[74:75], 0, s[96:97]
	s_add_u32 m0, s94, 0x2000
	s_nop 1
	global_load_lds_dwordx4 v[74:75], off
	v_lshl_add_u64 v[76:77], v[76:77], 0, s[96:97]
	s_add_u32 m0, s94, 0x6000
	s_nop 1
	global_load_lds_dwordx4 v[76:77], off
	v_lshl_add_u64 v[78:79], v[78:79], 0, s[96:97]
	s_add_u32 m0, s94, 0x3000
	s_nop 1
	global_load_lds_dwordx4 v[78:79], off
	v_lshl_add_u64 v[80:81], v[80:81], 0, s[96:97]
	s_add_u32 m0, s94, 0x7000
	s_nop 1
	global_load_lds_dwordx4 v[80:81], off
	s_waitcnt lgkmcnt(4)
	v_mfma_f32_32x32x16_bf16 v[32:47], v[88:91], v[92:95], v[32:47]
	s_waitcnt lgkmcnt(1)
	v_mfma_f32_32x32x16_bf16 v[48:63], v[88:91], v[106:109], v[48:63]
	ds_read_b128 v[88:91], v170 offset:36864
	ds_read_b128 v[114:117], v171 offset:36864
	s_waitcnt lgkmcnt(1)
	v_mfma_f32_32x32x16_bf16 v[0:15], v[88:91], v[92:95], v[0:15]
	v_mfma_f32_32x32x16_bf16 v[16:31], v[88:91], v[106:109], v[16:31]
	v_mfma_f32_32x32x16_bf16 v[32:47], v[98:101], v[102:105], v[32:47]
	v_mfma_f32_32x32x16_bf16 v[48:63], v[98:101], v[110:113], v[48:63]
	s_waitcnt lgkmcnt(0)
	v_mfma_f32_32x32x16_bf16 v[0:15], v[114:117], v[102:105], v[0:15]
	ds_read_b128 v[88:91], v172 offset:32768
	ds_read_b128 v[92:95], v176 offset:49152
	ds_read_b128 v[98:101], v173 offset:32768
	ds_read_b128 v[102:105], v177 offset:49152
	v_mfma_f32_32x32x16_bf16 v[16:31], v[114:117], v[110:113], v[16:31]
	ds_read_b128 v[106:109], v176 offset:53248
	ds_read_b128 v[110:113], v177 offset:53248
	s_waitcnt lgkmcnt(4)
	v_mfma_f32_32x32x16_bf16 v[32:47], v[88:91], v[92:95], v[32:47]
	s_waitcnt lgkmcnt(1)
	v_mfma_f32_32x32x16_bf16 v[48:63], v[88:91], v[106:109], v[48:63]
	ds_read_b128 v[88:91], v172 offset:36864
	ds_read_b128 v[114:117], v173 offset:36864
	s_waitcnt lgkmcnt(1)
	v_mfma_f32_32x32x16_bf16 v[0:15], v[88:91], v[92:95], v[0:15]
	v_mfma_f32_32x32x16_bf16 v[16:31], v[88:91], v[106:109], v[16:31]
	v_mfma_f32_32x32x16_bf16 v[32:47], v[98:101], v[102:105], v[32:47]
	v_mfma_f32_32x32x16_bf16 v[48:63], v[98:101], v[110:113], v[48:63]
	s_waitcnt lgkmcnt(0)
	v_mfma_f32_32x32x16_bf16 v[0:15], v[114:117], v[102:105], v[0:15]
	s_waitcnt vmcnt(0)
	s_barrier
	v_mfma_f32_32x32x16_bf16 v[16:31], v[114:117], v[110:113], v[16:31]
	ds_read_b128 v[88:91], v170 offset:0
	ds_read_b128 v[92:95], v174 offset:16384
	ds_read_b128 v[98:101], v171 offset:0
	ds_read_b128 v[102:105], v175 offset:16384
	ds_read_b128 v[106:109], v174 offset:20480
	ds_read_b128 v[110:113], v175 offset:20480
	v_lshl_add_u64 v[66:67], v[66:67], 0, s[96:97]
	s_add_u32 m0, s94, 0x8000
	s_nop 1
	global_load_lds_dwordx4 v[66:67], off
	v_lshl_add_u64 v[68:69], v[68:69], 0, s[96:97]
	s_add_u32 m0, s94, 0xc000
	s_nop 1
	global_load_lds_dwordx4 v[68:69], off
	v_lshl_add_u64 v[70:71], v[70:71], 0, s[96:97]
	s_add_u32 m0, s94, 0x9000
	s_nop 1
	global_load_lds_dwordx4 v[70:71], off
	v_lshl_add_u64 v[72:73], v[72:73], 0, s[96:97]
	s_add_u32 m0, s94, 0xd000
	s_nop 1
	global_load_lds_dwordx4 v[72:73], off
	v_lshl_add_u64 v[74:75], v[74:75], 0, s[96:97]
	s_add_u32 m0, s94, 0xa000
	s_nop 1
	global_load_lds_dwordx4 v[74:75], off
	v_lshl_add_u64 v[76:77], v[76:77], 0, s[96:97]
	s_add_u32 m0, s94, 0xe000
	s_nop 1
	global_load_lds_dwordx4 v[76:77], off
	v_lshl_add_u64 v[78:79], v[78:79], 0, s[96:97]
	s_add_u32 m0, s94, 0xb000
	s_nop 1
	global_load_lds_dwordx4 v[78:79], off
	v_lshl_add_u64 v[80:81], v[80:81], 0, s[96:97]
	s_add_u32 m0, s94, 0xf000
	s_nop 1
	global_load_lds_dwordx4 v[80:81], off
	s_waitcnt lgkmcnt(4)
	v_mfma_f32_32x32x16_bf16 v[32:47], v[88:91], v[92:95], v[32:47]
	s_waitcnt lgkmcnt(1)
	v_mfma_f32_32x32x16_bf16 v[48:63], v[88:91], v[106:109], v[48:63]
	ds_read_b128 v[88:91], v170 offset:4096
	ds_read_b128 v[114:117], v171 offset:4096
	s_waitcnt lgkmcnt(1)
	v_mfma_f32_32x32x16_bf16 v[0:15], v[88:91], v[92:95], v[0:15]
	v_mfma_f32_32x32x16_bf16 v[16:31], v[88:91], v[106:109], v[16:31]
	v_mfma_f32_32x32x16_bf16 v[32:47], v[98:101], v[102:105], v[32:47]
	v_mfma_f32_32x32x16_bf16 v[48:63], v[98:101], v[110:113], v[48:63]
	s_waitcnt lgkmcnt(0)
	v_mfma_f32_32x32x16_bf16 v[0:15], v[114:117], v[102:105], v[0:15]
	ds_read_b128 v[88:91], v172 offset:0
	ds_read_b128 v[92:95], v176 offset:16384
	ds_read_b128 v[98:101], v173 offset:0
	ds_read_b128 v[102:105], v177 offset:16384
	v_mfma_f32_32x32x16_bf16 v[16:31], v[114:117], v[110:113], v[16:31]
	ds_read_b128 v[106:109], v176 offset:20480
	ds_read_b128 v[110:113], v177 offset:20480
	s_waitcnt lgkmcnt(4)
	v_mfma_f32_32x32x16_bf16 v[32:47], v[88:91], v[92:95], v[32:47]
	s_waitcnt lgkmcnt(1)
	v_mfma_f32_32x32x16_bf16 v[48:63], v[88:91], v[106:109], v[48:63]
	ds_read_b128 v[88:91], v172 offset:4096
	ds_read_b128 v[114:117], v173 offset:4096
	s_waitcnt lgkmcnt(1)
	v_mfma_f32_32x32x16_bf16 v[0:15], v[88:91], v[92:95], v[0:15]
	v_mfma_f32_32x32x16_bf16 v[16:31], v[88:91], v[106:109], v[16:31]
	v_mfma_f32_32x32x16_bf16 v[32:47], v[98:101], v[102:105], v[32:47]
	v_mfma_f32_32x32x16_bf16 v[48:63], v[98:101], v[110:113], v[48:63]
	s_waitcnt lgkmcnt(0)
	v_mfma_f32_32x32x16_bf16 v[0:15], v[114:117], v[102:105], v[0:15]
	s_waitcnt vmcnt(0)
	s_barrier
;     ...
;   bf16* As1 = As + 2 * 128 * 72;
;   bf16* Bs1 = As1 + 128 * 72;
;   G_LOAD(ra0, rb0, 0);
;   if (nk > 1) G_LOAD(ra1, rb1, 1);
;   G_STORE(ra0, rb0, As, Bs);
;   __syncthreads();
;   for (int kt = 0; kt < nk; kt += 2) {
;     if (kt + 2 < nk) G_LOAD(ra0, rb0, kt + 2);
;     if (kt + 1 < nk) G_STORE(ra1, rb1, As1, Bs1);
;     G_COMPUTE(As, Bs);
;     __syncthreads();
;     if (kt + 1 < nk) {
;       if (kt + 3 < nk) G_LOAD(ra1, rb1, kt + 3);
;       if (kt + 2 < nk) G_STORE(ra0, rb0, As, Bs);
;       G_COMPUTE(As1, Bs1);
;       __syncthreads();
;     }
;   }
	v_mfma_f32_32x32x16_bf16 v[16:31], v[114:117], v[110:113], v[16:31]
	ds_read_b128 v[88:91], v170 offset:32768
	ds_read_b128 v[92:95], v174 offset:49152
	ds_read_b128 v[98:101], v171 offset:32768
	ds_read_b128 v[102:105], v175 offset:49152
	ds_read_b128 v[106:109], v174 offset:53248
	ds_read_b128 v[110:113], v175 offset:53248
	v_lshl_add_u64 v[66:67], v[66:67], 0, s[96:97]
	s_add_u32 m0, s94, 0x0
	s_nop 1
	global_load_lds_dwordx4 v[66:67], off
	v_lshl_add_u64 v[68:69], v[68:69], 0, s[96:97]
	s_add_u32 m0, s94, 0x4000
	s_nop 1
	global_load_lds_dwordx4 v[68:69], off
	v_lshl_add_u64 v[70:71], v[70:71], 0, s[96:97]
	s_add_u32 m0, s94, 0x1000
	s_nop 1
	global_load_lds_dwordx4 v[70:71], off
	v_lshl_add_u64 v[72:73], v[72:73], 0, s[96:97]
	s_add_u32 m0, s94, 0x5000
	s_nop 1
	global_load_lds_dwordx4 v[72:73], off
	v_lshl_add_u64 v[74:75], v[74:75], 0, s[96:97]
	s_add_u32 m0, s94, 0x2000
	s_nop 1
	global_load_lds_dwordx4 v[74:75], off
	v_lshl_add_u64 v[76:77], v[76:77], 0, s[96:97]
	s_add_u32 m0, s94, 0x6000
	s_nop 1
	global_load_lds_dwordx4 v[76:77], off
	v_lshl_add_u64 v[78:79], v[78:79], 0, s[96:97]
	s_add_u32 m0, s94, 0x3000
	s_nop 1
	global_load_lds_dwordx4 v[78:79], off
	v_lshl_add_u64 v[80:81], v[80:81], 0, s[96:97]
	s_add_u32 m0, s94, 0x7000
	s_nop 1
	global_load_lds_dwordx4 v[80:81], off
	s_waitcnt lgkmcnt(4)
	v_mfma_f32_32x32x16_bf16 v[32:47], v[88:91], v[92:95], v[32:47]
	s_waitcnt lgkmcnt(1)
	v_mfma_f32_32x32x16_bf16 v[48:63], v[88:91], v[106:109], v[48:63]
	ds_read_b128 v[88:91], v170 offset:36864
	ds_read_b128 v[114:117], v171 offset:36864
	s_waitcnt lgkmcnt(1)
	v_mfma_f32_32x32x16_bf16 v[0:15], v[88:91], v[92:95], v[0:15]
	v_mfma_f32_32x32x16_bf16 v[16:31], v[88:91], v[106:109], v[16:31]
	v_mfma_f32_32x32x16_bf16 v[32:47], v[98:101], v[102:105], v[32:47]
	v_mfma_f32_32x32x16_bf16 v[48:63], v[98:101], v[110:113], v[48:63]
	s_waitcnt lgkmcnt(0)
	v_mfma_f32_32x32x16_bf16 v[0:15], v[114:117], v[102:105], v[0:15]
	ds_read_b128 v[88:91], v172 offset:32768
	ds_read_b128 v[92:95], v176 offset:49152
	ds_read_b128 v[98:101], v173 offset:32768
	ds_read_b128 v[102:105], v177 offset:49152
	v_mfma_f32_32x32x16_bf16 v[16:31], v[114:117], v[110:113], v[16:31]
	ds_read_b128 v[106:109], v176 offset:53248
	ds_read_b128 v[110:113], v177 offset:53248
	s_waitcnt lgkmcnt(4)
	v_mfma_f32_32x32x16_bf16 v[32:47], v[88:91], v[92:95], v[32:47]
	s_waitcnt lgkmcnt(1)
	v_mfma_f32_32x32x16_bf16 v[48:63], v[88:91], v[106:109], v[48:63]
	ds_read_b128 v[88:91], v172 offset:36864
	ds_read_b128 v[114:117], v173 offset:36864
	s_waitcnt lgkmcnt(1)
	v_mfma_f32_32x32x16_bf16 v[0:15], v[88:91], v[92:95], v[0:15]
	v_mfma_f32_32x32x16_bf16 v[16:31], v[88:91], v[106:109], v[16:31]
	v_mfma_f32_32x32x16_bf16 v[32:47], v[98:101], v[102:105], v[32:47]
	v_mfma_f32_32x32x16_bf16 v[48:63], v[98:101], v[110:113], v[48:63]
	s_waitcnt lgkmcnt(0)
	v_mfma_f32_32x32x16_bf16 v[0:15], v[114:117], v[102:105], v[0:15]
	s_waitcnt vmcnt(0)
	s_barrier
	v_mfma_f32_32x32x16_bf16 v[16:31], v[114:117], v[110:113], v[16:31]
	ds_read_b128 v[88:91], v170 offset:0
	ds_read_b128 v[92:95], v174 offset:16384
	ds_read_b128 v[98:101], v171 offset:0
	ds_read_b128 v[102:105], v175 offset:16384
	ds_read_b128 v[106:109], v174 offset:20480
	ds_read_b128 v[110:113], v175 offset:20480
	v_lshl_add_u64 v[66:67], v[66:67], 0, s[96:97]
	s_add_u32 m0, s94, 0x8000
	s_nop 1
	global_load_lds_dwordx4 v[66:67], off
	v_lshl_add_u64 v[68:69], v[68:69], 0, s[96:97]
	s_add_u32 m0, s94, 0xc000
	s_nop 1
	global_load_lds_dwordx4 v[68:69], off
	v_lshl_add_u64 v[70:71], v[70:71], 0, s[96:97]
	s_add_u32 m0, s94, 0x9000
	s_nop 1
	global_load_lds_dwordx4 v[70:71], off
	v_lshl_add_u64 v[72:73], v[72:73], 0, s[96:97]
	s_add_u32 m0, s94, 0xd000
	s_nop 1
	global_load_lds_dwordx4 v[72:73], off
	v_lshl_add_u64 v[74:75], v[74:75], 0, s[96:97]
	s_add_u32 m0, s94, 0xa000
	s_nop 1
	global_load_lds_dwordx4 v[74:75], off
	v_lshl_add_u64 v[76:77], v[76:77], 0, s[96:97]
	s_add_u32 m0, s94, 0xe000
	s_nop 1
	global_load_lds_dwordx4 v[76:77], off
	v_lshl_add_u64 v[78:79], v[78:79], 0, s[96:97]
	s_add_u32 m0, s94, 0xb000
	s_nop 1
	global_load_lds_dwordx4 v[78:79], off
	v_lshl_add_u64 v[80:81], v[80:81], 0, s[96:97]
	s_add_u32 m0, s94, 0xf000
	s_nop 1
	global_load_lds_dwordx4 v[80:81], off
	s_waitcnt lgkmcnt(4)
	v_mfma_f32_32x32x16_bf16 v[32:47], v[88:91], v[92:95], v[32:47]
	s_waitcnt lgkmcnt(1)
	v_mfma_f32_32x32x16_bf16 v[48:63], v[88:91], v[106:109], v[48:63]
	ds_read_b128 v[88:91], v170 offset:4096
	ds_read_b128 v[114:117], v171 offset:4096
	s_waitcnt lgkmcnt(1)
	v_mfma_f32_32x32x16_bf16 v[0:15], v[88:91], v[92:95], v[0:15]
	v_mfma_f32_32x32x16_bf16 v[16:31], v[88:91], v[106:109], v[16:31]
	v_mfma_f32_32x32x16_bf16 v[32:47], v[98:101], v[102:105], v[32:47]
	v_mfma_f32_32x32x16_bf16 v[48:63], v[98:101], v[110:113], v[48:63]
	s_waitcnt lgkmcnt(0)
	v_mfma_f32_32x32x16_bf16 v[0:15], v[114:117], v[102:105], v[0:15]
	ds_read_b128 v[88:91], v172 offset:0
	ds_read_b128 v[92:95], v176 offset:16384
	ds_read_b128 v[98:101], v173 offset:0
	ds_read_b128 v[102:105], v177 offset:16384
	v_mfma_f32_32x32x16_bf16 v[16:31], v[114:117], v[110:113], v[16:31]
	ds_read_b128 v[106:109], v176 offset:20480
	ds_read_b128 v[110:113], v177 offset:20480
	s_waitcnt lgkmcnt(4)
	v_mfma_f32_32x32x16_bf16 v[32:47], v[88:91], v[92:95], v[32:47]
	s_waitcnt lgkmcnt(1)
	v_mfma_f32_32x32x16_bf16 v[48:63], v[88:91], v[106:109], v[48:63]
	ds_read_b128 v[88:91], v172 offset:4096
	ds_read_b128 v[114:117], v173 offset:4096
	s_waitcnt lgkmcnt(1)
	v_mfma_f32_32x32x16_bf16 v[0:15], v[88:91], v[92:95], v[0:15]
	v_mfma_f32_32x32x16_bf16 v[16:31], v[88:91], v[106:109], v[16:31]
	v_mfma_f32_32x32x16_bf16 v[32:47], v[98:101], v[102:105], v[32:47]
	v_mfma_f32_32x32x16_bf16 v[48:63], v[98:101], v[110:113], v[48:63]
	s_waitcnt lgkmcnt(0)
	v_mfma_f32_32x32x16_bf16 v[0:15], v[114:117], v[102:105], v[0:15]
	s_waitcnt vmcnt(0)
	s_barrier
;     ...
;   bf16* As1 = As + 2 * 128 * 72;
;   bf16* Bs1 = As1 + 128 * 72;
;   G_LOAD(ra0, rb0, 0);
;   if (nk > 1) G_LOAD(ra1, rb1, 1);
;   G_STORE(ra0, rb0, As, Bs);
;   __syncthreads();
;   for (int kt = 0; kt < nk; kt += 2) {
;     if (kt + 2 < nk) G_LOAD(ra0, rb0, kt + 2);
;     if (kt + 1 < nk) G_STORE(ra1, rb1, As1, Bs1);
;     G_COMPUTE(As, Bs);
;     __syncthreads();
;     if (kt + 1 < nk) {
;       if (kt + 3 < nk) G_LOAD(ra1, rb1, kt + 3);
;       if (kt + 2 < nk) G_STORE(ra0, rb0, As, Bs);
;       G_COMPUTE(As1, Bs1);
;       __syncthreads();
;     }
;   }
	v_mfma_f32_32x32x16_bf16 v[16:31], v[114:117], v[110:113], v[16:31]
	ds_read_b128 v[88:91], v170 offset:32768
	ds_read_b128 v[92:95], v174 offset:49152
	ds_read_b128 v[98:101], v171 offset:32768
	ds_read_b128 v[102:105], v175 offset:49152
	ds_read_b128 v[106:109], v174 offset:53248
	ds_read_b128 v[110:113], v175 offset:53248
	v_lshl_add_u64 v[66:67], v[66:67], 0, s[96:97]
	s_add_u32 m0, s94, 0x0
	s_nop 1
	global_load_lds_dwordx4 v[66:67], off
	v_lshl_add_u64 v[68:69], v[68:69], 0, s[96:97]
	s_add_u32 m0, s94, 0x4000
	s_nop 1
	global_load_lds_dwordx4 v[68:69], off
	v_lshl_add_u64 v[70:71], v[70:71], 0, s[96:97]
	s_add_u32 m0, s94, 0x1000
	s_nop 1
	global_load_lds_dwordx4 v[70:71], off
	v_lshl_add_u64 v[72:73], v[72:73], 0, s[96:97]
	s_add_u32 m0, s94, 0x5000
	s_nop 1
	global_load_lds_dwordx4 v[72:73], off
	v_lshl_add_u64 v[74:75], v[74:75], 0, s[96:97]
	s_add_u32 m0, s94, 0x2000
	s_nop 1
	global_load_lds_dwordx4 v[74:75], off
	v_lshl_add_u64 v[76:77], v[76:77], 0, s[96:97]
	s_add_u32 m0, s94, 0x6000
	s_nop 1
	global_load_lds_dwordx4 v[76:77], off
	v_lshl_add_u64 v[78:79], v[78:79], 0, s[96:97]
	s_add_u32 m0, s94, 0x3000
	s_nop 1
	global_load_lds_dwordx4 v[78:79], off
	v_lshl_add_u64 v[80:81], v[80:81], 0, s[96:97]
	s_add_u32 m0, s94, 0x7000
	s_nop 1
	global_load_lds_dwordx4 v[80:81], off
	s_waitcnt lgkmcnt(4)
	v_mfma_f32_32x32x16_bf16 v[32:47], v[88:91], v[92:95], v[32:47]
	s_waitcnt lgkmcnt(1)
	v_mfma_f32_32x32x16_bf16 v[48:63], v[88:91], v[106:109], v[48:63]
	ds_read_b128 v[88:91], v170 offset:36864
	ds_read_b128 v[114:117], v171 offset:36864
	s_waitcnt lgkmcnt(1)
	v_mfma_f32_32x32x16_bf16 v[0:15], v[88:91], v[92:95], v[0:15]
	v_mfma_f32_32x32x16_bf16 v[16:31], v[88:91], v[106:109], v[16:31]
	v_mfma_f32_32x32x16_bf16 v[32:47], v[98:101], v[102:105], v[32:47]
	v_mfma_f32_32x32x16_bf16 v[48:63], v[98:101], v[110:113], v[48:63]
	s_waitcnt lgkmcnt(0)
	v_mfma_f32_32x32x16_bf16 v[0:15], v[114:117], v[102:105], v[0:15]
	ds_read_b128 v[88:91], v172 offset:32768
	ds_read_b128 v[92:95], v176 offset:49152
	ds_read_b128 v[98:101], v173 offset:32768
	ds_read_b128 v[102:105], v177 offset:49152
	v_mfma_f32_32x32x16_bf16 v[16:31], v[114:117], v[110:113], v[16:31]
	ds_read_b128 v[106:109], v176 offset:53248
	ds_read_b128 v[110:113], v177 offset:53248
	s_waitcnt lgkmcnt(4)
	v_mfma_f32_32x32x16_bf16 v[32:47], v[88:91], v[92:95], v[32:47]
	s_waitcnt lgkmcnt(1)
	v_mfma_f32_32x32x16_bf16 v[48:63], v[88:91], v[106:109], v[48:63]
	ds_read_b128 v[88:91], v172 offset:36864
	ds_read_b128 v[114:117], v173 offset:36864
	s_waitcnt lgkmcnt(1)
	v_mfma_f32_32x32x16_bf16 v[0:15], v[88:91], v[92:95], v[0:15]
	v_mfma_f32_32x32x16_bf16 v[16:31], v[88:91], v[106:109], v[16:31]
	v_mfma_f32_32x32x16_bf16 v[32:47], v[98:101], v[102:105], v[32:47]
	v_mfma_f32_32x32x16_bf16 v[48:63], v[98:101], v[110:113], v[48:63]
	s_nop 0
	s_nop 0
	s_nop 0
	s_nop 0
	s_nop 0
	s_nop 0
	s_nop 0
	s_waitcnt lgkmcnt(0)
	s_waitcnt vmcnt(0)
	s_barrier
	v_lshl_add_u64 v[66:67], v[66:67], 0, s[96:97]
	s_add_u32 m0, s94, 0x8000
	s_nop 1
	global_load_lds_dwordx4 v[66:67], off
	v_lshl_add_u64 v[68:69], v[68:69], 0, s[96:97]
	s_add_u32 m0, s94, 0xc000
	s_nop 1
	global_load_lds_dwordx4 v[68:69], off
	v_lshl_add_u64 v[70:71], v[70:71], 0, s[96:97]
	s_add_u32 m0, s94, 0x9000
	s_nop 1
	global_load_lds_dwordx4 v[70:71], off
	v_lshl_add_u64 v[72:73], v[72:73], 0, s[96:97]
	s_add_u32 m0, s94, 0xd000
	s_nop 1
	global_load_lds_dwordx4 v[72:73], off
	v_lshl_add_u64 v[74:75], v[74:75], 0, s[96:97]
	s_add_u32 m0, s94, 0xa000
	s_nop 1
	global_load_lds_dwordx4 v[74:75], off
	v_lshl_add_u64 v[76:77], v[76:77], 0, s[96:97]
	s_add_u32 m0, s94, 0xe000
	s_nop 1
	global_load_lds_dwordx4 v[76:77], off
	v_lshl_add_u64 v[78:79], v[78:79], 0, s[96:97]
	s_add_u32 m0, s94, 0xb000
	s_nop 1
	global_load_lds_dwordx4 v[78:79], off
	v_lshl_add_u64 v[80:81], v[80:81], 0, s[96:97]
	s_add_u32 m0, s94, 0xf000
	s_nop 1
	global_load_lds_dwordx4 v[80:81], off
	v_mfma_f32_32x32x16_bf16 v[0:15], v[114:117], v[102:105], v[0:15]
	ds_read_b128 v[66:69], v170 offset:0
	ds_read_b128 v[70:73], v174 offset:16384
	ds_read_b128 v[74:77], v171 offset:0
	ds_read_b128 v[78:81], v175 offset:16384
	ds_read_b128 v[88:91], v174 offset:20480
	ds_read_b128 v[92:95], v175 offset:20480
	v_mfma_f32_32x32x16_bf16 v[16:31], v[114:117], v[110:113], v[16:31]
	s_waitcnt lgkmcnt(4)
	v_mfma_f32_32x32x16_bf16 v[32:47], v[66:69], v[70:73], v[32:47]
	s_waitcnt lgkmcnt(1)
	v_mfma_f32_32x32x16_bf16 v[48:63], v[66:69], v[88:91], v[48:63]
	ds_read_b128 v[66:69], v170 offset:4096
	ds_read_b128 v[98:101], v171 offset:4096
	s_waitcnt lgkmcnt(1)
	v_mfma_f32_32x32x16_bf16 v[0:15], v[66:69], v[70:73], v[0:15]
	v_mfma_f32_32x32x16_bf16 v[16:31], v[66:69], v[88:91], v[16:31]
	v_mfma_f32_32x32x16_bf16 v[32:47], v[74:77], v[78:81], v[32:47]
	v_mfma_f32_32x32x16_bf16 v[48:63], v[74:77], v[92:95], v[48:63]
	s_waitcnt lgkmcnt(0)
	v_mfma_f32_32x32x16_bf16 v[0:15], v[98:101], v[78:81], v[0:15]
	ds_read_b128 v[66:69], v172 offset:0
	ds_read_b128 v[70:73], v176 offset:16384
	ds_read_b128 v[74:77], v173 offset:0
	ds_read_b128 v[78:81], v177 offset:16384
	v_mfma_f32_32x32x16_bf16 v[16:31], v[98:101], v[92:95], v[16:31]
	ds_read_b128 v[88:91], v176 offset:20480
	ds_read_b128 v[92:95], v177 offset:20480
	s_waitcnt lgkmcnt(4)
	v_mfma_f32_32x32x16_bf16 v[32:47], v[66:69], v[70:73], v[32:47]
	s_waitcnt lgkmcnt(1)
	v_mfma_f32_32x32x16_bf16 v[48:63], v[66:69], v[88:91], v[48:63]
	ds_read_b128 v[66:69], v172 offset:4096
	ds_read_b128 v[98:101], v173 offset:4096
	s_waitcnt lgkmcnt(0)
	s_waitcnt vmcnt(0)
	s_barrier
; #define PW(T, off) ((T*)(lndp(p.ws) + (off)))
; DEVI void gemm_epi_qkv(const Params& p, f32x16 (&acc)[2][2], int rbase, int cbase, int lane) {
;   char* ar = PW(char, W_arena);
;   const int which = cbase >> 10, cc = cbase & 1023, d = lane & 31, hl = lane >> 5;
; #pragma unroll
;   for (int i = 0; i < 2; ++i) {
; #pragma unroll
;     for (int rq = 0; rq < 4; ++rq) {
;       const int row0 = rbase + i * 32 + 8 * rq + 4 * hl;
;       if (row0 >= M) continue;
;       const bool pr = row0 < TP;
;       const int b = pr ? 0 : (row0 - TP) >> 4, t0 = pr ? row0 : (row0 - TP) & 15;
;       if (which < 2) {
;     ...
;   for (int kt = 0; kt < nk; kt += 2) {
;     if (kt + 2 < nk) G_LOAD(ra0, rb0, kt + 2);
;     if (kt + 1 < nk) G_STORE(ra1, rb1, As1, Bs1);
;     G_COMPUTE(As, Bs);
;     __syncthreads();
;     if (kt + 1 < nk) {
;       if (kt + 3 < nk) G_LOAD(ra1, rb1, kt + 3);
;       if (kt + 2 < nk) G_STORE(ra0, rb0, As, Bs);
;       G_COMPUTE(As1, Bs1);
;       __syncthreads();
;     }
;   }
	v_mfma_f32_32x32x16_bf16 v[0:15], v[66:69], v[70:73], v[0:15]
	v_mfma_f32_32x32x16_bf16 v[32:47], v[74:77], v[78:81], v[32:47]
	v_mfma_f32_32x32x16_bf16 v[48:63], v[74:77], v[92:95], v[48:63]
	v_mfma_f32_32x32x16_bf16 v[16:31], v[66:69], v[88:91], v[16:31]
	v_mfma_f32_32x32x16_bf16 v[0:15], v[98:101], v[78:81], v[0:15]
	ds_read_b128 v[66:69], v170 offset:32768
	ds_read_b128 v[70:73], v174 offset:49152
	ds_read_b128 v[74:77], v175 offset:49152
	ds_read_b128 v[78:81], v171 offset:32768
	ds_read_b128 v[88:91], v174 offset:53248
	s_waitcnt lgkmcnt(3)
	v_mfma_f32_32x32x16_bf16 v[32:47], v[66:69], v[70:73], v[32:47]
	s_waitcnt lgkmcnt(0)
	v_mfma_f32_32x32x16_bf16 v[48:63], v[66:69], v[88:91], v[48:63]
	ds_read_b128 v[66:69], v170 offset:36864
	v_mfma_f32_32x32x16_bf16 v[16:31], v[98:101], v[92:95], v[16:31]
	s_waitcnt lgkmcnt(0)
	v_mfma_f32_32x32x16_bf16 v[0:15], v[66:69], v[70:73], v[0:15]
	ds_read_b128 v[70:73], v171 offset:36864
	v_mfma_f32_32x32x16_bf16 v[16:31], v[66:69], v[88:91], v[16:31]
	ds_read_b128 v[66:69], v175 offset:53248
	v_mfma_f32_32x32x16_bf16 v[32:47], v[78:81], v[74:77], v[32:47]
	s_waitcnt lgkmcnt(0)
	v_mfma_f32_32x32x16_bf16 v[48:63], v[78:81], v[66:69], v[48:63]
	v_or_b32_e32 v81, s6, v65
	v_and_or_b32 v80, v85, 64, s6
	s_mov_b64 s[6:7], 0x1e05c060
	v_mfma_f32_32x32x16_bf16 v[0:15], v[70:73], v[74:77], v[0:15]
	v_mfma_f32_32x32x16_bf16 v[16:31], v[70:73], v[66:69], v[16:31]
	ds_read_b128 v[66:69], v172 offset:32768
	ds_read_b128 v[70:73], v176 offset:49152
	ds_read_b128 v[74:77], v176 offset:53248
	s_waitcnt lgkmcnt(1)
	v_mfma_f32_32x32x16_bf16 v[32:47], v[66:69], v[70:73], v[32:47]
	s_waitcnt lgkmcnt(0)
	v_mfma_f32_32x32x16_bf16 v[48:63], v[66:69], v[74:77], v[48:63]
	ds_read_b128 v[66:69], v172 offset:36864
	s_waitcnt lgkmcnt(0)
	v_mfma_f32_32x32x16_bf16 v[0:15], v[66:69], v[70:73], v[0:15]
	ds_read_b128 v[88:91], v177 offset:53248
	ds_read_b128 v[92:95], v177 offset:49152
	ds_read_b128 v[70:73], v173 offset:32768
	v_mfma_f32_32x32x16_bf16 v[16:31], v[66:69], v[74:77], v[16:31]
	ds_read_b128 v[74:77], v173 offset:36864
	v_lshrrev_b32_e32 v66, 3, v85
	v_add_u32_e32 v64, s3, v86
	v_and_b32_e32 v82, 4, v66
	v_or_b32_e32 v68, v64, v82
	v_mul_u32_u24_e32 v64, 0x4040, v81
	v_lshlrev_b32_e32 v96, 1, v64
	s_waitcnt lgkmcnt(1)
	v_mfma_f32_32x32x16_bf16 v[32:47], v[70:73], v[92:95], v[32:47]
	s_waitcnt lgkmcnt(0)
	s_barrier
	s_cmp_gt_i32 s5, 1
	s_cselect_b64 s[2:3], -1, 0
	v_lshl_add_u64 v[64:65], s[22:23], 0, v[96:97]
	v_lshlrev_b32_e32 v96, 1, v80
	v_mfma_f32_32x32x16_bf16 v[48:63], v[70:73], v[88:91], v[48:63]
	v_lshl_add_u64 v[70:71], v[64:65], 0, s[6:7]
	s_cmpk_gt_u32 s4, 0x3ff
	v_lshl_add_u64 v[64:65], s[22:23], 0, v[96:97]
	s_mov_b64 s[6:7], 0x13e3c000
	s_cselect_b64 s[20:21], -1, 0
	v_lshl_add_u64 v[66:67], v[64:65], 0, s[6:7]
	s_mov_b64 s[6:7], 0x11d7c000
	v_mfma_f32_32x32x16_bf16 v[0:15], v[74:77], v[92:95], v[0:15]
	s_cmp_eq_u32 s5, 1
	v_lshl_add_u64 v[64:65], v[64:65], 0, s[6:7]
	s_cselect_b64 s[18:19], -1, 0
	v_cmp_gt_i32_e32 vcc, s90, v68
	v_mfma_f32_32x32x16_bf16 v[16:31], v[74:77], v[88:91], v[16:31]
	s_and_saveexec_b64 s[4:5], vcc
	s_cbranch_execz .LBB0_2373
	s_movk_i32 s6, 0x400f
	v_add_u32_e32 v72, 0xffffbff0, v68
	v_cmp_lt_i32_e64 s[6:7], s6, v68
	v_ashrrev_i32_e32 v78, 4, v72
	s_mov_b64 s[8:9], -1
	s_and_b64 vcc, exec, s[2:3]
	s_cbranch_vccz .LBB0_2352
	s_and_saveexec_b64 s[8:9], s[6:7]
	s_xor_b64 s[8:9], exec, s[8:9]
	s_cbranch_execz .LBB0_2345
	s_mov_b64 s[10:11], s[72:73]
	s_add_u32 s10, s10, 0xc48f000
	v_mov_b32_e32 v73, v97
	s_addc_u32 s11, s11, 0
	v_mov_b64_e32 v[74:75], v[72:73]

; DEVI int TID() { int t = threadIdx.x; asm volatile("" : "+v"(t)); return t; }
; DEVI int BID() { int b = blockIdx.x; asm volatile("" : "+s"(b)); return b; }
;     ...
;   const int tid = TID(), lane = tid & 63, wave = tid >> 6, wm = wave >> 1, wn = wave & 1;
;   f32x16 acc[2][2];
; #pragma unroll
;   for (int i = 0; i < 2; ++i)
; #pragma unroll
;     for (int j = 0; j < 2; ++j) acc[i][j] = zero16();
;   const int lrow = tid >> 3, lkc = (tid & 7) * 8;
;   const bf16* Ag = jb.A + (size_t)max(m0 + lrow, 0) * jb.lda + lkc;
;   const bf16* Ag1 = jb.A + (ptrdiff_t)(m0 + lrow) * jb.lda + lkc;
;   const bf16* Bg = jb.Bt + (size_t)(n0 + lrow) * jb.K + lkc;
;   const size_t astep = (size_t)32 * jb.lda, bstep = (size_t)32 * jb.K;
;   if (kt1 < 0) kt1 = jb.K >> 6;
;   const int nk = kt1 - kt0;
;   Ag += (size_t)kt0 * 64; Ag1 += (size_t)kt0 * 64; Bg += (size_t)kt0 * 64;
;   u32x4 ra0[4], rb0[4], ra1[4], rb1[4];
;     ...
;   bf16* As1 = As + 2 * 128 * 72;
;   bf16* Bs1 = As1 + 128 * 72;
;   G_LOAD(ra0, rb0, 0);
;   if (nk > 1) G_LOAD(ra1, rb1, 1);
;   G_STORE(ra0, rb0, As, Bs);
;   __syncthreads();
; DEVI void gemm_single(const Params& p, const GJob& jb, int nt, char* smem) {
;     ...
;     const int b = BID(), x = b & 7, lb = b >> 3, nlb = gridDim.x >> 3;
;     const int ng = x & 3, mh = x >> 2;
;     const int n_lo = ng * nt / 4, nnt = (ng + 1) * nt / 4 - n_lo;
;     const int m_lo = mh * mtn / 2, nmt = (mh + 1) * mtn / 2 - m_lo;
;     for (int t = lb; t < nmt * nnt; t += nlb) {
;       const int mt = m_lo + t / nnt, ntg = n_lo + t % nnt;
;       gemm_tile(p, jb, fused ? mt * 126 - 2 : mt * 128, ntg * 128, smem);
.LBB0_3493:
	s_abs_i32 s3, s23
	s_mul_hi_u32 s4, s3, s29
	s_mul_i32 s5, s4, s27
	s_ashr_i32 s2, s23, 31
	s_sub_i32 s3, s3, s5
	s_xor_b32 s2, s2, s28
	s_add_i32 s5, s4, 1
	s_sub_i32 s6, s3, s27
	s_cmp_ge_u32 s3, s27
	s_cselect_b32 s4, s5, s4
	s_cselect_b32 s3, s6, s3
	s_add_i32 s5, s4, 1
	s_cmp_ge_u32 s3, s27
	s_cselect_b32 s3, s5, s4
	s_xor_b32 s3, s3, s2
	s_sub_i32 s4, s3, s2
	s_add_i32 s4, s4, s25
	s_mul_i32 s30, s4, 0x7e
	s_waitcnt vmcnt(0)
	v_mov_b32_e32 v93, v208
	s_add_i32 s30, s30, -2
	s_mul_i32 s2, s2, 11
	v_ashrrev_i32_e32 v70, 3, v93
	v_add_u32_e32 v0, s30, v70
	s_mul_i32 s3, s3, 11
	v_max_i32_e32 v96, 0, v0
	v_lshlrev_b32_e32 v1, 4, v93
	s_sub_i32 s2, s2, s3
	s_add_i32 s3, s24, s23
	v_lshlrev_b64 v[2:3], 11, v[96:97]
	v_and_b32_e32 v96, 0x70, v1
	s_mov_b64 s[96:97], 0x80
	v_lshrrev_b32_e32 v178, 4, v208
	v_and_b32_e32 v178, 7, v178
	v_lshlrev_b32_e32 v178, 4, v178
	v_xor_b32_e32 v96, v96, v178
	v_lshrrev_b32_e32 v179, 6, v208
	v_lshlrev_b32_e32 v179, 10, v179
	v_lshrrev_b32_e32 v180, 5, v208
	v_lshrrev_b32_e32 v181, 1, v208
	v_xor_b32_e32 v180, v180, v181
	v_readfirstlane_b32 s94, v179
	v_and_b32_e32 v180, 1, v180
	v_lshlrev_b32_e32 v180, 4, v180
	v_and_b32_e32 v181, 31, v208
	v_lshlrev_b32_e32 v181, 7, v181
	v_or_b32_e32 v180, v180, v181
	v_lshrrev_b32_e32 v181, 7, v208
	v_lshlrev_b32_e32 v181, 13, v181
	v_or_b32_e32 v194, v180, v181
	v_bfe_u32 v181, v208, 6, 1
	v_lshlrev_b32_e32 v181, 13, v181
	v_or_b32_e32 v195, v180, v181
	v_bfe_u32 v178, v208, 2, 2
	v_xor_b32_e32 v179, 0, v178
	v_lshlrev_b32_e32 v179, 5, v179
	v_or_b32_e32 v170, v194, v179
	v_or_b32_e32 v174, v195, v179
	v_xor_b32_e32 v179, 1, v178
	v_lshlrev_b32_e32 v179, 5, v179
	v_or_b32_e32 v171, v194, v179
	v_or_b32_e32 v175, v195, v179
	v_xor_b32_e32 v179, 2, v178
	v_lshlrev_b32_e32 v179, 5, v179
	v_or_b32_e32 v172, v194, v179
	v_or_b32_e32 v176, v195, v179
	v_xor_b32_e32 v179, 3, v178
	v_lshlrev_b32_e32 v179, 5, v179
	v_or_b32_e32 v173, v194, v179
	v_or_b32_e32 v177, v195, v179
	v_ashrrev_i32_e32 v1, 31, v0
	s_add_i32 s3, s3, s2
	v_lshlrev_b64 v[0:1], 11, v[0:1]
	s_lshl_b32 s2, s3, 7
	v_lshl_add_u64 v[0:1], s[12:13], 0, v[0:1]
	v_lshl_add_u64 v[24:25], v[0:1], 0, v[96:97]
	v_add_u32_e32 v0, s2, v70
	v_ashrrev_i32_e32 v1, 31, v0
	v_lshlrev_b64 v[0:1], 11, v[0:1]
	v_lshl_add_u64 v[0:1], v[64:65], 0, v[0:1]
	v_add_co_u32_e32 v76, vcc, s63, v24
	v_lshl_add_u64 v[74:75], v[0:1], 0, v[96:97]
	s_nop 0
	v_addc_co_u32_e32 v77, vcc, 0, v25, vcc
	v_add_co_u32_e32 v78, vcc, s63, v74
	v_lshl_add_u64 v[2:3], s[12:13], 0, v[2:3]
	s_nop 0
	v_addc_co_u32_e32 v79, vcc, 0, v75, vcc
	v_add_co_u32_e32 v80, vcc, s64, v24
	v_lshl_add_u64 v[72:73], v[2:3], 0, v[96:97]
	s_nop 0
	v_addc_co_u32_e32 v81, vcc, 0, v25, vcc
	v_add_co_u32_e32 v82, vcc, s64, v74
	v_addc_co_u32_e32 v83, vcc, 0, v75, vcc
	v_add_co_u32_e32 v84, vcc, s65, v24
	s_nop 0
	v_addc_co_u32_e32 v85, vcc, 0, v25, vcc
	v_add_co_u32_e32 v86, vcc, s65, v74
	s_nop 0
	v_addc_co_u32_e32 v87, vcc, 0, v75, vcc
	v_ashrrev_i32_e32 v71, 1, v93
	v_mad_u64_u32 v[88:89], s[4:5], v70, s91, v[96:97]
	v_and_b32_e32 v94, 31, v93
	v_and_b32_e32 v92, 0xffffffc0, v71
	v_or_b32_e32 v71, v92, v94
	v_add_u32_e32 v96, 0xd800, v88
	v_bfe_u32 v95, v93, 6, 1
	s_mov_b32 s6, 43
	s_mov_b64 s[16:17], s[72:73]
	s_add_u32 m0, s94, 0x0
	s_nop 1
	global_load_lds_dwordx4 v[72:73], off
	s_add_u32 m0, s94, 0x4000
	s_nop 1
	global_load_lds_dwordx4 v[74:75], off
	s_add_u32 m0, s94, 0x1000
	s_nop 1
	global_load_lds_dwordx4 v[76:77], off
	s_add_u32 m0, s94, 0x5000
	s_nop 1
	global_load_lds_dwordx4 v[78:79], off
	s_add_u32 m0, s94, 0x2000
	s_nop 1
	global_load_lds_dwordx4 v[80:81], off
	s_add_u32 m0, s94, 0x6000
	s_nop 1
	global_load_lds_dwordx4 v[82:83], off
	s_add_u32 m0, s94, 0x3000
	s_nop 1
	global_load_lds_dwordx4 v[84:85], off
	s_add_u32 m0, s94, 0x7000
	s_nop 1
	global_load_lds_dwordx4 v[86:87], off
	v_lshrrev_b32_e32 v0, 1, v93
	v_and_b32_e32 v4, 16, v0
	s_waitcnt lgkmcnt(0)
	s_waitcnt vmcnt(0)
	s_barrier
	v_mad_u64_u32 v[70:71], s[4:5], v71, s91, v[4:5]
	ds_read_b128 v[0:3], v170 offset:0
	v_lshlrev_b32_e32 v71, 6, v95
	v_or_b32_e32 v5, v71, v94
	v_mad_u32_u24 v89, v5, s91, v4
	ds_read_b128 v[4:7], v174 offset:16384
	ds_read_b128 v[98:101], v171 offset:0
	ds_read_b128 v[102:105], v175 offset:16384
	ds_read_b128 v[8:11], v174 offset:20480
	ds_read_b128 v[106:109], v175 offset:20480
	v_lshl_add_u64 v[72:73], v[72:73], 0, s[96:97]
	s_add_u32 m0, s94, 0x8000
	s_nop 1
	global_load_lds_dwordx4 v[72:73], off
	v_lshl_add_u64 v[74:75], v[74:75], 0, s[96:97]
	s_add_u32 m0, s94, 0xc000
	s_nop 1
	global_load_lds_dwordx4 v[74:75], off
	v_lshl_add_u64 v[76:77], v[76:77], 0, s[96:97]
	s_add_u32 m0, s94, 0x9000
	s_nop 1
	global_load_lds_dwordx4 v[76:77], off
	v_lshl_add_u64 v[78:79], v[78:79], 0, s[96:97]
	s_add_u32 m0, s94, 0xd000
	s_nop 1
	global_load_lds_dwordx4 v[78:79], off
	v_lshl_add_u64 v[80:81], v[80:81], 0, s[96:97]
	s_add_u32 m0, s94, 0xa000
	s_nop 1
	global_load_lds_dwordx4 v[80:81], off
	v_lshl_add_u64 v[82:83], v[82:83], 0, s[96:97]
	s_add_u32 m0, s94, 0xe000
	s_nop 1
	global_load_lds_dwordx4 v[82:83], off
	v_lshl_add_u64 v[84:85], v[84:85], 0, s[96:97]
	s_add_u32 m0, s94, 0xb000
	s_nop 1
	global_load_lds_dwordx4 v[84:85], off
	v_lshl_add_u64 v[86:87], v[86:87], 0, s[96:97]
	s_add_u32 m0, s94, 0xf000
	s_nop 1
	global_load_lds_dwordx4 v[86:87], off
	s_waitcnt lgkmcnt(4)
	v_mfma_f32_32x32x16_bf16 v[48:63], v[0:3], v[4:7], 0
	s_mov_b32 s4, 8
	s_waitcnt lgkmcnt(1)
	v_mfma_f32_32x32x16_bf16 v[32:47], v[0:3], v[8:11], 0
	ds_read_b128 v[0:3], v170 offset:4096
	ds_read_b128 v[110:113], v171 offset:4096
	s_waitcnt lgkmcnt(1)
	v_mfma_f32_32x32x16_bf16 v[16:31], v[0:3], v[4:7], 0
	v_mfma_f32_32x32x16_bf16 v[0:15], v[0:3], v[8:11], 0
	v_mfma_f32_32x32x16_bf16 v[48:63], v[98:101], v[102:105], v[48:63]
	v_mfma_f32_32x32x16_bf16 v[32:47], v[98:101], v[106:109], v[32:47]
	s_waitcnt lgkmcnt(0)
	v_mfma_f32_32x32x16_bf16 v[16:31], v[110:113], v[102:105], v[16:31]
	v_mfma_f32_32x32x16_bf16 v[0:15], v[110:113], v[106:109], v[0:15]
	ds_read_b128 v[98:101], v172 offset:0
	ds_read_b128 v[102:105], v176 offset:16384
	ds_read_b128 v[106:109], v173 offset:0
	ds_read_b128 v[110:113], v177 offset:16384
	ds_read_b128 v[114:117], v176 offset:20480
	ds_read_b128 v[118:121], v177 offset:20480
	s_waitcnt lgkmcnt(4)
	v_mfma_f32_32x32x16_bf16 v[48:63], v[98:101], v[102:105], v[48:63]
	s_waitcnt lgkmcnt(1)
	v_mfma_f32_32x32x16_bf16 v[32:47], v[98:101], v[114:117], v[32:47]
	ds_read_b128 v[98:101], v172 offset:4096
	ds_read_b128 v[122:125], v173 offset:4096
	s_waitcnt lgkmcnt(1)
	v_mfma_f32_32x32x16_bf16 v[16:31], v[98:101], v[102:105], v[16:31]
	v_mfma_f32_32x32x16_bf16 v[0:15], v[98:101], v[114:117], v[0:15]
	v_mfma_f32_32x32x16_bf16 v[48:63], v[106:109], v[110:113], v[48:63]
	v_mfma_f32_32x32x16_bf16 v[32:47], v[106:109], v[118:121], v[32:47]
	s_waitcnt lgkmcnt(0)
	v_mfma_f32_32x32x16_bf16 v[16:31], v[122:125], v[110:113], v[16:31]
	s_waitcnt vmcnt(0)
	s_barrier
;     ...
;   bf16* As1 = As + 2 * 128 * 72;
;   bf16* Bs1 = As1 + 128 * 72;
;   G_LOAD(ra0, rb0, 0);
;   if (nk > 1) G_LOAD(ra1, rb1, 1);
;   G_STORE(ra0, rb0, As, Bs);
;   __syncthreads();
;   for (int kt = 0; kt < nk; kt += 2) {
;     if (kt + 2 < nk) G_LOAD(ra0, rb0, kt + 2);
;     if (kt + 1 < nk) G_STORE(ra1, rb1, As1, Bs1);
;     G_COMPUTE(As, Bs);
;     __syncthreads();
;     if (kt + 1 < nk) {
;       if (kt + 3 < nk) G_LOAD(ra1, rb1, kt + 3);
;       if (kt + 2 < nk) G_STORE(ra0, rb0, As, Bs);
;       G_COMPUTE(As1, Bs1);
;       __syncthreads();
;     }
;   }
	v_mfma_f32_32x32x16_bf16 v[0:15], v[122:125], v[118:121], v[0:15]
	ds_read_b128 v[98:101], v170 offset:32768
	ds_read_b128 v[102:105], v174 offset:49152
	ds_read_b128 v[106:109], v171 offset:32768
	ds_read_b128 v[110:113], v175 offset:49152
	ds_read_b128 v[114:117], v174 offset:53248
	ds_read_b128 v[118:121], v175 offset:53248
	v_lshl_add_u64 v[72:73], v[72:73], 0, s[96:97]
	s_add_u32 m0, s94, 0x0
	s_nop 1
	global_load_lds_dwordx4 v[72:73], off
	v_lshl_add_u64 v[74:75], v[74:75], 0, s[96:97]
	s_add_u32 m0, s94, 0x4000
	s_nop 1
	global_load_lds_dwordx4 v[74:75], off
	v_lshl_add_u64 v[76:77], v[76:77], 0, s[96:97]
	s_add_u32 m0, s94, 0x1000
	s_nop 1
	global_load_lds_dwordx4 v[76:77], off
	v_lshl_add_u64 v[78:79], v[78:79], 0, s[96:97]
	s_add_u32 m0, s94, 0x5000
	s_nop 1
	global_load_lds_dwordx4 v[78:79], off
	v_lshl_add_u64 v[80:81], v[80:81], 0, s[96:97]
	s_add_u32 m0, s94, 0x2000
	s_nop 1
	global_load_lds_dwordx4 v[80:81], off
	v_lshl_add_u64 v[82:83], v[82:83], 0, s[96:97]
	s_add_u32 m0, s94, 0x6000
	s_nop 1
	global_load_lds_dwordx4 v[82:83], off
	v_lshl_add_u64 v[84:85], v[84:85], 0, s[96:97]
	s_add_u32 m0, s94, 0x3000
	s_nop 1
	global_load_lds_dwordx4 v[84:85], off
	v_lshl_add_u64 v[86:87], v[86:87], 0, s[96:97]
	s_add_u32 m0, s94, 0x7000
	s_nop 1
	global_load_lds_dwordx4 v[86:87], off
	s_waitcnt lgkmcnt(4)
	v_mfma_f32_32x32x16_bf16 v[48:63], v[98:101], v[102:105], v[48:63]
	s_waitcnt lgkmcnt(1)
	v_mfma_f32_32x32x16_bf16 v[32:47], v[98:101], v[114:117], v[32:47]
	ds_read_b128 v[98:101], v170 offset:36864
	ds_read_b128 v[122:125], v171 offset:36864
	s_waitcnt lgkmcnt(1)
	v_mfma_f32_32x32x16_bf16 v[16:31], v[98:101], v[102:105], v[16:31]
	v_mfma_f32_32x32x16_bf16 v[0:15], v[98:101], v[114:117], v[0:15]
	v_mfma_f32_32x32x16_bf16 v[48:63], v[106:109], v[110:113], v[48:63]
	v_mfma_f32_32x32x16_bf16 v[32:47], v[106:109], v[118:121], v[32:47]
	s_waitcnt lgkmcnt(0)
	v_mfma_f32_32x32x16_bf16 v[16:31], v[122:125], v[110:113], v[16:31]
	ds_read_b128 v[98:101], v172 offset:32768
	ds_read_b128 v[102:105], v176 offset:49152
	ds_read_b128 v[106:109], v173 offset:32768
	ds_read_b128 v[110:113], v177 offset:49152
	v_mfma_f32_32x32x16_bf16 v[0:15], v[122:125], v[118:121], v[0:15]
	ds_read_b128 v[114:117], v176 offset:53248
	ds_read_b128 v[118:121], v177 offset:53248
	s_waitcnt lgkmcnt(4)
	v_mfma_f32_32x32x16_bf16 v[48:63], v[98:101], v[102:105], v[48:63]
	s_waitcnt lgkmcnt(1)
	v_mfma_f32_32x32x16_bf16 v[32:47], v[98:101], v[114:117], v[32:47]
	ds_read_b128 v[98:101], v172 offset:36864
	ds_read_b128 v[122:125], v173 offset:36864
	s_waitcnt lgkmcnt(1)
	v_mfma_f32_32x32x16_bf16 v[16:31], v[98:101], v[102:105], v[16:31]
	v_mfma_f32_32x32x16_bf16 v[0:15], v[98:101], v[114:117], v[0:15]
	v_mfma_f32_32x32x16_bf16 v[48:63], v[106:109], v[110:113], v[48:63]
	v_mfma_f32_32x32x16_bf16 v[32:47], v[106:109], v[118:121], v[32:47]
	s_waitcnt lgkmcnt(0)
	v_mfma_f32_32x32x16_bf16 v[16:31], v[122:125], v[110:113], v[16:31]
	s_waitcnt vmcnt(0)
	s_barrier
	v_mfma_f32_32x32x16_bf16 v[0:15], v[122:125], v[118:121], v[0:15]
	ds_read_b128 v[98:101], v170 offset:0
	ds_read_b128 v[102:105], v174 offset:16384
	ds_read_b128 v[106:109], v171 offset:0
	ds_read_b128 v[110:113], v175 offset:16384
	ds_read_b128 v[114:117], v174 offset:20480
	ds_read_b128 v[118:121], v175 offset:20480
	v_lshl_add_u64 v[72:73], v[72:73], 0, s[96:97]
	s_add_u32 m0, s94, 0x8000
	s_nop 1
	global_load_lds_dwordx4 v[72:73], off
	v_lshl_add_u64 v[74:75], v[74:75], 0, s[96:97]
	s_add_u32 m0, s94, 0xc000
	s_nop 1
	global_load_lds_dwordx4 v[74:75], off
	v_lshl_add_u64 v[76:77], v[76:77], 0, s[96:97]
	s_add_u32 m0, s94, 0x9000
	s_nop 1
	global_load_lds_dwordx4 v[76:77], off
	v_lshl_add_u64 v[78:79], v[78:79], 0, s[96:97]
	s_add_u32 m0, s94, 0xd000
	s_nop 1
	global_load_lds_dwordx4 v[78:79], off
	v_lshl_add_u64 v[80:81], v[80:81], 0, s[96:97]
	s_add_u32 m0, s94, 0xa000
	s_nop 1
	global_load_lds_dwordx4 v[80:81], off
	v_lshl_add_u64 v[82:83], v[82:83], 0, s[96:97]
	s_add_u32 m0, s94, 0xe000
	s_nop 1
	global_load_lds_dwordx4 v[82:83], off
	v_lshl_add_u64 v[84:85], v[84:85], 0, s[96:97]
	s_add_u32 m0, s94, 0xb000
	s_nop 1
	global_load_lds_dwordx4 v[84:85], off
	v_lshl_add_u64 v[86:87], v[86:87], 0, s[96:97]
	s_add_u32 m0, s94, 0xf000
	s_nop 1
	global_load_lds_dwordx4 v[86:87], off
	s_waitcnt lgkmcnt(4)
	v_mfma_f32_32x32x16_bf16 v[48:63], v[98:101], v[102:105], v[48:63]
	s_waitcnt lgkmcnt(1)
	v_mfma_f32_32x32x16_bf16 v[32:47], v[98:101], v[114:117], v[32:47]
	ds_read_b128 v[98:101], v170 offset:4096
	ds_read_b128 v[122:125], v171 offset:4096
	s_waitcnt lgkmcnt(1)
	v_mfma_f32_32x32x16_bf16 v[16:31], v[98:101], v[102:105], v[16:31]
	v_mfma_f32_32x32x16_bf16 v[0:15], v[98:101], v[114:117], v[0:15]
	v_mfma_f32_32x32x16_bf16 v[48:63], v[106:109], v[110:113], v[48:63]
	v_mfma_f32_32x32x16_bf16 v[32:47], v[106:109], v[118:121], v[32:47]
	s_waitcnt lgkmcnt(0)
	v_mfma_f32_32x32x16_bf16 v[16:31], v[122:125], v[110:113], v[16:31]
	ds_read_b128 v[98:101], v172 offset:0
	ds_read_b128 v[102:105], v176 offset:16384
	ds_read_b128 v[106:109], v173 offset:0
	ds_read_b128 v[110:113], v177 offset:16384
	v_mfma_f32_32x32x16_bf16 v[0:15], v[122:125], v[118:121], v[0:15]
	ds_read_b128 v[114:117], v176 offset:20480
	ds_read_b128 v[118:121], v177 offset:20480
	s_waitcnt lgkmcnt(4)
	v_mfma_f32_32x32x16_bf16 v[48:63], v[98:101], v[102:105], v[48:63]
	s_waitcnt lgkmcnt(1)
	v_mfma_f32_32x32x16_bf16 v[32:47], v[98:101], v[114:117], v[32:47]
	ds_read_b128 v[98:101], v172 offset:4096
	ds_read_b128 v[122:125], v173 offset:4096
	s_waitcnt lgkmcnt(1)
	v_mfma_f32_32x32x16_bf16 v[16:31], v[98:101], v[102:105], v[16:31]
	v_mfma_f32_32x32x16_bf16 v[0:15], v[98:101], v[114:117], v[0:15]
	v_mfma_f32_32x32x16_bf16 v[48:63], v[106:109], v[110:113], v[48:63]
	v_mfma_f32_32x32x16_bf16 v[32:47], v[106:109], v[118:121], v[32:47]
	s_waitcnt lgkmcnt(0)
	v_mfma_f32_32x32x16_bf16 v[16:31], v[122:125], v[110:113], v[16:31]
	s_waitcnt vmcnt(0)
	s_barrier
;     ...
;   bf16* As1 = As + 2 * 128 * 72;
;   bf16* Bs1 = As1 + 128 * 72;
;   G_LOAD(ra0, rb0, 0);
;   if (nk > 1) G_LOAD(ra1, rb1, 1);
;   G_STORE(ra0, rb0, As, Bs);
;   __syncthreads();
;   for (int kt = 0; kt < nk; kt += 2) {
;     if (kt + 2 < nk) G_LOAD(ra0, rb0, kt + 2);
;     if (kt + 1 < nk) G_STORE(ra1, rb1, As1, Bs1);
;     G_COMPUTE(As, Bs);
;     __syncthreads();
;     if (kt + 1 < nk) {
;       if (kt + 3 < nk) G_LOAD(ra1, rb1, kt + 3);
;       if (kt + 2 < nk) G_STORE(ra0, rb0, As, Bs);
;       G_COMPUTE(As1, Bs1);
;       __syncthreads();
;     }
;   }
	v_mfma_f32_32x32x16_bf16 v[0:15], v[122:125], v[118:121], v[0:15]
	ds_read_b128 v[98:101], v170 offset:32768
	ds_read_b128 v[102:105], v174 offset:49152
	ds_read_b128 v[106:109], v171 offset:32768
	ds_read_b128 v[110:113], v175 offset:49152
	ds_read_b128 v[114:117], v174 offset:53248
	ds_read_b128 v[118:121], v175 offset:53248
	v_lshl_add_u64 v[72:73], v[72:73], 0, s[96:97]
	s_add_u32 m0, s94, 0x0
	s_nop 1
	global_load_lds_dwordx4 v[72:73], off
	v_lshl_add_u64 v[74:75], v[74:75], 0, s[96:97]
	s_add_u32 m0, s94, 0x4000
	s_nop 1
	global_load_lds_dwordx4 v[74:75], off
	v_lshl_add_u64 v[76:77], v[76:77], 0, s[96:97]
	s_add_u32 m0, s94, 0x1000
	s_nop 1
	global_load_lds_dwordx4 v[76:77], off
	v_lshl_add_u64 v[78:79], v[78:79], 0, s[96:97]
	s_add_u32 m0, s94, 0x5000
	s_nop 1
	global_load_lds_dwordx4 v[78:79], off
	v_lshl_add_u64 v[80:81], v[80:81], 0, s[96:97]
	s_add_u32 m0, s94, 0x2000
	s_nop 1
	global_load_lds_dwordx4 v[80:81], off
	v_lshl_add_u64 v[82:83], v[82:83], 0, s[96:97]
	s_add_u32 m0, s94, 0x6000
	s_nop 1
	global_load_lds_dwordx4 v[82:83], off
	v_lshl_add_u64 v[84:85], v[84:85], 0, s[96:97]
	s_add_u32 m0, s94, 0x3000
	s_nop 1
	global_load_lds_dwordx4 v[84:85], off
	v_lshl_add_u64 v[86:87], v[86:87], 0, s[96:97]
	s_add_u32 m0, s94, 0x7000
	s_nop 1
	global_load_lds_dwordx4 v[86:87], off
	s_waitcnt lgkmcnt(4)
	v_mfma_f32_32x32x16_bf16 v[48:63], v[98:101], v[102:105], v[48:63]
	s_waitcnt lgkmcnt(1)
	v_mfma_f32_32x32x16_bf16 v[32:47], v[98:101], v[114:117], v[32:47]
	ds_read_b128 v[98:101], v170 offset:36864
	ds_read_b128 v[122:125], v171 offset:36864
	s_waitcnt lgkmcnt(1)
	v_mfma_f32_32x32x16_bf16 v[16:31], v[98:101], v[102:105], v[16:31]
	v_mfma_f32_32x32x16_bf16 v[0:15], v[98:101], v[114:117], v[0:15]
	v_mfma_f32_32x32x16_bf16 v[48:63], v[106:109], v[110:113], v[48:63]
	v_mfma_f32_32x32x16_bf16 v[32:47], v[106:109], v[118:121], v[32:47]
	s_waitcnt lgkmcnt(0)
	v_mfma_f32_32x32x16_bf16 v[16:31], v[122:125], v[110:113], v[16:31]
	ds_read_b128 v[98:101], v172 offset:32768
	ds_read_b128 v[102:105], v176 offset:49152
	ds_read_b128 v[106:109], v173 offset:32768
	ds_read_b128 v[110:113], v177 offset:49152
	v_mfma_f32_32x32x16_bf16 v[0:15], v[122:125], v[118:121], v[0:15]
	ds_read_b128 v[114:117], v176 offset:53248
	ds_read_b128 v[118:121], v177 offset:53248
	s_waitcnt lgkmcnt(4)
	v_mfma_f32_32x32x16_bf16 v[48:63], v[98:101], v[102:105], v[48:63]
	s_waitcnt lgkmcnt(1)
	v_mfma_f32_32x32x16_bf16 v[32:47], v[98:101], v[114:117], v[32:47]
	ds_read_b128 v[98:101], v172 offset:36864
	ds_read_b128 v[122:125], v173 offset:36864
	s_waitcnt lgkmcnt(1)
	v_mfma_f32_32x32x16_bf16 v[16:31], v[98:101], v[102:105], v[16:31]
	v_mfma_f32_32x32x16_bf16 v[0:15], v[98:101], v[114:117], v[0:15]
	v_mfma_f32_32x32x16_bf16 v[48:63], v[106:109], v[110:113], v[48:63]
	v_mfma_f32_32x32x16_bf16 v[32:47], v[106:109], v[118:121], v[32:47]
	s_waitcnt lgkmcnt(0)
	v_mfma_f32_32x32x16_bf16 v[16:31], v[122:125], v[110:113], v[16:31]
	s_waitcnt vmcnt(0)
	s_barrier
	v_mfma_f32_32x32x16_bf16 v[0:15], v[122:125], v[118:121], v[0:15]
	ds_read_b128 v[98:101], v170 offset:0
	ds_read_b128 v[102:105], v174 offset:16384
	ds_read_b128 v[106:109], v171 offset:0
	ds_read_b128 v[110:113], v175 offset:16384
	ds_read_b128 v[114:117], v174 offset:20480
	ds_read_b128 v[118:121], v175 offset:20480
	v_lshl_add_u64 v[72:73], v[72:73], 0, s[96:97]
	s_add_u32 m0, s94, 0x8000
	s_nop 1
	global_load_lds_dwordx4 v[72:73], off
	v_lshl_add_u64 v[74:75], v[74:75], 0, s[96:97]
	s_add_u32 m0, s94, 0xc000
	s_nop 1
	global_load_lds_dwordx4 v[74:75], off
	v_lshl_add_u64 v[76:77], v[76:77], 0, s[96:97]
	s_add_u32 m0, s94, 0x9000
	s_nop 1
	global_load_lds_dwordx4 v[76:77], off
	v_lshl_add_u64 v[78:79], v[78:79], 0, s[96:97]
	s_add_u32 m0, s94, 0xd000
	s_nop 1
	global_load_lds_dwordx4 v[78:79], off
	v_lshl_add_u64 v[80:81], v[80:81], 0, s[96:97]
	s_add_u32 m0, s94, 0xa000
	s_nop 1
	global_load_lds_dwordx4 v[80:81], off
	v_lshl_add_u64 v[82:83], v[82:83], 0, s[96:97]
	s_add_u32 m0, s94, 0xe000
	s_nop 1
	global_load_lds_dwordx4 v[82:83], off
	v_lshl_add_u64 v[84:85], v[84:85], 0, s[96:97]
	s_add_u32 m0, s94, 0xb000
	s_nop 1
	global_load_lds_dwordx4 v[84:85], off
	v_lshl_add_u64 v[86:87], v[86:87], 0, s[96:97]
	s_add_u32 m0, s94, 0xf000
	s_nop 1
	global_load_lds_dwordx4 v[86:87], off
	s_waitcnt lgkmcnt(4)
	v_mfma_f32_32x32x16_bf16 v[48:63], v[98:101], v[102:105], v[48:63]
	s_waitcnt lgkmcnt(1)
	v_mfma_f32_32x32x16_bf16 v[32:47], v[98:101], v[114:117], v[32:47]
	ds_read_b128 v[98:101], v170 offset:4096
	ds_read_b128 v[122:125], v171 offset:4096
	s_waitcnt lgkmcnt(1)
	v_mfma_f32_32x32x16_bf16 v[16:31], v[98:101], v[102:105], v[16:31]
	v_mfma_f32_32x32x16_bf16 v[0:15], v[98:101], v[114:117], v[0:15]
	v_mfma_f32_32x32x16_bf16 v[48:63], v[106:109], v[110:113], v[48:63]
	v_mfma_f32_32x32x16_bf16 v[32:47], v[106:109], v[118:121], v[32:47]
	s_waitcnt lgkmcnt(0)
	v_mfma_f32_32x32x16_bf16 v[16:31], v[122:125], v[110:113], v[16:31]
	ds_read_b128 v[98:101], v172 offset:0
	ds_read_b128 v[102:105], v176 offset:16384
	ds_read_b128 v[106:109], v173 offset:0
	ds_read_b128 v[110:113], v177 offset:16384
	v_mfma_f32_32x32x16_bf16 v[0:15], v[122:125], v[118:121], v[0:15]
	ds_read_b128 v[114:117], v176 offset:20480
	ds_read_b128 v[118:121], v177 offset:20480
	s_waitcnt lgkmcnt(4)
	v_mfma_f32_32x32x16_bf16 v[48:63], v[98:101], v[102:105], v[48:63]
	s_waitcnt lgkmcnt(1)
	v_mfma_f32_32x32x16_bf16 v[32:47], v[98:101], v[114:117], v[32:47]
	ds_read_b128 v[98:101], v172 offset:4096
	ds_read_b128 v[122:125], v173 offset:4096
	s_waitcnt lgkmcnt(1)
	v_mfma_f32_32x32x16_bf16 v[16:31], v[98:101], v[102:105], v[16:31]
	v_mfma_f32_32x32x16_bf16 v[0:15], v[98:101], v[114:117], v[0:15]
	v_mfma_f32_32x32x16_bf16 v[48:63], v[106:109], v[110:113], v[48:63]
	v_mfma_f32_32x32x16_bf16 v[32:47], v[106:109], v[118:121], v[32:47]
	s_waitcnt lgkmcnt(0)
	v_mfma_f32_32x32x16_bf16 v[16:31], v[122:125], v[110:113], v[16:31]
	s_waitcnt vmcnt(0)
	s_barrier
;     ...
;   bf16* As1 = As + 2 * 128 * 72;
;   bf16* Bs1 = As1 + 128 * 72;
;   G_LOAD(ra0, rb0, 0);
;   if (nk > 1) G_LOAD(ra1, rb1, 1);
;   G_STORE(ra0, rb0, As, Bs);
;   __syncthreads();
;   for (int kt = 0; kt < nk; kt += 2) {
;     if (kt + 2 < nk) G_LOAD(ra0, rb0, kt + 2);
;     if (kt + 1 < nk) G_STORE(ra1, rb1, As1, Bs1);
;     G_COMPUTE(As, Bs);
;     __syncthreads();
;     if (kt + 1 < nk) {
;       if (kt + 3 < nk) G_LOAD(ra1, rb1, kt + 3);
;       if (kt + 2 < nk) G_STORE(ra0, rb0, As, Bs);
;       G_COMPUTE(As1, Bs1);
;       __syncthreads();
;     }
;   }
	v_mfma_f32_32x32x16_bf16 v[0:15], v[122:125], v[118:121], v[0:15]
	ds_read_b128 v[98:101], v170 offset:32768
	ds_read_b128 v[102:105], v174 offset:49152
	ds_read_b128 v[106:109], v171 offset:32768
	ds_read_b128 v[110:113], v175 offset:49152
	ds_read_b128 v[114:117], v174 offset:53248
	ds_read_b128 v[118:121], v175 offset:53248
	v_lshl_add_u64 v[72:73], v[72:73], 0, s[96:97]
	s_add_u32 m0, s94, 0x0
	s_nop 1
	global_load_lds_dwordx4 v[72:73], off
	v_lshl_add_u64 v[74:75], v[74:75], 0, s[96:97]
	s_add_u32 m0, s94, 0x4000
	s_nop 1
	global_load_lds_dwordx4 v[74:75], off
	v_lshl_add_u64 v[76:77], v[76:77], 0, s[96:97]
	s_add_u32 m0, s94, 0x1000
	s_nop 1
	global_load_lds_dwordx4 v[76:77], off
	v_lshl_add_u64 v[78:79], v[78:79], 0, s[96:97]
	s_add_u32 m0, s94, 0x5000
	s_nop 1
	global_load_lds_dwordx4 v[78:79], off
	v_lshl_add_u64 v[80:81], v[80:81], 0, s[96:97]
	s_add_u32 m0, s94, 0x2000
	s_nop 1
	global_load_lds_dwordx4 v[80:81], off
	v_lshl_add_u64 v[82:83], v[82:83], 0, s[96:97]
	s_add_u32 m0, s94, 0x6000
	s_nop 1
	global_load_lds_dwordx4 v[82:83], off
	v_lshl_add_u64 v[84:85], v[84:85], 0, s[96:97]
	s_add_u32 m0, s94, 0x3000
	s_nop 1
	global_load_lds_dwordx4 v[84:85], off
	v_lshl_add_u64 v[86:87], v[86:87], 0, s[96:97]
	s_add_u32 m0, s94, 0x7000
	s_nop 1
	global_load_lds_dwordx4 v[86:87], off
	s_waitcnt lgkmcnt(4)
	v_mfma_f32_32x32x16_bf16 v[48:63], v[98:101], v[102:105], v[48:63]
	s_waitcnt lgkmcnt(1)
	v_mfma_f32_32x32x16_bf16 v[32:47], v[98:101], v[114:117], v[32:47]
	ds_read_b128 v[98:101], v170 offset:36864
	ds_read_b128 v[122:125], v171 offset:36864
	s_waitcnt lgkmcnt(1)
	v_mfma_f32_32x32x16_bf16 v[16:31], v[98:101], v[102:105], v[16:31]
	v_mfma_f32_32x32x16_bf16 v[0:15], v[98:101], v[114:117], v[0:15]
	v_mfma_f32_32x32x16_bf16 v[48:63], v[106:109], v[110:113], v[48:63]
	v_mfma_f32_32x32x16_bf16 v[32:47], v[106:109], v[118:121], v[32:47]
	s_waitcnt lgkmcnt(0)
	v_mfma_f32_32x32x16_bf16 v[16:31], v[122:125], v[110:113], v[16:31]
	ds_read_b128 v[98:101], v172 offset:32768
	ds_read_b128 v[102:105], v176 offset:49152
	ds_read_b128 v[106:109], v173 offset:32768
	ds_read_b128 v[110:113], v177 offset:49152
	v_mfma_f32_32x32x16_bf16 v[0:15], v[122:125], v[118:121], v[0:15]
	ds_read_b128 v[114:117], v176 offset:53248
	ds_read_b128 v[118:121], v177 offset:53248
	s_waitcnt lgkmcnt(4)
	v_mfma_f32_32x32x16_bf16 v[48:63], v[98:101], v[102:105], v[48:63]
	s_waitcnt lgkmcnt(1)
	v_mfma_f32_32x32x16_bf16 v[32:47], v[98:101], v[114:117], v[32:47]
	ds_read_b128 v[98:101], v172 offset:36864
	ds_read_b128 v[122:125], v173 offset:36864
	s_waitcnt lgkmcnt(1)
	v_mfma_f32_32x32x16_bf16 v[16:31], v[98:101], v[102:105], v[16:31]
	v_mfma_f32_32x32x16_bf16 v[0:15], v[98:101], v[114:117], v[0:15]
	v_mfma_f32_32x32x16_bf16 v[48:63], v[106:109], v[110:113], v[48:63]
	v_mfma_f32_32x32x16_bf16 v[32:47], v[106:109], v[118:121], v[32:47]
	s_waitcnt lgkmcnt(0)
	v_mfma_f32_32x32x16_bf16 v[16:31], v[122:125], v[110:113], v[16:31]
	s_waitcnt vmcnt(0)
	s_barrier
	v_mfma_f32_32x32x16_bf16 v[0:15], v[122:125], v[118:121], v[0:15]
	ds_read_b128 v[98:101], v170 offset:0
	ds_read_b128 v[102:105], v174 offset:16384
	ds_read_b128 v[106:109], v171 offset:0
	ds_read_b128 v[110:113], v175 offset:16384
	ds_read_b128 v[114:117], v174 offset:20480
	ds_read_b128 v[118:121], v175 offset:20480
	v_lshl_add_u64 v[72:73], v[72:73], 0, s[96:97]
	s_add_u32 m0, s94, 0x8000
	s_nop 1
	global_load_lds_dwordx4 v[72:73], off
	v_lshl_add_u64 v[74:75], v[74:75], 0, s[96:97]
	s_add_u32 m0, s94, 0xc000
	s_nop 1
	global_load_lds_dwordx4 v[74:75], off
	v_lshl_add_u64 v[76:77], v[76:77], 0, s[96:97]
	s_add_u32 m0, s94, 0x9000
	s_nop 1
	global_load_lds_dwordx4 v[76:77], off
	v_lshl_add_u64 v[78:79], v[78:79], 0, s[96:97]
	s_add_u32 m0, s94, 0xd000
	s_nop 1
	global_load_lds_dwordx4 v[78:79], off
	v_lshl_add_u64 v[80:81], v[80:81], 0, s[96:97]
	s_add_u32 m0, s94, 0xa000
	s_nop 1
	global_load_lds_dwordx4 v[80:81], off
	v_lshl_add_u64 v[82:83], v[82:83], 0, s[96:97]
	s_add_u32 m0, s94, 0xe000
	s_nop 1
	global_load_lds_dwordx4 v[82:83], off
	v_lshl_add_u64 v[84:85], v[84:85], 0, s[96:97]
	s_add_u32 m0, s94, 0xb000
	s_nop 1
	global_load_lds_dwordx4 v[84:85], off
	v_lshl_add_u64 v[86:87], v[86:87], 0, s[96:97]
	s_add_u32 m0, s94, 0xf000
	s_nop 1
	global_load_lds_dwordx4 v[86:87], off
	s_waitcnt lgkmcnt(4)
	v_mfma_f32_32x32x16_bf16 v[48:63], v[98:101], v[102:105], v[48:63]
	s_waitcnt lgkmcnt(1)
	v_mfma_f32_32x32x16_bf16 v[32:47], v[98:101], v[114:117], v[32:47]
	ds_read_b128 v[98:101], v170 offset:4096
	ds_read_b128 v[122:125], v171 offset:4096
	s_waitcnt lgkmcnt(1)
	v_mfma_f32_32x32x16_bf16 v[16:31], v[98:101], v[102:105], v[16:31]
	v_mfma_f32_32x32x16_bf16 v[0:15], v[98:101], v[114:117], v[0:15]
	v_mfma_f32_32x32x16_bf16 v[48:63], v[106:109], v[110:113], v[48:63]
	v_mfma_f32_32x32x16_bf16 v[32:47], v[106:109], v[118:121], v[32:47]
	s_waitcnt lgkmcnt(0)
	v_mfma_f32_32x32x16_bf16 v[16:31], v[122:125], v[110:113], v[16:31]
	ds_read_b128 v[98:101], v172 offset:0
	ds_read_b128 v[102:105], v176 offset:16384
	ds_read_b128 v[106:109], v173 offset:0
	ds_read_b128 v[110:113], v177 offset:16384
	v_mfma_f32_32x32x16_bf16 v[0:15], v[122:125], v[118:121], v[0:15]
	ds_read_b128 v[114:117], v176 offset:20480
	ds_read_b128 v[118:121], v177 offset:20480
	s_waitcnt lgkmcnt(4)
	v_mfma_f32_32x32x16_bf16 v[48:63], v[98:101], v[102:105], v[48:63]
	s_waitcnt lgkmcnt(1)
	v_mfma_f32_32x32x16_bf16 v[32:47], v[98:101], v[114:117], v[32:47]
	ds_read_b128 v[98:101], v172 offset:4096
	ds_read_b128 v[122:125], v173 offset:4096
	s_waitcnt lgkmcnt(1)
	v_mfma_f32_32x32x16_bf16 v[16:31], v[98:101], v[102:105], v[16:31]
	v_mfma_f32_32x32x16_bf16 v[0:15], v[98:101], v[114:117], v[0:15]
	v_mfma_f32_32x32x16_bf16 v[48:63], v[106:109], v[110:113], v[48:63]
	v_mfma_f32_32x32x16_bf16 v[32:47], v[106:109], v[118:121], v[32:47]
	s_waitcnt lgkmcnt(0)
	v_mfma_f32_32x32x16_bf16 v[16:31], v[122:125], v[110:113], v[16:31]
	s_waitcnt vmcnt(0)
	s_barrier
;     ...
;   bf16* As1 = As + 2 * 128 * 72;
;   bf16* Bs1 = As1 + 128 * 72;
;   G_LOAD(ra0, rb0, 0);
;   if (nk > 1) G_LOAD(ra1, rb1, 1);
;   G_STORE(ra0, rb0, As, Bs);
;   __syncthreads();
;   for (int kt = 0; kt < nk; kt += 2) {
;     if (kt + 2 < nk) G_LOAD(ra0, rb0, kt + 2);
;     if (kt + 1 < nk) G_STORE(ra1, rb1, As1, Bs1);
;     G_COMPUTE(As, Bs);
;     __syncthreads();
;     if (kt + 1 < nk) {
;       if (kt + 3 < nk) G_LOAD(ra1, rb1, kt + 3);
;       if (kt + 2 < nk) G_STORE(ra0, rb0, As, Bs);
;       G_COMPUTE(As1, Bs1);
;       __syncthreads();
;     }
;   }
	v_mfma_f32_32x32x16_bf16 v[0:15], v[122:125], v[118:121], v[0:15]
	ds_read_b128 v[98:101], v170 offset:32768
	ds_read_b128 v[102:105], v174 offset:49152
	ds_read_b128 v[106:109], v171 offset:32768
	ds_read_b128 v[110:113], v175 offset:49152
	ds_read_b128 v[114:117], v174 offset:53248
	ds_read_b128 v[118:121], v175 offset:53248
	v_lshl_add_u64 v[72:73], v[72:73], 0, s[96:97]
	s_add_u32 m0, s94, 0x0
	s_nop 1
	global_load_lds_dwordx4 v[72:73], off
	v_lshl_add_u64 v[74:75], v[74:75], 0, s[96:97]
	s_add_u32 m0, s94, 0x4000
	s_nop 1
	global_load_lds_dwordx4 v[74:75], off
	v_lshl_add_u64 v[76:77], v[76:77], 0, s[96:97]
	s_add_u32 m0, s94, 0x1000
	s_nop 1
	global_load_lds_dwordx4 v[76:77], off
	v_lshl_add_u64 v[78:79], v[78:79], 0, s[96:97]
	s_add_u32 m0, s94, 0x5000
	s_nop 1
	global_load_lds_dwordx4 v[78:79], off
	v_lshl_add_u64 v[80:81], v[80:81], 0, s[96:97]
	s_add_u32 m0, s94, 0x2000
	s_nop 1
	global_load_lds_dwordx4 v[80:81], off
	v_lshl_add_u64 v[82:83], v[82:83], 0, s[96:97]
	s_add_u32 m0, s94, 0x6000
	s_nop 1
	global_load_lds_dwordx4 v[82:83], off
	v_lshl_add_u64 v[84:85], v[84:85], 0, s[96:97]
	s_add_u32 m0, s94, 0x3000
	s_nop 1
	global_load_lds_dwordx4 v[84:85], off
	v_lshl_add_u64 v[86:87], v[86:87], 0, s[96:97]
	s_add_u32 m0, s94, 0x7000
	s_nop 1
	global_load_lds_dwordx4 v[86:87], off
	s_waitcnt lgkmcnt(4)
	v_mfma_f32_32x32x16_bf16 v[48:63], v[98:101], v[102:105], v[48:63]
	s_waitcnt lgkmcnt(1)
	v_mfma_f32_32x32x16_bf16 v[32:47], v[98:101], v[114:117], v[32:47]
	ds_read_b128 v[98:101], v170 offset:36864
	ds_read_b128 v[122:125], v171 offset:36864
	s_waitcnt lgkmcnt(1)
	v_mfma_f32_32x32x16_bf16 v[16:31], v[98:101], v[102:105], v[16:31]
	v_mfma_f32_32x32x16_bf16 v[0:15], v[98:101], v[114:117], v[0:15]
	v_mfma_f32_32x32x16_bf16 v[48:63], v[106:109], v[110:113], v[48:63]
	v_mfma_f32_32x32x16_bf16 v[32:47], v[106:109], v[118:121], v[32:47]
	s_waitcnt lgkmcnt(0)
	v_mfma_f32_32x32x16_bf16 v[16:31], v[122:125], v[110:113], v[16:31]
	ds_read_b128 v[98:101], v172 offset:32768
	ds_read_b128 v[102:105], v176 offset:49152
	ds_read_b128 v[106:109], v173 offset:32768
	ds_read_b128 v[110:113], v177 offset:49152
	v_mfma_f32_32x32x16_bf16 v[0:15], v[122:125], v[118:121], v[0:15]
	ds_read_b128 v[114:117], v176 offset:53248
	ds_read_b128 v[118:121], v177 offset:53248
	s_waitcnt lgkmcnt(4)
	v_mfma_f32_32x32x16_bf16 v[48:63], v[98:101], v[102:105], v[48:63]
	s_waitcnt lgkmcnt(1)
	v_mfma_f32_32x32x16_bf16 v[32:47], v[98:101], v[114:117], v[32:47]
	ds_read_b128 v[98:101], v172 offset:36864
	ds_read_b128 v[122:125], v173 offset:36864
	s_waitcnt lgkmcnt(1)
	v_mfma_f32_32x32x16_bf16 v[16:31], v[98:101], v[102:105], v[16:31]
	v_mfma_f32_32x32x16_bf16 v[0:15], v[98:101], v[114:117], v[0:15]
	v_mfma_f32_32x32x16_bf16 v[48:63], v[106:109], v[110:113], v[48:63]
	v_mfma_f32_32x32x16_bf16 v[32:47], v[106:109], v[118:121], v[32:47]
	s_waitcnt lgkmcnt(0)
	v_mfma_f32_32x32x16_bf16 v[16:31], v[122:125], v[110:113], v[16:31]
	s_waitcnt vmcnt(0)
	s_barrier
	v_mfma_f32_32x32x16_bf16 v[0:15], v[122:125], v[118:121], v[0:15]
	ds_read_b128 v[98:101], v170 offset:0
	ds_read_b128 v[102:105], v174 offset:16384
	ds_read_b128 v[106:109], v171 offset:0
	ds_read_b128 v[110:113], v175 offset:16384
	ds_read_b128 v[114:117], v174 offset:20480
	ds_read_b128 v[118:121], v175 offset:20480
	v_lshl_add_u64 v[72:73], v[72:73], 0, s[96:97]
	s_add_u32 m0, s94, 0x8000
	s_nop 1
	global_load_lds_dwordx4 v[72:73], off
	v_lshl_add_u64 v[74:75], v[74:75], 0, s[96:97]
	s_add_u32 m0, s94, 0xc000
	s_nop 1
	global_load_lds_dwordx4 v[74:75], off
	v_lshl_add_u64 v[76:77], v[76:77], 0, s[96:97]
	s_add_u32 m0, s94, 0x9000
	s_nop 1
	global_load_lds_dwordx4 v[76:77], off
	v_lshl_add_u64 v[78:79], v[78:79], 0, s[96:97]
	s_add_u32 m0, s94, 0xd000
	s_nop 1
	global_load_lds_dwordx4 v[78:79], off
	v_lshl_add_u64 v[80:81], v[80:81], 0, s[96:97]
	s_add_u32 m0, s94, 0xa000
	s_nop 1
	global_load_lds_dwordx4 v[80:81], off
	v_lshl_add_u64 v[82:83], v[82:83], 0, s[96:97]
	s_add_u32 m0, s94, 0xe000
	s_nop 1
	global_load_lds_dwordx4 v[82:83], off
	v_lshl_add_u64 v[84:85], v[84:85], 0, s[96:97]
	s_add_u32 m0, s94, 0xb000
	s_nop 1
	global_load_lds_dwordx4 v[84:85], off
	v_lshl_add_u64 v[86:87], v[86:87], 0, s[96:97]
	s_add_u32 m0, s94, 0xf000
	s_nop 1
	global_load_lds_dwordx4 v[86:87], off
	s_waitcnt lgkmcnt(4)
	v_mfma_f32_32x32x16_bf16 v[48:63], v[98:101], v[102:105], v[48:63]
	s_waitcnt lgkmcnt(1)
	v_mfma_f32_32x32x16_bf16 v[32:47], v[98:101], v[114:117], v[32:47]
	ds_read_b128 v[98:101], v170 offset:4096
	ds_read_b128 v[122:125], v171 offset:4096
	s_waitcnt lgkmcnt(1)
	v_mfma_f32_32x32x16_bf16 v[16:31], v[98:101], v[102:105], v[16:31]
	v_mfma_f32_32x32x16_bf16 v[0:15], v[98:101], v[114:117], v[0:15]
	v_mfma_f32_32x32x16_bf16 v[48:63], v[106:109], v[110:113], v[48:63]
	v_mfma_f32_32x32x16_bf16 v[32:47], v[106:109], v[118:121], v[32:47]
	s_waitcnt lgkmcnt(0)
	v_mfma_f32_32x32x16_bf16 v[16:31], v[122:125], v[110:113], v[16:31]
	ds_read_b128 v[98:101], v172 offset:0
	ds_read_b128 v[102:105], v176 offset:16384
	ds_read_b128 v[106:109], v173 offset:0
	ds_read_b128 v[110:113], v177 offset:16384
	v_mfma_f32_32x32x16_bf16 v[0:15], v[122:125], v[118:121], v[0:15]
	ds_read_b128 v[114:117], v176 offset:20480
	ds_read_b128 v[118:121], v177 offset:20480
	s_waitcnt lgkmcnt(4)
	v_mfma_f32_32x32x16_bf16 v[48:63], v[98:101], v[102:105], v[48:63]
	s_waitcnt lgkmcnt(1)
	v_mfma_f32_32x32x16_bf16 v[32:47], v[98:101], v[114:117], v[32:47]
	ds_read_b128 v[98:101], v172 offset:4096
	ds_read_b128 v[122:125], v173 offset:4096
	s_waitcnt lgkmcnt(1)
	v_mfma_f32_32x32x16_bf16 v[16:31], v[98:101], v[102:105], v[16:31]
	v_mfma_f32_32x32x16_bf16 v[0:15], v[98:101], v[114:117], v[0:15]
	v_mfma_f32_32x32x16_bf16 v[48:63], v[106:109], v[110:113], v[48:63]
	v_mfma_f32_32x32x16_bf16 v[32:47], v[106:109], v[118:121], v[32:47]
	s_waitcnt lgkmcnt(0)
	v_mfma_f32_32x32x16_bf16 v[16:31], v[122:125], v[110:113], v[16:31]
	s_waitcnt vmcnt(0)
	s_barrier
;     ...
;   bf16* As1 = As + 2 * 128 * 72;
;   bf16* Bs1 = As1 + 128 * 72;
;   G_LOAD(ra0, rb0, 0);
;   if (nk > 1) G_LOAD(ra1, rb1, 1);
;   G_STORE(ra0, rb0, As, Bs);
;   __syncthreads();
;   for (int kt = 0; kt < nk; kt += 2) {
;     if (kt + 2 < nk) G_LOAD(ra0, rb0, kt + 2);
;     if (kt + 1 < nk) G_STORE(ra1, rb1, As1, Bs1);
;     G_COMPUTE(As, Bs);
;     __syncthreads();
;     if (kt + 1 < nk) {
;       if (kt + 3 < nk) G_LOAD(ra1, rb1, kt + 3);
;       if (kt + 2 < nk) G_STORE(ra0, rb0, As, Bs);
;       G_COMPUTE(As1, Bs1);
;       __syncthreads();
;     }
;   }
	v_mfma_f32_32x32x16_bf16 v[0:15], v[122:125], v[118:121], v[0:15]
	ds_read_b128 v[98:101], v170 offset:32768
	ds_read_b128 v[102:105], v174 offset:49152
	ds_read_b128 v[106:109], v171 offset:32768
	ds_read_b128 v[110:113], v175 offset:49152
	ds_read_b128 v[114:117], v174 offset:53248
	ds_read_b128 v[118:121], v175 offset:53248
	v_lshl_add_u64 v[72:73], v[72:73], 0, s[96:97]
	s_add_u32 m0, s94, 0x0
	s_nop 1
	global_load_lds_dwordx4 v[72:73], off
	v_lshl_add_u64 v[74:75], v[74:75], 0, s[96:97]
	s_add_u32 m0, s94, 0x4000
	s_nop 1
	global_load_lds_dwordx4 v[74:75], off
	v_lshl_add_u64 v[76:77], v[76:77], 0, s[96:97]
	s_add_u32 m0, s94, 0x1000
	s_nop 1
	global_load_lds_dwordx4 v[76:77], off
	v_lshl_add_u64 v[78:79], v[78:79], 0, s[96:97]
	s_add_u32 m0, s94, 0x5000
	s_nop 1
	global_load_lds_dwordx4 v[78:79], off
	v_lshl_add_u64 v[80:81], v[80:81], 0, s[96:97]
	s_add_u32 m0, s94, 0x2000
	s_nop 1
	global_load_lds_dwordx4 v[80:81], off
	v_lshl_add_u64 v[82:83], v[82:83], 0, s[96:97]
	s_add_u32 m0, s94, 0x6000
	s_nop 1
	global_load_lds_dwordx4 v[82:83], off
	v_lshl_add_u64 v[84:85], v[84:85], 0, s[96:97]
	s_add_u32 m0, s94, 0x3000
	s_nop 1
	global_load_lds_dwordx4 v[84:85], off
	v_lshl_add_u64 v[86:87], v[86:87], 0, s[96:97]
	s_add_u32 m0, s94, 0x7000
	s_nop 1
	global_load_lds_dwordx4 v[86:87], off
	s_waitcnt lgkmcnt(4)
	v_mfma_f32_32x32x16_bf16 v[48:63], v[98:101], v[102:105], v[48:63]
	s_waitcnt lgkmcnt(1)
	v_mfma_f32_32x32x16_bf16 v[32:47], v[98:101], v[114:117], v[32:47]
	ds_read_b128 v[98:101], v170 offset:36864
	ds_read_b128 v[122:125], v171 offset:36864
	s_waitcnt lgkmcnt(1)
	v_mfma_f32_32x32x16_bf16 v[16:31], v[98:101], v[102:105], v[16:31]
	v_mfma_f32_32x32x16_bf16 v[0:15], v[98:101], v[114:117], v[0:15]
	v_mfma_f32_32x32x16_bf16 v[48:63], v[106:109], v[110:113], v[48:63]
	v_mfma_f32_32x32x16_bf16 v[32:47], v[106:109], v[118:121], v[32:47]
	s_waitcnt lgkmcnt(0)
	v_mfma_f32_32x32x16_bf16 v[16:31], v[122:125], v[110:113], v[16:31]
	ds_read_b128 v[98:101], v172 offset:32768
	ds_read_b128 v[102:105], v176 offset:49152
	ds_read_b128 v[106:109], v173 offset:32768
	ds_read_b128 v[110:113], v177 offset:49152
	v_mfma_f32_32x32x16_bf16 v[0:15], v[122:125], v[118:121], v[0:15]
	ds_read_b128 v[114:117], v176 offset:53248
	ds_read_b128 v[118:121], v177 offset:53248
	s_waitcnt lgkmcnt(4)
	v_mfma_f32_32x32x16_bf16 v[48:63], v[98:101], v[102:105], v[48:63]
	s_waitcnt lgkmcnt(1)
	v_mfma_f32_32x32x16_bf16 v[32:47], v[98:101], v[114:117], v[32:47]
	ds_read_b128 v[98:101], v172 offset:36864
	ds_read_b128 v[122:125], v173 offset:36864
	s_waitcnt lgkmcnt(1)
	v_mfma_f32_32x32x16_bf16 v[16:31], v[98:101], v[102:105], v[16:31]
	v_mfma_f32_32x32x16_bf16 v[0:15], v[98:101], v[114:117], v[0:15]
	v_mfma_f32_32x32x16_bf16 v[48:63], v[106:109], v[110:113], v[48:63]
	v_mfma_f32_32x32x16_bf16 v[32:47], v[106:109], v[118:121], v[32:47]
	s_waitcnt lgkmcnt(0)
	v_mfma_f32_32x32x16_bf16 v[16:31], v[122:125], v[110:113], v[16:31]
	s_waitcnt vmcnt(0)
	s_barrier
	v_mfma_f32_32x32x16_bf16 v[0:15], v[122:125], v[118:121], v[0:15]
	ds_read_b128 v[98:101], v170 offset:0
	ds_read_b128 v[102:105], v174 offset:16384
	ds_read_b128 v[106:109], v171 offset:0
	ds_read_b128 v[110:113], v175 offset:16384
	ds_read_b128 v[114:117], v174 offset:20480
	ds_read_b128 v[118:121], v175 offset:20480
	v_lshl_add_u64 v[72:73], v[72:73], 0, s[96:97]
	s_add_u32 m0, s94, 0x8000
	s_nop 1
	global_load_lds_dwordx4 v[72:73], off
	v_lshl_add_u64 v[74:75], v[74:75], 0, s[96:97]
	s_add_u32 m0, s94, 0xc000
	s_nop 1
	global_load_lds_dwordx4 v[74:75], off
	v_lshl_add_u64 v[76:77], v[76:77], 0, s[96:97]
	s_add_u32 m0, s94, 0x9000
	s_nop 1
	global_load_lds_dwordx4 v[76:77], off
	v_lshl_add_u64 v[78:79], v[78:79], 0, s[96:97]
	s_add_u32 m0, s94, 0xd000
	s_nop 1
	global_load_lds_dwordx4 v[78:79], off
	v_lshl_add_u64 v[80:81], v[80:81], 0, s[96:97]
	s_add_u32 m0, s94, 0xa000
	s_nop 1
	global_load_lds_dwordx4 v[80:81], off
	v_lshl_add_u64 v[82:83], v[82:83], 0, s[96:97]
	s_add_u32 m0, s94, 0xe000
	s_nop 1
	global_load_lds_dwordx4 v[82:83], off
	v_lshl_add_u64 v[84:85], v[84:85], 0, s[96:97]
	s_add_u32 m0, s94, 0xb000
	s_nop 1
	global_load_lds_dwordx4 v[84:85], off
	v_lshl_add_u64 v[86:87], v[86:87], 0, s[96:97]
	s_add_u32 m0, s94, 0xf000
	s_nop 1
	global_load_lds_dwordx4 v[86:87], off
	s_waitcnt lgkmcnt(4)
	v_mfma_f32_32x32x16_bf16 v[48:63], v[98:101], v[102:105], v[48:63]
	s_waitcnt lgkmcnt(1)
	v_mfma_f32_32x32x16_bf16 v[32:47], v[98:101], v[114:117], v[32:47]
	ds_read_b128 v[98:101], v170 offset:4096
	ds_read_b128 v[122:125], v171 offset:4096
	s_waitcnt lgkmcnt(1)
	v_mfma_f32_32x32x16_bf16 v[16:31], v[98:101], v[102:105], v[16:31]
	v_mfma_f32_32x32x16_bf16 v[0:15], v[98:101], v[114:117], v[0:15]
	v_mfma_f32_32x32x16_bf16 v[48:63], v[106:109], v[110:113], v[48:63]
	v_mfma_f32_32x32x16_bf16 v[32:47], v[106:109], v[118:121], v[32:47]
	s_waitcnt lgkmcnt(0)
	v_mfma_f32_32x32x16_bf16 v[16:31], v[122:125], v[110:113], v[16:31]
	ds_read_b128 v[98:101], v172 offset:0
	ds_read_b128 v[102:105], v176 offset:16384
	ds_read_b128 v[106:109], v173 offset:0
	ds_read_b128 v[110:113], v177 offset:16384
	v_mfma_f32_32x32x16_bf16 v[0:15], v[122:125], v[118:121], v[0:15]
	ds_read_b128 v[114:117], v176 offset:20480
	ds_read_b128 v[118:121], v177 offset:20480
	s_waitcnt lgkmcnt(4)
	v_mfma_f32_32x32x16_bf16 v[48:63], v[98:101], v[102:105], v[48:63]
	s_waitcnt lgkmcnt(1)
	v_mfma_f32_32x32x16_bf16 v[32:47], v[98:101], v[114:117], v[32:47]
	ds_read_b128 v[98:101], v172 offset:4096
	ds_read_b128 v[122:125], v173 offset:4096
	s_waitcnt lgkmcnt(1)
	v_mfma_f32_32x32x16_bf16 v[16:31], v[98:101], v[102:105], v[16:31]
	v_mfma_f32_32x32x16_bf16 v[0:15], v[98:101], v[114:117], v[0:15]
	v_mfma_f32_32x32x16_bf16 v[48:63], v[106:109], v[110:113], v[48:63]
	v_mfma_f32_32x32x16_bf16 v[32:47], v[106:109], v[118:121], v[32:47]
	s_waitcnt lgkmcnt(0)
	v_mfma_f32_32x32x16_bf16 v[16:31], v[122:125], v[110:113], v[16:31]
	s_waitcnt vmcnt(0)
	s_barrier
;     ...
;   bf16* As1 = As + 2 * 128 * 72;
;   bf16* Bs1 = As1 + 128 * 72;
;   G_LOAD(ra0, rb0, 0);
;   if (nk > 1) G_LOAD(ra1, rb1, 1);
;   G_STORE(ra0, rb0, As, Bs);
;   __syncthreads();
;   for (int kt = 0; kt < nk; kt += 2) {
;     if (kt + 2 < nk) G_LOAD(ra0, rb0, kt + 2);
;     if (kt + 1 < nk) G_STORE(ra1, rb1, As1, Bs1);
;     G_COMPUTE(As, Bs);
;     __syncthreads();
;     if (kt + 1 < nk) {
;       if (kt + 3 < nk) G_LOAD(ra1, rb1, kt + 3);
;       if (kt + 2 < nk) G_STORE(ra0, rb0, As, Bs);
;       G_COMPUTE(As1, Bs1);
;       __syncthreads();
;     }
;   }
	v_mfma_f32_32x32x16_bf16 v[0:15], v[122:125], v[118:121], v[0:15]
	ds_read_b128 v[98:101], v170 offset:32768
	ds_read_b128 v[102:105], v174 offset:49152
	ds_read_b128 v[106:109], v171 offset:32768
	ds_read_b128 v[110:113], v175 offset:49152
	ds_read_b128 v[114:117], v174 offset:53248
	ds_read_b128 v[118:121], v175 offset:53248
	v_lshl_add_u64 v[72:73], v[72:73], 0, s[96:97]
	s_add_u32 m0, s94, 0x0
	s_nop 1
	global_load_lds_dwordx4 v[72:73], off
	v_lshl_add_u64 v[74:75], v[74:75], 0, s[96:97]
	s_add_u32 m0, s94, 0x4000
	s_nop 1
	global_load_lds_dwordx4 v[74:75], off
	v_lshl_add_u64 v[76:77], v[76:77], 0, s[96:97]
	s_add_u32 m0, s94, 0x1000
	s_nop 1
	global_load_lds_dwordx4 v[76:77], off
	v_lshl_add_u64 v[78:79], v[78:79], 0, s[96:97]
	s_add_u32 m0, s94, 0x5000
	s_nop 1
	global_load_lds_dwordx4 v[78:79], off
	v_lshl_add_u64 v[80:81], v[80:81], 0, s[96:97]
	s_add_u32 m0, s94, 0x2000
	s_nop 1
	global_load_lds_dwordx4 v[80:81], off
	v_lshl_add_u64 v[82:83], v[82:83], 0, s[96:97]
	s_add_u32 m0, s94, 0x6000
	s_nop 1
	global_load_lds_dwordx4 v[82:83], off
	v_lshl_add_u64 v[84:85], v[84:85], 0, s[96:97]
	s_add_u32 m0, s94, 0x3000
	s_nop 1
	global_load_lds_dwordx4 v[84:85], off
	v_lshl_add_u64 v[86:87], v[86:87], 0, s[96:97]
	s_add_u32 m0, s94, 0x7000
	s_nop 1
	global_load_lds_dwordx4 v[86:87], off
	s_waitcnt lgkmcnt(4)
	v_mfma_f32_32x32x16_bf16 v[48:63], v[98:101], v[102:105], v[48:63]
	s_waitcnt lgkmcnt(1)
	v_mfma_f32_32x32x16_bf16 v[32:47], v[98:101], v[114:117], v[32:47]
	ds_read_b128 v[98:101], v170 offset:36864
	ds_read_b128 v[122:125], v171 offset:36864
	s_waitcnt lgkmcnt(1)
	v_mfma_f32_32x32x16_bf16 v[16:31], v[98:101], v[102:105], v[16:31]
	v_mfma_f32_32x32x16_bf16 v[0:15], v[98:101], v[114:117], v[0:15]
	v_mfma_f32_32x32x16_bf16 v[48:63], v[106:109], v[110:113], v[48:63]
	v_mfma_f32_32x32x16_bf16 v[32:47], v[106:109], v[118:121], v[32:47]
	s_waitcnt lgkmcnt(0)
	v_mfma_f32_32x32x16_bf16 v[16:31], v[122:125], v[110:113], v[16:31]
	ds_read_b128 v[98:101], v172 offset:32768
	ds_read_b128 v[102:105], v176 offset:49152
	ds_read_b128 v[106:109], v173 offset:32768
	ds_read_b128 v[110:113], v177 offset:49152
	v_mfma_f32_32x32x16_bf16 v[0:15], v[122:125], v[118:121], v[0:15]
	ds_read_b128 v[114:117], v176 offset:53248
	ds_read_b128 v[118:121], v177 offset:53248
	s_waitcnt lgkmcnt(4)
	v_mfma_f32_32x32x16_bf16 v[48:63], v[98:101], v[102:105], v[48:63]
	s_waitcnt lgkmcnt(1)
	v_mfma_f32_32x32x16_bf16 v[32:47], v[98:101], v[114:117], v[32:47]
	ds_read_b128 v[98:101], v172 offset:36864
	ds_read_b128 v[122:125], v173 offset:36864
	s_waitcnt lgkmcnt(1)
	v_mfma_f32_32x32x16_bf16 v[16:31], v[98:101], v[102:105], v[16:31]
	v_mfma_f32_32x32x16_bf16 v[0:15], v[98:101], v[114:117], v[0:15]
	v_mfma_f32_32x32x16_bf16 v[48:63], v[106:109], v[110:113], v[48:63]
	v_mfma_f32_32x32x16_bf16 v[32:47], v[106:109], v[118:121], v[32:47]
	s_waitcnt lgkmcnt(0)
	v_mfma_f32_32x32x16_bf16 v[16:31], v[122:125], v[110:113], v[16:31]
	s_waitcnt vmcnt(0)
	s_barrier
	v_mfma_f32_32x32x16_bf16 v[0:15], v[122:125], v[118:121], v[0:15]
	ds_read_b128 v[98:101], v170 offset:0
	ds_read_b128 v[102:105], v174 offset:16384
	ds_read_b128 v[106:109], v171 offset:0
	ds_read_b128 v[110:113], v175 offset:16384
	ds_read_b128 v[114:117], v174 offset:20480
	ds_read_b128 v[118:121], v175 offset:20480
	v_lshl_add_u64 v[72:73], v[72:73], 0, s[96:97]
	s_add_u32 m0, s94, 0x8000
	s_nop 1
	global_load_lds_dwordx4 v[72:73], off
	v_lshl_add_u64 v[74:75], v[74:75], 0, s[96:97]
	s_add_u32 m0, s94, 0xc000
	s_nop 1
	global_load_lds_dwordx4 v[74:75], off
	v_lshl_add_u64 v[76:77], v[76:77], 0, s[96:97]
	s_add_u32 m0, s94, 0x9000
	s_nop 1
	global_load_lds_dwordx4 v[76:77], off
	v_lshl_add_u64 v[78:79], v[78:79], 0, s[96:97]
	s_add_u32 m0, s94, 0xd000
	s_nop 1
	global_load_lds_dwordx4 v[78:79], off
	v_lshl_add_u64 v[80:81], v[80:81], 0, s[96:97]
	s_add_u32 m0, s94, 0xa000
	s_nop 1
	global_load_lds_dwordx4 v[80:81], off
	v_lshl_add_u64 v[82:83], v[82:83], 0, s[96:97]
	s_add_u32 m0, s94, 0xe000
	s_nop 1
	global_load_lds_dwordx4 v[82:83], off
	v_lshl_add_u64 v[84:85], v[84:85], 0, s[96:97]
	s_add_u32 m0, s94, 0xb000
	s_nop 1
	global_load_lds_dwordx4 v[84:85], off
	v_lshl_add_u64 v[86:87], v[86:87], 0, s[96:97]
	s_add_u32 m0, s94, 0xf000
	s_nop 1
	global_load_lds_dwordx4 v[86:87], off
	s_waitcnt lgkmcnt(4)
	v_mfma_f32_32x32x16_bf16 v[48:63], v[98:101], v[102:105], v[48:63]
	s_waitcnt lgkmcnt(1)
	v_mfma_f32_32x32x16_bf16 v[32:47], v[98:101], v[114:117], v[32:47]
	ds_read_b128 v[98:101], v170 offset:4096
	ds_read_b128 v[122:125], v171 offset:4096
	s_waitcnt lgkmcnt(1)
	v_mfma_f32_32x32x16_bf16 v[16:31], v[98:101], v[102:105], v[16:31]
	v_mfma_f32_32x32x16_bf16 v[0:15], v[98:101], v[114:117], v[0:15]
	v_mfma_f32_32x32x16_bf16 v[48:63], v[106:109], v[110:113], v[48:63]
	v_mfma_f32_32x32x16_bf16 v[32:47], v[106:109], v[118:121], v[32:47]
	s_waitcnt lgkmcnt(0)
	v_mfma_f32_32x32x16_bf16 v[16:31], v[122:125], v[110:113], v[16:31]
	ds_read_b128 v[98:101], v172 offset:0
	ds_read_b128 v[102:105], v176 offset:16384
	ds_read_b128 v[106:109], v173 offset:0
	ds_read_b128 v[110:113], v177 offset:16384
	v_mfma_f32_32x32x16_bf16 v[0:15], v[122:125], v[118:121], v[0:15]
	ds_read_b128 v[114:117], v176 offset:20480
	ds_read_b128 v[118:121], v177 offset:20480
	s_waitcnt lgkmcnt(4)
	v_mfma_f32_32x32x16_bf16 v[48:63], v[98:101], v[102:105], v[48:63]
	s_waitcnt lgkmcnt(1)
	v_mfma_f32_32x32x16_bf16 v[32:47], v[98:101], v[114:117], v[32:47]
	ds_read_b128 v[98:101], v172 offset:4096
	ds_read_b128 v[122:125], v173 offset:4096
	s_waitcnt lgkmcnt(1)
	v_mfma_f32_32x32x16_bf16 v[16:31], v[98:101], v[102:105], v[16:31]
	v_mfma_f32_32x32x16_bf16 v[0:15], v[98:101], v[114:117], v[0:15]
	v_mfma_f32_32x32x16_bf16 v[48:63], v[106:109], v[110:113], v[48:63]
	v_mfma_f32_32x32x16_bf16 v[32:47], v[106:109], v[118:121], v[32:47]
	s_waitcnt lgkmcnt(0)
	v_mfma_f32_32x32x16_bf16 v[16:31], v[122:125], v[110:113], v[16:31]
	s_waitcnt vmcnt(0)
	s_barrier
;     ...
;   bf16* As1 = As + 2 * 128 * 72;
;   bf16* Bs1 = As1 + 128 * 72;
;   G_LOAD(ra0, rb0, 0);
;   if (nk > 1) G_LOAD(ra1, rb1, 1);
;   G_STORE(ra0, rb0, As, Bs);
;   __syncthreads();
;   for (int kt = 0; kt < nk; kt += 2) {
;     if (kt + 2 < nk) G_LOAD(ra0, rb0, kt + 2);
;     if (kt + 1 < nk) G_STORE(ra1, rb1, As1, Bs1);
;     G_COMPUTE(As, Bs);
;     __syncthreads();
;     if (kt + 1 < nk) {
;       if (kt + 3 < nk) G_LOAD(ra1, rb1, kt + 3);
;       if (kt + 2 < nk) G_STORE(ra0, rb0, As, Bs);
;       G_COMPUTE(As1, Bs1);
;       __syncthreads();
;     }
;   }
	v_mfma_f32_32x32x16_bf16 v[0:15], v[122:125], v[118:121], v[0:15]
	ds_read_b128 v[98:101], v170 offset:32768
	ds_read_b128 v[102:105], v174 offset:49152
	ds_read_b128 v[106:109], v171 offset:32768
	ds_read_b128 v[110:113], v175 offset:49152
	ds_read_b128 v[114:117], v174 offset:53248
	ds_read_b128 v[118:121], v175 offset:53248
	v_lshl_add_u64 v[72:73], v[72:73], 0, s[96:97]
	s_add_u32 m0, s94, 0x0
	s_nop 1
	global_load_lds_dwordx4 v[72:73], off
	v_lshl_add_u64 v[74:75], v[74:75], 0, s[96:97]
	s_add_u32 m0, s94, 0x4000
	s_nop 1
	global_load_lds_dwordx4 v[74:75], off
	v_lshl_add_u64 v[76:77], v[76:77], 0, s[96:97]
	s_add_u32 m0, s94, 0x1000
	s_nop 1
	global_load_lds_dwordx4 v[76:77], off
	v_lshl_add_u64 v[78:79], v[78:79], 0, s[96:97]
	s_add_u32 m0, s94, 0x5000
	s_nop 1
	global_load_lds_dwordx4 v[78:79], off
	v_lshl_add_u64 v[80:81], v[80:81], 0, s[96:97]
	s_add_u32 m0, s94, 0x2000
	s_nop 1
	global_load_lds_dwordx4 v[80:81], off
	v_lshl_add_u64 v[82:83], v[82:83], 0, s[96:97]
	s_add_u32 m0, s94, 0x6000
	s_nop 1
	global_load_lds_dwordx4 v[82:83], off
	v_lshl_add_u64 v[84:85], v[84:85], 0, s[96:97]
	s_add_u32 m0, s94, 0x3000
	s_nop 1
	global_load_lds_dwordx4 v[84:85], off
	v_lshl_add_u64 v[86:87], v[86:87], 0, s[96:97]
	s_add_u32 m0, s94, 0x7000
	s_nop 1
	global_load_lds_dwordx4 v[86:87], off
	s_waitcnt lgkmcnt(4)
	v_mfma_f32_32x32x16_bf16 v[48:63], v[98:101], v[102:105], v[48:63]
	s_waitcnt lgkmcnt(1)
	v_mfma_f32_32x32x16_bf16 v[32:47], v[98:101], v[114:117], v[32:47]
	ds_read_b128 v[98:101], v170 offset:36864
	ds_read_b128 v[122:125], v171 offset:36864
	s_waitcnt lgkmcnt(1)
	v_mfma_f32_32x32x16_bf16 v[16:31], v[98:101], v[102:105], v[16:31]
	v_mfma_f32_32x32x16_bf16 v[0:15], v[98:101], v[114:117], v[0:15]
	v_mfma_f32_32x32x16_bf16 v[48:63], v[106:109], v[110:113], v[48:63]
	v_mfma_f32_32x32x16_bf16 v[32:47], v[106:109], v[118:121], v[32:47]
	s_waitcnt lgkmcnt(0)
	v_mfma_f32_32x32x16_bf16 v[16:31], v[122:125], v[110:113], v[16:31]
	ds_read_b128 v[98:101], v172 offset:32768
	ds_read_b128 v[102:105], v176 offset:49152
	ds_read_b128 v[106:109], v173 offset:32768
	ds_read_b128 v[110:113], v177 offset:49152
	v_mfma_f32_32x32x16_bf16 v[0:15], v[122:125], v[118:121], v[0:15]
	ds_read_b128 v[114:117], v176 offset:53248
	ds_read_b128 v[118:121], v177 offset:53248
	s_waitcnt lgkmcnt(4)
	v_mfma_f32_32x32x16_bf16 v[48:63], v[98:101], v[102:105], v[48:63]
	s_waitcnt lgkmcnt(1)
	v_mfma_f32_32x32x16_bf16 v[32:47], v[98:101], v[114:117], v[32:47]
	ds_read_b128 v[98:101], v172 offset:36864
	ds_read_b128 v[122:125], v173 offset:36864
	s_waitcnt lgkmcnt(1)
	v_mfma_f32_32x32x16_bf16 v[16:31], v[98:101], v[102:105], v[16:31]
	v_mfma_f32_32x32x16_bf16 v[0:15], v[98:101], v[114:117], v[0:15]
	v_mfma_f32_32x32x16_bf16 v[48:63], v[106:109], v[110:113], v[48:63]
	v_mfma_f32_32x32x16_bf16 v[32:47], v[106:109], v[118:121], v[32:47]
	s_nop 0
	s_nop 0
	s_nop 0
	s_nop 0
	s_nop 0
	s_nop 0
	s_nop 0
	s_waitcnt lgkmcnt(0)
	s_waitcnt vmcnt(0)
	s_barrier
	v_lshl_add_u64 v[72:73], v[72:73], 0, s[96:97]
	s_add_u32 m0, s94, 0x8000
	s_nop 1
	global_load_lds_dwordx4 v[72:73], off
	v_lshl_add_u64 v[74:75], v[74:75], 0, s[96:97]
	s_add_u32 m0, s94, 0xc000
	s_nop 1
	global_load_lds_dwordx4 v[74:75], off
	v_lshl_add_u64 v[76:77], v[76:77], 0, s[96:97]
	s_add_u32 m0, s94, 0x9000
	s_nop 1
	global_load_lds_dwordx4 v[76:77], off
	v_lshl_add_u64 v[78:79], v[78:79], 0, s[96:97]
	s_add_u32 m0, s94, 0xd000
	s_nop 1
	global_load_lds_dwordx4 v[78:79], off
	v_lshl_add_u64 v[80:81], v[80:81], 0, s[96:97]
	s_add_u32 m0, s94, 0xa000
	s_nop 1
	global_load_lds_dwordx4 v[80:81], off
	v_lshl_add_u64 v[82:83], v[82:83], 0, s[96:97]
	s_add_u32 m0, s94, 0xe000
	s_nop 1
	global_load_lds_dwordx4 v[82:83], off
	v_lshl_add_u64 v[84:85], v[84:85], 0, s[96:97]
	s_add_u32 m0, s94, 0xb000
	s_nop 1
	global_load_lds_dwordx4 v[84:85], off
	v_lshl_add_u64 v[86:87], v[86:87], 0, s[96:97]
	s_add_u32 m0, s94, 0xf000
	s_nop 1
	global_load_lds_dwordx4 v[86:87], off
	v_mfma_f32_32x32x16_bf16 v[16:31], v[122:125], v[110:113], v[16:31]
	ds_read_b128 v[72:75], v170 offset:0
	ds_read_b128 v[76:79], v174 offset:16384
	ds_read_b128 v[80:83], v171 offset:0
	ds_read_b128 v[84:87], v175 offset:16384
	ds_read_b128 v[98:101], v174 offset:20480
	ds_read_b128 v[102:105], v175 offset:20480
	v_mfma_f32_32x32x16_bf16 v[0:15], v[122:125], v[118:121], v[0:15]
	s_waitcnt lgkmcnt(4)
	v_mfma_f32_32x32x16_bf16 v[48:63], v[72:75], v[76:79], v[48:63]
	s_waitcnt lgkmcnt(1)
	v_mfma_f32_32x32x16_bf16 v[32:47], v[72:75], v[98:101], v[32:47]
	ds_read_b128 v[72:75], v170 offset:4096
	ds_read_b128 v[106:109], v171 offset:4096
	s_waitcnt lgkmcnt(1)
	v_mfma_f32_32x32x16_bf16 v[16:31], v[72:75], v[76:79], v[16:31]
	v_mfma_f32_32x32x16_bf16 v[0:15], v[72:75], v[98:101], v[0:15]
	v_mfma_f32_32x32x16_bf16 v[48:63], v[80:83], v[84:87], v[48:63]
	v_mfma_f32_32x32x16_bf16 v[32:47], v[80:83], v[102:105], v[32:47]
	s_waitcnt lgkmcnt(0)
	v_mfma_f32_32x32x16_bf16 v[16:31], v[106:109], v[84:87], v[16:31]
	ds_read_b128 v[72:75], v172 offset:0
	ds_read_b128 v[76:79], v176 offset:16384
	ds_read_b128 v[80:83], v173 offset:0
	ds_read_b128 v[84:87], v177 offset:16384
	v_mfma_f32_32x32x16_bf16 v[0:15], v[106:109], v[102:105], v[0:15]
	ds_read_b128 v[98:101], v176 offset:20480
	ds_read_b128 v[102:105], v177 offset:20480
	s_waitcnt lgkmcnt(4)
	v_mfma_f32_32x32x16_bf16 v[48:63], v[72:75], v[76:79], v[48:63]
	s_waitcnt lgkmcnt(1)
	v_mfma_f32_32x32x16_bf16 v[32:47], v[72:75], v[98:101], v[32:47]
	ds_read_b128 v[72:75], v172 offset:4096
	ds_read_b128 v[106:109], v173 offset:4096
	s_waitcnt lgkmcnt(0)
	s_waitcnt vmcnt(0)
	s_barrier
; #define PIN(i) (gl_in(p.in[lnd(i)]))
; #define PW(T, off) ((T*)(lndp(p.ws) + (off)))
; #define POUT (lndf(p.out))
; DEVI int accrow(int r, int lane) { return (r & 3) + 8 * (r >> 2) + 4 * (lane >> 5); }
; DEVI void gemm_epi_gu(const Params& p, const GJob& jb, f32x16 (&acc)[2][2], int m0, int cbase, int wm, int wn, int lane, char* smem) {
;   const float* i_state_ffn_conv = PIN(8);
;   const float* i_ffn_conv_w = PIN(42);
;   const float* i_ffn_conv_b = PIN(43);
;   const int layer = jb.aux;
;   float* Gs = (float*)smem;
;   const int col = wn * 32 + (lane & 31);
; #pragma unroll
;   for (int i = 0; i < 2; ++i)
; #pragma unroll
;     for (int r = 0; r < 16; ++r) Gs[(wm * 64 + i * 32 + accrow(r, lane)) * 64 + col] = acc[i][0][r];
;   __syncthreads();
;   const int c = (cbase >> 6) * 32 + (lane & 31);
;   const float w0 = i_ffn_conv_w[(size_t)layer * 3 * 2816 + c], w1 = i_ffn_conv_w[(size_t)layer * 3 * 2816 + 2816 + c];
;   const float w2 = i_ffn_conv_w[(size_t)layer * 3 * 2816 + 2 * 2816 + c], cb = i_ffn_conv_b[(size_t)layer * 2816 + c];
;   bf16* Hb = (bf16*)(PW(char, W_arena) + F_HB);
;   float* outp = POUT;
;   if (m0 >= 0 && m0 + 128 <= TP - 2) {
;     bf16* hrow = Hb + (size_t)m0 * 2816 + c;
; #pragma unroll
;     for (int i = 0; i < 2; ++i) {
; #pragma unroll
;       for (int r = 0; r < 16; ++r) {
;         const int trow = wm * 64 + i * 32 + accrow(r, lane);
;         if (trow >= 2) {
;           const float cv = cb + w0 * Gs[(trow - 2) * 64 + col] + w1 * Gs[(trow - 1) * 64 + col] + w2 * acc[i][0][r];
;     ...
;   for (int kt = 0; kt < nk; kt += 2) {
;     if (kt + 2 < nk) G_LOAD(ra0, rb0, kt + 2);
;     if (kt + 1 < nk) G_STORE(ra1, rb1, As1, Bs1);
;     G_COMPUTE(As, Bs);
;     __syncthreads();
;     if (kt + 1 < nk) {
;       if (kt + 3 < nk) G_LOAD(ra1, rb1, kt + 3);
;       if (kt + 2 < nk) G_STORE(ra0, rb0, As, Bs);
;       G_COMPUTE(As1, Bs1);
;       __syncthreads();
;     }
;   }
	v_mfma_f32_32x32x16_bf16 v[16:31], v[72:75], v[76:79], v[16:31]
	v_mfma_f32_32x32x16_bf16 v[0:15], v[72:75], v[98:101], v[0:15]
	v_mfma_f32_32x32x16_bf16 v[48:63], v[80:83], v[84:87], v[48:63]
	v_mfma_f32_32x32x16_bf16 v[32:47], v[80:83], v[102:105], v[32:47]
	ds_read_b128 v[72:75], v170 offset:32768
	ds_read_b128 v[76:79], v174 offset:49152
	ds_read_b128 v[80:83], v175 offset:49152
	ds_read_b128 v[98:101], v171 offset:32768
	v_mfma_f32_32x32x16_bf16 v[16:31], v[106:109], v[84:87], v[16:31]
	ds_read_b128 v[84:87], v174 offset:53248
	v_mfma_f32_32x32x16_bf16 v[0:15], v[106:109], v[102:105], v[0:15]
	s_waitcnt lgkmcnt(3)
	v_mfma_f32_32x32x16_bf16 v[48:63], v[72:75], v[76:79], v[48:63]
	s_waitcnt lgkmcnt(0)
	v_mfma_f32_32x32x16_bf16 v[32:47], v[72:75], v[84:87], v[32:47]
	ds_read_b128 v[72:75], v170 offset:36864
	ds_read_b128 v[102:105], v175 offset:53248
	s_waitcnt lgkmcnt(1)
	v_mfma_f32_32x32x16_bf16 v[16:31], v[72:75], v[76:79], v[16:31]
	ds_read_b128 v[76:79], v171 offset:36864
	ds_read_b128 v[106:109], v177 offset:53248
	ds_read_b128 v[110:113], v176 offset:53248
	ds_read_b128 v[114:117], v177 offset:49152
	ds_read_b128 v[118:121], v176 offset:49152
	ds_read_b128 v[122:125], v173 offset:36864
	ds_read_b128 v[126:129], v172 offset:36864
	ds_read_b128 v[130:133], v173 offset:32768
	ds_read_b128 v[134:137], v172 offset:32768
	s_waitcnt lgkmcnt(0)
	s_barrier
	s_ashr_i32 s5, s4, 31
	v_mfma_f32_32x32x16_bf16 v[48:63], v[98:101], v[80:83], v[48:63]
	s_lshl_b64 s[4:5], s[4:5], 3
	s_add_u32 s4, s0, s4
	s_addc_u32 s5, s1, s5
	s_load_dwordx2 s[18:19], s[4:5], 0x0
	s_mov_b32 s4, 42
	s_waitcnt lgkmcnt(0)
	v_mfma_f32_32x32x16_bf16 v[16:31], v[76:79], v[80:83], v[16:31]
	s_ashr_i32 s5, s4, 31
	s_lshl_b64 s[4:5], s[4:5], 3
	s_add_u32 s4, s0, s4
	s_addc_u32 s5, s1, s5
	s_load_dwordx2 s[4:5], s[4:5], 0x0
	s_waitcnt lgkmcnt(0)
	v_mfma_f32_32x32x16_bf16 v[48:63], v[134:137], v[118:121], v[48:63]
	s_ashr_i32 s7, s6, 31
	v_or_b32_e32 v70, s2, v71
	v_lshrrev_b32_e32 v71, 3, v93
	s_lshl_b64 s[6:7], s[6:7], 3
	v_and_b32_e32 v82, 4, v71
	s_add_u32 s6, s0, s6
	v_ashrrev_i32_e32 v70, 1, v70
	v_mfma_f32_32x32x16_bf16 v[16:31], v[126:129], v[118:121], v[16:31]
	s_addc_u32 s7, s1, s7
	s_load_dwordx2 s[6:7], s[6:7], 0x0
	s_waitcnt lgkmcnt(0)
	s_movk_i32 s2, 0x2000
	v_bfe_u32 v83, v93, 3, 3
	v_mfma_f32_32x32x16_bf16 v[48:63], v[130:133], v[114:117], v[48:63]
	v_mfma_f32_32x32x16_bf16 v[16:31], v[122:125], v[114:117], v[16:31]
	v_mfma_f32_32x32x16_bf16 v[0:15], v[72:75], v[84:87], v[0:15]
	v_or_b32_e32 v85, v92, v82
	v_lshl_or_b32 v84, v95, 5, v94
	v_lshlrev_b32_e32 v86, 8, v85
	v_or_b32_e32 v72, v70, v94
	v_lshl_or_b32 v71, v84, 2, v86
	v_ashrrev_i32_e32 v73, 31, v72
	s_nop 3
	ds_write2st64_b32 v71, v48, v49 offset1:1
	ds_write2st64_b32 v71, v50, v51 offset0:2 offset1:3
	ds_write2st64_b32 v71, v52, v53 offset0:8 offset1:9
	ds_write2st64_b32 v71, v54, v55 offset0:10 offset1:11
	ds_write2st64_b32 v71, v56, v57 offset0:16 offset1:17
	ds_write2st64_b32 v71, v58, v59 offset0:18 offset1:19
	ds_write2st64_b32 v71, v60, v61 offset0:24 offset1:25
	ds_write2st64_b32 v71, v62, v63 offset0:26 offset1:27
	ds_write2st64_b32 v71, v16, v17 offset0:32 offset1:33
	ds_write2st64_b32 v71, v18, v19 offset0:34 offset1:35
	ds_write2st64_b32 v71, v20, v21 offset0:40 offset1:41
	ds_write2st64_b32 v71, v22, v23 offset0:42 offset1:43
	ds_write2st64_b32 v71, v24, v25 offset0:48 offset1:49
	ds_write2st64_b32 v71, v26, v27 offset0:50 offset1:51
	ds_write2st64_b32 v71, v28, v29 offset0:56 offset1:57
	ds_write2st64_b32 v71, v30, v31 offset0:58 offset1:59
	v_lshl_add_u64 v[70:71], s[4:5], 0, v[66:67]
	v_lshlrev_b64 v[74:75], 2, v[72:73]
	v_lshl_add_u64 v[70:71], v[70:71], 0, v[74:75]
	v_mfma_f32_32x32x16_bf16 v[0:15], v[76:79], v[102:105], v[0:15]
	v_add_co_u32_e32 v76, vcc, s2, v70
	s_movk_i32 s2, 0x5000
	s_nop 0
	v_addc_co_u32_e32 v77, vcc, 0, v71, vcc
	v_add_co_u32_e32 v78, vcc, s2, v70
	s_waitcnt lgkmcnt(0)
	s_barrier
	v_addc_co_u32_e32 v79, vcc, 0, v71, vcc
	global_load_dword v80, v[70:71], off
	s_nop 0
	global_load_dword v71, v[76:77], off offset:3072
	global_load_dword v70, v[78:79], off offset:2048
	v_lshl_add_u64 v[76:77], s[6:7], 0, v[68:69]
	v_lshl_add_u64 v[74:75], v[76:77], 0, v[74:75]
	global_load_dword v81, v[74:75], off
	v_mfma_f32_32x32x16_bf16 v[32:47], v[98:101], v[102:105], v[32:47]
	s_mov_b64 s[2:3], s[74:75]
	s_add_u32 s14, s2, 0x1d19c000
	s_addc_u32 s15, s3, 0
	s_cmpk_lt_u32 s30, 0x3f8f
	v_cmp_lt_i32_e64 s[6:7], 1, v85
	s_mov_b64 s[2:3], -1
	v_mfma_f32_32x32x16_bf16 v[32:47], v[134:137], v[110:113], v[32:47]
	v_mfma_f32_32x32x16_bf16 v[0:15], v[126:129], v[110:113], v[0:15]
	v_mfma_f32_32x32x16_bf16 v[32:47], v[130:133], v[106:109], v[32:47]
	v_mfma_f32_32x32x16_bf16 v[0:15], v[122:125], v[106:109], v[0:15]
	s_cbranch_scc1 .LBB0_3975
	v_add_u32_e32 v87, s30, v85
	v_cmp_gt_i32_e32 vcc, s90, v87
	v_lshl_add_u64 v[76:77], v[72:73], 2, s[18:19]
	v_lshl_add_u64 v[74:75], v[72:73], 1, s[14:15]
	s_and_b64 s[4:5], s[6:7], vcc
	s_and_saveexec_b64 s[2:3], s[4:5]
	s_cbranch_execz .LBB0_3509
	v_and_b32_e32 v89, 14, v87
	v_cmp_gt_i32_e64 s[8:9], s92, v87
	s_movk_i32 s4, 0x400f
	v_add_u32_e32 v78, 0xffffbff0, v87
	v_cndmask_b32_e64 v93, v89, v87, s[8:9]
	v_cmp_lt_i32_e64 s[10:11], s4, v87
	v_lshrrev_b32_e32 v88, 4, v78
	v_cmp_gt_i32_e32 vcc, 1, v93
	s_and_saveexec_b64 s[4:5], vcc
	s_xor_b64 s[4:5], exec, s[4:5]
	s_cbranch_execz .LBB0_3499
	v_mov_b32_e32 v79, 0
	s_and_saveexec_b64 s[20:21], s[10:11]
	s_cbranch_execz .LBB0_3498
	v_add_u32_e32 v94, v88, v90
	v_mov_b64_e32 v[78:79], s[18:19]
	s_movk_i32 s31, 0x5800
	v_mad_u64_u32 v[78:79], s[34:35], v94, s31, v[78:79]
	v_lshl_add_u64 v[78:79], v[72:73], 2, v[78:79]
	v_add_co_u32_e32 v78, vcc, 0x2000, v78
	s_nop 1
	v_addc_co_u32_e32 v79, vcc, 0, v79, vcc
	global_load_dword v79, v[78:79], off offset:3072

; DEVI int TID() { int t = threadIdx.x; asm volatile("" : "+v"(t)); return t; }
;   bf16* As = (bf16*)smem;
;   bf16* Bs = As + 128 * 72;
;   const int tid = TID(), lane = tid & 63, wave = tid >> 6, wm = wave >> 1, wn = wave & 1;
;   f32x16 acc[2][2];
; #pragma unroll
;   for (int i = 0; i < 2; ++i)
; #pragma unroll
;     for (int j = 0; j < 2; ++j) acc[i][j] = zero16();
;   const int lrow = tid >> 3, lkc = (tid & 7) * 8;
;   const bf16* Ag = jb.A + (size_t)max(m0 + lrow, 0) * jb.lda + lkc;
;   const bf16* Ag1 = jb.A + (ptrdiff_t)(m0 + lrow) * jb.lda + lkc;
;   const bf16* Bg = jb.Bt + (size_t)(n0 + lrow) * jb.K + lkc;
;   const size_t astep = (size_t)32 * jb.lda, bstep = (size_t)32 * jb.K;
;   if (kt1 < 0) kt1 = jb.K >> 6;
;   const int nk = kt1 - kt0;
;   Ag += (size_t)kt0 * 64; Ag1 += (size_t)kt0 * 64; Bg += (size_t)kt0 * 64;
;   u32x4 ra0[4], rb0[4], ra1[4], rb1[4];
;     ...
;   bf16* As1 = As + 2 * 128 * 72;
;   bf16* Bs1 = As1 + 128 * 72;
;   G_LOAD(ra0, rb0, 0);
;   if (nk > 1) G_LOAD(ra1, rb1, 1);
;   G_STORE(ra0, rb0, As, Bs);
;   __syncthreads();
.LBB0_4695:
	s_cmpk_gt_i32 s11, 0x1912
	s_cbranch_scc1 .LBB0_4827
	s_mul_hi_i32 s2, s11, 0x5397829d
	s_lshr_b32 s3, s2, 31
	s_ashr_i32 s2, s2, 8
	s_add_i32 s2, s2, s3
	s_lshl_b32 s3, s2, 4
	s_sub_i32 s4, 0x83, s3
	s_min_u32 s4, s4, 16
	v_cvt_f32_ubyte0_e32 v0, s4
	v_rcp_iflag_f32_e32 v0, v0
	s_sub_i32 s7, 0, s4
	s_mulk_i32 s2, 0xfcf0
	s_add_i32 s2, s11, s2
	v_mul_f32_e32 v0, 0x4f7ffffe, v0
	v_cvt_u32_f32_e32 v0, v0
	s_abs_i32 s6, s2
	s_ashr_i32 s5, s2, 31
	v_mov_b32_e32 v86, v208
	v_readfirstlane_b32 s12, v0
	s_mul_i32 s7, s7, s12
	s_mul_hi_u32 s7, s12, s7
	s_add_i32 s12, s12, s7
	s_mul_hi_u32 s7, s6, s12
	s_mul_i32 s12, s7, s4
	s_sub_i32 s6, s6, s12
	s_add_i32 s12, s7, 1
	s_sub_i32 s13, s6, s4
	s_cmp_ge_u32 s6, s4
	s_cselect_b32 s7, s12, s7
	s_cselect_b32 s6, s13, s6
	s_add_i32 s12, s7, 1
	s_cmp_ge_u32 s6, s4
	s_cselect_b32 s6, s12, s7
	s_xor_b32 s6, s6, s5
	s_sub_i32 s5, s6, s5
	s_mul_i32 s4, s5, s4
	s_sub_i32 s2, s2, s4
	s_add_i32 s3, s3, s2
	s_lshl_b32 s2, s3, 7
	s_lshl_b32 s3, s5, 7
	v_ashrrev_i32_e32 v84, 3, v86
	v_add_u32_e32 v0, s2, v84
	v_max_i32_e32 v96, 0, v0
	v_lshlrev_b32_e32 v1, 4, v86
	v_lshlrev_b64 v[2:3], 11, v[96:97]
	v_and_b32_e32 v96, 0x70, v1
	s_mov_b64 s[96:97], 0x80
	v_lshrrev_b32_e32 v178, 4, v208
	v_and_b32_e32 v178, 7, v178
	v_lshlrev_b32_e32 v178, 4, v178
	v_xor_b32_e32 v96, v96, v178
	v_lshrrev_b32_e32 v179, 6, v208
	v_lshlrev_b32_e32 v179, 10, v179
	v_lshrrev_b32_e32 v180, 5, v208
	v_lshrrev_b32_e32 v181, 1, v208
	v_xor_b32_e32 v180, v180, v181
	v_readfirstlane_b32 s94, v179
	v_and_b32_e32 v180, 1, v180
	v_lshlrev_b32_e32 v180, 4, v180
	v_and_b32_e32 v181, 31, v208
	v_lshlrev_b32_e32 v181, 7, v181
	v_or_b32_e32 v180, v180, v181
	v_lshrrev_b32_e32 v181, 7, v208
	v_lshlrev_b32_e32 v181, 13, v181
	v_or_b32_e32 v194, v180, v181
	v_bfe_u32 v181, v208, 6, 1
	v_lshlrev_b32_e32 v181, 13, v181
	v_or_b32_e32 v195, v180, v181
	v_bfe_u32 v178, v208, 2, 2
	v_xor_b32_e32 v179, 0, v178
	v_lshlrev_b32_e32 v179, 5, v179
	v_or_b32_e32 v170, v194, v179
	v_or_b32_e32 v174, v195, v179
	v_xor_b32_e32 v179, 1, v178
	v_lshlrev_b32_e32 v179, 5, v179
	v_or_b32_e32 v171, v194, v179
	v_or_b32_e32 v175, v195, v179
	v_xor_b32_e32 v179, 2, v178
	v_lshlrev_b32_e32 v179, 5, v179
	v_or_b32_e32 v172, v194, v179
	v_or_b32_e32 v176, v195, v179
	v_xor_b32_e32 v179, 3, v178
	v_lshlrev_b32_e32 v179, 5, v179
	v_or_b32_e32 v173, v194, v179
	v_or_b32_e32 v177, v195, v179
	v_ashrrev_i32_e32 v1, 31, v0
	v_lshlrev_b64 v[0:1], 11, v[0:1]
	v_lshl_add_u64 v[0:1], s[8:9], 0, v[0:1]
	v_lshl_add_u64 v[28:29], v[0:1], 0, v[96:97]
	v_add_u32_e32 v0, s3, v84
	v_ashrrev_i32_e32 v1, 31, v0
	v_lshlrev_b64 v[0:1], 11, v[0:1]
	v_lshl_add_u64 v[0:1], v[64:65], 0, v[0:1]
	v_add_co_u32_e32 v72, vcc, s63, v28
	v_lshl_add_u64 v[70:71], v[0:1], 0, v[96:97]
	s_nop 0
	v_addc_co_u32_e32 v73, vcc, 0, v29, vcc
	v_add_co_u32_e32 v74, vcc, s63, v70
	v_lshl_add_u64 v[2:3], s[8:9], 0, v[2:3]
	s_nop 0
	v_addc_co_u32_e32 v75, vcc, 0, v71, vcc
	v_add_co_u32_e32 v76, vcc, s64, v28
	v_lshl_add_u64 v[68:69], v[2:3], 0, v[96:97]
	s_nop 0
	v_addc_co_u32_e32 v77, vcc, 0, v29, vcc
	v_add_co_u32_e32 v78, vcc, s64, v70
	v_addc_co_u32_e32 v79, vcc, 0, v71, vcc
	v_add_co_u32_e32 v80, vcc, s65, v70
	s_nop 0
	v_addc_co_u32_e32 v81, vcc, 0, v71, vcc
	v_add_co_u32_e32 v82, vcc, s65, v28
	s_nop 0
	v_addc_co_u32_e32 v83, vcc, 0, v29, vcc
	v_ashrrev_i32_e32 v66, 1, v86
	v_and_b32_e32 v87, 31, v86
	v_lshrrev_b32_e32 v67, 1, v86
	v_and_b32_e32 v88, 0xffffffc0, v66
	v_and_b32_e32 v90, 16, v67
	v_or_b32_e32 v66, v88, v87
	v_mad_u64_u32 v[84:85], s[4:5], v84, s91, v[96:97]
	v_mad_u64_u32 v[66:67], s[4:5], v66, s91, v[90:91]
	v_add_u32_e32 v85, 0xd800, v84
	s_mov_b64 s[4:5], s[74:75]
	s_add_u32 m0, s94, 0x4000
	s_nop 1
	global_load_lds_dwordx4 v[70:71], off
	s_add_u32 m0, s94, 0x0
	s_nop 1
	global_load_lds_dwordx4 v[68:69], off
	s_add_u32 m0, s94, 0x5000
	s_nop 1
	global_load_lds_dwordx4 v[74:75], off
	s_add_u32 m0, s94, 0x6000
	s_nop 1
	global_load_lds_dwordx4 v[78:79], off
	s_add_u32 m0, s94, 0x7000
	s_nop 1
	global_load_lds_dwordx4 v[80:81], off
	s_add_u32 m0, s94, 0x1000
	s_nop 1
	global_load_lds_dwordx4 v[72:73], off
	s_add_u32 m0, s94, 0x2000
	s_nop 1
	global_load_lds_dwordx4 v[76:77], off
	s_add_u32 m0, s94, 0x3000
	s_nop 1
	global_load_lds_dwordx4 v[82:83], off
	s_waitcnt lgkmcnt(0)
	s_waitcnt vmcnt(0)
	s_barrier
;     ...
;   bf16* As1 = As + 2 * 128 * 72;
;   bf16* Bs1 = As1 + 128 * 72;
;   G_LOAD(ra0, rb0, 0);
;   if (nk > 1) G_LOAD(ra1, rb1, 1);
;   G_STORE(ra0, rb0, As, Bs);
;   __syncthreads();
;   for (int kt = 0; kt < nk; kt += 2) {
;     if (kt + 2 < nk) G_LOAD(ra0, rb0, kt + 2);
;     if (kt + 1 < nk) G_STORE(ra1, rb1, As1, Bs1);
;     G_COMPUTE(As, Bs);
;     __syncthreads();
;     if (kt + 1 < nk) {
;       if (kt + 3 < nk) G_LOAD(ra1, rb1, kt + 3);
;       if (kt + 2 < nk) G_STORE(ra0, rb0, As, Bs);
;       G_COMPUTE(As1, Bs1);
;       __syncthreads();
;     }
;   }
	ds_read_b128 v[0:3], v170 offset:0
	v_and_b32_e32 v4, 0x5f, v86
	v_mad_u32_u24 v67, v4, s91, v90
	ds_read_b128 v[4:7], v174 offset:16384
	ds_read_b128 v[90:93], v171 offset:0
	ds_read_b128 v[98:101], v175 offset:16384
	ds_read_b128 v[32:35], v174 offset:20480
	ds_read_b128 v[102:105], v175 offset:20480
	v_lshl_add_u64 v[68:69], v[68:69], 0, s[96:97]
	s_add_u32 m0, s94, 0x8000
	s_nop 1
	global_load_lds_dwordx4 v[68:69], off
	v_lshl_add_u64 v[70:71], v[70:71], 0, s[96:97]
	s_add_u32 m0, s94, 0xc000
	s_nop 1
	global_load_lds_dwordx4 v[70:71], off
	v_lshl_add_u64 v[72:73], v[72:73], 0, s[96:97]
	s_add_u32 m0, s94, 0x9000
	s_nop 1
	global_load_lds_dwordx4 v[72:73], off
	v_lshl_add_u64 v[74:75], v[74:75], 0, s[96:97]
	s_add_u32 m0, s94, 0xd000
	s_nop 1
	global_load_lds_dwordx4 v[74:75], off
	v_lshl_add_u64 v[76:77], v[76:77], 0, s[96:97]
	s_add_u32 m0, s94, 0xa000
	s_nop 1
	global_load_lds_dwordx4 v[76:77], off
	v_lshl_add_u64 v[78:79], v[78:79], 0, s[96:97]
	s_add_u32 m0, s94, 0xe000
	s_nop 1
	global_load_lds_dwordx4 v[78:79], off
	v_lshl_add_u64 v[82:83], v[82:83], 0, s[96:97]
	s_add_u32 m0, s94, 0xb000
	s_nop 1
	global_load_lds_dwordx4 v[82:83], off
	v_lshl_add_u64 v[80:81], v[80:81], 0, s[96:97]
	s_add_u32 m0, s94, 0xf000
	s_nop 1
	global_load_lds_dwordx4 v[80:81], off
	s_waitcnt lgkmcnt(4)
	v_mfma_f32_32x32x16_bf16 v[16:31], v[0:3], v[4:7], 0
	ds_read_b128 v[36:39], v170 offset:4096
	ds_read_b128 v[106:109], v171 offset:4096
	s_waitcnt lgkmcnt(3)
	v_mfma_f32_32x32x16_bf16 v[48:63], v[0:3], v[32:35], 0
	s_waitcnt lgkmcnt(1)
	v_mfma_f32_32x32x16_bf16 v[0:15], v[36:39], v[4:7], 0
	v_mfma_f32_32x32x16_bf16 v[32:47], v[36:39], v[32:35], 0
	v_mfma_f32_32x32x16_bf16 v[16:31], v[90:93], v[98:101], v[16:31]
	v_mfma_f32_32x32x16_bf16 v[48:63], v[90:93], v[102:105], v[48:63]
	s_waitcnt lgkmcnt(0)
	v_mfma_f32_32x32x16_bf16 v[0:15], v[106:109], v[98:101], v[0:15]
	v_mfma_f32_32x32x16_bf16 v[32:47], v[106:109], v[102:105], v[32:47]
	ds_read_b128 v[90:93], v172 offset:0
	ds_read_b128 v[98:101], v176 offset:16384
	ds_read_b128 v[102:105], v173 offset:0
	ds_read_b128 v[106:109], v177 offset:16384
	ds_read_b128 v[110:113], v176 offset:20480
	ds_read_b128 v[114:117], v177 offset:20480
	s_waitcnt lgkmcnt(4)
	v_mfma_f32_32x32x16_bf16 v[16:31], v[90:93], v[98:101], v[16:31]
	s_waitcnt lgkmcnt(1)
	v_mfma_f32_32x32x16_bf16 v[48:63], v[90:93], v[110:113], v[48:63]
	ds_read_b128 v[90:93], v172 offset:4096
	ds_read_b128 v[118:121], v173 offset:4096
	s_waitcnt lgkmcnt(1)
	v_mfma_f32_32x32x16_bf16 v[0:15], v[90:93], v[98:101], v[0:15]
	v_mfma_f32_32x32x16_bf16 v[32:47], v[90:93], v[110:113], v[32:47]
	v_mfma_f32_32x32x16_bf16 v[16:31], v[102:105], v[106:109], v[16:31]
	v_mfma_f32_32x32x16_bf16 v[48:63], v[102:105], v[114:117], v[48:63]
	s_waitcnt lgkmcnt(0)
	v_mfma_f32_32x32x16_bf16 v[0:15], v[118:121], v[106:109], v[0:15]
	s_waitcnt vmcnt(0)
	s_barrier
	v_mfma_f32_32x32x16_bf16 v[32:47], v[118:121], v[114:117], v[32:47]
	ds_read_b128 v[90:93], v170 offset:32768
	ds_read_b128 v[98:101], v174 offset:49152
	ds_read_b128 v[102:105], v171 offset:32768
	ds_read_b128 v[106:109], v175 offset:49152
	ds_read_b128 v[110:113], v174 offset:53248
	ds_read_b128 v[114:117], v175 offset:53248
	v_lshl_add_u64 v[68:69], v[68:69], 0, s[96:97]
	s_add_u32 m0, s94, 0x0
	s_nop 1
	global_load_lds_dwordx4 v[68:69], off
	v_lshl_add_u64 v[70:71], v[70:71], 0, s[96:97]
	s_add_u32 m0, s94, 0x4000
	s_nop 1
	global_load_lds_dwordx4 v[70:71], off
	v_lshl_add_u64 v[72:73], v[72:73], 0, s[96:97]
	s_add_u32 m0, s94, 0x1000
	s_nop 1
	global_load_lds_dwordx4 v[72:73], off
	v_lshl_add_u64 v[74:75], v[74:75], 0, s[96:97]
	s_add_u32 m0, s94, 0x5000
	s_nop 1
	global_load_lds_dwordx4 v[74:75], off
	v_lshl_add_u64 v[76:77], v[76:77], 0, s[96:97]
	s_add_u32 m0, s94, 0x2000
	s_nop 1
	global_load_lds_dwordx4 v[76:77], off
	v_lshl_add_u64 v[78:79], v[78:79], 0, s[96:97]
	s_add_u32 m0, s94, 0x6000
	s_nop 1
	global_load_lds_dwordx4 v[78:79], off
	v_lshl_add_u64 v[82:83], v[82:83], 0, s[96:97]
	s_add_u32 m0, s94, 0x3000
	s_nop 1
	global_load_lds_dwordx4 v[82:83], off
	v_lshl_add_u64 v[80:81], v[80:81], 0, s[96:97]
	s_add_u32 m0, s94, 0x7000
	s_nop 1
	global_load_lds_dwordx4 v[80:81], off
	s_waitcnt lgkmcnt(4)
	v_mfma_f32_32x32x16_bf16 v[16:31], v[90:93], v[98:101], v[16:31]
	s_waitcnt lgkmcnt(1)
	v_mfma_f32_32x32x16_bf16 v[48:63], v[90:93], v[110:113], v[48:63]
	ds_read_b128 v[90:93], v170 offset:36864
	ds_read_b128 v[118:121], v171 offset:36864
	s_waitcnt lgkmcnt(1)
	v_mfma_f32_32x32x16_bf16 v[0:15], v[90:93], v[98:101], v[0:15]
	v_mfma_f32_32x32x16_bf16 v[32:47], v[90:93], v[110:113], v[32:47]
	v_mfma_f32_32x32x16_bf16 v[16:31], v[102:105], v[106:109], v[16:31]
	v_mfma_f32_32x32x16_bf16 v[48:63], v[102:105], v[114:117], v[48:63]
	s_waitcnt lgkmcnt(0)
	v_mfma_f32_32x32x16_bf16 v[0:15], v[118:121], v[106:109], v[0:15]
	ds_read_b128 v[90:93], v172 offset:32768
	ds_read_b128 v[98:101], v176 offset:49152
	ds_read_b128 v[102:105], v173 offset:32768
	ds_read_b128 v[106:109], v177 offset:49152
	v_mfma_f32_32x32x16_bf16 v[32:47], v[118:121], v[114:117], v[32:47]
	ds_read_b128 v[110:113], v176 offset:53248
	ds_read_b128 v[114:117], v177 offset:53248
	s_waitcnt lgkmcnt(4)
	v_mfma_f32_32x32x16_bf16 v[16:31], v[90:93], v[98:101], v[16:31]
	s_waitcnt lgkmcnt(1)
	v_mfma_f32_32x32x16_bf16 v[48:63], v[90:93], v[110:113], v[48:63]
	ds_read_b128 v[90:93], v172 offset:36864
	ds_read_b128 v[118:121], v173 offset:36864
	s_waitcnt lgkmcnt(1)
	v_mfma_f32_32x32x16_bf16 v[0:15], v[90:93], v[98:101], v[0:15]
	v_mfma_f32_32x32x16_bf16 v[32:47], v[90:93], v[110:113], v[32:47]
	v_mfma_f32_32x32x16_bf16 v[16:31], v[102:105], v[106:109], v[16:31]
	v_mfma_f32_32x32x16_bf16 v[48:63], v[102:105], v[114:117], v[48:63]
	s_waitcnt lgkmcnt(0)
	v_mfma_f32_32x32x16_bf16 v[0:15], v[118:121], v[106:109], v[0:15]
	s_waitcnt vmcnt(0)
	s_barrier
;     ...
;   bf16* As1 = As + 2 * 128 * 72;
;   bf16* Bs1 = As1 + 128 * 72;
;   G_LOAD(ra0, rb0, 0);
;   if (nk > 1) G_LOAD(ra1, rb1, 1);
;   G_STORE(ra0, rb0, As, Bs);
;   __syncthreads();
;   for (int kt = 0; kt < nk; kt += 2) {
;     if (kt + 2 < nk) G_LOAD(ra0, rb0, kt + 2);
;     if (kt + 1 < nk) G_STORE(ra1, rb1, As1, Bs1);
;     G_COMPUTE(As, Bs);
;     __syncthreads();
;     if (kt + 1 < nk) {
;       if (kt + 3 < nk) G_LOAD(ra1, rb1, kt + 3);
;       if (kt + 2 < nk) G_STORE(ra0, rb0, As, Bs);
;       G_COMPUTE(As1, Bs1);
;       __syncthreads();
;     }
;   }
	v_mfma_f32_32x32x16_bf16 v[32:47], v[118:121], v[114:117], v[32:47]
	ds_read_b128 v[90:93], v170 offset:0
	ds_read_b128 v[98:101], v174 offset:16384
	ds_read_b128 v[102:105], v171 offset:0
	ds_read_b128 v[106:109], v175 offset:16384
	ds_read_b128 v[110:113], v174 offset:20480
	ds_read_b128 v[114:117], v175 offset:20480
	v_lshl_add_u64 v[68:69], v[68:69], 0, s[96:97]
	s_add_u32 m0, s94, 0x8000
	s_nop 1
	global_load_lds_dwordx4 v[68:69], off
	v_lshl_add_u64 v[70:71], v[70:71], 0, s[96:97]
	s_add_u32 m0, s94, 0xc000
	s_nop 1
	global_load_lds_dwordx4 v[70:71], off
	v_lshl_add_u64 v[72:73], v[72:73], 0, s[96:97]
	s_add_u32 m0, s94, 0x9000
	s_nop 1
	global_load_lds_dwordx4 v[72:73], off
	v_lshl_add_u64 v[74:75], v[74:75], 0, s[96:97]
	s_add_u32 m0, s94, 0xd000
	s_nop 1
	global_load_lds_dwordx4 v[74:75], off
	v_lshl_add_u64 v[76:77], v[76:77], 0, s[96:97]
	s_add_u32 m0, s94, 0xa000
	s_nop 1
	global_load_lds_dwordx4 v[76:77], off
	v_lshl_add_u64 v[78:79], v[78:79], 0, s[96:97]
	s_add_u32 m0, s94, 0xe000
	s_nop 1
	global_load_lds_dwordx4 v[78:79], off
	v_lshl_add_u64 v[82:83], v[82:83], 0, s[96:97]
	s_add_u32 m0, s94, 0xb000
	s_nop 1
	global_load_lds_dwordx4 v[82:83], off
	v_lshl_add_u64 v[80:81], v[80:81], 0, s[96:97]
	s_add_u32 m0, s94, 0xf000
	s_nop 1
	global_load_lds_dwordx4 v[80:81], off
	s_waitcnt lgkmcnt(4)
	v_mfma_f32_32x32x16_bf16 v[16:31], v[90:93], v[98:101], v[16:31]
	s_waitcnt lgkmcnt(1)
	v_mfma_f32_32x32x16_bf16 v[48:63], v[90:93], v[110:113], v[48:63]
	ds_read_b128 v[90:93], v170 offset:4096
	ds_read_b128 v[118:121], v171 offset:4096
	s_waitcnt lgkmcnt(1)
	v_mfma_f32_32x32x16_bf16 v[0:15], v[90:93], v[98:101], v[0:15]
	v_mfma_f32_32x32x16_bf16 v[32:47], v[90:93], v[110:113], v[32:47]
	v_mfma_f32_32x32x16_bf16 v[16:31], v[102:105], v[106:109], v[16:31]
	v_mfma_f32_32x32x16_bf16 v[48:63], v[102:105], v[114:117], v[48:63]
	s_waitcnt lgkmcnt(0)
	v_mfma_f32_32x32x16_bf16 v[0:15], v[118:121], v[106:109], v[0:15]
	ds_read_b128 v[90:93], v172 offset:0
	ds_read_b128 v[98:101], v176 offset:16384
	ds_read_b128 v[102:105], v173 offset:0
	ds_read_b128 v[106:109], v177 offset:16384
	v_mfma_f32_32x32x16_bf16 v[32:47], v[118:121], v[114:117], v[32:47]
	ds_read_b128 v[110:113], v176 offset:20480
	ds_read_b128 v[114:117], v177 offset:20480
	s_waitcnt lgkmcnt(4)
	v_mfma_f32_32x32x16_bf16 v[16:31], v[90:93], v[98:101], v[16:31]
	s_waitcnt lgkmcnt(1)
	v_mfma_f32_32x32x16_bf16 v[48:63], v[90:93], v[110:113], v[48:63]
	ds_read_b128 v[90:93], v172 offset:4096
	ds_read_b128 v[118:121], v173 offset:4096
	s_waitcnt lgkmcnt(1)
	v_mfma_f32_32x32x16_bf16 v[0:15], v[90:93], v[98:101], v[0:15]
	v_mfma_f32_32x32x16_bf16 v[32:47], v[90:93], v[110:113], v[32:47]
	v_mfma_f32_32x32x16_bf16 v[16:31], v[102:105], v[106:109], v[16:31]
	v_mfma_f32_32x32x16_bf16 v[48:63], v[102:105], v[114:117], v[48:63]
	s_waitcnt lgkmcnt(0)
	v_mfma_f32_32x32x16_bf16 v[0:15], v[118:121], v[106:109], v[0:15]
	s_waitcnt vmcnt(0)
	s_barrier
	v_mfma_f32_32x32x16_bf16 v[32:47], v[118:121], v[114:117], v[32:47]
	ds_read_b128 v[90:93], v170 offset:32768
	ds_read_b128 v[98:101], v174 offset:49152
	ds_read_b128 v[102:105], v171 offset:32768
	ds_read_b128 v[106:109], v175 offset:49152
	ds_read_b128 v[110:113], v174 offset:53248
	ds_read_b128 v[114:117], v175 offset:53248
	v_lshl_add_u64 v[68:69], v[68:69], 0, s[96:97]
	s_add_u32 m0, s94, 0x0
	s_nop 1
	global_load_lds_dwordx4 v[68:69], off
	v_lshl_add_u64 v[70:71], v[70:71], 0, s[96:97]
	s_add_u32 m0, s94, 0x4000
	s_nop 1
	global_load_lds_dwordx4 v[70:71], off
	v_lshl_add_u64 v[72:73], v[72:73], 0, s[96:97]
	s_add_u32 m0, s94, 0x1000
	s_nop 1
	global_load_lds_dwordx4 v[72:73], off
	v_lshl_add_u64 v[74:75], v[74:75], 0, s[96:97]
	s_add_u32 m0, s94, 0x5000
	s_nop 1
	global_load_lds_dwordx4 v[74:75], off
	v_lshl_add_u64 v[76:77], v[76:77], 0, s[96:97]
	s_add_u32 m0, s94, 0x2000
	s_nop 1
	global_load_lds_dwordx4 v[76:77], off
	v_lshl_add_u64 v[78:79], v[78:79], 0, s[96:97]
	s_add_u32 m0, s94, 0x6000
	s_nop 1
	global_load_lds_dwordx4 v[78:79], off
	v_lshl_add_u64 v[82:83], v[82:83], 0, s[96:97]
	s_add_u32 m0, s94, 0x3000
	s_nop 1
	global_load_lds_dwordx4 v[82:83], off
	v_lshl_add_u64 v[80:81], v[80:81], 0, s[96:97]
	s_add_u32 m0, s94, 0x7000
	s_nop 1
	global_load_lds_dwordx4 v[80:81], off
	s_waitcnt lgkmcnt(4)
	v_mfma_f32_32x32x16_bf16 v[16:31], v[90:93], v[98:101], v[16:31]
	s_waitcnt lgkmcnt(1)
	v_mfma_f32_32x32x16_bf16 v[48:63], v[90:93], v[110:113], v[48:63]
	ds_read_b128 v[90:93], v170 offset:36864
	ds_read_b128 v[118:121], v171 offset:36864
	s_waitcnt lgkmcnt(1)
	v_mfma_f32_32x32x16_bf16 v[0:15], v[90:93], v[98:101], v[0:15]
	v_mfma_f32_32x32x16_bf16 v[32:47], v[90:93], v[110:113], v[32:47]
	v_mfma_f32_32x32x16_bf16 v[16:31], v[102:105], v[106:109], v[16:31]
	v_mfma_f32_32x32x16_bf16 v[48:63], v[102:105], v[114:117], v[48:63]
	s_waitcnt lgkmcnt(0)
	v_mfma_f32_32x32x16_bf16 v[0:15], v[118:121], v[106:109], v[0:15]
	ds_read_b128 v[90:93], v172 offset:32768
	ds_read_b128 v[98:101], v176 offset:49152
	ds_read_b128 v[102:105], v173 offset:32768
	ds_read_b128 v[106:109], v177 offset:49152
	v_mfma_f32_32x32x16_bf16 v[32:47], v[118:121], v[114:117], v[32:47]
	ds_read_b128 v[110:113], v176 offset:53248
	ds_read_b128 v[114:117], v177 offset:53248
	s_waitcnt lgkmcnt(4)
	v_mfma_f32_32x32x16_bf16 v[16:31], v[90:93], v[98:101], v[16:31]
	s_waitcnt lgkmcnt(1)
	v_mfma_f32_32x32x16_bf16 v[48:63], v[90:93], v[110:113], v[48:63]
	ds_read_b128 v[90:93], v172 offset:36864
	ds_read_b128 v[118:121], v173 offset:36864
	s_waitcnt lgkmcnt(1)
	v_mfma_f32_32x32x16_bf16 v[0:15], v[90:93], v[98:101], v[0:15]
	v_mfma_f32_32x32x16_bf16 v[32:47], v[90:93], v[110:113], v[32:47]
	v_mfma_f32_32x32x16_bf16 v[16:31], v[102:105], v[106:109], v[16:31]
	v_mfma_f32_32x32x16_bf16 v[48:63], v[102:105], v[114:117], v[48:63]
	s_waitcnt lgkmcnt(0)
	v_mfma_f32_32x32x16_bf16 v[0:15], v[118:121], v[106:109], v[0:15]
	s_waitcnt vmcnt(0)
	s_barrier
;     ...
;   bf16* As1 = As + 2 * 128 * 72;
;   bf16* Bs1 = As1 + 128 * 72;
;   G_LOAD(ra0, rb0, 0);
;   if (nk > 1) G_LOAD(ra1, rb1, 1);
;   G_STORE(ra0, rb0, As, Bs);
;   __syncthreads();
;   for (int kt = 0; kt < nk; kt += 2) {
;     if (kt + 2 < nk) G_LOAD(ra0, rb0, kt + 2);
;     if (kt + 1 < nk) G_STORE(ra1, rb1, As1, Bs1);
;     G_COMPUTE(As, Bs);
;     __syncthreads();
;     if (kt + 1 < nk) {
;       if (kt + 3 < nk) G_LOAD(ra1, rb1, kt + 3);
;       if (kt + 2 < nk) G_STORE(ra0, rb0, As, Bs);
;       G_COMPUTE(As1, Bs1);
;       __syncthreads();
;     }
;   }
	v_mfma_f32_32x32x16_bf16 v[32:47], v[118:121], v[114:117], v[32:47]
	ds_read_b128 v[90:93], v170 offset:0
	ds_read_b128 v[98:101], v174 offset:16384
	ds_read_b128 v[102:105], v171 offset:0
	ds_read_b128 v[106:109], v175 offset:16384
	ds_read_b128 v[110:113], v174 offset:20480
	ds_read_b128 v[114:117], v175 offset:20480
	v_lshl_add_u64 v[68:69], v[68:69], 0, s[96:97]
	s_add_u32 m0, s94, 0x8000
	s_nop 1
	global_load_lds_dwordx4 v[68:69], off
	v_lshl_add_u64 v[70:71], v[70:71], 0, s[96:97]
	s_add_u32 m0, s94, 0xc000
	s_nop 1
	global_load_lds_dwordx4 v[70:71], off
	v_lshl_add_u64 v[72:73], v[72:73], 0, s[96:97]
	s_add_u32 m0, s94, 0x9000
	s_nop 1
	global_load_lds_dwordx4 v[72:73], off
	v_lshl_add_u64 v[74:75], v[74:75], 0, s[96:97]
	s_add_u32 m0, s94, 0xd000
	s_nop 1
	global_load_lds_dwordx4 v[74:75], off
	v_lshl_add_u64 v[76:77], v[76:77], 0, s[96:97]
	s_add_u32 m0, s94, 0xa000
	s_nop 1
	global_load_lds_dwordx4 v[76:77], off
	v_lshl_add_u64 v[78:79], v[78:79], 0, s[96:97]
	s_add_u32 m0, s94, 0xe000
	s_nop 1
	global_load_lds_dwordx4 v[78:79], off
	v_lshl_add_u64 v[82:83], v[82:83], 0, s[96:97]
	s_add_u32 m0, s94, 0xb000
	s_nop 1
	global_load_lds_dwordx4 v[82:83], off
	v_lshl_add_u64 v[80:81], v[80:81], 0, s[96:97]
	s_add_u32 m0, s94, 0xf000
	s_nop 1
	global_load_lds_dwordx4 v[80:81], off
	s_waitcnt lgkmcnt(4)
	v_mfma_f32_32x32x16_bf16 v[16:31], v[90:93], v[98:101], v[16:31]
	s_waitcnt lgkmcnt(1)
	v_mfma_f32_32x32x16_bf16 v[48:63], v[90:93], v[110:113], v[48:63]
	ds_read_b128 v[90:93], v170 offset:4096
	ds_read_b128 v[118:121], v171 offset:4096
	s_waitcnt lgkmcnt(1)
	v_mfma_f32_32x32x16_bf16 v[0:15], v[90:93], v[98:101], v[0:15]
	v_mfma_f32_32x32x16_bf16 v[32:47], v[90:93], v[110:113], v[32:47]
	v_mfma_f32_32x32x16_bf16 v[16:31], v[102:105], v[106:109], v[16:31]
	v_mfma_f32_32x32x16_bf16 v[48:63], v[102:105], v[114:117], v[48:63]
	s_waitcnt lgkmcnt(0)
	v_mfma_f32_32x32x16_bf16 v[0:15], v[118:121], v[106:109], v[0:15]
	ds_read_b128 v[90:93], v172 offset:0
	ds_read_b128 v[98:101], v176 offset:16384
	ds_read_b128 v[102:105], v173 offset:0
	ds_read_b128 v[106:109], v177 offset:16384
	v_mfma_f32_32x32x16_bf16 v[32:47], v[118:121], v[114:117], v[32:47]
	ds_read_b128 v[110:113], v176 offset:20480
	ds_read_b128 v[114:117], v177 offset:20480
	s_waitcnt lgkmcnt(4)
	v_mfma_f32_32x32x16_bf16 v[16:31], v[90:93], v[98:101], v[16:31]
	s_waitcnt lgkmcnt(1)
	v_mfma_f32_32x32x16_bf16 v[48:63], v[90:93], v[110:113], v[48:63]
	ds_read_b128 v[90:93], v172 offset:4096
	ds_read_b128 v[118:121], v173 offset:4096
	s_waitcnt lgkmcnt(1)
	v_mfma_f32_32x32x16_bf16 v[0:15], v[90:93], v[98:101], v[0:15]
	v_mfma_f32_32x32x16_bf16 v[32:47], v[90:93], v[110:113], v[32:47]
	v_mfma_f32_32x32x16_bf16 v[16:31], v[102:105], v[106:109], v[16:31]
	v_mfma_f32_32x32x16_bf16 v[48:63], v[102:105], v[114:117], v[48:63]
	s_waitcnt lgkmcnt(0)
	v_mfma_f32_32x32x16_bf16 v[0:15], v[118:121], v[106:109], v[0:15]
	s_waitcnt vmcnt(0)
	s_barrier
	v_mfma_f32_32x32x16_bf16 v[32:47], v[118:121], v[114:117], v[32:47]
	ds_read_b128 v[90:93], v170 offset:32768
	ds_read_b128 v[98:101], v174 offset:49152
	ds_read_b128 v[102:105], v171 offset:32768
	ds_read_b128 v[106:109], v175 offset:49152
	ds_read_b128 v[110:113], v174 offset:53248
	ds_read_b128 v[114:117], v175 offset:53248
	v_lshl_add_u64 v[68:69], v[68:69], 0, s[96:97]
	s_add_u32 m0, s94, 0x0
	s_nop 1
	global_load_lds_dwordx4 v[68:69], off
	v_lshl_add_u64 v[70:71], v[70:71], 0, s[96:97]
	s_add_u32 m0, s94, 0x4000
	s_nop 1
	global_load_lds_dwordx4 v[70:71], off
	v_lshl_add_u64 v[72:73], v[72:73], 0, s[96:97]
	s_add_u32 m0, s94, 0x1000
	s_nop 1
	global_load_lds_dwordx4 v[72:73], off
	v_lshl_add_u64 v[74:75], v[74:75], 0, s[96:97]
	s_add_u32 m0, s94, 0x5000
	s_nop 1
	global_load_lds_dwordx4 v[74:75], off
	v_lshl_add_u64 v[76:77], v[76:77], 0, s[96:97]
	s_add_u32 m0, s94, 0x2000
	s_nop 1
	global_load_lds_dwordx4 v[76:77], off
	v_lshl_add_u64 v[78:79], v[78:79], 0, s[96:97]
	s_add_u32 m0, s94, 0x6000
	s_nop 1
	global_load_lds_dwordx4 v[78:79], off
	v_lshl_add_u64 v[82:83], v[82:83], 0, s[96:97]
	s_add_u32 m0, s94, 0x3000
	s_nop 1
	global_load_lds_dwordx4 v[82:83], off
	v_lshl_add_u64 v[80:81], v[80:81], 0, s[96:97]
	s_add_u32 m0, s94, 0x7000
	s_nop 1
	global_load_lds_dwordx4 v[80:81], off
	s_waitcnt lgkmcnt(4)
	v_mfma_f32_32x32x16_bf16 v[16:31], v[90:93], v[98:101], v[16:31]
	s_waitcnt lgkmcnt(1)
	v_mfma_f32_32x32x16_bf16 v[48:63], v[90:93], v[110:113], v[48:63]
	ds_read_b128 v[90:93], v170 offset:36864
	ds_read_b128 v[118:121], v171 offset:36864
	s_waitcnt lgkmcnt(1)
	v_mfma_f32_32x32x16_bf16 v[0:15], v[90:93], v[98:101], v[0:15]
	v_mfma_f32_32x32x16_bf16 v[32:47], v[90:93], v[110:113], v[32:47]
	v_mfma_f32_32x32x16_bf16 v[16:31], v[102:105], v[106:109], v[16:31]
	v_mfma_f32_32x32x16_bf16 v[48:63], v[102:105], v[114:117], v[48:63]
	s_waitcnt lgkmcnt(0)
	v_mfma_f32_32x32x16_bf16 v[0:15], v[118:121], v[106:109], v[0:15]
	ds_read_b128 v[90:93], v172 offset:32768
	ds_read_b128 v[98:101], v176 offset:49152
	ds_read_b128 v[102:105], v173 offset:32768
	ds_read_b128 v[106:109], v177 offset:49152
	v_mfma_f32_32x32x16_bf16 v[32:47], v[118:121], v[114:117], v[32:47]
	ds_read_b128 v[110:113], v176 offset:53248
	ds_read_b128 v[114:117], v177 offset:53248
	s_waitcnt lgkmcnt(4)
	v_mfma_f32_32x32x16_bf16 v[16:31], v[90:93], v[98:101], v[16:31]
	s_waitcnt lgkmcnt(1)
	v_mfma_f32_32x32x16_bf16 v[48:63], v[90:93], v[110:113], v[48:63]
	ds_read_b128 v[90:93], v172 offset:36864
	ds_read_b128 v[118:121], v173 offset:36864
	s_waitcnt lgkmcnt(1)
	v_mfma_f32_32x32x16_bf16 v[0:15], v[90:93], v[98:101], v[0:15]
	v_mfma_f32_32x32x16_bf16 v[32:47], v[90:93], v[110:113], v[32:47]
	v_mfma_f32_32x32x16_bf16 v[16:31], v[102:105], v[106:109], v[16:31]
	v_mfma_f32_32x32x16_bf16 v[48:63], v[102:105], v[114:117], v[48:63]
	s_waitcnt lgkmcnt(0)
	v_mfma_f32_32x32x16_bf16 v[0:15], v[118:121], v[106:109], v[0:15]
	s_waitcnt vmcnt(0)
	s_barrier
;     ...
;   bf16* As1 = As + 2 * 128 * 72;
;   bf16* Bs1 = As1 + 128 * 72;
;   G_LOAD(ra0, rb0, 0);
;   if (nk > 1) G_LOAD(ra1, rb1, 1);
;   G_STORE(ra0, rb0, As, Bs);
;   __syncthreads();
;   for (int kt = 0; kt < nk; kt += 2) {
;     if (kt + 2 < nk) G_LOAD(ra0, rb0, kt + 2);
;     if (kt + 1 < nk) G_STORE(ra1, rb1, As1, Bs1);
;     G_COMPUTE(As, Bs);
;     __syncthreads();
;     if (kt + 1 < nk) {
;       if (kt + 3 < nk) G_LOAD(ra1, rb1, kt + 3);
;       if (kt + 2 < nk) G_STORE(ra0, rb0, As, Bs);
;       G_COMPUTE(As1, Bs1);
;       __syncthreads();
;     }
;   }
	v_mfma_f32_32x32x16_bf16 v[32:47], v[118:121], v[114:117], v[32:47]
	ds_read_b128 v[90:93], v170 offset:0
	ds_read_b128 v[98:101], v174 offset:16384
	ds_read_b128 v[102:105], v171 offset:0
	ds_read_b128 v[106:109], v175 offset:16384
	ds_read_b128 v[110:113], v174 offset:20480
	ds_read_b128 v[114:117], v175 offset:20480
	v_lshl_add_u64 v[68:69], v[68:69], 0, s[96:97]
	s_add_u32 m0, s94, 0x8000
	s_nop 1
	global_load_lds_dwordx4 v[68:69], off
	v_lshl_add_u64 v[70:71], v[70:71], 0, s[96:97]
	s_add_u32 m0, s94, 0xc000
	s_nop 1
	global_load_lds_dwordx4 v[70:71], off
	v_lshl_add_u64 v[72:73], v[72:73], 0, s[96:97]
	s_add_u32 m0, s94, 0x9000
	s_nop 1
	global_load_lds_dwordx4 v[72:73], off
	v_lshl_add_u64 v[74:75], v[74:75], 0, s[96:97]
	s_add_u32 m0, s94, 0xd000
	s_nop 1
	global_load_lds_dwordx4 v[74:75], off
	v_lshl_add_u64 v[76:77], v[76:77], 0, s[96:97]
	s_add_u32 m0, s94, 0xa000
	s_nop 1
	global_load_lds_dwordx4 v[76:77], off
	v_lshl_add_u64 v[78:79], v[78:79], 0, s[96:97]
	s_add_u32 m0, s94, 0xe000
	s_nop 1
	global_load_lds_dwordx4 v[78:79], off
	v_lshl_add_u64 v[82:83], v[82:83], 0, s[96:97]
	s_add_u32 m0, s94, 0xb000
	s_nop 1
	global_load_lds_dwordx4 v[82:83], off
	v_lshl_add_u64 v[80:81], v[80:81], 0, s[96:97]
	s_add_u32 m0, s94, 0xf000
	s_nop 1
	global_load_lds_dwordx4 v[80:81], off
	s_waitcnt lgkmcnt(4)
	v_mfma_f32_32x32x16_bf16 v[16:31], v[90:93], v[98:101], v[16:31]
	s_waitcnt lgkmcnt(1)
	v_mfma_f32_32x32x16_bf16 v[48:63], v[90:93], v[110:113], v[48:63]
	ds_read_b128 v[90:93], v170 offset:4096
	ds_read_b128 v[118:121], v171 offset:4096
	s_waitcnt lgkmcnt(1)
	v_mfma_f32_32x32x16_bf16 v[0:15], v[90:93], v[98:101], v[0:15]
	v_mfma_f32_32x32x16_bf16 v[32:47], v[90:93], v[110:113], v[32:47]
	v_mfma_f32_32x32x16_bf16 v[16:31], v[102:105], v[106:109], v[16:31]
	v_mfma_f32_32x32x16_bf16 v[48:63], v[102:105], v[114:117], v[48:63]
	s_waitcnt lgkmcnt(0)
	v_mfma_f32_32x32x16_bf16 v[0:15], v[118:121], v[106:109], v[0:15]
	ds_read_b128 v[90:93], v172 offset:0
	ds_read_b128 v[98:101], v176 offset:16384
	ds_read_b128 v[102:105], v173 offset:0
	ds_read_b128 v[106:109], v177 offset:16384
	v_mfma_f32_32x32x16_bf16 v[32:47], v[118:121], v[114:117], v[32:47]
	ds_read_b128 v[110:113], v176 offset:20480
	ds_read_b128 v[114:117], v177 offset:20480
	s_waitcnt lgkmcnt(4)
	v_mfma_f32_32x32x16_bf16 v[16:31], v[90:93], v[98:101], v[16:31]
	s_waitcnt lgkmcnt(1)
	v_mfma_f32_32x32x16_bf16 v[48:63], v[90:93], v[110:113], v[48:63]
	ds_read_b128 v[90:93], v172 offset:4096
	ds_read_b128 v[118:121], v173 offset:4096
	s_waitcnt lgkmcnt(1)
	v_mfma_f32_32x32x16_bf16 v[0:15], v[90:93], v[98:101], v[0:15]
	v_mfma_f32_32x32x16_bf16 v[32:47], v[90:93], v[110:113], v[32:47]
	v_mfma_f32_32x32x16_bf16 v[16:31], v[102:105], v[106:109], v[16:31]
	v_mfma_f32_32x32x16_bf16 v[48:63], v[102:105], v[114:117], v[48:63]
	s_waitcnt lgkmcnt(0)
	v_mfma_f32_32x32x16_bf16 v[0:15], v[118:121], v[106:109], v[0:15]
	s_waitcnt vmcnt(0)
	s_barrier
	v_mfma_f32_32x32x16_bf16 v[32:47], v[118:121], v[114:117], v[32:47]
	ds_read_b128 v[90:93], v170 offset:32768
	ds_read_b128 v[98:101], v174 offset:49152
	ds_read_b128 v[102:105], v171 offset:32768
	ds_read_b128 v[106:109], v175 offset:49152
	ds_read_b128 v[110:113], v174 offset:53248
	ds_read_b128 v[114:117], v175 offset:53248
	v_lshl_add_u64 v[68:69], v[68:69], 0, s[96:97]
	s_add_u32 m0, s94, 0x0
	s_nop 1
	global_load_lds_dwordx4 v[68:69], off
	v_lshl_add_u64 v[70:71], v[70:71], 0, s[96:97]
	s_add_u32 m0, s94, 0x4000
	s_nop 1
	global_load_lds_dwordx4 v[70:71], off
	v_lshl_add_u64 v[72:73], v[72:73], 0, s[96:97]
	s_add_u32 m0, s94, 0x1000
	s_nop 1
	global_load_lds_dwordx4 v[72:73], off
	v_lshl_add_u64 v[74:75], v[74:75], 0, s[96:97]
	s_add_u32 m0, s94, 0x5000
	s_nop 1
	global_load_lds_dwordx4 v[74:75], off
	v_lshl_add_u64 v[76:77], v[76:77], 0, s[96:97]
	s_add_u32 m0, s94, 0x2000
	s_nop 1
	global_load_lds_dwordx4 v[76:77], off
	v_lshl_add_u64 v[78:79], v[78:79], 0, s[96:97]
	s_add_u32 m0, s94, 0x6000
	s_nop 1
	global_load_lds_dwordx4 v[78:79], off
	v_lshl_add_u64 v[82:83], v[82:83], 0, s[96:97]
	s_add_u32 m0, s94, 0x3000
	s_nop 1
	global_load_lds_dwordx4 v[82:83], off
	v_lshl_add_u64 v[80:81], v[80:81], 0, s[96:97]
	s_add_u32 m0, s94, 0x7000
	s_nop 1
	global_load_lds_dwordx4 v[80:81], off
	s_waitcnt lgkmcnt(4)
	v_mfma_f32_32x32x16_bf16 v[16:31], v[90:93], v[98:101], v[16:31]
	s_waitcnt lgkmcnt(1)
	v_mfma_f32_32x32x16_bf16 v[48:63], v[90:93], v[110:113], v[48:63]
	ds_read_b128 v[90:93], v170 offset:36864
	ds_read_b128 v[118:121], v171 offset:36864
	s_waitcnt lgkmcnt(1)
	v_mfma_f32_32x32x16_bf16 v[0:15], v[90:93], v[98:101], v[0:15]
	v_mfma_f32_32x32x16_bf16 v[32:47], v[90:93], v[110:113], v[32:47]
	v_mfma_f32_32x32x16_bf16 v[16:31], v[102:105], v[106:109], v[16:31]
	v_mfma_f32_32x32x16_bf16 v[48:63], v[102:105], v[114:117], v[48:63]
	s_waitcnt lgkmcnt(0)
	v_mfma_f32_32x32x16_bf16 v[0:15], v[118:121], v[106:109], v[0:15]
	ds_read_b128 v[90:93], v172 offset:32768
	ds_read_b128 v[98:101], v176 offset:49152
	ds_read_b128 v[102:105], v173 offset:32768
	ds_read_b128 v[106:109], v177 offset:49152
	v_mfma_f32_32x32x16_bf16 v[32:47], v[118:121], v[114:117], v[32:47]
	ds_read_b128 v[110:113], v176 offset:53248
	ds_read_b128 v[114:117], v177 offset:53248
	s_waitcnt lgkmcnt(4)
	v_mfma_f32_32x32x16_bf16 v[16:31], v[90:93], v[98:101], v[16:31]
	s_waitcnt lgkmcnt(1)
	v_mfma_f32_32x32x16_bf16 v[48:63], v[90:93], v[110:113], v[48:63]
	ds_read_b128 v[90:93], v172 offset:36864
	ds_read_b128 v[118:121], v173 offset:36864
	s_waitcnt lgkmcnt(1)
	v_mfma_f32_32x32x16_bf16 v[0:15], v[90:93], v[98:101], v[0:15]
	v_mfma_f32_32x32x16_bf16 v[32:47], v[90:93], v[110:113], v[32:47]
	v_mfma_f32_32x32x16_bf16 v[16:31], v[102:105], v[106:109], v[16:31]
	v_mfma_f32_32x32x16_bf16 v[48:63], v[102:105], v[114:117], v[48:63]
	s_waitcnt lgkmcnt(0)
	v_mfma_f32_32x32x16_bf16 v[0:15], v[118:121], v[106:109], v[0:15]
	s_waitcnt vmcnt(0)
	s_barrier
;     ...
;   bf16* As1 = As + 2 * 128 * 72;
;   bf16* Bs1 = As1 + 128 * 72;
;   G_LOAD(ra0, rb0, 0);
;   if (nk > 1) G_LOAD(ra1, rb1, 1);
;   G_STORE(ra0, rb0, As, Bs);
;   __syncthreads();
;   for (int kt = 0; kt < nk; kt += 2) {
;     if (kt + 2 < nk) G_LOAD(ra0, rb0, kt + 2);
;     if (kt + 1 < nk) G_STORE(ra1, rb1, As1, Bs1);
;     G_COMPUTE(As, Bs);
;     __syncthreads();
;     if (kt + 1 < nk) {
;       if (kt + 3 < nk) G_LOAD(ra1, rb1, kt + 3);
;       if (kt + 2 < nk) G_STORE(ra0, rb0, As, Bs);
;       G_COMPUTE(As1, Bs1);
;       __syncthreads();
;     }
;   }
	v_mfma_f32_32x32x16_bf16 v[32:47], v[118:121], v[114:117], v[32:47]
	ds_read_b128 v[90:93], v170 offset:0
	ds_read_b128 v[98:101], v174 offset:16384
	ds_read_b128 v[102:105], v171 offset:0
	ds_read_b128 v[106:109], v175 offset:16384
	ds_read_b128 v[110:113], v174 offset:20480
	ds_read_b128 v[114:117], v175 offset:20480
	v_lshl_add_u64 v[68:69], v[68:69], 0, s[96:97]
	s_add_u32 m0, s94, 0x8000
	s_nop 1
	global_load_lds_dwordx4 v[68:69], off
	v_lshl_add_u64 v[70:71], v[70:71], 0, s[96:97]
	s_add_u32 m0, s94, 0xc000
	s_nop 1
	global_load_lds_dwordx4 v[70:71], off
	v_lshl_add_u64 v[72:73], v[72:73], 0, s[96:97]
	s_add_u32 m0, s94, 0x9000
	s_nop 1
	global_load_lds_dwordx4 v[72:73], off
	v_lshl_add_u64 v[74:75], v[74:75], 0, s[96:97]
	s_add_u32 m0, s94, 0xd000
	s_nop 1
	global_load_lds_dwordx4 v[74:75], off
	v_lshl_add_u64 v[76:77], v[76:77], 0, s[96:97]
	s_add_u32 m0, s94, 0xa000
	s_nop 1
	global_load_lds_dwordx4 v[76:77], off
	v_lshl_add_u64 v[78:79], v[78:79], 0, s[96:97]
	s_add_u32 m0, s94, 0xe000
	s_nop 1
	global_load_lds_dwordx4 v[78:79], off
	v_lshl_add_u64 v[82:83], v[82:83], 0, s[96:97]
	s_add_u32 m0, s94, 0xb000
	s_nop 1
	global_load_lds_dwordx4 v[82:83], off
	v_lshl_add_u64 v[80:81], v[80:81], 0, s[96:97]
	s_add_u32 m0, s94, 0xf000
	s_nop 1
	global_load_lds_dwordx4 v[80:81], off
	s_waitcnt lgkmcnt(4)
	v_mfma_f32_32x32x16_bf16 v[16:31], v[90:93], v[98:101], v[16:31]
	s_waitcnt lgkmcnt(1)
	v_mfma_f32_32x32x16_bf16 v[48:63], v[90:93], v[110:113], v[48:63]
	ds_read_b128 v[90:93], v170 offset:4096
	ds_read_b128 v[118:121], v171 offset:4096
	s_waitcnt lgkmcnt(1)
	v_mfma_f32_32x32x16_bf16 v[0:15], v[90:93], v[98:101], v[0:15]
	v_mfma_f32_32x32x16_bf16 v[32:47], v[90:93], v[110:113], v[32:47]
	v_mfma_f32_32x32x16_bf16 v[16:31], v[102:105], v[106:109], v[16:31]
	v_mfma_f32_32x32x16_bf16 v[48:63], v[102:105], v[114:117], v[48:63]
	s_waitcnt lgkmcnt(0)
	v_mfma_f32_32x32x16_bf16 v[0:15], v[118:121], v[106:109], v[0:15]
	ds_read_b128 v[90:93], v172 offset:0
	ds_read_b128 v[98:101], v176 offset:16384
	ds_read_b128 v[102:105], v173 offset:0
	ds_read_b128 v[106:109], v177 offset:16384
	v_mfma_f32_32x32x16_bf16 v[32:47], v[118:121], v[114:117], v[32:47]
	ds_read_b128 v[110:113], v176 offset:20480
	ds_read_b128 v[114:117], v177 offset:20480
	s_waitcnt lgkmcnt(4)
	v_mfma_f32_32x32x16_bf16 v[16:31], v[90:93], v[98:101], v[16:31]
	s_waitcnt lgkmcnt(1)
	v_mfma_f32_32x32x16_bf16 v[48:63], v[90:93], v[110:113], v[48:63]
	ds_read_b128 v[90:93], v172 offset:4096
	ds_read_b128 v[118:121], v173 offset:4096
	s_waitcnt lgkmcnt(1)
	v_mfma_f32_32x32x16_bf16 v[0:15], v[90:93], v[98:101], v[0:15]
	v_mfma_f32_32x32x16_bf16 v[32:47], v[90:93], v[110:113], v[32:47]
	v_mfma_f32_32x32x16_bf16 v[16:31], v[102:105], v[106:109], v[16:31]
	v_mfma_f32_32x32x16_bf16 v[48:63], v[102:105], v[114:117], v[48:63]
	s_waitcnt lgkmcnt(0)
	v_mfma_f32_32x32x16_bf16 v[0:15], v[118:121], v[106:109], v[0:15]
	s_waitcnt vmcnt(0)
	s_barrier
	v_mfma_f32_32x32x16_bf16 v[32:47], v[118:121], v[114:117], v[32:47]
	ds_read_b128 v[90:93], v170 offset:32768
	ds_read_b128 v[98:101], v174 offset:49152
	ds_read_b128 v[102:105], v171 offset:32768
	ds_read_b128 v[106:109], v175 offset:49152
	ds_read_b128 v[110:113], v174 offset:53248
	ds_read_b128 v[114:117], v175 offset:53248
	v_lshl_add_u64 v[68:69], v[68:69], 0, s[96:97]
	s_add_u32 m0, s94, 0x0
	s_nop 1
	global_load_lds_dwordx4 v[68:69], off
	v_lshl_add_u64 v[70:71], v[70:71], 0, s[96:97]
	s_add_u32 m0, s94, 0x4000
	s_nop 1
	global_load_lds_dwordx4 v[70:71], off
	v_lshl_add_u64 v[72:73], v[72:73], 0, s[96:97]
	s_add_u32 m0, s94, 0x1000
	s_nop 1
	global_load_lds_dwordx4 v[72:73], off
	v_lshl_add_u64 v[74:75], v[74:75], 0, s[96:97]
	s_add_u32 m0, s94, 0x5000
	s_nop 1
	global_load_lds_dwordx4 v[74:75], off
	v_lshl_add_u64 v[76:77], v[76:77], 0, s[96:97]
	s_add_u32 m0, s94, 0x2000
	s_nop 1
	global_load_lds_dwordx4 v[76:77], off
	v_lshl_add_u64 v[78:79], v[78:79], 0, s[96:97]
	s_add_u32 m0, s94, 0x6000
	s_nop 1
	global_load_lds_dwordx4 v[78:79], off
	v_lshl_add_u64 v[82:83], v[82:83], 0, s[96:97]
	s_add_u32 m0, s94, 0x3000
	s_nop 1
	global_load_lds_dwordx4 v[82:83], off
	v_lshl_add_u64 v[80:81], v[80:81], 0, s[96:97]
	s_add_u32 m0, s94, 0x7000
	s_nop 1
	global_load_lds_dwordx4 v[80:81], off
	s_waitcnt lgkmcnt(4)
	v_mfma_f32_32x32x16_bf16 v[16:31], v[90:93], v[98:101], v[16:31]
	s_waitcnt lgkmcnt(1)
	v_mfma_f32_32x32x16_bf16 v[48:63], v[90:93], v[110:113], v[48:63]
	ds_read_b128 v[90:93], v170 offset:36864
	ds_read_b128 v[118:121], v171 offset:36864
	s_waitcnt lgkmcnt(1)
	v_mfma_f32_32x32x16_bf16 v[0:15], v[90:93], v[98:101], v[0:15]
	v_mfma_f32_32x32x16_bf16 v[32:47], v[90:93], v[110:113], v[32:47]
	v_mfma_f32_32x32x16_bf16 v[16:31], v[102:105], v[106:109], v[16:31]
	v_mfma_f32_32x32x16_bf16 v[48:63], v[102:105], v[114:117], v[48:63]
	s_waitcnt lgkmcnt(0)
	v_mfma_f32_32x32x16_bf16 v[0:15], v[118:121], v[106:109], v[0:15]
	ds_read_b128 v[90:93], v172 offset:32768
	ds_read_b128 v[98:101], v176 offset:49152
	ds_read_b128 v[102:105], v173 offset:32768
	ds_read_b128 v[106:109], v177 offset:49152
	v_mfma_f32_32x32x16_bf16 v[32:47], v[118:121], v[114:117], v[32:47]
	ds_read_b128 v[110:113], v176 offset:53248
	ds_read_b128 v[114:117], v177 offset:53248
	s_waitcnt lgkmcnt(4)
	v_mfma_f32_32x32x16_bf16 v[16:31], v[90:93], v[98:101], v[16:31]
	s_waitcnt lgkmcnt(1)
	v_mfma_f32_32x32x16_bf16 v[48:63], v[90:93], v[110:113], v[48:63]
	ds_read_b128 v[90:93], v172 offset:36864
	ds_read_b128 v[118:121], v173 offset:36864
	s_waitcnt lgkmcnt(1)
	v_mfma_f32_32x32x16_bf16 v[0:15], v[90:93], v[98:101], v[0:15]
	v_mfma_f32_32x32x16_bf16 v[32:47], v[90:93], v[110:113], v[32:47]
	v_mfma_f32_32x32x16_bf16 v[16:31], v[102:105], v[106:109], v[16:31]
	v_mfma_f32_32x32x16_bf16 v[48:63], v[102:105], v[114:117], v[48:63]
	s_waitcnt lgkmcnt(0)
	v_mfma_f32_32x32x16_bf16 v[0:15], v[118:121], v[106:109], v[0:15]
	s_waitcnt vmcnt(0)
	s_barrier
;     ...
;   bf16* As1 = As + 2 * 128 * 72;
;   bf16* Bs1 = As1 + 128 * 72;
;   G_LOAD(ra0, rb0, 0);
;   if (nk > 1) G_LOAD(ra1, rb1, 1);
;   G_STORE(ra0, rb0, As, Bs);
;   __syncthreads();
;   for (int kt = 0; kt < nk; kt += 2) {
;     if (kt + 2 < nk) G_LOAD(ra0, rb0, kt + 2);
;     if (kt + 1 < nk) G_STORE(ra1, rb1, As1, Bs1);
;     G_COMPUTE(As, Bs);
;     __syncthreads();
;     if (kt + 1 < nk) {
;       if (kt + 3 < nk) G_LOAD(ra1, rb1, kt + 3);
;       if (kt + 2 < nk) G_STORE(ra0, rb0, As, Bs);
;       G_COMPUTE(As1, Bs1);
;       __syncthreads();
;     }
;   }
	v_mfma_f32_32x32x16_bf16 v[32:47], v[118:121], v[114:117], v[32:47]
	ds_read_b128 v[90:93], v170 offset:0
	ds_read_b128 v[98:101], v174 offset:16384
	ds_read_b128 v[102:105], v171 offset:0
	ds_read_b128 v[106:109], v175 offset:16384
	ds_read_b128 v[110:113], v174 offset:20480
	ds_read_b128 v[114:117], v175 offset:20480
	v_lshl_add_u64 v[68:69], v[68:69], 0, s[96:97]
	s_add_u32 m0, s94, 0x8000
	s_nop 1
	global_load_lds_dwordx4 v[68:69], off
	v_lshl_add_u64 v[70:71], v[70:71], 0, s[96:97]
	s_add_u32 m0, s94, 0xc000
	s_nop 1
	global_load_lds_dwordx4 v[70:71], off
	v_lshl_add_u64 v[72:73], v[72:73], 0, s[96:97]
	s_add_u32 m0, s94, 0x9000
	s_nop 1
	global_load_lds_dwordx4 v[72:73], off
	v_lshl_add_u64 v[74:75], v[74:75], 0, s[96:97]
	s_add_u32 m0, s94, 0xd000
	s_nop 1
	global_load_lds_dwordx4 v[74:75], off
	v_lshl_add_u64 v[76:77], v[76:77], 0, s[96:97]
	s_add_u32 m0, s94, 0xa000
	s_nop 1
	global_load_lds_dwordx4 v[76:77], off
	v_lshl_add_u64 v[78:79], v[78:79], 0, s[96:97]
	s_add_u32 m0, s94, 0xe000
	s_nop 1
	global_load_lds_dwordx4 v[78:79], off
	v_lshl_add_u64 v[82:83], v[82:83], 0, s[96:97]
	s_add_u32 m0, s94, 0xb000
	s_nop 1
	global_load_lds_dwordx4 v[82:83], off
	v_lshl_add_u64 v[80:81], v[80:81], 0, s[96:97]
	s_add_u32 m0, s94, 0xf000
	s_nop 1
	global_load_lds_dwordx4 v[80:81], off
	s_waitcnt lgkmcnt(4)
	v_mfma_f32_32x32x16_bf16 v[16:31], v[90:93], v[98:101], v[16:31]
	s_waitcnt lgkmcnt(1)
	v_mfma_f32_32x32x16_bf16 v[48:63], v[90:93], v[110:113], v[48:63]
	ds_read_b128 v[90:93], v170 offset:4096
	ds_read_b128 v[118:121], v171 offset:4096
	s_waitcnt lgkmcnt(1)
	v_mfma_f32_32x32x16_bf16 v[0:15], v[90:93], v[98:101], v[0:15]
	v_mfma_f32_32x32x16_bf16 v[32:47], v[90:93], v[110:113], v[32:47]
	v_mfma_f32_32x32x16_bf16 v[16:31], v[102:105], v[106:109], v[16:31]
	v_mfma_f32_32x32x16_bf16 v[48:63], v[102:105], v[114:117], v[48:63]
	s_waitcnt lgkmcnt(0)
	v_mfma_f32_32x32x16_bf16 v[0:15], v[118:121], v[106:109], v[0:15]
	ds_read_b128 v[90:93], v172 offset:0
	ds_read_b128 v[98:101], v176 offset:16384
	ds_read_b128 v[102:105], v173 offset:0
	ds_read_b128 v[106:109], v177 offset:16384
	v_mfma_f32_32x32x16_bf16 v[32:47], v[118:121], v[114:117], v[32:47]
	ds_read_b128 v[110:113], v176 offset:20480
	ds_read_b128 v[114:117], v177 offset:20480
	s_waitcnt lgkmcnt(4)
	v_mfma_f32_32x32x16_bf16 v[16:31], v[90:93], v[98:101], v[16:31]
	s_waitcnt lgkmcnt(1)
	v_mfma_f32_32x32x16_bf16 v[48:63], v[90:93], v[110:113], v[48:63]
	ds_read_b128 v[90:93], v172 offset:4096
	ds_read_b128 v[118:121], v173 offset:4096
	s_waitcnt lgkmcnt(1)
	v_mfma_f32_32x32x16_bf16 v[0:15], v[90:93], v[98:101], v[0:15]
	v_mfma_f32_32x32x16_bf16 v[32:47], v[90:93], v[110:113], v[32:47]
	v_mfma_f32_32x32x16_bf16 v[16:31], v[102:105], v[106:109], v[16:31]
	v_mfma_f32_32x32x16_bf16 v[48:63], v[102:105], v[114:117], v[48:63]
	s_waitcnt lgkmcnt(0)
	v_mfma_f32_32x32x16_bf16 v[0:15], v[118:121], v[106:109], v[0:15]
	s_waitcnt vmcnt(0)
	s_barrier
	v_mfma_f32_32x32x16_bf16 v[32:47], v[118:121], v[114:117], v[32:47]
	ds_read_b128 v[90:93], v170 offset:32768
	ds_read_b128 v[98:101], v174 offset:49152
	ds_read_b128 v[102:105], v171 offset:32768
	ds_read_b128 v[106:109], v175 offset:49152
	ds_read_b128 v[110:113], v174 offset:53248
	ds_read_b128 v[114:117], v175 offset:53248
	v_lshl_add_u64 v[68:69], v[68:69], 0, s[96:97]
	s_add_u32 m0, s94, 0x0
	s_nop 1
	global_load_lds_dwordx4 v[68:69], off
	v_lshl_add_u64 v[70:71], v[70:71], 0, s[96:97]
	s_add_u32 m0, s94, 0x4000
	s_nop 1
	global_load_lds_dwordx4 v[70:71], off
	v_lshl_add_u64 v[72:73], v[72:73], 0, s[96:97]
	s_add_u32 m0, s94, 0x1000
	s_nop 1
	global_load_lds_dwordx4 v[72:73], off
	v_lshl_add_u64 v[74:75], v[74:75], 0, s[96:97]
	s_add_u32 m0, s94, 0x5000
	s_nop 1
	global_load_lds_dwordx4 v[74:75], off
	v_lshl_add_u64 v[76:77], v[76:77], 0, s[96:97]
	s_add_u32 m0, s94, 0x2000
	s_nop 1
	global_load_lds_dwordx4 v[76:77], off
	v_lshl_add_u64 v[78:79], v[78:79], 0, s[96:97]
	s_add_u32 m0, s94, 0x6000
	s_nop 1
	global_load_lds_dwordx4 v[78:79], off
	v_lshl_add_u64 v[82:83], v[82:83], 0, s[96:97]
	s_add_u32 m0, s94, 0x3000
	s_nop 1
	global_load_lds_dwordx4 v[82:83], off
	v_lshl_add_u64 v[80:81], v[80:81], 0, s[96:97]
	s_add_u32 m0, s94, 0x7000
	s_nop 1
	global_load_lds_dwordx4 v[80:81], off
	s_waitcnt lgkmcnt(4)
	v_mfma_f32_32x32x16_bf16 v[16:31], v[90:93], v[98:101], v[16:31]
	s_waitcnt lgkmcnt(1)
	v_mfma_f32_32x32x16_bf16 v[48:63], v[90:93], v[110:113], v[48:63]
	ds_read_b128 v[90:93], v170 offset:36864
	ds_read_b128 v[118:121], v171 offset:36864
	s_waitcnt lgkmcnt(1)
	v_mfma_f32_32x32x16_bf16 v[0:15], v[90:93], v[98:101], v[0:15]
	v_mfma_f32_32x32x16_bf16 v[32:47], v[90:93], v[110:113], v[32:47]
	v_mfma_f32_32x32x16_bf16 v[16:31], v[102:105], v[106:109], v[16:31]
	v_mfma_f32_32x32x16_bf16 v[48:63], v[102:105], v[114:117], v[48:63]
	s_waitcnt lgkmcnt(0)
	v_mfma_f32_32x32x16_bf16 v[0:15], v[118:121], v[106:109], v[0:15]
	ds_read_b128 v[90:93], v172 offset:32768
	ds_read_b128 v[98:101], v176 offset:49152
	ds_read_b128 v[102:105], v173 offset:32768
	ds_read_b128 v[106:109], v177 offset:49152
	v_mfma_f32_32x32x16_bf16 v[32:47], v[118:121], v[114:117], v[32:47]
	ds_read_b128 v[110:113], v176 offset:53248
	ds_read_b128 v[114:117], v177 offset:53248
	s_waitcnt lgkmcnt(4)
	v_mfma_f32_32x32x16_bf16 v[16:31], v[90:93], v[98:101], v[16:31]
	s_waitcnt lgkmcnt(1)
	v_mfma_f32_32x32x16_bf16 v[48:63], v[90:93], v[110:113], v[48:63]
	ds_read_b128 v[90:93], v172 offset:36864
	ds_read_b128 v[118:121], v173 offset:36864
	s_waitcnt lgkmcnt(1)
	v_mfma_f32_32x32x16_bf16 v[0:15], v[90:93], v[98:101], v[0:15]
	v_mfma_f32_32x32x16_bf16 v[32:47], v[90:93], v[110:113], v[32:47]
	v_mfma_f32_32x32x16_bf16 v[16:31], v[102:105], v[106:109], v[16:31]
	v_mfma_f32_32x32x16_bf16 v[48:63], v[102:105], v[114:117], v[48:63]
	s_waitcnt lgkmcnt(0)
	v_mfma_f32_32x32x16_bf16 v[0:15], v[118:121], v[106:109], v[0:15]
	s_waitcnt vmcnt(0)
	s_barrier
;     ...
;   bf16* As1 = As + 2 * 128 * 72;
;   bf16* Bs1 = As1 + 128 * 72;
;   G_LOAD(ra0, rb0, 0);
;   if (nk > 1) G_LOAD(ra1, rb1, 1);
;   G_STORE(ra0, rb0, As, Bs);
;   __syncthreads();
;   for (int kt = 0; kt < nk; kt += 2) {
;     if (kt + 2 < nk) G_LOAD(ra0, rb0, kt + 2);
;     if (kt + 1 < nk) G_STORE(ra1, rb1, As1, Bs1);
;     G_COMPUTE(As, Bs);
;     __syncthreads();
;     if (kt + 1 < nk) {
;       if (kt + 3 < nk) G_LOAD(ra1, rb1, kt + 3);
;       if (kt + 2 < nk) G_STORE(ra0, rb0, As, Bs);
;       G_COMPUTE(As1, Bs1);
;       __syncthreads();
;     }
;   }
	v_mfma_f32_32x32x16_bf16 v[32:47], v[118:121], v[114:117], v[32:47]
	ds_read_b128 v[90:93], v170 offset:0
	ds_read_b128 v[98:101], v174 offset:16384
	ds_read_b128 v[102:105], v171 offset:0
	ds_read_b128 v[106:109], v175 offset:16384
	ds_read_b128 v[110:113], v174 offset:20480
	ds_read_b128 v[114:117], v175 offset:20480
	v_lshl_add_u64 v[68:69], v[68:69], 0, s[96:97]
	s_add_u32 m0, s94, 0x8000
	s_nop 1
	global_load_lds_dwordx4 v[68:69], off
	v_lshl_add_u64 v[70:71], v[70:71], 0, s[96:97]
	s_add_u32 m0, s94, 0xc000
	s_nop 1
	global_load_lds_dwordx4 v[70:71], off
	v_lshl_add_u64 v[72:73], v[72:73], 0, s[96:97]
	s_add_u32 m0, s94, 0x9000
	s_nop 1
	global_load_lds_dwordx4 v[72:73], off
	v_lshl_add_u64 v[74:75], v[74:75], 0, s[96:97]
	s_add_u32 m0, s94, 0xd000
	s_nop 1
	global_load_lds_dwordx4 v[74:75], off
	v_lshl_add_u64 v[76:77], v[76:77], 0, s[96:97]
	s_add_u32 m0, s94, 0xa000
	s_nop 1
	global_load_lds_dwordx4 v[76:77], off
	v_lshl_add_u64 v[78:79], v[78:79], 0, s[96:97]
	s_add_u32 m0, s94, 0xe000
	s_nop 1
	global_load_lds_dwordx4 v[78:79], off
	v_lshl_add_u64 v[82:83], v[82:83], 0, s[96:97]
	s_add_u32 m0, s94, 0xb000
	s_nop 1
	global_load_lds_dwordx4 v[82:83], off
	v_lshl_add_u64 v[80:81], v[80:81], 0, s[96:97]
	s_add_u32 m0, s94, 0xf000
	s_nop 1
	global_load_lds_dwordx4 v[80:81], off
	s_waitcnt lgkmcnt(4)
	v_mfma_f32_32x32x16_bf16 v[16:31], v[90:93], v[98:101], v[16:31]
	s_waitcnt lgkmcnt(1)
	v_mfma_f32_32x32x16_bf16 v[48:63], v[90:93], v[110:113], v[48:63]
	ds_read_b128 v[90:93], v170 offset:4096
	ds_read_b128 v[118:121], v171 offset:4096
	s_waitcnt lgkmcnt(1)
	v_mfma_f32_32x32x16_bf16 v[0:15], v[90:93], v[98:101], v[0:15]
	v_mfma_f32_32x32x16_bf16 v[32:47], v[90:93], v[110:113], v[32:47]
	v_mfma_f32_32x32x16_bf16 v[16:31], v[102:105], v[106:109], v[16:31]
	v_mfma_f32_32x32x16_bf16 v[48:63], v[102:105], v[114:117], v[48:63]
	s_waitcnt lgkmcnt(0)
	v_mfma_f32_32x32x16_bf16 v[0:15], v[118:121], v[106:109], v[0:15]
	ds_read_b128 v[90:93], v172 offset:0
	ds_read_b128 v[98:101], v176 offset:16384
	ds_read_b128 v[102:105], v173 offset:0
	ds_read_b128 v[106:109], v177 offset:16384
	v_mfma_f32_32x32x16_bf16 v[32:47], v[118:121], v[114:117], v[32:47]
	ds_read_b128 v[110:113], v176 offset:20480
	ds_read_b128 v[114:117], v177 offset:20480
	s_waitcnt lgkmcnt(4)
	v_mfma_f32_32x32x16_bf16 v[16:31], v[90:93], v[98:101], v[16:31]
	s_waitcnt lgkmcnt(1)
	v_mfma_f32_32x32x16_bf16 v[48:63], v[90:93], v[110:113], v[48:63]
	ds_read_b128 v[90:93], v172 offset:4096
	ds_read_b128 v[118:121], v173 offset:4096
	s_waitcnt lgkmcnt(1)
	v_mfma_f32_32x32x16_bf16 v[0:15], v[90:93], v[98:101], v[0:15]
	v_mfma_f32_32x32x16_bf16 v[32:47], v[90:93], v[110:113], v[32:47]
	v_mfma_f32_32x32x16_bf16 v[16:31], v[102:105], v[106:109], v[16:31]
	v_mfma_f32_32x32x16_bf16 v[48:63], v[102:105], v[114:117], v[48:63]
	s_waitcnt lgkmcnt(0)
	v_mfma_f32_32x32x16_bf16 v[0:15], v[118:121], v[106:109], v[0:15]
	s_waitcnt vmcnt(0)
	s_barrier
	v_mfma_f32_32x32x16_bf16 v[32:47], v[118:121], v[114:117], v[32:47]
	ds_read_b128 v[90:93], v170 offset:32768
	ds_read_b128 v[98:101], v174 offset:49152
	ds_read_b128 v[102:105], v171 offset:32768
	ds_read_b128 v[106:109], v175 offset:49152
	ds_read_b128 v[110:113], v174 offset:53248
	ds_read_b128 v[114:117], v175 offset:53248
	v_lshl_add_u64 v[68:69], v[68:69], 0, s[96:97]
	s_add_u32 m0, s94, 0x0
	s_nop 1
	global_load_lds_dwordx4 v[68:69], off
	v_lshl_add_u64 v[70:71], v[70:71], 0, s[96:97]
	s_add_u32 m0, s94, 0x4000
	s_nop 1
	global_load_lds_dwordx4 v[70:71], off
	v_lshl_add_u64 v[72:73], v[72:73], 0, s[96:97]
	s_add_u32 m0, s94, 0x1000
	s_nop 1
	global_load_lds_dwordx4 v[72:73], off
	v_lshl_add_u64 v[74:75], v[74:75], 0, s[96:97]
	s_add_u32 m0, s94, 0x5000
	s_nop 1
	global_load_lds_dwordx4 v[74:75], off
	v_lshl_add_u64 v[76:77], v[76:77], 0, s[96:97]
	s_add_u32 m0, s94, 0x2000
	s_nop 1
	global_load_lds_dwordx4 v[76:77], off
	v_lshl_add_u64 v[78:79], v[78:79], 0, s[96:97]
	s_add_u32 m0, s94, 0x6000
	s_nop 1
	global_load_lds_dwordx4 v[78:79], off
	v_lshl_add_u64 v[82:83], v[82:83], 0, s[96:97]
	s_add_u32 m0, s94, 0x3000
	s_nop 1
	global_load_lds_dwordx4 v[82:83], off
	v_lshl_add_u64 v[80:81], v[80:81], 0, s[96:97]
	s_add_u32 m0, s94, 0x7000
	s_nop 1
	global_load_lds_dwordx4 v[80:81], off
	s_waitcnt lgkmcnt(4)
	v_mfma_f32_32x32x16_bf16 v[16:31], v[90:93], v[98:101], v[16:31]
	s_waitcnt lgkmcnt(1)
	v_mfma_f32_32x32x16_bf16 v[48:63], v[90:93], v[110:113], v[48:63]
	ds_read_b128 v[90:93], v170 offset:36864
	ds_read_b128 v[118:121], v171 offset:36864
	s_waitcnt lgkmcnt(1)
	v_mfma_f32_32x32x16_bf16 v[0:15], v[90:93], v[98:101], v[0:15]
	v_mfma_f32_32x32x16_bf16 v[32:47], v[90:93], v[110:113], v[32:47]
	v_mfma_f32_32x32x16_bf16 v[16:31], v[102:105], v[106:109], v[16:31]
	v_mfma_f32_32x32x16_bf16 v[48:63], v[102:105], v[114:117], v[48:63]
	s_waitcnt lgkmcnt(0)
	v_mfma_f32_32x32x16_bf16 v[0:15], v[118:121], v[106:109], v[0:15]
	ds_read_b128 v[90:93], v172 offset:32768
	ds_read_b128 v[98:101], v176 offset:49152
	ds_read_b128 v[102:105], v173 offset:32768
	ds_read_b128 v[106:109], v177 offset:49152
	v_mfma_f32_32x32x16_bf16 v[32:47], v[118:121], v[114:117], v[32:47]
	ds_read_b128 v[110:113], v176 offset:53248
	ds_read_b128 v[114:117], v177 offset:53248
	s_waitcnt lgkmcnt(4)
	v_mfma_f32_32x32x16_bf16 v[16:31], v[90:93], v[98:101], v[16:31]
	s_waitcnt lgkmcnt(1)
	v_mfma_f32_32x32x16_bf16 v[48:63], v[90:93], v[110:113], v[48:63]
	ds_read_b128 v[90:93], v172 offset:36864
	ds_read_b128 v[118:121], v173 offset:36864
	s_waitcnt lgkmcnt(1)
	v_mfma_f32_32x32x16_bf16 v[0:15], v[90:93], v[98:101], v[0:15]
	v_mfma_f32_32x32x16_bf16 v[32:47], v[90:93], v[110:113], v[32:47]
	v_mfma_f32_32x32x16_bf16 v[16:31], v[102:105], v[106:109], v[16:31]
	v_mfma_f32_32x32x16_bf16 v[48:63], v[102:105], v[114:117], v[48:63]
	s_nop 0
	s_nop 0
	s_nop 0
	s_nop 0
	s_nop 0
	s_nop 0
	s_nop 0
	s_waitcnt lgkmcnt(0)
	s_waitcnt vmcnt(0)
	s_barrier
; #define PW(T, off) ((T*)(lndp(p.ws) + (off)))
; DEVI int accrow(int r, int lane) { return (r & 3) + 8 * (r >> 2) + 4 * (lane >> 5); }
; DEVI void gemm_epi_ssd_in(const Params& p, f32x16 (&acc)[2][2], int rbase, int cbase, int lane) {
;   char* ar = PW(char, W_arena);
;   const int d = lane & 31;
;   if (cbase < 6144) {
;     const bool isz = cbase < 2048;
;     const int ld = isz ? 2048 : 4096;
;     bf16* dst = (isz ? (bf16*)(ar + S_ZB) + cbase : (bf16*)(ar + S_XBC) + (cbase - 2048)) + d;
; #pragma unroll
;     for (int i = 0; i < 2; ++i)
; #pragma unroll
;       for (int r = 0; r < 16; ++r) {
;         const int row = rbase + i * 32 + accrow(r, lane);
;         if (row < M) {
;           bf16* q = dst + (size_t)row * ld;
;           q[0] = f2bf(acc[i][0][r]);
;           q[32] = f2bf(acc[i][1][r]);
;         }
;       }
;   } else {
;     float* dtr = (float*)(ar + S_DTRAW);
; #pragma unroll
;     for (int i = 0; i < 2; ++i)
; #pragma unroll
;       for (int r = 0; r < 16; ++r) {
;         const int row = rbase + i * 32 + accrow(r, lane);
;         if (row < M && cbase == 6144) dtr[(size_t)row * 32 + d] = acc[i][0][r];
;       }
;   }
;     ...
;   for (int kt = 0; kt < nk; kt += 2) {
;     if (kt + 2 < nk) G_LOAD(ra0, rb0, kt + 2);
;     if (kt + 1 < nk) G_STORE(ra1, rb1, As1, Bs1);
;     G_COMPUTE(As, Bs);
;     __syncthreads();
;     if (kt + 1 < nk) {
;       if (kt + 3 < nk) G_LOAD(ra1, rb1, kt + 3);
;       if (kt + 2 < nk) G_STORE(ra0, rb0, As, Bs);
;       G_COMPUTE(As1, Bs1);
;       __syncthreads();
;     }
;   }
	v_lshl_add_u64 v[68:69], v[68:69], 0, s[96:97]
	s_add_u32 m0, s94, 0x8000
	s_nop 1
	global_load_lds_dwordx4 v[68:69], off
	v_lshl_add_u64 v[70:71], v[70:71], 0, s[96:97]
	s_add_u32 m0, s94, 0xc000
	s_nop 1
	global_load_lds_dwordx4 v[70:71], off
	v_lshl_add_u64 v[72:73], v[72:73], 0, s[96:97]
	s_add_u32 m0, s94, 0x9000
	s_nop 1
	global_load_lds_dwordx4 v[72:73], off
	v_lshl_add_u64 v[74:75], v[74:75], 0, s[96:97]
	s_add_u32 m0, s94, 0xd000
	s_nop 1
	global_load_lds_dwordx4 v[74:75], off
	v_lshl_add_u64 v[76:77], v[76:77], 0, s[96:97]
	s_add_u32 m0, s94, 0xa000
	s_nop 1
	global_load_lds_dwordx4 v[76:77], off
	v_lshl_add_u64 v[78:79], v[78:79], 0, s[96:97]
	s_add_u32 m0, s94, 0xe000
	s_nop 1
	global_load_lds_dwordx4 v[78:79], off
	v_lshl_add_u64 v[82:83], v[82:83], 0, s[96:97]
	s_add_u32 m0, s94, 0xb000
	s_nop 1
	global_load_lds_dwordx4 v[82:83], off
	v_lshl_add_u64 v[80:81], v[80:81], 0, s[96:97]
	s_add_u32 m0, s94, 0xf000
	s_nop 1
	global_load_lds_dwordx4 v[80:81], off
	v_mfma_f32_32x32x16_bf16 v[0:15], v[118:121], v[106:109], v[0:15]
	ds_read_b128 v[68:71], v170 offset:0
	ds_read_b128 v[72:75], v174 offset:16384
	ds_read_b128 v[76:79], v171 offset:0
	ds_read_b128 v[80:83], v175 offset:16384
	ds_read_b128 v[90:93], v174 offset:20480
	ds_read_b128 v[98:101], v175 offset:20480
	v_mfma_f32_32x32x16_bf16 v[32:47], v[118:121], v[114:117], v[32:47]
	s_waitcnt lgkmcnt(4)
	v_mfma_f32_32x32x16_bf16 v[16:31], v[68:71], v[72:75], v[16:31]
	s_waitcnt lgkmcnt(1)
	v_mfma_f32_32x32x16_bf16 v[48:63], v[68:71], v[90:93], v[48:63]
	ds_read_b128 v[68:71], v170 offset:4096
	ds_read_b128 v[102:105], v171 offset:4096
	s_waitcnt lgkmcnt(1)
	v_mfma_f32_32x32x16_bf16 v[0:15], v[68:71], v[72:75], v[0:15]
	v_mfma_f32_32x32x16_bf16 v[32:47], v[68:71], v[90:93], v[32:47]
	v_mfma_f32_32x32x16_bf16 v[16:31], v[76:79], v[80:83], v[16:31]
	v_mfma_f32_32x32x16_bf16 v[48:63], v[76:79], v[98:101], v[48:63]
	s_waitcnt lgkmcnt(0)
	v_mfma_f32_32x32x16_bf16 v[0:15], v[102:105], v[80:83], v[0:15]
	ds_read_b128 v[68:71], v172 offset:0
	ds_read_b128 v[72:75], v176 offset:16384
	ds_read_b128 v[76:79], v173 offset:0
	ds_read_b128 v[80:83], v177 offset:16384
	v_mfma_f32_32x32x16_bf16 v[32:47], v[102:105], v[98:101], v[32:47]
	ds_read_b128 v[90:93], v176 offset:20480
	ds_read_b128 v[98:101], v177 offset:20480
	s_waitcnt lgkmcnt(4)
	v_mfma_f32_32x32x16_bf16 v[16:31], v[68:71], v[72:75], v[16:31]
	s_waitcnt lgkmcnt(1)
	v_mfma_f32_32x32x16_bf16 v[48:63], v[68:71], v[90:93], v[48:63]
	ds_read_b128 v[68:71], v172 offset:4096
	ds_read_b128 v[102:105], v173 offset:4096
	s_waitcnt lgkmcnt(0)
	s_waitcnt vmcnt(0)
	s_barrier
	v_mfma_f32_32x32x16_bf16 v[0:15], v[68:71], v[72:75], v[0:15]
	v_mfma_f32_32x32x16_bf16 v[16:31], v[76:79], v[80:83], v[16:31]
	v_mfma_f32_32x32x16_bf16 v[48:63], v[76:79], v[98:101], v[48:63]
	v_mfma_f32_32x32x16_bf16 v[32:47], v[68:71], v[90:93], v[32:47]
	v_mfma_f32_32x32x16_bf16 v[0:15], v[102:105], v[80:83], v[0:15]
	ds_read_b128 v[68:71], v170 offset:32768
	ds_read_b128 v[72:75], v174 offset:49152
	ds_read_b128 v[76:79], v175 offset:49152
	ds_read_b128 v[80:83], v171 offset:32768
	ds_read_b128 v[90:93], v174 offset:53248
	s_waitcnt lgkmcnt(3)
	v_mfma_f32_32x32x16_bf16 v[16:31], v[68:71], v[72:75], v[16:31]
	s_waitcnt lgkmcnt(0)
	v_mfma_f32_32x32x16_bf16 v[48:63], v[68:71], v[90:93], v[48:63]
	ds_read_b128 v[68:71], v170 offset:36864
	v_mfma_f32_32x32x16_bf16 v[32:47], v[102:105], v[98:101], v[32:47]
	s_waitcnt lgkmcnt(0)
	v_mfma_f32_32x32x16_bf16 v[0:15], v[68:71], v[72:75], v[0:15]
	ds_read_b128 v[72:75], v171 offset:36864
	v_mfma_f32_32x32x16_bf16 v[32:47], v[68:71], v[90:93], v[32:47]
	ds_read_b128 v[68:71], v175 offset:53248
	v_mfma_f32_32x32x16_bf16 v[16:31], v[80:83], v[76:79], v[16:31]
	s_waitcnt lgkmcnt(0)
	v_mfma_f32_32x32x16_bf16 v[48:63], v[80:83], v[68:71], v[48:63]
	v_mfma_f32_32x32x16_bf16 v[0:15], v[72:75], v[76:79], v[0:15]
	v_mfma_f32_32x32x16_bf16 v[32:47], v[72:75], v[68:71], v[32:47]
	ds_read_b128 v[68:71], v172 offset:32768
	ds_read_b128 v[72:75], v176 offset:49152
	ds_read_b128 v[76:79], v176 offset:53248
	s_waitcnt lgkmcnt(1)
	v_mfma_f32_32x32x16_bf16 v[16:31], v[68:71], v[72:75], v[16:31]
	s_waitcnt lgkmcnt(0)
	v_mfma_f32_32x32x16_bf16 v[48:63], v[68:71], v[76:79], v[48:63]
	ds_read_b128 v[68:71], v172 offset:36864
	s_waitcnt lgkmcnt(0)
	v_mfma_f32_32x32x16_bf16 v[0:15], v[68:71], v[72:75], v[0:15]
	v_mfma_f32_32x32x16_bf16 v[32:47], v[68:71], v[76:79], v[32:47]
	ds_read_b128 v[68:71], v173 offset:32768
	ds_read_b128 v[72:75], v177 offset:49152
	ds_read_b128 v[76:79], v177 offset:53248
	ds_read_b128 v[80:83], v173 offset:36864
	v_and_b32_e32 v67, 63, v86
	v_and_or_b32 v66, v86, 64, s3
	s_waitcnt lgkmcnt(0)
	s_barrier
	v_mfma_f32_32x32x16_bf16 v[16:31], v[68:71], v[72:75], v[16:31]
	v_mfma_f32_32x32x16_bf16 v[48:63], v[68:71], v[76:79], v[48:63]
	v_add_u32_e32 v70, s2, v88
	s_movk_i32 s2, 0x17ff
	v_cmp_lt_i32_e32 vcc, s2, v66
	v_mfma_f32_32x32x16_bf16 v[0:15], v[80:83], v[72:75], v[0:15]
	v_lshrrev_b32_e32 v72, 3, v67
	v_and_b32_e32 v71, 4, v72
	v_mfma_f32_32x32x16_bf16 v[32:47], v[80:83], v[76:79], v[32:47]
	s_and_saveexec_b64 s[2:3], vcc
	s_xor_b64 s[2:3], exec, s[2:3]
	s_cbranch_execz .LBB0_4762
	s_movk_i32 s6, 0x1800
	v_lshlrev_b32_e32 v96, 2, v87
	v_cmp_eq_u32_e32 vcc, s6, v66
	s_nop 5
	v_lshl_add_u64 v[32:33], s[4:5], 0, v[96:97]
	s_mov_b64 s[6:7], 0x2cb5c000
	v_or_b32_e32 v34, v70, v71
	v_lshl_add_u64 v[32:33], v[32:33], 0, s[6:7]
	v_cmp_gt_i32_e64 s[6:7], s90, v34
	s_and_b64 s[12:13], vcc, s[6:7]
	s_and_saveexec_b64 s[6:7], s[12:13]
	s_cbranch_execz .LBB0_4699
	v_ashrrev_i32_e32 v35, 31, v34
	v_lshlrev_b64 v[34:35], 7, v[34:35]
	v_lshl_add_u64 v[34:35], v[32:33], 0, v[34:35]
	global_store_dword v[34:35], v16, off

; DEVI int TID() { int t = threadIdx.x; asm volatile("" : "+v"(t)); return t; }
; DEVI int BID() { int b = blockIdx.x; asm volatile("" : "+s"(b)); return b; }
;   bf16* As = (bf16*)smem;
;   bf16* Bs = As + 128 * 72;
;   const int tid = TID(), lane = tid & 63, wave = tid >> 6, wm = wave >> 1, wn = wave & 1;
;   f32x16 acc[2][2];
; #pragma unroll
;   for (int i = 0; i < 2; ++i)
; #pragma unroll
;     for (int j = 0; j < 2; ++j) acc[i][j] = zero16();
;   const int lrow = tid >> 3, lkc = (tid & 7) * 8;
;   const bf16* Ag = jb.A + (size_t)max(m0 + lrow, 0) * jb.lda + lkc;
;   const bf16* Ag1 = jb.A + (ptrdiff_t)(m0 + lrow) * jb.lda + lkc;
;   const bf16* Bg = jb.Bt + (size_t)(n0 + lrow) * jb.K + lkc;
;   const size_t astep = (size_t)32 * jb.lda, bstep = (size_t)32 * jb.K;
;   if (kt1 < 0) kt1 = jb.K >> 6;
;   const int nk = kt1 - kt0;
;   Ag += (size_t)kt0 * 64; Ag1 += (size_t)kt0 * 64; Bg += (size_t)kt0 * 64;
;   u32x4 ra0[4], rb0[4], ra1[4], rb1[4];
;     ...
;   bf16* As1 = As + 2 * 128 * 72;
;   bf16* Bs1 = As1 + 128 * 72;
;   G_LOAD(ra0, rb0, 0);
;   if (nk > 1) G_LOAD(ra1, rb1, 1);
;   G_STORE(ra0, rb0, As, Bs);
;   __syncthreads();
; DEVI void gemm_single(const Params& p, const GJob& jb, int nt, char* smem) {
;     ...
;   if (nt >= 16 && (gridDim.x & 7) == 0) {
;     const int b = BID(), x = b & 7, lb = b >> 3, nlb = gridDim.x >> 3;
;     const int ng = x & 3, mh = x >> 2;
;     const int n_lo = ng * nt / 4, nnt = (ng + 1) * nt / 4 - n_lo;
;     const int m_lo = mh * mtn / 2, nmt = (mh + 1) * mtn / 2 - m_lo;
;     for (int t = lb; t < nmt * nnt; t += nlb) {
;       const int mt = m_lo + t / nnt, ntg = n_lo + t % nnt;
;       gemm_tile(p, jb, fused ? mt * 126 - 2 : mt * 128, ntg * 128, smem);
.LBB0_4833:
	s_abs_i32 s3, s11
	s_mul_hi_u32 s4, s3, s18
	s_mul_i32 s5, s4, s14
	s_ashr_i32 s2, s11, 31
	s_sub_i32 s3, s3, s5
	s_xor_b32 s2, s2, s15
	s_add_i32 s5, s4, 1
	s_sub_i32 s6, s3, s14
	s_cmp_ge_u32 s3, s14
	s_cselect_b32 s4, s5, s4
	s_cselect_b32 s3, s6, s3
	s_add_i32 s5, s4, 1
	s_cmp_ge_u32 s3, s14
	s_cselect_b32 s3, s5, s4
	s_xor_b32 s3, s3, s2
	s_sub_i32 s3, s3, s2
	s_add_i32 s2, s3, s12
	v_mov_b32_e32 v86, v208
	s_lshl_b32 s2, s2, 7
	s_mul_i32 s3, s16, s3
	v_ashrrev_i32_e32 v84, 3, v86
	v_add_u32_e32 v0, s2, v84
	v_max_i32_e32 v96, 0, v0
	v_lshlrev_b32_e32 v1, 4, v86
	v_lshlrev_b64 v[2:3], 11, v[96:97]
	v_and_b32_e32 v96, 0x70, v1
	s_mov_b64 s[96:97], 0x80
	v_lshrrev_b32_e32 v178, 4, v208
	v_and_b32_e32 v178, 7, v178
	v_lshlrev_b32_e32 v178, 4, v178
	v_xor_b32_e32 v96, v96, v178
	v_lshrrev_b32_e32 v179, 6, v208
	v_lshlrev_b32_e32 v179, 10, v179
	v_lshrrev_b32_e32 v180, 5, v208
	v_lshrrev_b32_e32 v181, 1, v208
	v_xor_b32_e32 v180, v180, v181
	v_readfirstlane_b32 s94, v179
	v_and_b32_e32 v180, 1, v180
	v_lshlrev_b32_e32 v180, 4, v180
	v_and_b32_e32 v181, 31, v208
	v_lshlrev_b32_e32 v181, 7, v181
	v_or_b32_e32 v180, v180, v181
	v_lshrrev_b32_e32 v181, 7, v208
	v_lshlrev_b32_e32 v181, 13, v181
	v_or_b32_e32 v194, v180, v181
	v_bfe_u32 v181, v208, 6, 1
	v_lshlrev_b32_e32 v181, 13, v181
	v_or_b32_e32 v195, v180, v181
	v_bfe_u32 v178, v208, 2, 2
	v_xor_b32_e32 v179, 0, v178
	v_lshlrev_b32_e32 v179, 5, v179
	v_or_b32_e32 v170, v194, v179
	v_or_b32_e32 v174, v195, v179
	v_xor_b32_e32 v179, 1, v178
	v_lshlrev_b32_e32 v179, 5, v179
	v_or_b32_e32 v171, v194, v179
	v_or_b32_e32 v175, v195, v179
	v_xor_b32_e32 v179, 2, v178
	v_lshlrev_b32_e32 v179, 5, v179
	v_or_b32_e32 v172, v194, v179
	v_or_b32_e32 v176, v195, v179
	v_xor_b32_e32 v179, 3, v178
	v_lshlrev_b32_e32 v179, 5, v179
	v_or_b32_e32 v173, v194, v179
	v_or_b32_e32 v177, v195, v179
	v_ashrrev_i32_e32 v1, 31, v0
	v_lshlrev_b64 v[0:1], 11, v[0:1]
	v_lshl_add_u64 v[0:1], s[8:9], 0, v[0:1]
	v_lshl_add_u64 v[24:25], v[0:1], 0, v[96:97]
	v_subrev_u32_e32 v0, s3, v84
	v_add_u32_e32 v0, s17, v0
	v_ashrrev_i32_e32 v1, 31, v0
	v_lshlrev_b64 v[0:1], 11, v[0:1]
	v_lshl_add_u64 v[0:1], v[64:65], 0, v[0:1]
	v_add_co_u32_e32 v72, vcc, s63, v24
	v_lshl_add_u64 v[70:71], v[0:1], 0, v[96:97]
	s_nop 0
	v_addc_co_u32_e32 v73, vcc, 0, v25, vcc
	v_add_co_u32_e32 v74, vcc, s63, v70
	v_lshl_add_u64 v[2:3], s[8:9], 0, v[2:3]
	s_nop 0
	v_addc_co_u32_e32 v75, vcc, 0, v71, vcc
	v_add_co_u32_e32 v76, vcc, s64, v24
	v_lshl_add_u64 v[68:69], v[2:3], 0, v[96:97]
	s_nop 0
	v_addc_co_u32_e32 v77, vcc, 0, v25, vcc
	v_add_co_u32_e32 v78, vcc, s64, v70
	v_addc_co_u32_e32 v79, vcc, 0, v71, vcc
	v_add_co_u32_e32 v80, vcc, s65, v24
	s_nop 0
	v_addc_co_u32_e32 v81, vcc, 0, v25, vcc
	v_add_co_u32_e32 v82, vcc, s65, v70
	s_nop 0
	v_addc_co_u32_e32 v83, vcc, 0, v71, vcc
	v_ashrrev_i32_e32 v66, 1, v86
	v_and_b32_e32 v87, 31, v86
	v_lshrrev_b32_e32 v67, 1, v86
	v_and_b32_e32 v88, 0xffffffc0, v66
	v_and_b32_e32 v90, 16, v67
	v_or_b32_e32 v66, v88, v87
	v_mad_u64_u32 v[84:85], s[4:5], v84, s91, v[96:97]
	v_mad_u64_u32 v[66:67], s[4:5], v66, s91, v[90:91]
	v_add_u32_e32 v85, 0xd800, v84
	s_mov_b64 s[4:5], s[74:75]
	s_add_u32 m0, s94, 0x0
	s_nop 1
	global_load_lds_dwordx4 v[68:69], off
	s_add_u32 m0, s94, 0x4000
	s_nop 1
	global_load_lds_dwordx4 v[70:71], off
	s_add_u32 m0, s94, 0x1000
	s_nop 1
	global_load_lds_dwordx4 v[72:73], off
	s_add_u32 m0, s94, 0x5000
	s_nop 1
	global_load_lds_dwordx4 v[74:75], off
	s_add_u32 m0, s94, 0x2000
	s_nop 1
	global_load_lds_dwordx4 v[76:77], off
	s_add_u32 m0, s94, 0x6000
	s_nop 1
	global_load_lds_dwordx4 v[78:79], off
	s_add_u32 m0, s94, 0x3000
	s_nop 1
	global_load_lds_dwordx4 v[80:81], off
	s_add_u32 m0, s94, 0x7000
	s_nop 1
	global_load_lds_dwordx4 v[82:83], off
	s_waitcnt lgkmcnt(0)
	s_waitcnt vmcnt(0)
	s_barrier
	ds_read_b128 v[0:3], v170 offset:0
	v_and_b32_e32 v4, 0x5f, v86
	v_mad_u32_u24 v67, v4, s91, v90
	ds_read_b128 v[4:7], v174 offset:16384
	ds_read_b128 v[90:93], v171 offset:0
	ds_read_b128 v[98:101], v175 offset:16384
	ds_read_b128 v[32:35], v174 offset:20480
	ds_read_b128 v[102:105], v175 offset:20480
	v_lshl_add_u64 v[68:69], v[68:69], 0, s[96:97]
	s_add_u32 m0, s94, 0x8000
	s_nop 1
	global_load_lds_dwordx4 v[68:69], off
	v_lshl_add_u64 v[70:71], v[70:71], 0, s[96:97]
	s_add_u32 m0, s94, 0xc000
	s_nop 1
	global_load_lds_dwordx4 v[70:71], off
	v_lshl_add_u64 v[72:73], v[72:73], 0, s[96:97]
	s_add_u32 m0, s94, 0x9000
	s_nop 1
	global_load_lds_dwordx4 v[72:73], off
	v_lshl_add_u64 v[74:75], v[74:75], 0, s[96:97]
	s_add_u32 m0, s94, 0xd000
	s_nop 1
	global_load_lds_dwordx4 v[74:75], off
	v_lshl_add_u64 v[76:77], v[76:77], 0, s[96:97]
	s_add_u32 m0, s94, 0xa000
	s_nop 1
	global_load_lds_dwordx4 v[76:77], off
	v_lshl_add_u64 v[78:79], v[78:79], 0, s[96:97]
	s_add_u32 m0, s94, 0xe000
	s_nop 1
	global_load_lds_dwordx4 v[78:79], off
	v_lshl_add_u64 v[80:81], v[80:81], 0, s[96:97]
	s_add_u32 m0, s94, 0xb000
	s_nop 1
	global_load_lds_dwordx4 v[80:81], off
	v_lshl_add_u64 v[82:83], v[82:83], 0, s[96:97]
	s_add_u32 m0, s94, 0xf000
	s_nop 1
	global_load_lds_dwordx4 v[82:83], off
	s_waitcnt lgkmcnt(4)
	v_mfma_f32_32x32x16_bf16 v[16:31], v[0:3], v[4:7], 0
	ds_read_b128 v[36:39], v170 offset:4096
	ds_read_b128 v[106:109], v171 offset:4096
	s_waitcnt lgkmcnt(3)
	v_mfma_f32_32x32x16_bf16 v[48:63], v[0:3], v[32:35], 0
	s_waitcnt lgkmcnt(1)
	v_mfma_f32_32x32x16_bf16 v[0:15], v[36:39], v[4:7], 0
	v_mfma_f32_32x32x16_bf16 v[32:47], v[36:39], v[32:35], 0
	v_mfma_f32_32x32x16_bf16 v[16:31], v[90:93], v[98:101], v[16:31]
	v_mfma_f32_32x32x16_bf16 v[48:63], v[90:93], v[102:105], v[48:63]
	s_waitcnt lgkmcnt(0)
	v_mfma_f32_32x32x16_bf16 v[0:15], v[106:109], v[98:101], v[0:15]
	v_mfma_f32_32x32x16_bf16 v[32:47], v[106:109], v[102:105], v[32:47]
	ds_read_b128 v[90:93], v172 offset:0
	ds_read_b128 v[98:101], v176 offset:16384
	ds_read_b128 v[102:105], v173 offset:0
	ds_read_b128 v[106:109], v177 offset:16384
	ds_read_b128 v[110:113], v176 offset:20480
	ds_read_b128 v[114:117], v177 offset:20480
	s_waitcnt lgkmcnt(4)
	v_mfma_f32_32x32x16_bf16 v[16:31], v[90:93], v[98:101], v[16:31]
	s_waitcnt lgkmcnt(1)
	v_mfma_f32_32x32x16_bf16 v[48:63], v[90:93], v[110:113], v[48:63]
	ds_read_b128 v[90:93], v172 offset:4096
	ds_read_b128 v[118:121], v173 offset:4096
	s_waitcnt lgkmcnt(1)
	v_mfma_f32_32x32x16_bf16 v[0:15], v[90:93], v[98:101], v[0:15]
	v_mfma_f32_32x32x16_bf16 v[32:47], v[90:93], v[110:113], v[32:47]
	v_mfma_f32_32x32x16_bf16 v[16:31], v[102:105], v[106:109], v[16:31]
	v_mfma_f32_32x32x16_bf16 v[48:63], v[102:105], v[114:117], v[48:63]
	s_waitcnt lgkmcnt(0)
	v_mfma_f32_32x32x16_bf16 v[0:15], v[118:121], v[106:109], v[0:15]
	s_waitcnt vmcnt(0)
	s_barrier
;     ...
;   bf16* As1 = As + 2 * 128 * 72;
;   bf16* Bs1 = As1 + 128 * 72;
;   G_LOAD(ra0, rb0, 0);
;   if (nk > 1) G_LOAD(ra1, rb1, 1);
;   G_STORE(ra0, rb0, As, Bs);
;   __syncthreads();
;   for (int kt = 0; kt < nk; kt += 2) {
;     if (kt + 2 < nk) G_LOAD(ra0, rb0, kt + 2);
;     if (kt + 1 < nk) G_STORE(ra1, rb1, As1, Bs1);
;     G_COMPUTE(As, Bs);
;     __syncthreads();
;     if (kt + 1 < nk) {
;       if (kt + 3 < nk) G_LOAD(ra1, rb1, kt + 3);
;       if (kt + 2 < nk) G_STORE(ra0, rb0, As, Bs);
;       G_COMPUTE(As1, Bs1);
;       __syncthreads();
;     }
;   }
	v_mfma_f32_32x32x16_bf16 v[32:47], v[118:121], v[114:117], v[32:47]
	ds_read_b128 v[90:93], v170 offset:32768
	ds_read_b128 v[98:101], v174 offset:49152
	ds_read_b128 v[102:105], v171 offset:32768
	ds_read_b128 v[106:109], v175 offset:49152
	ds_read_b128 v[110:113], v174 offset:53248
	ds_read_b128 v[114:117], v175 offset:53248
	v_lshl_add_u64 v[68:69], v[68:69], 0, s[96:97]
	s_add_u32 m0, s94, 0x0
	s_nop 1
	global_load_lds_dwordx4 v[68:69], off
	v_lshl_add_u64 v[70:71], v[70:71], 0, s[96:97]
	s_add_u32 m0, s94, 0x4000
	s_nop 1
	global_load_lds_dwordx4 v[70:71], off
	v_lshl_add_u64 v[72:73], v[72:73], 0, s[96:97]
	s_add_u32 m0, s94, 0x1000
	s_nop 1
	global_load_lds_dwordx4 v[72:73], off
	v_lshl_add_u64 v[74:75], v[74:75], 0, s[96:97]
	s_add_u32 m0, s94, 0x5000
	s_nop 1
	global_load_lds_dwordx4 v[74:75], off
	v_lshl_add_u64 v[76:77], v[76:77], 0, s[96:97]
	s_add_u32 m0, s94, 0x2000
	s_nop 1
	global_load_lds_dwordx4 v[76:77], off
	v_lshl_add_u64 v[78:79], v[78:79], 0, s[96:97]
	s_add_u32 m0, s94, 0x6000
	s_nop 1
	global_load_lds_dwordx4 v[78:79], off
	v_lshl_add_u64 v[80:81], v[80:81], 0, s[96:97]
	s_add_u32 m0, s94, 0x3000
	s_nop 1
	global_load_lds_dwordx4 v[80:81], off
	v_lshl_add_u64 v[82:83], v[82:83], 0, s[96:97]
	s_add_u32 m0, s94, 0x7000
	s_nop 1
	global_load_lds_dwordx4 v[82:83], off
	s_waitcnt lgkmcnt(4)
	v_mfma_f32_32x32x16_bf16 v[16:31], v[90:93], v[98:101], v[16:31]
	s_waitcnt lgkmcnt(1)
	v_mfma_f32_32x32x16_bf16 v[48:63], v[90:93], v[110:113], v[48:63]
	ds_read_b128 v[90:93], v170 offset:36864
	ds_read_b128 v[118:121], v171 offset:36864
	s_waitcnt lgkmcnt(1)
	v_mfma_f32_32x32x16_bf16 v[0:15], v[90:93], v[98:101], v[0:15]
	v_mfma_f32_32x32x16_bf16 v[32:47], v[90:93], v[110:113], v[32:47]
	v_mfma_f32_32x32x16_bf16 v[16:31], v[102:105], v[106:109], v[16:31]
	v_mfma_f32_32x32x16_bf16 v[48:63], v[102:105], v[114:117], v[48:63]
	s_waitcnt lgkmcnt(0)
	v_mfma_f32_32x32x16_bf16 v[0:15], v[118:121], v[106:109], v[0:15]
	ds_read_b128 v[90:93], v172 offset:32768
	ds_read_b128 v[98:101], v176 offset:49152
	ds_read_b128 v[102:105], v173 offset:32768
	ds_read_b128 v[106:109], v177 offset:49152
	v_mfma_f32_32x32x16_bf16 v[32:47], v[118:121], v[114:117], v[32:47]
	ds_read_b128 v[110:113], v176 offset:53248
	ds_read_b128 v[114:117], v177 offset:53248
	s_waitcnt lgkmcnt(4)
	v_mfma_f32_32x32x16_bf16 v[16:31], v[90:93], v[98:101], v[16:31]
	s_waitcnt lgkmcnt(1)
	v_mfma_f32_32x32x16_bf16 v[48:63], v[90:93], v[110:113], v[48:63]
	ds_read_b128 v[90:93], v172 offset:36864
	ds_read_b128 v[118:121], v173 offset:36864
	s_waitcnt lgkmcnt(1)
	v_mfma_f32_32x32x16_bf16 v[0:15], v[90:93], v[98:101], v[0:15]
	v_mfma_f32_32x32x16_bf16 v[32:47], v[90:93], v[110:113], v[32:47]
	v_mfma_f32_32x32x16_bf16 v[16:31], v[102:105], v[106:109], v[16:31]
	v_mfma_f32_32x32x16_bf16 v[48:63], v[102:105], v[114:117], v[48:63]
	s_waitcnt lgkmcnt(0)
	v_mfma_f32_32x32x16_bf16 v[0:15], v[118:121], v[106:109], v[0:15]
	s_waitcnt vmcnt(0)
	s_barrier
	v_mfma_f32_32x32x16_bf16 v[32:47], v[118:121], v[114:117], v[32:47]
	ds_read_b128 v[90:93], v170 offset:0
	ds_read_b128 v[98:101], v174 offset:16384
	ds_read_b128 v[102:105], v171 offset:0
	ds_read_b128 v[106:109], v175 offset:16384
	ds_read_b128 v[110:113], v174 offset:20480
	ds_read_b128 v[114:117], v175 offset:20480
	v_lshl_add_u64 v[68:69], v[68:69], 0, s[96:97]
	s_add_u32 m0, s94, 0x8000
	s_nop 1
	global_load_lds_dwordx4 v[68:69], off
	v_lshl_add_u64 v[70:71], v[70:71], 0, s[96:97]
	s_add_u32 m0, s94, 0xc000
	s_nop 1
	global_load_lds_dwordx4 v[70:71], off
	v_lshl_add_u64 v[72:73], v[72:73], 0, s[96:97]
	s_add_u32 m0, s94, 0x9000
	s_nop 1
	global_load_lds_dwordx4 v[72:73], off
	v_lshl_add_u64 v[74:75], v[74:75], 0, s[96:97]
	s_add_u32 m0, s94, 0xd000
	s_nop 1
	global_load_lds_dwordx4 v[74:75], off
	v_lshl_add_u64 v[76:77], v[76:77], 0, s[96:97]
	s_add_u32 m0, s94, 0xa000
	s_nop 1
	global_load_lds_dwordx4 v[76:77], off
	v_lshl_add_u64 v[78:79], v[78:79], 0, s[96:97]
	s_add_u32 m0, s94, 0xe000
	s_nop 1
	global_load_lds_dwordx4 v[78:79], off
	v_lshl_add_u64 v[80:81], v[80:81], 0, s[96:97]
	s_add_u32 m0, s94, 0xb000
	s_nop 1
	global_load_lds_dwordx4 v[80:81], off
	v_lshl_add_u64 v[82:83], v[82:83], 0, s[96:97]
	s_add_u32 m0, s94, 0xf000
	s_nop 1
	global_load_lds_dwordx4 v[82:83], off
	s_waitcnt lgkmcnt(4)
	v_mfma_f32_32x32x16_bf16 v[16:31], v[90:93], v[98:101], v[16:31]
	s_waitcnt lgkmcnt(1)
	v_mfma_f32_32x32x16_bf16 v[48:63], v[90:93], v[110:113], v[48:63]
	ds_read_b128 v[90:93], v170 offset:4096
	ds_read_b128 v[118:121], v171 offset:4096
	s_waitcnt lgkmcnt(1)
	v_mfma_f32_32x32x16_bf16 v[0:15], v[90:93], v[98:101], v[0:15]
	v_mfma_f32_32x32x16_bf16 v[32:47], v[90:93], v[110:113], v[32:47]
	v_mfma_f32_32x32x16_bf16 v[16:31], v[102:105], v[106:109], v[16:31]
	v_mfma_f32_32x32x16_bf16 v[48:63], v[102:105], v[114:117], v[48:63]
	s_waitcnt lgkmcnt(0)
	v_mfma_f32_32x32x16_bf16 v[0:15], v[118:121], v[106:109], v[0:15]
	ds_read_b128 v[90:93], v172 offset:0
	ds_read_b128 v[98:101], v176 offset:16384
	ds_read_b128 v[102:105], v173 offset:0
	ds_read_b128 v[106:109], v177 offset:16384
	v_mfma_f32_32x32x16_bf16 v[32:47], v[118:121], v[114:117], v[32:47]
	ds_read_b128 v[110:113], v176 offset:20480
	ds_read_b128 v[114:117], v177 offset:20480
	s_waitcnt lgkmcnt(4)
	v_mfma_f32_32x32x16_bf16 v[16:31], v[90:93], v[98:101], v[16:31]
	s_waitcnt lgkmcnt(1)
	v_mfma_f32_32x32x16_bf16 v[48:63], v[90:93], v[110:113], v[48:63]
	ds_read_b128 v[90:93], v172 offset:4096
	ds_read_b128 v[118:121], v173 offset:4096
	s_waitcnt lgkmcnt(1)
	v_mfma_f32_32x32x16_bf16 v[0:15], v[90:93], v[98:101], v[0:15]
	v_mfma_f32_32x32x16_bf16 v[32:47], v[90:93], v[110:113], v[32:47]
	v_mfma_f32_32x32x16_bf16 v[16:31], v[102:105], v[106:109], v[16:31]
	v_mfma_f32_32x32x16_bf16 v[48:63], v[102:105], v[114:117], v[48:63]
	s_waitcnt lgkmcnt(0)
	v_mfma_f32_32x32x16_bf16 v[0:15], v[118:121], v[106:109], v[0:15]
	s_waitcnt vmcnt(0)
	s_barrier
;     ...
;   bf16* As1 = As + 2 * 128 * 72;
;   bf16* Bs1 = As1 + 128 * 72;
;   G_LOAD(ra0, rb0, 0);
;   if (nk > 1) G_LOAD(ra1, rb1, 1);
;   G_STORE(ra0, rb0, As, Bs);
;   __syncthreads();
;   for (int kt = 0; kt < nk; kt += 2) {
;     if (kt + 2 < nk) G_LOAD(ra0, rb0, kt + 2);
;     if (kt + 1 < nk) G_STORE(ra1, rb1, As1, Bs1);
;     G_COMPUTE(As, Bs);
;     __syncthreads();
;     if (kt + 1 < nk) {
;       if (kt + 3 < nk) G_LOAD(ra1, rb1, kt + 3);
;       if (kt + 2 < nk) G_STORE(ra0, rb0, As, Bs);
;       G_COMPUTE(As1, Bs1);
;       __syncthreads();
;     }
;   }
	v_mfma_f32_32x32x16_bf16 v[32:47], v[118:121], v[114:117], v[32:47]
	ds_read_b128 v[90:93], v170 offset:32768
	ds_read_b128 v[98:101], v174 offset:49152
	ds_read_b128 v[102:105], v171 offset:32768
	ds_read_b128 v[106:109], v175 offset:49152
	ds_read_b128 v[110:113], v174 offset:53248
	ds_read_b128 v[114:117], v175 offset:53248
	v_lshl_add_u64 v[68:69], v[68:69], 0, s[96:97]
	s_add_u32 m0, s94, 0x0
	s_nop 1
	global_load_lds_dwordx4 v[68:69], off
	v_lshl_add_u64 v[70:71], v[70:71], 0, s[96:97]
	s_add_u32 m0, s94, 0x4000
	s_nop 1
	global_load_lds_dwordx4 v[70:71], off
	v_lshl_add_u64 v[72:73], v[72:73], 0, s[96:97]
	s_add_u32 m0, s94, 0x1000
	s_nop 1
	global_load_lds_dwordx4 v[72:73], off
	v_lshl_add_u64 v[74:75], v[74:75], 0, s[96:97]
	s_add_u32 m0, s94, 0x5000
	s_nop 1
	global_load_lds_dwordx4 v[74:75], off
	v_lshl_add_u64 v[76:77], v[76:77], 0, s[96:97]
	s_add_u32 m0, s94, 0x2000
	s_nop 1
	global_load_lds_dwordx4 v[76:77], off
	v_lshl_add_u64 v[78:79], v[78:79], 0, s[96:97]
	s_add_u32 m0, s94, 0x6000
	s_nop 1
	global_load_lds_dwordx4 v[78:79], off
	v_lshl_add_u64 v[80:81], v[80:81], 0, s[96:97]
	s_add_u32 m0, s94, 0x3000
	s_nop 1
	global_load_lds_dwordx4 v[80:81], off
	v_lshl_add_u64 v[82:83], v[82:83], 0, s[96:97]
	s_add_u32 m0, s94, 0x7000
	s_nop 1
	global_load_lds_dwordx4 v[82:83], off
	s_waitcnt lgkmcnt(4)
	v_mfma_f32_32x32x16_bf16 v[16:31], v[90:93], v[98:101], v[16:31]
	s_waitcnt lgkmcnt(1)
	v_mfma_f32_32x32x16_bf16 v[48:63], v[90:93], v[110:113], v[48:63]
	ds_read_b128 v[90:93], v170 offset:36864
	ds_read_b128 v[118:121], v171 offset:36864
	s_waitcnt lgkmcnt(1)
	v_mfma_f32_32x32x16_bf16 v[0:15], v[90:93], v[98:101], v[0:15]
	v_mfma_f32_32x32x16_bf16 v[32:47], v[90:93], v[110:113], v[32:47]
	v_mfma_f32_32x32x16_bf16 v[16:31], v[102:105], v[106:109], v[16:31]
	v_mfma_f32_32x32x16_bf16 v[48:63], v[102:105], v[114:117], v[48:63]
	s_waitcnt lgkmcnt(0)
	v_mfma_f32_32x32x16_bf16 v[0:15], v[118:121], v[106:109], v[0:15]
	ds_read_b128 v[90:93], v172 offset:32768
	ds_read_b128 v[98:101], v176 offset:49152
	ds_read_b128 v[102:105], v173 offset:32768
	ds_read_b128 v[106:109], v177 offset:49152
	v_mfma_f32_32x32x16_bf16 v[32:47], v[118:121], v[114:117], v[32:47]
	ds_read_b128 v[110:113], v176 offset:53248
	ds_read_b128 v[114:117], v177 offset:53248
	s_waitcnt lgkmcnt(4)
	v_mfma_f32_32x32x16_bf16 v[16:31], v[90:93], v[98:101], v[16:31]
	s_waitcnt lgkmcnt(1)
	v_mfma_f32_32x32x16_bf16 v[48:63], v[90:93], v[110:113], v[48:63]
	ds_read_b128 v[90:93], v172 offset:36864
	ds_read_b128 v[118:121], v173 offset:36864
	s_waitcnt lgkmcnt(1)
	v_mfma_f32_32x32x16_bf16 v[0:15], v[90:93], v[98:101], v[0:15]
	v_mfma_f32_32x32x16_bf16 v[32:47], v[90:93], v[110:113], v[32:47]
	v_mfma_f32_32x32x16_bf16 v[16:31], v[102:105], v[106:109], v[16:31]
	v_mfma_f32_32x32x16_bf16 v[48:63], v[102:105], v[114:117], v[48:63]
	s_waitcnt lgkmcnt(0)
	v_mfma_f32_32x32x16_bf16 v[0:15], v[118:121], v[106:109], v[0:15]
	s_waitcnt vmcnt(0)
	s_barrier
	v_mfma_f32_32x32x16_bf16 v[32:47], v[118:121], v[114:117], v[32:47]
	ds_read_b128 v[90:93], v170 offset:0
	ds_read_b128 v[98:101], v174 offset:16384
	ds_read_b128 v[102:105], v171 offset:0
	ds_read_b128 v[106:109], v175 offset:16384
	ds_read_b128 v[110:113], v174 offset:20480
	ds_read_b128 v[114:117], v175 offset:20480
	v_lshl_add_u64 v[68:69], v[68:69], 0, s[96:97]
	s_add_u32 m0, s94, 0x8000
	s_nop 1
	global_load_lds_dwordx4 v[68:69], off
	v_lshl_add_u64 v[70:71], v[70:71], 0, s[96:97]
	s_add_u32 m0, s94, 0xc000
	s_nop 1
	global_load_lds_dwordx4 v[70:71], off
	v_lshl_add_u64 v[72:73], v[72:73], 0, s[96:97]
	s_add_u32 m0, s94, 0x9000
	s_nop 1
	global_load_lds_dwordx4 v[72:73], off
	v_lshl_add_u64 v[74:75], v[74:75], 0, s[96:97]
	s_add_u32 m0, s94, 0xd000
	s_nop 1
	global_load_lds_dwordx4 v[74:75], off
	v_lshl_add_u64 v[76:77], v[76:77], 0, s[96:97]
	s_add_u32 m0, s94, 0xa000
	s_nop 1
	global_load_lds_dwordx4 v[76:77], off
	v_lshl_add_u64 v[78:79], v[78:79], 0, s[96:97]
	s_add_u32 m0, s94, 0xe000
	s_nop 1
	global_load_lds_dwordx4 v[78:79], off
	v_lshl_add_u64 v[80:81], v[80:81], 0, s[96:97]
	s_add_u32 m0, s94, 0xb000
	s_nop 1
	global_load_lds_dwordx4 v[80:81], off
	v_lshl_add_u64 v[82:83], v[82:83], 0, s[96:97]
	s_add_u32 m0, s94, 0xf000
	s_nop 1
	global_load_lds_dwordx4 v[82:83], off
	s_waitcnt lgkmcnt(4)
	v_mfma_f32_32x32x16_bf16 v[16:31], v[90:93], v[98:101], v[16:31]
	s_waitcnt lgkmcnt(1)
	v_mfma_f32_32x32x16_bf16 v[48:63], v[90:93], v[110:113], v[48:63]
	ds_read_b128 v[90:93], v170 offset:4096
	ds_read_b128 v[118:121], v171 offset:4096
	s_waitcnt lgkmcnt(1)
	v_mfma_f32_32x32x16_bf16 v[0:15], v[90:93], v[98:101], v[0:15]
	v_mfma_f32_32x32x16_bf16 v[32:47], v[90:93], v[110:113], v[32:47]
	v_mfma_f32_32x32x16_bf16 v[16:31], v[102:105], v[106:109], v[16:31]
	v_mfma_f32_32x32x16_bf16 v[48:63], v[102:105], v[114:117], v[48:63]
	s_waitcnt lgkmcnt(0)
	v_mfma_f32_32x32x16_bf16 v[0:15], v[118:121], v[106:109], v[0:15]
	ds_read_b128 v[90:93], v172 offset:0
	ds_read_b128 v[98:101], v176 offset:16384
	ds_read_b128 v[102:105], v173 offset:0
	ds_read_b128 v[106:109], v177 offset:16384
	v_mfma_f32_32x32x16_bf16 v[32:47], v[118:121], v[114:117], v[32:47]
	ds_read_b128 v[110:113], v176 offset:20480
	ds_read_b128 v[114:117], v177 offset:20480
	s_waitcnt lgkmcnt(4)
	v_mfma_f32_32x32x16_bf16 v[16:31], v[90:93], v[98:101], v[16:31]
	s_waitcnt lgkmcnt(1)
	v_mfma_f32_32x32x16_bf16 v[48:63], v[90:93], v[110:113], v[48:63]
	ds_read_b128 v[90:93], v172 offset:4096
	ds_read_b128 v[118:121], v173 offset:4096
	s_waitcnt lgkmcnt(1)
	v_mfma_f32_32x32x16_bf16 v[0:15], v[90:93], v[98:101], v[0:15]
	v_mfma_f32_32x32x16_bf16 v[32:47], v[90:93], v[110:113], v[32:47]
	v_mfma_f32_32x32x16_bf16 v[16:31], v[102:105], v[106:109], v[16:31]
	v_mfma_f32_32x32x16_bf16 v[48:63], v[102:105], v[114:117], v[48:63]
	s_waitcnt lgkmcnt(0)
	v_mfma_f32_32x32x16_bf16 v[0:15], v[118:121], v[106:109], v[0:15]
	s_waitcnt vmcnt(0)
	s_barrier
;     ...
;   bf16* As1 = As + 2 * 128 * 72;
;   bf16* Bs1 = As1 + 128 * 72;
;   G_LOAD(ra0, rb0, 0);
;   if (nk > 1) G_LOAD(ra1, rb1, 1);
;   G_STORE(ra0, rb0, As, Bs);
;   __syncthreads();
;   for (int kt = 0; kt < nk; kt += 2) {
;     if (kt + 2 < nk) G_LOAD(ra0, rb0, kt + 2);
;     if (kt + 1 < nk) G_STORE(ra1, rb1, As1, Bs1);
;     G_COMPUTE(As, Bs);
;     __syncthreads();
;     if (kt + 1 < nk) {
;       if (kt + 3 < nk) G_LOAD(ra1, rb1, kt + 3);
;       if (kt + 2 < nk) G_STORE(ra0, rb0, As, Bs);
;       G_COMPUTE(As1, Bs1);
;       __syncthreads();
;     }
;   }
	v_mfma_f32_32x32x16_bf16 v[32:47], v[118:121], v[114:117], v[32:47]
	ds_read_b128 v[90:93], v170 offset:32768
	ds_read_b128 v[98:101], v174 offset:49152
	ds_read_b128 v[102:105], v171 offset:32768
	ds_read_b128 v[106:109], v175 offset:49152
	ds_read_b128 v[110:113], v174 offset:53248
	ds_read_b128 v[114:117], v175 offset:53248
	v_lshl_add_u64 v[68:69], v[68:69], 0, s[96:97]
	s_add_u32 m0, s94, 0x0
	s_nop 1
	global_load_lds_dwordx4 v[68:69], off
	v_lshl_add_u64 v[70:71], v[70:71], 0, s[96:97]
	s_add_u32 m0, s94, 0x4000
	s_nop 1
	global_load_lds_dwordx4 v[70:71], off
	v_lshl_add_u64 v[72:73], v[72:73], 0, s[96:97]
	s_add_u32 m0, s94, 0x1000
	s_nop 1
	global_load_lds_dwordx4 v[72:73], off
	v_lshl_add_u64 v[74:75], v[74:75], 0, s[96:97]
	s_add_u32 m0, s94, 0x5000
	s_nop 1
	global_load_lds_dwordx4 v[74:75], off
	v_lshl_add_u64 v[76:77], v[76:77], 0, s[96:97]
	s_add_u32 m0, s94, 0x2000
	s_nop 1
	global_load_lds_dwordx4 v[76:77], off
	v_lshl_add_u64 v[78:79], v[78:79], 0, s[96:97]
	s_add_u32 m0, s94, 0x6000
	s_nop 1
	global_load_lds_dwordx4 v[78:79], off
	v_lshl_add_u64 v[80:81], v[80:81], 0, s[96:97]
	s_add_u32 m0, s94, 0x3000
	s_nop 1
	global_load_lds_dwordx4 v[80:81], off
	v_lshl_add_u64 v[82:83], v[82:83], 0, s[96:97]
	s_add_u32 m0, s94, 0x7000
	s_nop 1
	global_load_lds_dwordx4 v[82:83], off
	s_waitcnt lgkmcnt(4)
	v_mfma_f32_32x32x16_bf16 v[16:31], v[90:93], v[98:101], v[16:31]
	s_waitcnt lgkmcnt(1)
	v_mfma_f32_32x32x16_bf16 v[48:63], v[90:93], v[110:113], v[48:63]
	ds_read_b128 v[90:93], v170 offset:36864
	ds_read_b128 v[118:121], v171 offset:36864
	s_waitcnt lgkmcnt(1)
	v_mfma_f32_32x32x16_bf16 v[0:15], v[90:93], v[98:101], v[0:15]
	v_mfma_f32_32x32x16_bf16 v[32:47], v[90:93], v[110:113], v[32:47]
	v_mfma_f32_32x32x16_bf16 v[16:31], v[102:105], v[106:109], v[16:31]
	v_mfma_f32_32x32x16_bf16 v[48:63], v[102:105], v[114:117], v[48:63]
	s_waitcnt lgkmcnt(0)
	v_mfma_f32_32x32x16_bf16 v[0:15], v[118:121], v[106:109], v[0:15]
	ds_read_b128 v[90:93], v172 offset:32768
	ds_read_b128 v[98:101], v176 offset:49152
	ds_read_b128 v[102:105], v173 offset:32768
	ds_read_b128 v[106:109], v177 offset:49152
	v_mfma_f32_32x32x16_bf16 v[32:47], v[118:121], v[114:117], v[32:47]
	ds_read_b128 v[110:113], v176 offset:53248
	ds_read_b128 v[114:117], v177 offset:53248
	s_waitcnt lgkmcnt(4)
	v_mfma_f32_32x32x16_bf16 v[16:31], v[90:93], v[98:101], v[16:31]
	s_waitcnt lgkmcnt(1)
	v_mfma_f32_32x32x16_bf16 v[48:63], v[90:93], v[110:113], v[48:63]
	ds_read_b128 v[90:93], v172 offset:36864
	ds_read_b128 v[118:121], v173 offset:36864
	s_waitcnt lgkmcnt(1)
	v_mfma_f32_32x32x16_bf16 v[0:15], v[90:93], v[98:101], v[0:15]
	v_mfma_f32_32x32x16_bf16 v[32:47], v[90:93], v[110:113], v[32:47]
	v_mfma_f32_32x32x16_bf16 v[16:31], v[102:105], v[106:109], v[16:31]
	v_mfma_f32_32x32x16_bf16 v[48:63], v[102:105], v[114:117], v[48:63]
	s_waitcnt lgkmcnt(0)
	v_mfma_f32_32x32x16_bf16 v[0:15], v[118:121], v[106:109], v[0:15]
	s_waitcnt vmcnt(0)
	s_barrier
	v_mfma_f32_32x32x16_bf16 v[32:47], v[118:121], v[114:117], v[32:47]
	ds_read_b128 v[90:93], v170 offset:0
	ds_read_b128 v[98:101], v174 offset:16384
	ds_read_b128 v[102:105], v171 offset:0
	ds_read_b128 v[106:109], v175 offset:16384
	ds_read_b128 v[110:113], v174 offset:20480
	ds_read_b128 v[114:117], v175 offset:20480
	v_lshl_add_u64 v[68:69], v[68:69], 0, s[96:97]
	s_add_u32 m0, s94, 0x8000
	s_nop 1
	global_load_lds_dwordx4 v[68:69], off
	v_lshl_add_u64 v[70:71], v[70:71], 0, s[96:97]
	s_add_u32 m0, s94, 0xc000
	s_nop 1
	global_load_lds_dwordx4 v[70:71], off
	v_lshl_add_u64 v[72:73], v[72:73], 0, s[96:97]
	s_add_u32 m0, s94, 0x9000
	s_nop 1
	global_load_lds_dwordx4 v[72:73], off
	v_lshl_add_u64 v[74:75], v[74:75], 0, s[96:97]
	s_add_u32 m0, s94, 0xd000
	s_nop 1
	global_load_lds_dwordx4 v[74:75], off
	v_lshl_add_u64 v[76:77], v[76:77], 0, s[96:97]
	s_add_u32 m0, s94, 0xa000
	s_nop 1
	global_load_lds_dwordx4 v[76:77], off
	v_lshl_add_u64 v[78:79], v[78:79], 0, s[96:97]
	s_add_u32 m0, s94, 0xe000
	s_nop 1
	global_load_lds_dwordx4 v[78:79], off
	v_lshl_add_u64 v[80:81], v[80:81], 0, s[96:97]
	s_add_u32 m0, s94, 0xb000
	s_nop 1
	global_load_lds_dwordx4 v[80:81], off
	v_lshl_add_u64 v[82:83], v[82:83], 0, s[96:97]
	s_add_u32 m0, s94, 0xf000
	s_nop 1
	global_load_lds_dwordx4 v[82:83], off
	s_waitcnt lgkmcnt(4)
	v_mfma_f32_32x32x16_bf16 v[16:31], v[90:93], v[98:101], v[16:31]
	s_waitcnt lgkmcnt(1)
	v_mfma_f32_32x32x16_bf16 v[48:63], v[90:93], v[110:113], v[48:63]
	ds_read_b128 v[90:93], v170 offset:4096
	ds_read_b128 v[118:121], v171 offset:4096
	s_waitcnt lgkmcnt(1)
	v_mfma_f32_32x32x16_bf16 v[0:15], v[90:93], v[98:101], v[0:15]
	v_mfma_f32_32x32x16_bf16 v[32:47], v[90:93], v[110:113], v[32:47]
	v_mfma_f32_32x32x16_bf16 v[16:31], v[102:105], v[106:109], v[16:31]
	v_mfma_f32_32x32x16_bf16 v[48:63], v[102:105], v[114:117], v[48:63]
	s_waitcnt lgkmcnt(0)
	v_mfma_f32_32x32x16_bf16 v[0:15], v[118:121], v[106:109], v[0:15]
	ds_read_b128 v[90:93], v172 offset:0
	ds_read_b128 v[98:101], v176 offset:16384
	ds_read_b128 v[102:105], v173 offset:0
	ds_read_b128 v[106:109], v177 offset:16384
	v_mfma_f32_32x32x16_bf16 v[32:47], v[118:121], v[114:117], v[32:47]
	ds_read_b128 v[110:113], v176 offset:20480
	ds_read_b128 v[114:117], v177 offset:20480
	s_waitcnt lgkmcnt(4)
	v_mfma_f32_32x32x16_bf16 v[16:31], v[90:93], v[98:101], v[16:31]
	s_waitcnt lgkmcnt(1)
	v_mfma_f32_32x32x16_bf16 v[48:63], v[90:93], v[110:113], v[48:63]
	ds_read_b128 v[90:93], v172 offset:4096
	ds_read_b128 v[118:121], v173 offset:4096
	s_waitcnt lgkmcnt(1)
	v_mfma_f32_32x32x16_bf16 v[0:15], v[90:93], v[98:101], v[0:15]
	v_mfma_f32_32x32x16_bf16 v[32:47], v[90:93], v[110:113], v[32:47]
	v_mfma_f32_32x32x16_bf16 v[16:31], v[102:105], v[106:109], v[16:31]
	v_mfma_f32_32x32x16_bf16 v[48:63], v[102:105], v[114:117], v[48:63]
	s_waitcnt lgkmcnt(0)
	v_mfma_f32_32x32x16_bf16 v[0:15], v[118:121], v[106:109], v[0:15]
	s_waitcnt vmcnt(0)
	s_barrier
;     ...
;   bf16* As1 = As + 2 * 128 * 72;
;   bf16* Bs1 = As1 + 128 * 72;
;   G_LOAD(ra0, rb0, 0);
;   if (nk > 1) G_LOAD(ra1, rb1, 1);
;   G_STORE(ra0, rb0, As, Bs);
;   __syncthreads();
;   for (int kt = 0; kt < nk; kt += 2) {
;     if (kt + 2 < nk) G_LOAD(ra0, rb0, kt + 2);
;     if (kt + 1 < nk) G_STORE(ra1, rb1, As1, Bs1);
;     G_COMPUTE(As, Bs);
;     __syncthreads();
;     if (kt + 1 < nk) {
;       if (kt + 3 < nk) G_LOAD(ra1, rb1, kt + 3);
;       if (kt + 2 < nk) G_STORE(ra0, rb0, As, Bs);
;       G_COMPUTE(As1, Bs1);
;       __syncthreads();
;     }
;   }
	v_mfma_f32_32x32x16_bf16 v[32:47], v[118:121], v[114:117], v[32:47]
	ds_read_b128 v[90:93], v170 offset:32768
	ds_read_b128 v[98:101], v174 offset:49152
	ds_read_b128 v[102:105], v171 offset:32768
	ds_read_b128 v[106:109], v175 offset:49152
	ds_read_b128 v[110:113], v174 offset:53248
	ds_read_b128 v[114:117], v175 offset:53248
	v_lshl_add_u64 v[68:69], v[68:69], 0, s[96:97]
	s_add_u32 m0, s94, 0x0
	s_nop 1
	global_load_lds_dwordx4 v[68:69], off
	v_lshl_add_u64 v[70:71], v[70:71], 0, s[96:97]
	s_add_u32 m0, s94, 0x4000
	s_nop 1
	global_load_lds_dwordx4 v[70:71], off
	v_lshl_add_u64 v[72:73], v[72:73], 0, s[96:97]
	s_add_u32 m0, s94, 0x1000
	s_nop 1
	global_load_lds_dwordx4 v[72:73], off
	v_lshl_add_u64 v[74:75], v[74:75], 0, s[96:97]
	s_add_u32 m0, s94, 0x5000
	s_nop 1
	global_load_lds_dwordx4 v[74:75], off
	v_lshl_add_u64 v[76:77], v[76:77], 0, s[96:97]
	s_add_u32 m0, s94, 0x2000
	s_nop 1
	global_load_lds_dwordx4 v[76:77], off
	v_lshl_add_u64 v[78:79], v[78:79], 0, s[96:97]
	s_add_u32 m0, s94, 0x6000
	s_nop 1
	global_load_lds_dwordx4 v[78:79], off
	v_lshl_add_u64 v[80:81], v[80:81], 0, s[96:97]
	s_add_u32 m0, s94, 0x3000
	s_nop 1
	global_load_lds_dwordx4 v[80:81], off
	v_lshl_add_u64 v[82:83], v[82:83], 0, s[96:97]
	s_add_u32 m0, s94, 0x7000
	s_nop 1
	global_load_lds_dwordx4 v[82:83], off
	s_waitcnt lgkmcnt(4)
	v_mfma_f32_32x32x16_bf16 v[16:31], v[90:93], v[98:101], v[16:31]
	s_waitcnt lgkmcnt(1)
	v_mfma_f32_32x32x16_bf16 v[48:63], v[90:93], v[110:113], v[48:63]
	ds_read_b128 v[90:93], v170 offset:36864
	ds_read_b128 v[118:121], v171 offset:36864
	s_waitcnt lgkmcnt(1)
	v_mfma_f32_32x32x16_bf16 v[0:15], v[90:93], v[98:101], v[0:15]
	v_mfma_f32_32x32x16_bf16 v[32:47], v[90:93], v[110:113], v[32:47]
	v_mfma_f32_32x32x16_bf16 v[16:31], v[102:105], v[106:109], v[16:31]
	v_mfma_f32_32x32x16_bf16 v[48:63], v[102:105], v[114:117], v[48:63]
	s_waitcnt lgkmcnt(0)
	v_mfma_f32_32x32x16_bf16 v[0:15], v[118:121], v[106:109], v[0:15]
	ds_read_b128 v[90:93], v172 offset:32768
	ds_read_b128 v[98:101], v176 offset:49152
	ds_read_b128 v[102:105], v173 offset:32768
	ds_read_b128 v[106:109], v177 offset:49152
	v_mfma_f32_32x32x16_bf16 v[32:47], v[118:121], v[114:117], v[32:47]
	ds_read_b128 v[110:113], v176 offset:53248
	ds_read_b128 v[114:117], v177 offset:53248
	s_waitcnt lgkmcnt(4)
	v_mfma_f32_32x32x16_bf16 v[16:31], v[90:93], v[98:101], v[16:31]
	s_waitcnt lgkmcnt(1)
	v_mfma_f32_32x32x16_bf16 v[48:63], v[90:93], v[110:113], v[48:63]
	ds_read_b128 v[90:93], v172 offset:36864
	ds_read_b128 v[118:121], v173 offset:36864
	s_waitcnt lgkmcnt(1)
	v_mfma_f32_32x32x16_bf16 v[0:15], v[90:93], v[98:101], v[0:15]
	v_mfma_f32_32x32x16_bf16 v[32:47], v[90:93], v[110:113], v[32:47]
	v_mfma_f32_32x32x16_bf16 v[16:31], v[102:105], v[106:109], v[16:31]
	v_mfma_f32_32x32x16_bf16 v[48:63], v[102:105], v[114:117], v[48:63]
	s_waitcnt lgkmcnt(0)
	v_mfma_f32_32x32x16_bf16 v[0:15], v[118:121], v[106:109], v[0:15]
	s_waitcnt vmcnt(0)
	s_barrier
	v_mfma_f32_32x32x16_bf16 v[32:47], v[118:121], v[114:117], v[32:47]
	ds_read_b128 v[90:93], v170 offset:0
	ds_read_b128 v[98:101], v174 offset:16384
	ds_read_b128 v[102:105], v171 offset:0
	ds_read_b128 v[106:109], v175 offset:16384
	ds_read_b128 v[110:113], v174 offset:20480
	ds_read_b128 v[114:117], v175 offset:20480
	v_lshl_add_u64 v[68:69], v[68:69], 0, s[96:97]
	s_add_u32 m0, s94, 0x8000
	s_nop 1
	global_load_lds_dwordx4 v[68:69], off
	v_lshl_add_u64 v[70:71], v[70:71], 0, s[96:97]
	s_add_u32 m0, s94, 0xc000
	s_nop 1
	global_load_lds_dwordx4 v[70:71], off
	v_lshl_add_u64 v[72:73], v[72:73], 0, s[96:97]
	s_add_u32 m0, s94, 0x9000
	s_nop 1
	global_load_lds_dwordx4 v[72:73], off
	v_lshl_add_u64 v[74:75], v[74:75], 0, s[96:97]
	s_add_u32 m0, s94, 0xd000
	s_nop 1
	global_load_lds_dwordx4 v[74:75], off
	v_lshl_add_u64 v[76:77], v[76:77], 0, s[96:97]
	s_add_u32 m0, s94, 0xa000
	s_nop 1
	global_load_lds_dwordx4 v[76:77], off
	v_lshl_add_u64 v[78:79], v[78:79], 0, s[96:97]
	s_add_u32 m0, s94, 0xe000
	s_nop 1
	global_load_lds_dwordx4 v[78:79], off
	v_lshl_add_u64 v[80:81], v[80:81], 0, s[96:97]
	s_add_u32 m0, s94, 0xb000
	s_nop 1
	global_load_lds_dwordx4 v[80:81], off
	v_lshl_add_u64 v[82:83], v[82:83], 0, s[96:97]
	s_add_u32 m0, s94, 0xf000
	s_nop 1
	global_load_lds_dwordx4 v[82:83], off
	s_waitcnt lgkmcnt(4)
	v_mfma_f32_32x32x16_bf16 v[16:31], v[90:93], v[98:101], v[16:31]
	s_waitcnt lgkmcnt(1)
	v_mfma_f32_32x32x16_bf16 v[48:63], v[90:93], v[110:113], v[48:63]
	ds_read_b128 v[90:93], v170 offset:4096
	ds_read_b128 v[118:121], v171 offset:4096
	s_waitcnt lgkmcnt(1)
	v_mfma_f32_32x32x16_bf16 v[0:15], v[90:93], v[98:101], v[0:15]
	v_mfma_f32_32x32x16_bf16 v[32:47], v[90:93], v[110:113], v[32:47]
	v_mfma_f32_32x32x16_bf16 v[16:31], v[102:105], v[106:109], v[16:31]
	v_mfma_f32_32x32x16_bf16 v[48:63], v[102:105], v[114:117], v[48:63]
	s_waitcnt lgkmcnt(0)
	v_mfma_f32_32x32x16_bf16 v[0:15], v[118:121], v[106:109], v[0:15]
	ds_read_b128 v[90:93], v172 offset:0
	ds_read_b128 v[98:101], v176 offset:16384
	ds_read_b128 v[102:105], v173 offset:0
	ds_read_b128 v[106:109], v177 offset:16384
	v_mfma_f32_32x32x16_bf16 v[32:47], v[118:121], v[114:117], v[32:47]
	ds_read_b128 v[110:113], v176 offset:20480
	ds_read_b128 v[114:117], v177 offset:20480
	s_waitcnt lgkmcnt(4)
	v_mfma_f32_32x32x16_bf16 v[16:31], v[90:93], v[98:101], v[16:31]
	s_waitcnt lgkmcnt(1)
	v_mfma_f32_32x32x16_bf16 v[48:63], v[90:93], v[110:113], v[48:63]
	ds_read_b128 v[90:93], v172 offset:4096
	ds_read_b128 v[118:121], v173 offset:4096
	s_waitcnt lgkmcnt(1)
	v_mfma_f32_32x32x16_bf16 v[0:15], v[90:93], v[98:101], v[0:15]
	v_mfma_f32_32x32x16_bf16 v[32:47], v[90:93], v[110:113], v[32:47]
	v_mfma_f32_32x32x16_bf16 v[16:31], v[102:105], v[106:109], v[16:31]
	v_mfma_f32_32x32x16_bf16 v[48:63], v[102:105], v[114:117], v[48:63]
	s_waitcnt lgkmcnt(0)
	v_mfma_f32_32x32x16_bf16 v[0:15], v[118:121], v[106:109], v[0:15]
	s_waitcnt vmcnt(0)
	s_barrier
;     ...
;   bf16* As1 = As + 2 * 128 * 72;
;   bf16* Bs1 = As1 + 128 * 72;
;   G_LOAD(ra0, rb0, 0);
;   if (nk > 1) G_LOAD(ra1, rb1, 1);
;   G_STORE(ra0, rb0, As, Bs);
;   __syncthreads();
;   for (int kt = 0; kt < nk; kt += 2) {
;     if (kt + 2 < nk) G_LOAD(ra0, rb0, kt + 2);
;     if (kt + 1 < nk) G_STORE(ra1, rb1, As1, Bs1);
;     G_COMPUTE(As, Bs);
;     __syncthreads();
;     if (kt + 1 < nk) {
;       if (kt + 3 < nk) G_LOAD(ra1, rb1, kt + 3);
;       if (kt + 2 < nk) G_STORE(ra0, rb0, As, Bs);
;       G_COMPUTE(As1, Bs1);
;       __syncthreads();
;     }
;   }
	v_mfma_f32_32x32x16_bf16 v[32:47], v[118:121], v[114:117], v[32:47]
	ds_read_b128 v[90:93], v170 offset:32768
	ds_read_b128 v[98:101], v174 offset:49152
	ds_read_b128 v[102:105], v171 offset:32768
	ds_read_b128 v[106:109], v175 offset:49152
	ds_read_b128 v[110:113], v174 offset:53248
	ds_read_b128 v[114:117], v175 offset:53248
	v_lshl_add_u64 v[68:69], v[68:69], 0, s[96:97]
	s_add_u32 m0, s94, 0x0
	s_nop 1
	global_load_lds_dwordx4 v[68:69], off
	v_lshl_add_u64 v[70:71], v[70:71], 0, s[96:97]
	s_add_u32 m0, s94, 0x4000
	s_nop 1
	global_load_lds_dwordx4 v[70:71], off
	v_lshl_add_u64 v[72:73], v[72:73], 0, s[96:97]
	s_add_u32 m0, s94, 0x1000
	s_nop 1
	global_load_lds_dwordx4 v[72:73], off
	v_lshl_add_u64 v[74:75], v[74:75], 0, s[96:97]
	s_add_u32 m0, s94, 0x5000
	s_nop 1
	global_load_lds_dwordx4 v[74:75], off
	v_lshl_add_u64 v[76:77], v[76:77], 0, s[96:97]
	s_add_u32 m0, s94, 0x2000
	s_nop 1
	global_load_lds_dwordx4 v[76:77], off
	v_lshl_add_u64 v[78:79], v[78:79], 0, s[96:97]
	s_add_u32 m0, s94, 0x6000
	s_nop 1
	global_load_lds_dwordx4 v[78:79], off
	v_lshl_add_u64 v[80:81], v[80:81], 0, s[96:97]
	s_add_u32 m0, s94, 0x3000
	s_nop 1
	global_load_lds_dwordx4 v[80:81], off
	v_lshl_add_u64 v[82:83], v[82:83], 0, s[96:97]
	s_add_u32 m0, s94, 0x7000
	s_nop 1
	global_load_lds_dwordx4 v[82:83], off
	s_waitcnt lgkmcnt(4)
	v_mfma_f32_32x32x16_bf16 v[16:31], v[90:93], v[98:101], v[16:31]
	s_waitcnt lgkmcnt(1)
	v_mfma_f32_32x32x16_bf16 v[48:63], v[90:93], v[110:113], v[48:63]
	ds_read_b128 v[90:93], v170 offset:36864
	ds_read_b128 v[118:121], v171 offset:36864
	s_waitcnt lgkmcnt(1)
	v_mfma_f32_32x32x16_bf16 v[0:15], v[90:93], v[98:101], v[0:15]
	v_mfma_f32_32x32x16_bf16 v[32:47], v[90:93], v[110:113], v[32:47]
	v_mfma_f32_32x32x16_bf16 v[16:31], v[102:105], v[106:109], v[16:31]
	v_mfma_f32_32x32x16_bf16 v[48:63], v[102:105], v[114:117], v[48:63]
	s_waitcnt lgkmcnt(0)
	v_mfma_f32_32x32x16_bf16 v[0:15], v[118:121], v[106:109], v[0:15]
	ds_read_b128 v[90:93], v172 offset:32768
	ds_read_b128 v[98:101], v176 offset:49152
	ds_read_b128 v[102:105], v173 offset:32768
	ds_read_b128 v[106:109], v177 offset:49152
	v_mfma_f32_32x32x16_bf16 v[32:47], v[118:121], v[114:117], v[32:47]
	ds_read_b128 v[110:113], v176 offset:53248
	ds_read_b128 v[114:117], v177 offset:53248
	s_waitcnt lgkmcnt(4)
	v_mfma_f32_32x32x16_bf16 v[16:31], v[90:93], v[98:101], v[16:31]
	s_waitcnt lgkmcnt(1)
	v_mfma_f32_32x32x16_bf16 v[48:63], v[90:93], v[110:113], v[48:63]
	ds_read_b128 v[90:93], v172 offset:36864
	ds_read_b128 v[118:121], v173 offset:36864
	s_waitcnt lgkmcnt(1)
	v_mfma_f32_32x32x16_bf16 v[0:15], v[90:93], v[98:101], v[0:15]
	v_mfma_f32_32x32x16_bf16 v[32:47], v[90:93], v[110:113], v[32:47]
	v_mfma_f32_32x32x16_bf16 v[16:31], v[102:105], v[106:109], v[16:31]
	v_mfma_f32_32x32x16_bf16 v[48:63], v[102:105], v[114:117], v[48:63]
	s_waitcnt lgkmcnt(0)
	v_mfma_f32_32x32x16_bf16 v[0:15], v[118:121], v[106:109], v[0:15]
	s_waitcnt vmcnt(0)
	s_barrier
	v_mfma_f32_32x32x16_bf16 v[32:47], v[118:121], v[114:117], v[32:47]
	ds_read_b128 v[90:93], v170 offset:0
	ds_read_b128 v[98:101], v174 offset:16384
	ds_read_b128 v[102:105], v171 offset:0
	ds_read_b128 v[106:109], v175 offset:16384
	ds_read_b128 v[110:113], v174 offset:20480
	ds_read_b128 v[114:117], v175 offset:20480
	v_lshl_add_u64 v[68:69], v[68:69], 0, s[96:97]
	s_add_u32 m0, s94, 0x8000
	s_nop 1
	global_load_lds_dwordx4 v[68:69], off
	v_lshl_add_u64 v[70:71], v[70:71], 0, s[96:97]
	s_add_u32 m0, s94, 0xc000
	s_nop 1
	global_load_lds_dwordx4 v[70:71], off
	v_lshl_add_u64 v[72:73], v[72:73], 0, s[96:97]
	s_add_u32 m0, s94, 0x9000
	s_nop 1
	global_load_lds_dwordx4 v[72:73], off
	v_lshl_add_u64 v[74:75], v[74:75], 0, s[96:97]
	s_add_u32 m0, s94, 0xd000
	s_nop 1
	global_load_lds_dwordx4 v[74:75], off
	v_lshl_add_u64 v[76:77], v[76:77], 0, s[96:97]
	s_add_u32 m0, s94, 0xa000
	s_nop 1
	global_load_lds_dwordx4 v[76:77], off
	v_lshl_add_u64 v[78:79], v[78:79], 0, s[96:97]
	s_add_u32 m0, s94, 0xe000
	s_nop 1
	global_load_lds_dwordx4 v[78:79], off
	v_lshl_add_u64 v[80:81], v[80:81], 0, s[96:97]
	s_add_u32 m0, s94, 0xb000
	s_nop 1
	global_load_lds_dwordx4 v[80:81], off
	v_lshl_add_u64 v[82:83], v[82:83], 0, s[96:97]
	s_add_u32 m0, s94, 0xf000
	s_nop 1
	global_load_lds_dwordx4 v[82:83], off
	s_waitcnt lgkmcnt(4)
	v_mfma_f32_32x32x16_bf16 v[16:31], v[90:93], v[98:101], v[16:31]
	s_waitcnt lgkmcnt(1)
	v_mfma_f32_32x32x16_bf16 v[48:63], v[90:93], v[110:113], v[48:63]
	ds_read_b128 v[90:93], v170 offset:4096
	ds_read_b128 v[118:121], v171 offset:4096
	s_waitcnt lgkmcnt(1)
	v_mfma_f32_32x32x16_bf16 v[0:15], v[90:93], v[98:101], v[0:15]
	v_mfma_f32_32x32x16_bf16 v[32:47], v[90:93], v[110:113], v[32:47]
	v_mfma_f32_32x32x16_bf16 v[16:31], v[102:105], v[106:109], v[16:31]
	v_mfma_f32_32x32x16_bf16 v[48:63], v[102:105], v[114:117], v[48:63]
	s_waitcnt lgkmcnt(0)
	v_mfma_f32_32x32x16_bf16 v[0:15], v[118:121], v[106:109], v[0:15]
	ds_read_b128 v[90:93], v172 offset:0
	ds_read_b128 v[98:101], v176 offset:16384
	ds_read_b128 v[102:105], v173 offset:0
	ds_read_b128 v[106:109], v177 offset:16384
	v_mfma_f32_32x32x16_bf16 v[32:47], v[118:121], v[114:117], v[32:47]
	ds_read_b128 v[110:113], v176 offset:20480
	ds_read_b128 v[114:117], v177 offset:20480
	s_waitcnt lgkmcnt(4)
	v_mfma_f32_32x32x16_bf16 v[16:31], v[90:93], v[98:101], v[16:31]
	s_waitcnt lgkmcnt(1)
	v_mfma_f32_32x32x16_bf16 v[48:63], v[90:93], v[110:113], v[48:63]
	ds_read_b128 v[90:93], v172 offset:4096
	ds_read_b128 v[118:121], v173 offset:4096
	s_waitcnt lgkmcnt(1)
	v_mfma_f32_32x32x16_bf16 v[0:15], v[90:93], v[98:101], v[0:15]
	v_mfma_f32_32x32x16_bf16 v[32:47], v[90:93], v[110:113], v[32:47]
	v_mfma_f32_32x32x16_bf16 v[16:31], v[102:105], v[106:109], v[16:31]
	v_mfma_f32_32x32x16_bf16 v[48:63], v[102:105], v[114:117], v[48:63]
	s_waitcnt lgkmcnt(0)
	v_mfma_f32_32x32x16_bf16 v[0:15], v[118:121], v[106:109], v[0:15]
	s_waitcnt vmcnt(0)
	s_barrier
;     ...
;   bf16* As1 = As + 2 * 128 * 72;
;   bf16* Bs1 = As1 + 128 * 72;
;   G_LOAD(ra0, rb0, 0);
;   if (nk > 1) G_LOAD(ra1, rb1, 1);
;   G_STORE(ra0, rb0, As, Bs);
;   __syncthreads();
;   for (int kt = 0; kt < nk; kt += 2) {
;     if (kt + 2 < nk) G_LOAD(ra0, rb0, kt + 2);
;     if (kt + 1 < nk) G_STORE(ra1, rb1, As1, Bs1);
;     G_COMPUTE(As, Bs);
;     __syncthreads();
;     if (kt + 1 < nk) {
;       if (kt + 3 < nk) G_LOAD(ra1, rb1, kt + 3);
;       if (kt + 2 < nk) G_STORE(ra0, rb0, As, Bs);
;       G_COMPUTE(As1, Bs1);
;       __syncthreads();
;     }
;   }
	v_mfma_f32_32x32x16_bf16 v[32:47], v[118:121], v[114:117], v[32:47]
	ds_read_b128 v[90:93], v170 offset:32768
	ds_read_b128 v[98:101], v174 offset:49152
	ds_read_b128 v[102:105], v171 offset:32768
	ds_read_b128 v[106:109], v175 offset:49152
	ds_read_b128 v[110:113], v174 offset:53248
	ds_read_b128 v[114:117], v175 offset:53248
	v_lshl_add_u64 v[68:69], v[68:69], 0, s[96:97]
	s_add_u32 m0, s94, 0x0
	s_nop 1
	global_load_lds_dwordx4 v[68:69], off
	v_lshl_add_u64 v[70:71], v[70:71], 0, s[96:97]
	s_add_u32 m0, s94, 0x4000
	s_nop 1
	global_load_lds_dwordx4 v[70:71], off
	v_lshl_add_u64 v[72:73], v[72:73], 0, s[96:97]
	s_add_u32 m0, s94, 0x1000
	s_nop 1
	global_load_lds_dwordx4 v[72:73], off
	v_lshl_add_u64 v[74:75], v[74:75], 0, s[96:97]
	s_add_u32 m0, s94, 0x5000
	s_nop 1
	global_load_lds_dwordx4 v[74:75], off
	v_lshl_add_u64 v[76:77], v[76:77], 0, s[96:97]
	s_add_u32 m0, s94, 0x2000
	s_nop 1
	global_load_lds_dwordx4 v[76:77], off
	v_lshl_add_u64 v[78:79], v[78:79], 0, s[96:97]
	s_add_u32 m0, s94, 0x6000
	s_nop 1
	global_load_lds_dwordx4 v[78:79], off
	v_lshl_add_u64 v[80:81], v[80:81], 0, s[96:97]
	s_add_u32 m0, s94, 0x3000
	s_nop 1
	global_load_lds_dwordx4 v[80:81], off
	v_lshl_add_u64 v[82:83], v[82:83], 0, s[96:97]
	s_add_u32 m0, s94, 0x7000
	s_nop 1
	global_load_lds_dwordx4 v[82:83], off
	s_waitcnt lgkmcnt(4)
	v_mfma_f32_32x32x16_bf16 v[16:31], v[90:93], v[98:101], v[16:31]
	s_waitcnt lgkmcnt(1)
	v_mfma_f32_32x32x16_bf16 v[48:63], v[90:93], v[110:113], v[48:63]
	ds_read_b128 v[90:93], v170 offset:36864
	ds_read_b128 v[118:121], v171 offset:36864
	s_waitcnt lgkmcnt(1)
	v_mfma_f32_32x32x16_bf16 v[0:15], v[90:93], v[98:101], v[0:15]
	v_mfma_f32_32x32x16_bf16 v[32:47], v[90:93], v[110:113], v[32:47]
	v_mfma_f32_32x32x16_bf16 v[16:31], v[102:105], v[106:109], v[16:31]
	v_mfma_f32_32x32x16_bf16 v[48:63], v[102:105], v[114:117], v[48:63]
	s_waitcnt lgkmcnt(0)
	v_mfma_f32_32x32x16_bf16 v[0:15], v[118:121], v[106:109], v[0:15]
	ds_read_b128 v[90:93], v172 offset:32768
	ds_read_b128 v[98:101], v176 offset:49152
	ds_read_b128 v[102:105], v173 offset:32768
	ds_read_b128 v[106:109], v177 offset:49152
	v_mfma_f32_32x32x16_bf16 v[32:47], v[118:121], v[114:117], v[32:47]
	ds_read_b128 v[110:113], v176 offset:53248
	ds_read_b128 v[114:117], v177 offset:53248
	s_waitcnt lgkmcnt(4)
	v_mfma_f32_32x32x16_bf16 v[16:31], v[90:93], v[98:101], v[16:31]
	s_waitcnt lgkmcnt(1)
	v_mfma_f32_32x32x16_bf16 v[48:63], v[90:93], v[110:113], v[48:63]
	ds_read_b128 v[90:93], v172 offset:36864
	ds_read_b128 v[118:121], v173 offset:36864
	s_waitcnt lgkmcnt(1)
	v_mfma_f32_32x32x16_bf16 v[0:15], v[90:93], v[98:101], v[0:15]
	v_mfma_f32_32x32x16_bf16 v[32:47], v[90:93], v[110:113], v[32:47]
	v_mfma_f32_32x32x16_bf16 v[16:31], v[102:105], v[106:109], v[16:31]
	v_mfma_f32_32x32x16_bf16 v[48:63], v[102:105], v[114:117], v[48:63]
	s_waitcnt lgkmcnt(0)
	v_mfma_f32_32x32x16_bf16 v[0:15], v[118:121], v[106:109], v[0:15]
	s_waitcnt vmcnt(0)
	s_barrier
	v_mfma_f32_32x32x16_bf16 v[32:47], v[118:121], v[114:117], v[32:47]
	ds_read_b128 v[90:93], v170 offset:0
	ds_read_b128 v[98:101], v174 offset:16384
	ds_read_b128 v[102:105], v171 offset:0
	ds_read_b128 v[106:109], v175 offset:16384
	ds_read_b128 v[110:113], v174 offset:20480
	ds_read_b128 v[114:117], v175 offset:20480
	v_lshl_add_u64 v[68:69], v[68:69], 0, s[96:97]
	s_add_u32 m0, s94, 0x8000
	s_nop 1
	global_load_lds_dwordx4 v[68:69], off
	v_lshl_add_u64 v[70:71], v[70:71], 0, s[96:97]
	s_add_u32 m0, s94, 0xc000
	s_nop 1
	global_load_lds_dwordx4 v[70:71], off
	v_lshl_add_u64 v[72:73], v[72:73], 0, s[96:97]
	s_add_u32 m0, s94, 0x9000
	s_nop 1
	global_load_lds_dwordx4 v[72:73], off
	v_lshl_add_u64 v[74:75], v[74:75], 0, s[96:97]
	s_add_u32 m0, s94, 0xd000
	s_nop 1
	global_load_lds_dwordx4 v[74:75], off
	v_lshl_add_u64 v[76:77], v[76:77], 0, s[96:97]
	s_add_u32 m0, s94, 0xa000
	s_nop 1
	global_load_lds_dwordx4 v[76:77], off
	v_lshl_add_u64 v[78:79], v[78:79], 0, s[96:97]
	s_add_u32 m0, s94, 0xe000
	s_nop 1
	global_load_lds_dwordx4 v[78:79], off
	v_lshl_add_u64 v[80:81], v[80:81], 0, s[96:97]
	s_add_u32 m0, s94, 0xb000
	s_nop 1
	global_load_lds_dwordx4 v[80:81], off
	v_lshl_add_u64 v[82:83], v[82:83], 0, s[96:97]
	s_add_u32 m0, s94, 0xf000
	s_nop 1
	global_load_lds_dwordx4 v[82:83], off
	s_waitcnt lgkmcnt(4)
	v_mfma_f32_32x32x16_bf16 v[16:31], v[90:93], v[98:101], v[16:31]
	s_waitcnt lgkmcnt(1)
	v_mfma_f32_32x32x16_bf16 v[48:63], v[90:93], v[110:113], v[48:63]
	ds_read_b128 v[90:93], v170 offset:4096
	ds_read_b128 v[118:121], v171 offset:4096
	s_waitcnt lgkmcnt(1)
	v_mfma_f32_32x32x16_bf16 v[0:15], v[90:93], v[98:101], v[0:15]
	v_mfma_f32_32x32x16_bf16 v[32:47], v[90:93], v[110:113], v[32:47]
	v_mfma_f32_32x32x16_bf16 v[16:31], v[102:105], v[106:109], v[16:31]
	v_mfma_f32_32x32x16_bf16 v[48:63], v[102:105], v[114:117], v[48:63]
	s_waitcnt lgkmcnt(0)
	v_mfma_f32_32x32x16_bf16 v[0:15], v[118:121], v[106:109], v[0:15]
	ds_read_b128 v[90:93], v172 offset:0
	ds_read_b128 v[98:101], v176 offset:16384
	ds_read_b128 v[102:105], v173 offset:0
	ds_read_b128 v[106:109], v177 offset:16384
	v_mfma_f32_32x32x16_bf16 v[32:47], v[118:121], v[114:117], v[32:47]
	ds_read_b128 v[110:113], v176 offset:20480
	ds_read_b128 v[114:117], v177 offset:20480
	s_waitcnt lgkmcnt(4)
	v_mfma_f32_32x32x16_bf16 v[16:31], v[90:93], v[98:101], v[16:31]
	s_waitcnt lgkmcnt(1)
	v_mfma_f32_32x32x16_bf16 v[48:63], v[90:93], v[110:113], v[48:63]
	ds_read_b128 v[90:93], v172 offset:4096
	ds_read_b128 v[118:121], v173 offset:4096
	s_waitcnt lgkmcnt(1)
	v_mfma_f32_32x32x16_bf16 v[0:15], v[90:93], v[98:101], v[0:15]
	v_mfma_f32_32x32x16_bf16 v[32:47], v[90:93], v[110:113], v[32:47]
	v_mfma_f32_32x32x16_bf16 v[16:31], v[102:105], v[106:109], v[16:31]
	v_mfma_f32_32x32x16_bf16 v[48:63], v[102:105], v[114:117], v[48:63]
	s_waitcnt lgkmcnt(0)
	v_mfma_f32_32x32x16_bf16 v[0:15], v[118:121], v[106:109], v[0:15]
	s_waitcnt vmcnt(0)
	s_barrier
;     ...
;   bf16* As1 = As + 2 * 128 * 72;
;   bf16* Bs1 = As1 + 128 * 72;
;   G_LOAD(ra0, rb0, 0);
;   if (nk > 1) G_LOAD(ra1, rb1, 1);
;   G_STORE(ra0, rb0, As, Bs);
;   __syncthreads();
;   for (int kt = 0; kt < nk; kt += 2) {
;     if (kt + 2 < nk) G_LOAD(ra0, rb0, kt + 2);
;     if (kt + 1 < nk) G_STORE(ra1, rb1, As1, Bs1);
;     G_COMPUTE(As, Bs);
;     __syncthreads();
;     if (kt + 1 < nk) {
;       if (kt + 3 < nk) G_LOAD(ra1, rb1, kt + 3);
;       if (kt + 2 < nk) G_STORE(ra0, rb0, As, Bs);
;       G_COMPUTE(As1, Bs1);
;       __syncthreads();
;     }
;   }
	v_mfma_f32_32x32x16_bf16 v[32:47], v[118:121], v[114:117], v[32:47]
	ds_read_b128 v[90:93], v170 offset:32768
	ds_read_b128 v[98:101], v174 offset:49152
	ds_read_b128 v[102:105], v171 offset:32768
	ds_read_b128 v[106:109], v175 offset:49152
	ds_read_b128 v[110:113], v174 offset:53248
	ds_read_b128 v[114:117], v175 offset:53248
	v_lshl_add_u64 v[68:69], v[68:69], 0, s[96:97]
	s_add_u32 m0, s94, 0x0
	s_nop 1
	global_load_lds_dwordx4 v[68:69], off
	v_lshl_add_u64 v[70:71], v[70:71], 0, s[96:97]
	s_add_u32 m0, s94, 0x4000
	s_nop 1
	global_load_lds_dwordx4 v[70:71], off
	v_lshl_add_u64 v[72:73], v[72:73], 0, s[96:97]
	s_add_u32 m0, s94, 0x1000
	s_nop 1
	global_load_lds_dwordx4 v[72:73], off
	v_lshl_add_u64 v[74:75], v[74:75], 0, s[96:97]
	s_add_u32 m0, s94, 0x5000
	s_nop 1
	global_load_lds_dwordx4 v[74:75], off
	v_lshl_add_u64 v[76:77], v[76:77], 0, s[96:97]
	s_add_u32 m0, s94, 0x2000
	s_nop 1
	global_load_lds_dwordx4 v[76:77], off
	v_lshl_add_u64 v[78:79], v[78:79], 0, s[96:97]
	s_add_u32 m0, s94, 0x6000
	s_nop 1
	global_load_lds_dwordx4 v[78:79], off
	v_lshl_add_u64 v[80:81], v[80:81], 0, s[96:97]
	s_add_u32 m0, s94, 0x3000
	s_nop 1
	global_load_lds_dwordx4 v[80:81], off
	v_lshl_add_u64 v[82:83], v[82:83], 0, s[96:97]
	s_add_u32 m0, s94, 0x7000
	s_nop 1
	global_load_lds_dwordx4 v[82:83], off
	s_waitcnt lgkmcnt(4)
	v_mfma_f32_32x32x16_bf16 v[16:31], v[90:93], v[98:101], v[16:31]
	s_waitcnt lgkmcnt(1)
	v_mfma_f32_32x32x16_bf16 v[48:63], v[90:93], v[110:113], v[48:63]
	ds_read_b128 v[90:93], v170 offset:36864
	ds_read_b128 v[118:121], v171 offset:36864
	s_waitcnt lgkmcnt(1)
	v_mfma_f32_32x32x16_bf16 v[0:15], v[90:93], v[98:101], v[0:15]
	v_mfma_f32_32x32x16_bf16 v[32:47], v[90:93], v[110:113], v[32:47]
	v_mfma_f32_32x32x16_bf16 v[16:31], v[102:105], v[106:109], v[16:31]
	v_mfma_f32_32x32x16_bf16 v[48:63], v[102:105], v[114:117], v[48:63]
	s_waitcnt lgkmcnt(0)
	v_mfma_f32_32x32x16_bf16 v[0:15], v[118:121], v[106:109], v[0:15]
	ds_read_b128 v[90:93], v172 offset:32768
	ds_read_b128 v[98:101], v176 offset:49152
	ds_read_b128 v[102:105], v173 offset:32768
	ds_read_b128 v[106:109], v177 offset:49152
	v_mfma_f32_32x32x16_bf16 v[32:47], v[118:121], v[114:117], v[32:47]
	ds_read_b128 v[110:113], v176 offset:53248
	ds_read_b128 v[114:117], v177 offset:53248
	s_waitcnt lgkmcnt(4)
	v_mfma_f32_32x32x16_bf16 v[16:31], v[90:93], v[98:101], v[16:31]
	s_waitcnt lgkmcnt(1)
	v_mfma_f32_32x32x16_bf16 v[48:63], v[90:93], v[110:113], v[48:63]
	ds_read_b128 v[90:93], v172 offset:36864
	ds_read_b128 v[118:121], v173 offset:36864
	s_waitcnt lgkmcnt(1)
	v_mfma_f32_32x32x16_bf16 v[0:15], v[90:93], v[98:101], v[0:15]
	v_mfma_f32_32x32x16_bf16 v[32:47], v[90:93], v[110:113], v[32:47]
	v_mfma_f32_32x32x16_bf16 v[16:31], v[102:105], v[106:109], v[16:31]
	v_mfma_f32_32x32x16_bf16 v[48:63], v[102:105], v[114:117], v[48:63]
	s_nop 0
	s_nop 0
	s_nop 0
	s_nop 0
	s_nop 0
	s_nop 0
	s_nop 0
	s_waitcnt lgkmcnt(0)
	s_waitcnt vmcnt(0)
	s_barrier
	v_lshl_add_u64 v[68:69], v[68:69], 0, s[96:97]
	s_add_u32 m0, s94, 0x8000
	s_nop 1
	global_load_lds_dwordx4 v[68:69], off
	v_lshl_add_u64 v[70:71], v[70:71], 0, s[96:97]
	s_add_u32 m0, s94, 0xc000
	s_nop 1
	global_load_lds_dwordx4 v[70:71], off
	v_lshl_add_u64 v[72:73], v[72:73], 0, s[96:97]
	s_add_u32 m0, s94, 0x9000
	s_nop 1
	global_load_lds_dwordx4 v[72:73], off
	v_lshl_add_u64 v[74:75], v[74:75], 0, s[96:97]
	s_add_u32 m0, s94, 0xd000
	s_nop 1
	global_load_lds_dwordx4 v[74:75], off
	v_lshl_add_u64 v[76:77], v[76:77], 0, s[96:97]
	s_add_u32 m0, s94, 0xa000
	s_nop 1
	global_load_lds_dwordx4 v[76:77], off
	v_lshl_add_u64 v[78:79], v[78:79], 0, s[96:97]
	s_add_u32 m0, s94, 0xe000
	s_nop 1
	global_load_lds_dwordx4 v[78:79], off
	v_lshl_add_u64 v[80:81], v[80:81], 0, s[96:97]
	s_add_u32 m0, s94, 0xb000
	s_nop 1
	global_load_lds_dwordx4 v[80:81], off
	v_lshl_add_u64 v[82:83], v[82:83], 0, s[96:97]
	s_add_u32 m0, s94, 0xf000
	s_nop 1
	global_load_lds_dwordx4 v[82:83], off
	v_mfma_f32_32x32x16_bf16 v[0:15], v[118:121], v[106:109], v[0:15]
	ds_read_b128 v[68:71], v170 offset:0
	ds_read_b128 v[72:75], v174 offset:16384
	ds_read_b128 v[76:79], v171 offset:0
	ds_read_b128 v[80:83], v175 offset:16384
	ds_read_b128 v[90:93], v174 offset:20480
	ds_read_b128 v[98:101], v175 offset:20480
	v_mfma_f32_32x32x16_bf16 v[32:47], v[118:121], v[114:117], v[32:47]
	s_waitcnt lgkmcnt(4)
	v_mfma_f32_32x32x16_bf16 v[16:31], v[68:71], v[72:75], v[16:31]
	s_waitcnt lgkmcnt(1)
	v_mfma_f32_32x32x16_bf16 v[48:63], v[68:71], v[90:93], v[48:63]
	ds_read_b128 v[68:71], v170 offset:4096
	ds_read_b128 v[102:105], v171 offset:4096
	s_waitcnt lgkmcnt(1)
	v_mfma_f32_32x32x16_bf16 v[0:15], v[68:71], v[72:75], v[0:15]
	v_mfma_f32_32x32x16_bf16 v[32:47], v[68:71], v[90:93], v[32:47]
	v_mfma_f32_32x32x16_bf16 v[16:31], v[76:79], v[80:83], v[16:31]
	v_mfma_f32_32x32x16_bf16 v[48:63], v[76:79], v[98:101], v[48:63]
	s_waitcnt lgkmcnt(0)
	v_mfma_f32_32x32x16_bf16 v[0:15], v[102:105], v[80:83], v[0:15]
	ds_read_b128 v[68:71], v172 offset:0
	ds_read_b128 v[72:75], v176 offset:16384
	ds_read_b128 v[76:79], v173 offset:0
	ds_read_b128 v[80:83], v177 offset:16384
	v_mfma_f32_32x32x16_bf16 v[32:47], v[102:105], v[98:101], v[32:47]
	ds_read_b128 v[90:93], v176 offset:20480
	ds_read_b128 v[98:101], v177 offset:20480
	s_waitcnt lgkmcnt(4)
	v_mfma_f32_32x32x16_bf16 v[16:31], v[68:71], v[72:75], v[16:31]
	s_waitcnt lgkmcnt(1)
	v_mfma_f32_32x32x16_bf16 v[48:63], v[68:71], v[90:93], v[48:63]
	ds_read_b128 v[68:71], v172 offset:4096
	ds_read_b128 v[102:105], v173 offset:4096
	s_waitcnt lgkmcnt(0)
	s_waitcnt vmcnt(0)
	s_barrier
; DEVI int accrow(int r, int lane) { return (r & 3) + 8 * (r >> 2) + 4 * (lane >> 5); }
; DEVI void gemm_epi_ssd_in(const Params& p, f32x16 (&acc)[2][2], int rbase, int cbase, int lane) {
;     ...
;   } else {
;     float* dtr = (float*)(ar + S_DTRAW);
; #pragma unroll
;     for (int i = 0; i < 2; ++i)
; #pragma unroll
;       for (int r = 0; r < 16; ++r) {
;         const int row = rbase + i * 32 + accrow(r, lane);
;         if (row < M && cbase == 6144) dtr[(size_t)row * 32 + d] = acc[i][0][r];
;       }
;     ...
;   bf16* As1 = As + 2 * 128 * 72;
;   bf16* Bs1 = As1 + 128 * 72;
;   G_LOAD(ra0, rb0, 0);
;   if (nk > 1) G_LOAD(ra1, rb1, 1);
;   G_STORE(ra0, rb0, As, Bs);
;   __syncthreads();
;   for (int kt = 0; kt < nk; kt += 2) {
;     if (kt + 2 < nk) G_LOAD(ra0, rb0, kt + 2);
;     if (kt + 1 < nk) G_STORE(ra1, rb1, As1, Bs1);
;     G_COMPUTE(As, Bs);
;     __syncthreads();
;     if (kt + 1 < nk) {
;       if (kt + 3 < nk) G_LOAD(ra1, rb1, kt + 3);
;       if (kt + 2 < nk) G_STORE(ra0, rb0, As, Bs);
;       G_COMPUTE(As1, Bs1);
;       __syncthreads();
;     }
;   }
	v_mfma_f32_32x32x16_bf16 v[0:15], v[68:71], v[72:75], v[0:15]
	v_mfma_f32_32x32x16_bf16 v[16:31], v[76:79], v[80:83], v[16:31]
	v_mfma_f32_32x32x16_bf16 v[48:63], v[76:79], v[98:101], v[48:63]
	v_mfma_f32_32x32x16_bf16 v[32:47], v[68:71], v[90:93], v[32:47]
	v_mfma_f32_32x32x16_bf16 v[0:15], v[102:105], v[80:83], v[0:15]
	ds_read_b128 v[68:71], v170 offset:32768
	ds_read_b128 v[72:75], v174 offset:49152
	ds_read_b128 v[76:79], v175 offset:49152
	ds_read_b128 v[80:83], v171 offset:32768
	ds_read_b128 v[90:93], v174 offset:53248
	s_waitcnt lgkmcnt(3)
	v_mfma_f32_32x32x16_bf16 v[16:31], v[68:71], v[72:75], v[16:31]
	s_waitcnt lgkmcnt(0)
	v_mfma_f32_32x32x16_bf16 v[48:63], v[68:71], v[90:93], v[48:63]
	ds_read_b128 v[68:71], v170 offset:36864
	v_mfma_f32_32x32x16_bf16 v[32:47], v[102:105], v[98:101], v[32:47]
	s_waitcnt lgkmcnt(0)
	v_mfma_f32_32x32x16_bf16 v[0:15], v[68:71], v[72:75], v[0:15]
	ds_read_b128 v[72:75], v171 offset:36864
	v_mfma_f32_32x32x16_bf16 v[32:47], v[68:71], v[90:93], v[32:47]
	ds_read_b128 v[68:71], v175 offset:53248
	v_mfma_f32_32x32x16_bf16 v[16:31], v[80:83], v[76:79], v[16:31]
	s_waitcnt lgkmcnt(0)
	v_mfma_f32_32x32x16_bf16 v[48:63], v[80:83], v[68:71], v[48:63]
	v_mfma_f32_32x32x16_bf16 v[0:15], v[72:75], v[76:79], v[0:15]
	v_mfma_f32_32x32x16_bf16 v[32:47], v[72:75], v[68:71], v[32:47]
	ds_read_b128 v[68:71], v172 offset:32768
	ds_read_b128 v[72:75], v176 offset:49152
	ds_read_b128 v[76:79], v176 offset:53248
	s_waitcnt lgkmcnt(1)
	v_mfma_f32_32x32x16_bf16 v[16:31], v[68:71], v[72:75], v[16:31]
	s_waitcnt lgkmcnt(0)
	v_mfma_f32_32x32x16_bf16 v[48:63], v[68:71], v[76:79], v[48:63]
	ds_read_b128 v[68:71], v172 offset:36864
	s_waitcnt lgkmcnt(0)
	v_mfma_f32_32x32x16_bf16 v[0:15], v[68:71], v[72:75], v[0:15]
	v_mfma_f32_32x32x16_bf16 v[32:47], v[68:71], v[76:79], v[32:47]
	ds_read_b128 v[68:71], v173 offset:32768
	ds_read_b128 v[72:75], v177 offset:49152
	ds_read_b128 v[76:79], v177 offset:53248
	ds_read_b128 v[80:83], v173 offset:36864
	v_and_b32_e32 v66, 64, v86
	v_and_b32_e32 v67, 63, v86
	v_subrev_u32_e32 v66, s3, v66
	v_add_u32_e32 v66, s17, v66
	s_waitcnt lgkmcnt(2)
	v_mfma_f32_32x32x16_bf16 v[16:31], v[68:71], v[72:75], v[16:31]
	s_waitcnt lgkmcnt(0)
	s_barrier
	v_mfma_f32_32x32x16_bf16 v[48:63], v[68:71], v[76:79], v[48:63]
	v_add_u32_e32 v70, s2, v88
	s_movk_i32 s2, 0x17ff
	v_cmp_lt_i32_e32 vcc, s2, v66
	v_mfma_f32_32x32x16_bf16 v[0:15], v[80:83], v[72:75], v[0:15]
	v_lshrrev_b32_e32 v72, 3, v67
	v_and_b32_e32 v71, 4, v72
	v_mfma_f32_32x32x16_bf16 v[32:47], v[80:83], v[76:79], v[32:47]
	s_and_saveexec_b64 s[2:3], vcc
	s_xor_b64 s[2:3], exec, s[2:3]
	s_cbranch_execz .LBB0_4899
	s_movk_i32 s6, 0x1800
	v_lshlrev_b32_e32 v96, 2, v87
	v_cmp_eq_u32_e32 vcc, s6, v66
	s_nop 5
	v_lshl_add_u64 v[32:33], s[4:5], 0, v[96:97]
	s_mov_b64 s[6:7], 0x2cb5c000
	v_or_b32_e32 v34, v70, v71
	v_lshl_add_u64 v[32:33], v[32:33], 0, s[6:7]
	v_cmp_gt_i32_e64 s[6:7], s90, v34
	s_and_b64 s[20:21], vcc, s[6:7]
	s_and_saveexec_b64 s[6:7], s[20:21]
	s_cbranch_execz .LBB0_4836
	v_ashrrev_i32_e32 v35, 31, v34
	v_lshlrev_b64 v[34:35], 7, v[34:35]
	v_lshl_add_u64 v[34:35], v[32:33], 0, v[34:35]
	global_store_dword v[34:35], v16, off
